# hand-written DeltaNet D1 (gate scan, KK/attn MFMA from LDS-staged tiles, row-wise qg, quad-broadcast DPP solve, LDS-transposed w stores) replaces both compiled dn_d1 calls
# speedup vs baseline: 1.0132x; 1.0132x over previous
; #define PIN16(a, o) asm volatile("" : "+v"(a[(o)+0]), "+v"(a[(o)+1]), "+v"(a[(o)+2]), "+v"(a[(o)+3]), "+v"(a[(o)+4]), "+v"(a[(o)+5]), "+v"(a[(o)+6]), "+v"(a[(o)+7]), \
;     "+v"(a[(o)+8]), "+v"(a[(o)+9]), "+v"(a[(o)+10]), "+v"(a[(o)+11]), "+v"(a[(o)+12]), "+v"(a[(o)+13]), "+v"(a[(o)+14]), "+v"(a[(o)+15]))
;     template <class Tp> __device__ __forceinline__ Tp* W(size_t off) const { return (Tp*)(ws + off); }
; __device__ void prep_gla(const Ctx& c, int ck, int blk) {
;     ...
;         const int ch = (blk - 1) * 512 + tid, h = ch >> 8, v = ch & 255;
;         bf16_t* gVT = c.W<bf16_t>(WS_GVT);
;         unsigned e[64];
; #pragma unroll
;         for (int l = 0; l < 64; ++l) e[l] = proj[(size_t)(t0 + l) * NP + C_GV + ch];
;         PIN16(e, 0); PIN16(e, 16); PIN16(e, 32); PIN16(e, 48);
.LBB0_666:
	s_or_b64 exec, exec, s[0:1]
	v_readlane_b32 s0, v249, 53
	v_readlane_b32 s1, v249, 54
	s_waitcnt vmcnt(63) expcnt(7) lgkmcnt(15)
	s_barrier
	v_lshl_add_u64 v[0:1], s[0:1], 0, v[18:19]
	v_readlane_b32 s0, v249, 57
	v_add_co_u32_e32 v0, vcc, 0x3000, v0
	v_readlane_b32 s1, v249, 58
	s_nop 0
	v_addc_co_u32_e32 v1, vcc, 0, v1, vcc
	v_lshl_add_u64 v[2:3], s[0:1], 0, v[18:19]
	v_add_co_u32_e32 v2, vcc, 0x3000, v2
	v_readlane_b32 s0, v249, 61
	s_nop 0
	v_addc_co_u32_e32 v3, vcc, 0, v3, vcc
	v_readlane_b32 s1, v249, 62
	global_load_ushort v0, v[0:1], off offset:3136
	v_ashrrev_i32_e32 v16, 8, v16
	global_load_ushort v1, v[2:3], off offset:3136
	v_lshl_add_u64 v[2:3], s[0:1], 0, v[18:19]
	v_readlane_b32 s0, v254, 1
	v_add_co_u32_e32 v2, vcc, 0x3000, v2
	v_readlane_b32 s1, v254, 2
	s_nop 0
	v_addc_co_u32_e32 v3, vcc, 0, v3, vcc
	v_lshl_add_u64 v[4:5], s[0:1], 0, v[18:19]
	v_add_co_u32_e32 v4, vcc, 0x3000, v4
	v_readlane_b32 s0, v254, 5
	s_nop 0
	v_addc_co_u32_e32 v5, vcc, 0, v5, vcc
	v_readlane_b32 s1, v254, 6
	global_load_ushort v2, v[2:3], off offset:3136
	v_and_b32_e32 v196, 0xff, v144
	global_load_ushort v3, v[4:5], off offset:3136
	v_lshl_add_u64 v[4:5], s[0:1], 0, v[18:19]
	v_readlane_b32 s0, v254, 9
	v_add_co_u32_e32 v4, vcc, 0x3000, v4
	v_readlane_b32 s1, v254, 10
	s_nop 0
	v_addc_co_u32_e32 v5, vcc, 0, v5, vcc
	v_lshl_add_u64 v[6:7], s[0:1], 0, v[18:19]
	v_add_co_u32_e32 v6, vcc, 0x3000, v6
	v_readlane_b32 s0, v254, 13
	s_nop 0
	v_addc_co_u32_e32 v7, vcc, 0, v7, vcc
	v_readlane_b32 s1, v254, 14
	global_load_ushort v4, v[4:5], off offset:3136
	v_cmp_gt_u32_e64 s[72:73], 64, v196
	global_load_ushort v5, v[6:7], off offset:3136
	v_lshl_add_u64 v[6:7], s[0:1], 0, v[18:19]
	v_readlane_b32 s0, v254, 17
	v_add_co_u32_e32 v6, vcc, 0x3000, v6
	v_readlane_b32 s1, v254, 18
	s_nop 0
	v_addc_co_u32_e32 v7, vcc, 0, v7, vcc
	v_lshl_add_u64 v[8:9], s[0:1], 0, v[18:19]
	v_add_co_u32_e32 v8, vcc, 0x3000, v8
	v_readlane_b32 s0, v254, 21
	s_nop 0
	v_addc_co_u32_e32 v9, vcc, 0, v9, vcc
	v_readlane_b32 s1, v254, 22
	global_load_ushort v6, v[6:7], off offset:3136
	s_nop 0
	global_load_ushort v7, v[8:9], off offset:3136
	v_lshl_add_u64 v[8:9], s[0:1], 0, v[18:19]
	v_readlane_b32 s0, v254, 25
	v_add_co_u32_e32 v8, vcc, 0x3000, v8
	v_readlane_b32 s1, v254, 26
	s_nop 0
	v_addc_co_u32_e32 v9, vcc, 0, v9, vcc
	v_lshl_add_u64 v[10:11], s[0:1], 0, v[18:19]
	v_add_co_u32_e32 v10, vcc, 0x3000, v10
	v_readlane_b32 s0, v254, 29
	s_nop 0
	v_addc_co_u32_e32 v11, vcc, 0, v11, vcc
	v_readlane_b32 s1, v254, 30
	global_load_ushort v8, v[8:9], off offset:3136
	s_nop 0
	global_load_ushort v9, v[10:11], off offset:3136
	v_lshl_add_u64 v[10:11], s[0:1], 0, v[18:19]
	v_readlane_b32 s0, v254, 35
	v_add_co_u32_e32 v10, vcc, 0x3000, v10
	v_readlane_b32 s1, v254, 36
	s_nop 0
	v_addc_co_u32_e32 v11, vcc, 0, v11, vcc
	v_lshl_add_u64 v[12:13], s[0:1], 0, v[18:19]
	v_add_co_u32_e32 v12, vcc, 0x3000, v12
	v_readlane_b32 s0, v254, 39
	s_nop 0
	v_addc_co_u32_e32 v13, vcc, 0, v13, vcc
	v_readlane_b32 s1, v254, 40
	global_load_ushort v10, v[10:11], off offset:3136
	s_nop 0
	global_load_ushort v11, v[12:13], off offset:3136
	v_lshl_add_u64 v[12:13], s[0:1], 0, v[18:19]
	v_readlane_b32 s0, v254, 43
	v_add_co_u32_e32 v12, vcc, 0x3000, v12
	v_readlane_b32 s1, v254, 44
	s_nop 0
	v_addc_co_u32_e32 v13, vcc, 0, v13, vcc
	v_lshl_add_u64 v[14:15], s[0:1], 0, v[18:19]
	v_add_co_u32_e32 v14, vcc, 0x3000, v14
	v_readlane_b32 s0, v254, 47
	s_nop 0
	v_addc_co_u32_e32 v15, vcc, 0, v15, vcc
	v_readlane_b32 s1, v254, 48
	global_load_ushort v12, v[12:13], off offset:3136
	s_nop 0
	global_load_ushort v13, v[14:15], off offset:3136
	v_lshl_add_u64 v[14:15], s[0:1], 0, v[18:19]
	v_readlane_b32 s0, v254, 51
	v_add_co_u32_e32 v14, vcc, 0x3000, v14
	v_readlane_b32 s1, v254, 52
	s_nop 0
	v_addc_co_u32_e32 v15, vcc, 0, v15, vcc
	v_lshl_add_u64 v[22:23], s[0:1], 0, v[18:19]
	v_add_co_u32_e32 v22, vcc, 0x3000, v22
	v_readlane_b32 s0, v254, 55
	s_nop 0
	v_addc_co_u32_e32 v23, vcc, 0, v23, vcc
	v_readlane_b32 s1, v254, 56
	global_load_ushort v14, v[14:15], off offset:3136
	s_nop 0
	global_load_ushort v15, v[22:23], off offset:3136
	v_lshl_add_u64 v[22:23], s[0:1], 0, v[18:19]
	v_add_co_u32_e32 v22, vcc, 0x3000, v22
	v_readlane_b32 s0, v254, 59
	s_nop 0
	v_addc_co_u32_e32 v23, vcc, 0, v23, vcc
	v_readlane_b32 s1, v254, 60
	global_load_ushort v17, v[22:23], off offset:3136
	s_nop 0
	v_lshl_add_u64 v[22:23], s[0:1], 0, v[18:19]
	v_add_co_u32_e32 v22, vcc, 0x3000, v22
	v_readlane_b32 s0, v254, 63
	s_nop 0
	v_addc_co_u32_e32 v23, vcc, 0, v23, vcc
	v_readlane_b32 s1, v250, 0
	global_load_ushort v21, v[22:23], off offset:3136
	s_nop 0
	v_lshl_add_u64 v[22:23], s[0:1], 0, v[18:19]
	v_readlane_b32 s0, v250, 3
	v_add_co_u32_e32 v22, vcc, 0x3000, v22
	v_readlane_b32 s1, v250, 4
	s_nop 0
	v_addc_co_u32_e32 v23, vcc, 0, v23, vcc
	v_lshl_add_u64 v[24:25], s[0:1], 0, v[18:19]
	v_add_co_u32_e32 v24, vcc, 0x3000, v24
	v_readlane_b32 s0, v250, 7
	s_nop 0
	v_addc_co_u32_e32 v25, vcc, 0, v25, vcc
	v_readlane_b32 s1, v250, 8
	global_load_ushort v22, v[22:23], off offset:3136
	s_nop 0
	global_load_ushort v23, v[24:25], off offset:3136
	v_lshl_add_u64 v[24:25], s[0:1], 0, v[18:19]
	v_readlane_b32 s0, v250, 11
	v_add_co_u32_e32 v24, vcc, 0x3000, v24
	v_readlane_b32 s1, v250, 12
	s_nop 0
	v_addc_co_u32_e32 v25, vcc, 0, v25, vcc
	v_lshl_add_u64 v[26:27], s[0:1], 0, v[18:19]
	v_add_co_u32_e32 v26, vcc, 0x3000, v26
	v_readlane_b32 s0, v250, 15
	s_nop 0
	v_addc_co_u32_e32 v27, vcc, 0, v27, vcc
	v_readlane_b32 s1, v250, 16
	global_load_ushort v24, v[24:25], off offset:3136
	s_nop 0
	global_load_ushort v25, v[26:27], off offset:3136
; #define PIN16(a, o) asm volatile("" : "+v"(a[(o)+0]), "+v"(a[(o)+1]), "+v"(a[(o)+2]), "+v"(a[(o)+3]), "+v"(a[(o)+4]), "+v"(a[(o)+5]), "+v"(a[(o)+6]), "+v"(a[(o)+7]), \
;     "+v"(a[(o)+8]), "+v"(a[(o)+9]), "+v"(a[(o)+10]), "+v"(a[(o)+11]), "+v"(a[(o)+12]), "+v"(a[(o)+13]), "+v"(a[(o)+14]), "+v"(a[(o)+15]))
; __device__ void prep_gla(const Ctx& c, int ck, int blk) {
;     ...
;         unsigned e[64];
; #pragma unroll
;         for (int l = 0; l < 64; ++l) e[l] = proj[(size_t)(t0 + l) * NP + C_GV + ch];
;         PIN16(e, 0); PIN16(e, 16); PIN16(e, 32); PIN16(e, 48);
	v_lshl_add_u64 v[26:27], s[0:1], 0, v[18:19]
	v_readlane_b32 s0, v250, 19
	v_add_co_u32_e32 v26, vcc, 0x3000, v26
	v_readlane_b32 s1, v250, 20
	s_nop 0
	v_addc_co_u32_e32 v27, vcc, 0, v27, vcc
	v_lshl_add_u64 v[28:29], s[0:1], 0, v[18:19]
	v_add_co_u32_e32 v28, vcc, 0x3000, v28
	v_readlane_b32 s0, v250, 23
	s_nop 0
	v_addc_co_u32_e32 v29, vcc, 0, v29, vcc
	v_readlane_b32 s1, v250, 24
	global_load_ushort v26, v[26:27], off offset:3136
	s_nop 0
	global_load_ushort v27, v[28:29], off offset:3136
	v_lshl_add_u64 v[28:29], s[0:1], 0, v[18:19]
	v_readlane_b32 s0, v250, 27
	v_add_co_u32_e32 v28, vcc, 0x3000, v28
	v_readlane_b32 s1, v250, 28
	s_nop 0
	v_addc_co_u32_e32 v29, vcc, 0, v29, vcc
	v_lshl_add_u64 v[30:31], s[0:1], 0, v[18:19]
	v_add_co_u32_e32 v30, vcc, 0x3000, v30
	v_readlane_b32 s0, v250, 31
	s_nop 0
	v_addc_co_u32_e32 v31, vcc, 0, v31, vcc
	v_readlane_b32 s1, v250, 32
	global_load_ushort v28, v[28:29], off offset:3136
	s_nop 0
	global_load_ushort v29, v[30:31], off offset:3136
	v_lshl_add_u64 v[30:31], s[0:1], 0, v[18:19]
	v_readlane_b32 s0, v250, 35
	v_add_co_u32_e32 v30, vcc, 0x3000, v30
	v_readlane_b32 s1, v250, 36
	s_nop 0
	v_addc_co_u32_e32 v31, vcc, 0, v31, vcc
	v_lshl_add_u64 v[32:33], s[0:1], 0, v[18:19]
	v_add_co_u32_e32 v32, vcc, 0x3000, v32
	v_readlane_b32 s0, v250, 39
	s_nop 0
	v_addc_co_u32_e32 v33, vcc, 0, v33, vcc
	v_readlane_b32 s1, v250, 40
	global_load_ushort v30, v[30:31], off offset:3136
	s_nop 0
	global_load_ushort v31, v[32:33], off offset:3136
	v_lshl_add_u64 v[32:33], s[0:1], 0, v[18:19]
	v_readlane_b32 s0, v250, 43
	v_add_co_u32_e32 v32, vcc, 0x3000, v32
	v_readlane_b32 s1, v250, 44
	s_nop 0
	v_addc_co_u32_e32 v33, vcc, 0, v33, vcc
	v_lshl_add_u64 v[34:35], s[0:1], 0, v[18:19]
	v_add_co_u32_e32 v34, vcc, 0x3000, v34
	v_readlane_b32 s0, v250, 47
	s_nop 0
	v_addc_co_u32_e32 v35, vcc, 0, v35, vcc
	v_readlane_b32 s1, v250, 48
	global_load_ushort v32, v[32:33], off offset:3136
	s_nop 0
	global_load_ushort v33, v[34:35], off offset:3136
	v_lshl_add_u64 v[34:35], s[0:1], 0, v[18:19]
	v_readlane_b32 s0, v250, 51
	v_add_co_u32_e32 v34, vcc, 0x3000, v34
	v_readlane_b32 s1, v250, 52
	s_nop 0
	v_addc_co_u32_e32 v35, vcc, 0, v35, vcc
	v_lshl_add_u64 v[36:37], s[0:1], 0, v[18:19]
	v_add_co_u32_e32 v36, vcc, 0x3000, v36
	v_readlane_b32 s0, v250, 55
	s_nop 0
	v_addc_co_u32_e32 v37, vcc, 0, v37, vcc
	v_readlane_b32 s1, v250, 56
	global_load_ushort v34, v[34:35], off offset:3136
	s_nop 0
	global_load_ushort v35, v[36:37], off offset:3136
	v_lshl_add_u64 v[36:37], s[0:1], 0, v[18:19]
	v_readlane_b32 s0, v250, 59
	v_add_co_u32_e32 v36, vcc, 0x3000, v36
	v_readlane_b32 s1, v250, 60
	s_nop 0
	v_addc_co_u32_e32 v37, vcc, 0, v37, vcc
	v_lshl_add_u64 v[38:39], s[0:1], 0, v[18:19]
	v_add_co_u32_e32 v38, vcc, 0x3000, v38
	v_readlane_b32 s0, v251, 1
	s_nop 0
	v_addc_co_u32_e32 v39, vcc, 0, v39, vcc
	v_readlane_b32 s1, v251, 2
	global_load_ushort v36, v[36:37], off offset:3136
	s_nop 0
	global_load_ushort v37, v[38:39], off offset:3136
	v_lshl_add_u64 v[38:39], s[0:1], 0, v[18:19]
	v_readlane_b32 s0, v251, 5
	v_add_co_u32_e32 v38, vcc, 0x3000, v38
	v_readlane_b32 s1, v251, 6
	s_nop 0
	v_addc_co_u32_e32 v39, vcc, 0, v39, vcc
	v_lshl_add_u64 v[40:41], s[0:1], 0, v[18:19]
	v_add_co_u32_e32 v40, vcc, 0x3000, v40
	v_readlane_b32 s0, v251, 9
	s_nop 0
	v_addc_co_u32_e32 v41, vcc, 0, v41, vcc
	v_readlane_b32 s1, v251, 10
	global_load_ushort v38, v[38:39], off offset:3136
	s_nop 0
	global_load_ushort v39, v[40:41], off offset:3136
	v_lshl_add_u64 v[40:41], s[0:1], 0, v[18:19]
	v_readlane_b32 s0, v251, 13
	v_add_co_u32_e32 v40, vcc, 0x3000, v40
	v_readlane_b32 s1, v251, 14
	s_nop 0
	v_addc_co_u32_e32 v41, vcc, 0, v41, vcc
	v_lshl_add_u64 v[42:43], s[0:1], 0, v[18:19]
	v_add_co_u32_e32 v42, vcc, 0x3000, v42
	v_readlane_b32 s0, v251, 17
	s_nop 0
	v_addc_co_u32_e32 v43, vcc, 0, v43, vcc
	v_readlane_b32 s1, v251, 18
	global_load_ushort v40, v[40:41], off offset:3136
	s_nop 0
	global_load_ushort v41, v[42:43], off offset:3136
	v_lshl_add_u64 v[42:43], s[0:1], 0, v[18:19]
	v_readlane_b32 s0, v251, 21
	v_add_co_u32_e32 v42, vcc, 0x3000, v42
	v_readlane_b32 s1, v251, 22
	s_nop 0
	v_addc_co_u32_e32 v43, vcc, 0, v43, vcc
	v_lshl_add_u64 v[44:45], s[0:1], 0, v[18:19]
	v_add_co_u32_e32 v44, vcc, 0x3000, v44
	v_readlane_b32 s0, v251, 25
	s_nop 0
	v_addc_co_u32_e32 v45, vcc, 0, v45, vcc
	v_readlane_b32 s1, v251, 26
	global_load_ushort v42, v[42:43], off offset:3136
	s_nop 0
	global_load_ushort v43, v[44:45], off offset:3136
	v_lshl_add_u64 v[44:45], s[0:1], 0, v[18:19]
	v_add_co_u32_e32 v44, vcc, 0x3000, v44
	v_readlane_b32 s0, v251, 31
	s_nop 0
	v_addc_co_u32_e32 v45, vcc, 0, v45, vcc
	v_readlane_b32 s1, v251, 32
	global_load_ushort v46, v[44:45], off offset:3136
	s_nop 0
	v_lshl_add_u64 v[44:45], s[0:1], 0, v[18:19]
	v_add_co_u32_e32 v44, vcc, 0x3000, v44
	v_readlane_b32 s0, v251, 37
	s_nop 0
	v_addc_co_u32_e32 v45, vcc, 0, v45, vcc
	v_readlane_b32 s1, v251, 38
	global_load_ushort v47, v[44:45], off offset:3136
	s_nop 0
	v_lshl_add_u64 v[44:45], s[0:1], 0, v[18:19]
	v_add_co_u32_e32 v44, vcc, 0x3000, v44
	v_readlane_b32 s0, v251, 43
	s_nop 0
	v_addc_co_u32_e32 v45, vcc, 0, v45, vcc
	v_readlane_b32 s1, v251, 44
	global_load_ushort v48, v[44:45], off offset:3136
	s_nop 0
	v_lshl_add_u64 v[44:45], s[0:1], 0, v[18:19]
	v_add_co_u32_e32 v44, vcc, 0x3000, v44
	v_readlane_b32 s0, v251, 49
	s_nop 0
	v_addc_co_u32_e32 v45, vcc, 0, v45, vcc
	v_readlane_b32 s1, v251, 50
	global_load_ushort v49, v[44:45], off offset:3136
	s_nop 0
	v_lshl_add_u64 v[44:45], s[0:1], 0, v[18:19]
	v_add_co_u32_e32 v44, vcc, 0x3000, v44
	v_readlane_b32 s0, v251, 55
	s_nop 0
; #define PIN16(a, o) asm volatile("" : "+v"(a[(o)+0]), "+v"(a[(o)+1]), "+v"(a[(o)+2]), "+v"(a[(o)+3]), "+v"(a[(o)+4]), "+v"(a[(o)+5]), "+v"(a[(o)+6]), "+v"(a[(o)+7]), \
;     "+v"(a[(o)+8]), "+v"(a[(o)+9]), "+v"(a[(o)+10]), "+v"(a[(o)+11]), "+v"(a[(o)+12]), "+v"(a[(o)+13]), "+v"(a[(o)+14]), "+v"(a[(o)+15]))
; __device__ void prep_gla(const Ctx& c, int ck, int blk) {
;     ...
;         for (int l = 0; l < 64; ++l) e[l] = proj[(size_t)(t0 + l) * NP + C_GV + ch];
;         PIN16(e, 0); PIN16(e, 16); PIN16(e, 32); PIN16(e, 48);
; #pragma unroll
;         for (int l0 = 0; l0 < 64; l0 += 8) {
;             u32x4 a; a.x = e[l0] | (e[l0 + 1] << 16); a.y = e[l0 + 2] | (e[l0 + 3] << 16); a.z = e[l0 + 4] | (e[l0 + 5] << 16); a.w = e[l0 + 6] | (e[l0 + 7] << 16);
;             *(u32x4*)(gVT + ((size_t)(ck * 4 + h) * 256 + v) * 64 + l0) = a;
;         }
	v_addc_co_u32_e32 v45, vcc, 0, v45, vcc
	v_readlane_b32 s1, v251, 56
	global_load_ushort v50, v[44:45], off offset:3136
	s_nop 0
	v_lshl_add_u64 v[44:45], s[0:1], 0, v[18:19]
	v_add_co_u32_e32 v44, vcc, 0x3000, v44
	v_readlane_b32 s0, v251, 61
	s_nop 0
	v_addc_co_u32_e32 v45, vcc, 0, v45, vcc
	v_readlane_b32 s1, v251, 62
	global_load_ushort v51, v[44:45], off offset:3136
	s_nop 0
	v_lshl_add_u64 v[44:45], s[0:1], 0, v[18:19]
	v_add_co_u32_e32 v44, vcc, 0x3000, v44
	v_readlane_b32 s0, v252, 1
	s_nop 0
	v_addc_co_u32_e32 v45, vcc, 0, v45, vcc
	v_readlane_b32 s1, v252, 2
	global_load_ushort v52, v[44:45], off offset:3136
	s_nop 0
	v_lshl_add_u64 v[44:45], s[0:1], 0, v[18:19]
	v_add_co_u32_e32 v44, vcc, 0x3000, v44
	v_readlane_b32 s0, v252, 7
	s_nop 0
	v_addc_co_u32_e32 v45, vcc, 0, v45, vcc
	v_readlane_b32 s1, v252, 8
	global_load_ushort v53, v[44:45], off offset:3136
	s_nop 0
	v_lshl_add_u64 v[44:45], s[0:1], 0, v[18:19]
	v_add_co_u32_e32 v44, vcc, 0x3000, v44
	v_readlane_b32 s0, v252, 13
	s_nop 0
	v_addc_co_u32_e32 v45, vcc, 0, v45, vcc
	v_readlane_b32 s1, v252, 14
	global_load_ushort v54, v[44:45], off offset:3136
	s_nop 0
	v_lshl_add_u64 v[44:45], s[0:1], 0, v[18:19]
	v_add_co_u32_e32 v44, vcc, 0x3000, v44
	v_readlane_b32 s0, v252, 19
	s_nop 0
	v_addc_co_u32_e32 v45, vcc, 0, v45, vcc
	v_readlane_b32 s1, v252, 20
	global_load_ushort v55, v[44:45], off offset:3136
	s_nop 0
	v_lshl_add_u64 v[44:45], s[0:1], 0, v[18:19]
	v_add_co_u32_e32 v44, vcc, 0x3000, v44
	v_readlane_b32 s0, v252, 25
	s_nop 0
	v_addc_co_u32_e32 v45, vcc, 0, v45, vcc
	v_readlane_b32 s1, v252, 26
	global_load_ushort v56, v[44:45], off offset:3136
	s_nop 0
	v_lshl_add_u64 v[44:45], s[0:1], 0, v[18:19]
	v_add_co_u32_e32 v44, vcc, 0x3000, v44
	v_readlane_b32 s0, v252, 31
	s_nop 0
	v_addc_co_u32_e32 v45, vcc, 0, v45, vcc
	v_readlane_b32 s1, v252, 32
	global_load_ushort v57, v[44:45], off offset:3136
	s_nop 0
	v_lshl_add_u64 v[44:45], s[0:1], 0, v[18:19]
	v_add_co_u32_e32 v44, vcc, 0x3000, v44
	v_readlane_b32 s0, v252, 35
	s_nop 0
	v_addc_co_u32_e32 v45, vcc, 0, v45, vcc
	v_readlane_b32 s1, v252, 36
	global_load_ushort v58, v[44:45], off offset:3136
	s_nop 0
	v_lshl_add_u64 v[44:45], s[0:1], 0, v[18:19]
	v_add_co_u32_e32 v44, vcc, 0x3000, v44
	v_readlane_b32 s0, v252, 39
	s_nop 0
	v_addc_co_u32_e32 v45, vcc, 0, v45, vcc
	v_readlane_b32 s1, v252, 40
	global_load_ushort v59, v[44:45], off offset:3136
	s_nop 0
	v_lshl_add_u64 v[44:45], s[0:1], 0, v[18:19]
	v_add_co_u32_e32 v44, vcc, 0x3000, v44
	v_readlane_b32 s0, v252, 43
	s_nop 0
	v_addc_co_u32_e32 v45, vcc, 0, v45, vcc
	v_readlane_b32 s1, v252, 44
	global_load_ushort v61, v[44:45], off offset:3136
	s_nop 0
	v_lshl_add_u64 v[44:45], s[0:1], 0, v[18:19]
	v_add_co_u32_e32 v44, vcc, 0x3000, v44
	v_readlane_b32 s0, v252, 47
	s_nop 0
	v_addc_co_u32_e32 v45, vcc, 0, v45, vcc
	v_readlane_b32 s1, v252, 48
	global_load_ushort v63, v[44:45], off offset:3136
	s_nop 0
	v_lshl_add_u64 v[44:45], s[0:1], 0, v[18:19]
	v_add_co_u32_e32 v44, vcc, 0x3000, v44
	v_readlane_b32 s0, v252, 51
	s_nop 0
	v_addc_co_u32_e32 v45, vcc, 0, v45, vcc
	v_readlane_b32 s1, v252, 52
	global_load_ushort v65, v[44:45], off offset:3136
	s_nop 0
	v_lshl_add_u64 v[44:45], s[0:1], 0, v[18:19]
	v_add_co_u32_e32 v44, vcc, 0x3000, v44
	v_readlane_b32 s0, v252, 57
	s_nop 0
	v_addc_co_u32_e32 v45, vcc, 0, v45, vcc
	v_readlane_b32 s1, v252, 58
	global_load_ushort v66, v[44:45], off offset:3136
	s_nop 0
	v_lshl_add_u64 v[44:45], s[0:1], 0, v[18:19]
	v_add_co_u32_e32 v44, vcc, 0x3000, v44
	v_readlane_b32 s0, v252, 63
	s_nop 0
	v_addc_co_u32_e32 v45, vcc, 0, v45, vcc
	v_readlane_b32 s1, v253, 0
	global_load_ushort v67, v[44:45], off offset:3136
	s_nop 0
	v_lshl_add_u64 v[44:45], s[0:1], 0, v[18:19]
	v_add_co_u32_e32 v44, vcc, 0x3000, v44
	v_readlane_b32 s0, v253, 5
	s_nop 0
	v_addc_co_u32_e32 v45, vcc, 0, v45, vcc
	v_readlane_b32 s1, v253, 6
	global_load_ushort v68, v[44:45], off offset:3136
	s_nop 0
	v_lshl_add_u64 v[44:45], s[0:1], 0, v[18:19]
	v_add_co_u32_e32 v44, vcc, 0x3000, v44
	v_readlane_b32 s0, v253, 11
	s_nop 0
	v_addc_co_u32_e32 v45, vcc, 0, v45, vcc
	v_readlane_b32 s1, v253, 12
	global_load_ushort v69, v[44:45], off offset:3136
	s_nop 0
	v_lshl_add_u64 v[44:45], s[0:1], 0, v[18:19]
	v_add_co_u32_e32 v44, vcc, 0x3000, v44
	v_readlane_b32 s0, v253, 17
	s_nop 0
	v_addc_co_u32_e32 v45, vcc, 0, v45, vcc
	v_readlane_b32 s1, v253, 18
	global_load_ushort v70, v[44:45], off offset:3136
	s_nop 0
	v_lshl_add_u64 v[44:45], s[0:1], 0, v[18:19]
	v_readlane_b32 s0, v253, 23
	v_add_co_u32_e32 v44, vcc, 0x3000, v44
	v_readlane_b32 s1, v253, 24
	s_nop 0
	v_addc_co_u32_e32 v45, vcc, 0, v45, vcc
	v_lshl_add_u64 v[18:19], s[0:1], 0, v[18:19]
	v_add_co_u32_e32 v18, vcc, 0x3000, v18
	global_load_ushort v44, v[44:45], off offset:3136
	s_nop 0
	v_addc_co_u32_e32 v19, vcc, 0, v19, vcc
	global_load_ushort v45, v[18:19], off offset:3136
	v_add_u32_e32 v18, v151, v16
	v_ashrrev_i32_e32 v19, 31, v18
	v_readlane_b32 s0, v249, 5
	v_and_b32_e32 v16, 0x3fc0, v20
	v_lshlrev_b64 v[18:19], 15, v[18:19]
	v_readlane_b32 s1, v249, 6
	s_waitcnt vmcnt(48)
	v_lshlrev_b32_e32 v176, 1, v16
	v_lshl_or_b32 v0, v1, 16, v0
	v_lshl_add_u64 v[18:19], s[0:1], 0, v[18:19]
	v_lshl_add_u64 v[18:19], v[18:19], 0, v[176:177]
	v_lshl_or_b32 v1, v3, 16, v2
	v_lshl_or_b32 v2, v5, 16, v4
	v_lshl_or_b32 v3, v7, 16, v6
	s_waitcnt vmcnt(32)
	s_waitcnt vmcnt(16)
	s_waitcnt vmcnt(0)
	global_store_dwordx4 v[18:19], v[0:3], off
	v_readlane_b32 s0, v249, 37
	s_lshl_b32 s39, s0, 1
	v_lshl_or_b32 v0, v9, 16, v8
	v_lshl_or_b32 v1, v11, 16, v10
	v_lshl_or_b32 v2, v13, 16, v12
	v_lshl_or_b32 v3, v15, 16, v14
	global_store_dwordx4 v[18:19], v[0:3], off offset:16
	s_movk_i32 s0, 0x4600
	s_nop 0
	v_lshl_or_b32 v0, v21, 16, v17
	v_lshl_or_b32 v1, v23, 16, v22
	v_lshl_or_b32 v2, v25, 16, v24
	v_lshl_or_b32 v3, v27, 16, v26
	global_store_dwordx4 v[18:19], v[0:3], off offset:32
	s_nop 1
	v_lshl_or_b32 v0, v29, 16, v28
	v_lshl_or_b32 v1, v31, 16, v30
	v_lshl_or_b32 v2, v33, 16, v32
	v_lshl_or_b32 v3, v35, 16, v34
	global_store_dwordx4 v[18:19], v[0:3], off offset:48
	s_nop 1
	v_lshl_or_b32 v0, v37, 16, v36
	v_lshl_or_b32 v1, v39, 16, v38
	v_lshl_or_b32 v2, v41, 16, v40
	v_lshl_or_b32 v3, v43, 16, v42
	global_store_dwordx4 v[18:19], v[0:3], off offset:64
	s_nop 1
	v_lshl_or_b32 v0, v47, 16, v46
	v_lshl_or_b32 v1, v49, 16, v48
	v_lshl_or_b32 v2, v51, 16, v50
	v_lshl_or_b32 v3, v53, 16, v52
	global_store_dwordx4 v[18:19], v[0:3], off offset:80
	s_nop 1
	v_lshl_or_b32 v0, v55, 16, v54
	v_lshl_or_b32 v1, v57, 16, v56
	v_lshl_or_b32 v2, v59, 16, v58
	v_lshl_or_b32 v3, v63, 16, v61
	global_store_dwordx4 v[18:19], v[0:3], off offset:96
	s_nop 1
	v_lshl_or_b32 v0, v66, 16, v65
	v_lshl_or_b32 v1, v68, 16, v67
	v_lshl_or_b32 v2, v70, 16, v69
	v_lshl_or_b32 v3, v45, 16, v44
	global_store_dwordx4 v[18:19], v[0:3], off offset:112
	s_barrier
; __device__ __forceinline__ float bf2f(bf16_t b) { return __uint_as_float(((unsigned)b) << 16); }
; __device__ __forceinline__ float sigmoidf_(float x) { return __builtin_amdgcn_rcpf(1.0f + __expf(-x)); }
; __device__ __forceinline__ float softplusf_(float x) { return fmaxf(x, 0.f) + __logf(1.0f + __expf(-fabsf(x))); }
;     template <class Tp> __device__ __forceinline__ Tp* W(size_t off) const { return (Tp*)(ws + off); }
; __device__ void dn_d1(const Ctx& c, int ip) {
;     const bf16_t* proj = c.W<bf16_t>(WS_PROJ);
;     const bf16_t* dq = c.W<bf16_t>(WS_DQ); const bf16_t* dk = c.W<bf16_t>(WS_DK); const bf16_t* dv = c.W<bf16_t>(WS_DV);
;     const int tid = c.tid, half = tid >> 8, lt = tid & 255, lw = c.wave & 3, r = c.r, q = c.q;
;     const int item = ip * 2 + half, ck = item >> 3, h = item & 7, t0 = ck * 64;
;     float* Ms = c.ldsf + half * (64 * 68 + 128); float* beta_s = Ms + 64 * 68; float* gc_s = beta_s + 64;
;     const size_t ch = (size_t)(ck * 8 + h);
;     __syncthreads();
;     if (lt < 64) { const size_t rb = (size_t)(t0 + lt) * NP;
;         beta_s[lt] = sigmoidf_(bf2f(proj[rb + C_DNB + h]));
;         float g = -__expf(c.in(I_DNALOG)[c.layer * 8 + h]) * softplusf_(bf2f(proj[rb + C_DNA + h]) + c.in(I_DNDTB)[c.layer * 8 + h]);
; #pragma unroll
;         for (int d = 1; d < 64; d <<= 1) { const float o = __shfl_up(g, d); if ((lt & 63) >= d) g += o; }
;         gc_s[lt] = g; }
;     ...
;     if (lt == 0) c.W<float>(WS_DGL)[ch] = __expf(glast);
.Ldnd_entry:
	s_mov_b64 exec, -1
	v_readlane_b32 s0, v247, 1
	v_readlane_b32 s1, v247, 2
	v_readlane_b32 s6, v247, 0
	v_readlane_b32 s16, v248, 25
	v_readfirstlane_b32 s9, v234
	s_load_dwordx2 s[4:5], s[0:1], 0xe8
	s_load_dwordx4 s[32:35], s[0:1], 0x28
	s_lshr_b32 s16, s16, 3
	s_lshr_b32 s9, s9, 6
	s_lshr_b32 s7, s6, 1
	s_and_b32 s8, s6, 1
	s_and_b32 s10, s9, 3
	s_lshr_b32 s11, s9, 2
	s_lshl_b32 s15, s7, 6
	s_mul_i32 s24, s11, 0xd000
	v_and_b32_e32 v0, 0xff, v234
	v_and_b32_e32 v3, 63, v234
	v_and_b32_e32 v1, 15, v234
	v_bfe_u32 v2, v234, 4, 2
	s_mov_b32 s12, 0
	s_waitcnt lgkmcnt(0)
.Ldnd_call:
	s_lshl_b32 s13, s8, 2
	s_lshl_b32 s22, s12, 1
	s_add_u32 s13, s13, s22
	s_add_u32 s13, s13, s11
	s_lshl_b32 s14, s7, 3
	s_add_u32 s14, s14, s13
	v_lshrrev_b32_e32 v12, 4, v0
	v_and_b32_e32 v13, 15, v0
	s_lshl_b32 s22, s15, 11
	s_lshl_b32 s23, s13, 8
	s_add_u32 s22, s22, s23
	v_lshlrev_b32_e32 v5, 11, v12
	v_lshl_add_u32 v5, v13, 4, v5
	v_add_u32_e32 v5, s22, v5
	v_mul_u32_u24_e32 v6, 272, v12
	v_lshl_add_u32 v6, v13, 4, v6
	v_add_u32_e32 v6, s24, v6
	s_lshl_b32 s22, s14, 14
	v_lshl_add_u32 v7, v0, 4, s22
	v_lshl_add_u32 v8, v12, 2, s24
	s_waitcnt vmcnt(0) lgkmcnt(0)
	s_barrier
	v_add_u32_e32 v12, 0x20100000, v5
	global_load_dwordx4 v[16:19], v12, s[4:5]
	v_add_u32_e32 v12, 0x20108000, v5
	global_load_dwordx4 v[20:23], v12, s[4:5]
	v_add_u32_e32 v12, 0x20110000, v5
	global_load_dwordx4 v[24:27], v12, s[4:5]
	v_add_u32_e32 v12, 0x20118000, v5
	global_load_dwordx4 v[28:31], v12, s[4:5]
	v_add_u32_e32 v12, 0x21100000, v5
	global_load_dwordx4 v[32:35], v12, s[4:5]
	v_add_u32_e32 v12, 0x21108000, v5
	global_load_dwordx4 v[36:39], v12, s[4:5]
	v_add_u32_e32 v12, 0x21110000, v5
	global_load_dwordx4 v[40:43], v12, s[4:5]
	v_add_u32_e32 v12, 0x21118000, v5
	global_load_dwordx4 v[44:47], v12, s[4:5]
	v_add_u32_e32 v12, 0x1f100000, v5
	global_load_dwordx4 v[48:51], v12, s[4:5]
	v_add_u32_e32 v12, 0x1f108000, v5
	global_load_dwordx4 v[52:55], v12, s[4:5]
	v_add_u32_e32 v12, 0x1f110000, v5
	global_load_dwordx4 v[56:59], v12, s[4:5]
	v_add_u32_e32 v12, 0x1f118000, v5
	global_load_dwordx4 v[60:63], v12, s[4:5]
	s_cmp_lg_u32 s10, 0
	s_cbranch_scc1 .Ldnd_scan_done
	v_add_u32_e32 v12, s15, v3
	s_mov_b32 s25, 0x7e00
	v_mul_lo_u32 v12, v12, s25
	s_lshl_b32 s22, s13, 1
	v_add_u32_e32 v12, s22, v12
	v_add_u32_e32 v13, 0x9c01800, v12
	v_add_u32_e32 v14, 0x9c01810, v12
	global_load_ushort v13, v13, s[4:5]
	global_load_ushort v14, v14, s[4:5]
	s_lshl_b32 s22, s16, 3
	s_add_u32 s22, s22, s13
	s_lshl_b32 s22, s22, 2
	s_load_dword s26, s[32:33], s22
	s_load_dword s27, s[34:35], s22
	s_waitcnt vmcnt(0) lgkmcnt(0)
	v_lshlrev_b32_e32 v13, 16, v13
	v_lshlrev_b32_e32 v14, 16, v14
	v_mul_f32_e32 v13, 0xbfb8aa3b, v13
	v_exp_f32_e32 v13, v13
	s_nop 0
	v_add_f32_e32 v13, 1.0, v13
	v_rcp_f32_e32 v13, v13
	v_add_f32_e32 v14, s27, v14
	s_mov_b32 s28, 0xbfb8aa3b
	v_mul_f32_e64 v15, |v14|, s28
	v_exp_f32_e32 v15, v15
	s_nop 0
	v_add_f32_e32 v15, 1.0, v15
	v_log_f32_e32 v15, v15
	v_max_f32_e32 v14, 0, v14
	v_mov_b32_e32 v12, s26
	v_mul_f32_e32 v12, 0x3fb8aa3b, v12
	v_exp_f32_e32 v12, v12
	v_fmac_f32_e32 v14, 0x3f317218, v15
	s_nop 0
	v_mul_f32_e64 v14, v14, -v12
	v_subrev_u32_e32 v12, 1, v3
	v_max_i32_e32 v12, 0, v12
	v_lshlrev_b32_e32 v12, 2, v12
	ds_bpermute_b32 v15, v12, v14
	v_cmp_le_u32_e32 vcc, 1, v3
	s_waitcnt lgkmcnt(0)
	v_add_f32_e32 v15, v14, v15
	v_cndmask_b32_e32 v14, v14, v15, vcc
	v_subrev_u32_e32 v12, 2, v3
	v_max_i32_e32 v12, 0, v12
	v_lshlrev_b32_e32 v12, 2, v12
	ds_bpermute_b32 v15, v12, v14
	v_cmp_le_u32_e32 vcc, 2, v3
	s_waitcnt lgkmcnt(0)
	v_add_f32_e32 v15, v14, v15
	v_cndmask_b32_e32 v14, v14, v15, vcc
	v_subrev_u32_e32 v12, 4, v3
	v_max_i32_e32 v12, 0, v12
	v_lshlrev_b32_e32 v12, 2, v12
	ds_bpermute_b32 v15, v12, v14
	v_cmp_le_u32_e32 vcc, 4, v3
	s_waitcnt lgkmcnt(0)
	v_add_f32_e32 v15, v14, v15
	v_cndmask_b32_e32 v14, v14, v15, vcc
	v_subrev_u32_e32 v12, 8, v3
	v_max_i32_e32 v12, 0, v12
	v_lshlrev_b32_e32 v12, 2, v12
	ds_bpermute_b32 v15, v12, v14
	v_cmp_le_u32_e32 vcc, 8, v3
	s_waitcnt lgkmcnt(0)
	v_add_f32_e32 v15, v14, v15
	v_cndmask_b32_e32 v14, v14, v15, vcc
	v_subrev_u32_e32 v12, 16, v3
	v_max_i32_e32 v12, 0, v12
	v_lshlrev_b32_e32 v12, 2, v12
	ds_bpermute_b32 v15, v12, v14
	v_cmp_le_u32_e32 vcc, 16, v3
	s_waitcnt lgkmcnt(0)
	v_add_f32_e32 v15, v14, v15
	v_cndmask_b32_e32 v14, v14, v15, vcc
	v_subrev_u32_e32 v12, 32, v3
	v_max_i32_e32 v12, 0, v12
	v_lshlrev_b32_e32 v12, 2, v12
	ds_bpermute_b32 v15, v12, v14
	v_cmp_le_u32_e32 vcc, 32, v3
	s_waitcnt lgkmcnt(0)
	v_add_f32_e32 v15, v14, v15
	v_cndmask_b32_e32 v14, v14, v15, vcc
	s_nop 1
	v_readlane_b32 s29, v14, 63
	v_lshl_add_u32 v12, v3, 2, s24
	ds_write_b32 v12, v14 offset:52224
	ds_write_b32 v12, v13 offset:52480
	v_sub_f32_e32 v15, s29, v14
	v_mul_f32_e32 v15, 0x3fb8aa3b, v15
	v_exp_f32_e32 v15, v15
	v_mul_f32_e32 v14, 0x3fb8aa3b, v14
	v_exp_f32_e32 v14, v14
	ds_write_b32 v12, v15 offset:52736
	v_mul_f32_e32 v14, v13, v14
	ds_write_b32 v12, v14 offset:52992
	v_mov_b32_e32 v15, s29
	v_mul_f32_e32 v15, 0x3fb8aa3b, v15
	v_exp_f32_e32 v15, v15
	s_lshl_b32 s22, s14, 2
	v_mov_b32_e32 v12, s22
	v_add_u32_e32 v12, 0x29900000, v12
	s_mov_b64 s[30:31], exec
	s_mov_b64 exec, 1
	global_store_dword v12, v15, s[4:5]
	s_mov_b64 exec, s[30:31]
; __device__ __forceinline__ unsigned pk2(float lo, float hi) { const f32v2_t v = {lo, hi}; const bf16v2_t b = __builtin_convertvector(v, bf16v2_t); return __builtin_bit_cast(unsigned, b); }
; #define PIN16(a, o) asm volatile("" : "+v"(a[(o)+0]), "+v"(a[(o)+1]), "+v"(a[(o)+2]), "+v"(a[(o)+3]), "+v"(a[(o)+4]), "+v"(a[(o)+5]), "+v"(a[(o)+6]), "+v"(a[(o)+7]), \
;     "+v"(a[(o)+8]), "+v"(a[(o)+9]), "+v"(a[(o)+10]), "+v"(a[(o)+11]), "+v"(a[(o)+12]), "+v"(a[(o)+13]), "+v"(a[(o)+14]), "+v"(a[(o)+15]))
; __device__ void dn_d1(const Ctx& c, int ip) {
;     ...
;     const int col = lt & 127; const bool isw = lt >= 128;
;     const float glast = gc_s[63];
;     {
;         const bf16_t* src = (isw ? dk : dv) + (size_t)t0 * 1024 + h * 128 + col;
;         { unsigned rw[64];
; #pragma unroll
;           for (int i = 0; i < 64; ++i) rw[i] = src[(size_t)i * 1024];
;           PIN16(rw, 0); PIN16(rw, 16); PIN16(rw, 32); PIN16(rw, 48);
; #pragma unroll
;           for (int i = 0; i < 64; ++i) x[i] = __uint_as_float(rw[i] << 16); }
;         if (isw) {
;             bf16_t* dKdT = c.W<bf16_t>(WS_DKDT);
; #pragma unroll
;             for (int l0 = 0; l0 < 64; l0 += 8) { u32x4 a;
;                 a.x = pk2(x[l0 + 0] * __expf(glast - gc_s[l0 + 0]), x[l0 + 1] * __expf(glast - gc_s[l0 + 1])); a.y = pk2(x[l0 + 2] * __expf(glast - gc_s[l0 + 2]), x[l0 + 3] * __expf(glast - gc_s[l0 + 3]));
;                 a.z = pk2(x[l0 + 4] * __expf(glast - gc_s[l0 + 4]), x[l0 + 5] * __expf(glast - gc_s[l0 + 5])); a.w = pk2(x[l0 + 6] * __expf(glast - gc_s[l0 + 6]), x[l0 + 7] * __expf(glast - gc_s[l0 + 7]));
;                 *(u32x4*)(dKdT + (ch * 128 + col) * 64 + l0) = a; }
; #pragma unroll
;             for (int i = 0; i < 64; ++i) x[i] *= beta_s[i] * __expf(gc_s[i]);
;         } else {
;             bf16_t* dQg = c.W<bf16_t>(WS_DQG); const bf16_t* qs = dq + (size_t)t0 * 1024 + h * 128 + col;
;             unsigned qv[64];
; #pragma unroll
;             for (int i = 0; i < 64; ++i) qv[i] = qs[(size_t)i * 1024];
;             PIN16(qv, 0); PIN16(qv, 16); PIN16(qv, 32); PIN16(qv, 48);
; #pragma unroll
;             for (int i = 0; i < 64; ++i) dQg[(ch * 64 + i) * 128 + col] = f2bf(__uint_as_float(qv[i] << 16) * __expf(gc_s[i]));
; #pragma unroll
;             for (int i = 0; i < 64; ++i) x[i] *= beta_s[i];
.Ldnd_scan_done:
	s_waitcnt lgkmcnt(0)
	s_barrier
	ds_read_b32 v136, v8 offset:52224
	ds_read_b32 v137, v8 offset:52288
	ds_read_b32 v138, v8 offset:52352
	ds_read_b32 v139, v8 offset:52416
	s_waitcnt vmcnt(0)
	ds_write_b128 v6, v[16:19] offset:17408
	ds_write_b128 v6, v[20:23] offset:21760
	ds_write_b128 v6, v[24:27] offset:26112
	ds_write_b128 v6, v[28:31] offset:30464
	ds_write_b128 v6, v[32:35] offset:34816
	ds_write_b128 v6, v[36:39] offset:39168
	ds_write_b128 v6, v[40:43] offset:43520
	ds_write_b128 v6, v[44:47] offset:47872
	s_waitcnt lgkmcnt(8)
	v_mul_f32_e32 v136, 0x3fb8aa3b, v136
	v_exp_f32_e32 v136, v136
	v_mul_f32_e32 v137, 0x3fb8aa3b, v137
	v_exp_f32_e32 v137, v137
	v_mul_f32_e32 v138, 0x3fb8aa3b, v138
	v_exp_f32_e32 v138, v138
	v_mul_f32_e32 v139, 0x3fb8aa3b, v139
	v_exp_f32_e32 v139, v139
	v_lshlrev_b32_e32 v144, 16, v48
	v_and_b32_e32 v145, 0xffff0000, v48
	v_lshlrev_b32_e32 v146, 16, v49
	v_and_b32_e32 v147, 0xffff0000, v49
	v_lshlrev_b32_e32 v148, 16, v50
	v_and_b32_e32 v149, 0xffff0000, v50
	v_lshlrev_b32_e32 v150, 16, v51
	v_and_b32_e32 v151, 0xffff0000, v51
	v_mul_f32_e32 v144, v144, v136
	v_mul_f32_e32 v145, v145, v136
	v_mul_f32_e32 v146, v146, v136
	v_mul_f32_e32 v147, v147, v136
	v_mul_f32_e32 v148, v148, v136
	v_mul_f32_e32 v149, v149, v136
	v_mul_f32_e32 v150, v150, v136
	v_mul_f32_e32 v151, v151, v136
	v_cvt_pk_bf16_f32 v48, v144, v145
	v_cvt_pk_bf16_f32 v49, v146, v147
	v_cvt_pk_bf16_f32 v50, v148, v149
	v_cvt_pk_bf16_f32 v51, v150, v151
	v_add_u32_e32 v12, 0x25100000, v7
	global_store_dwordx4 v12, v[48:51], s[4:5]
	v_lshlrev_b32_e32 v144, 16, v52
	v_and_b32_e32 v145, 0xffff0000, v52
	v_lshlrev_b32_e32 v146, 16, v53
	v_and_b32_e32 v147, 0xffff0000, v53
	v_lshlrev_b32_e32 v148, 16, v54
	v_and_b32_e32 v149, 0xffff0000, v54
	v_lshlrev_b32_e32 v150, 16, v55
	v_and_b32_e32 v151, 0xffff0000, v55
	v_mul_f32_e32 v144, v144, v137
	v_mul_f32_e32 v145, v145, v137
	v_mul_f32_e32 v146, v146, v137
	v_mul_f32_e32 v147, v147, v137
	v_mul_f32_e32 v148, v148, v137
	v_mul_f32_e32 v149, v149, v137
	v_mul_f32_e32 v150, v150, v137
	v_mul_f32_e32 v151, v151, v137
	v_cvt_pk_bf16_f32 v52, v144, v145
	v_cvt_pk_bf16_f32 v53, v146, v147
	v_cvt_pk_bf16_f32 v54, v148, v149
	v_cvt_pk_bf16_f32 v55, v150, v151
	v_add_u32_e32 v12, 0x25101000, v7
	global_store_dwordx4 v12, v[52:55], s[4:5]
	v_lshlrev_b32_e32 v144, 16, v56
	v_and_b32_e32 v145, 0xffff0000, v56
	v_lshlrev_b32_e32 v146, 16, v57
	v_and_b32_e32 v147, 0xffff0000, v57
	v_lshlrev_b32_e32 v148, 16, v58
	v_and_b32_e32 v149, 0xffff0000, v58
	v_lshlrev_b32_e32 v150, 16, v59
	v_and_b32_e32 v151, 0xffff0000, v59
	v_mul_f32_e32 v144, v144, v138
	v_mul_f32_e32 v145, v145, v138
	v_mul_f32_e32 v146, v146, v138
	v_mul_f32_e32 v147, v147, v138
	v_mul_f32_e32 v148, v148, v138
	v_mul_f32_e32 v149, v149, v138
	v_mul_f32_e32 v150, v150, v138
	v_mul_f32_e32 v151, v151, v138
	v_cvt_pk_bf16_f32 v56, v144, v145
	v_cvt_pk_bf16_f32 v57, v146, v147
	v_cvt_pk_bf16_f32 v58, v148, v149
	v_cvt_pk_bf16_f32 v59, v150, v151
	v_add_u32_e32 v12, 0x25102000, v7
	global_store_dwordx4 v12, v[56:59], s[4:5]
	v_lshlrev_b32_e32 v144, 16, v60
	v_and_b32_e32 v145, 0xffff0000, v60
	v_lshlrev_b32_e32 v146, 16, v61
	v_and_b32_e32 v147, 0xffff0000, v61
	v_lshlrev_b32_e32 v148, 16, v62
	v_and_b32_e32 v149, 0xffff0000, v62
	v_lshlrev_b32_e32 v150, 16, v63
	v_and_b32_e32 v151, 0xffff0000, v63
	v_mul_f32_e32 v144, v144, v139
	v_mul_f32_e32 v145, v145, v139
	v_mul_f32_e32 v146, v146, v139
	v_mul_f32_e32 v147, v147, v139
	v_mul_f32_e32 v148, v148, v139
	v_mul_f32_e32 v149, v149, v139
	v_mul_f32_e32 v150, v150, v139
	v_mul_f32_e32 v151, v151, v139
	v_cvt_pk_bf16_f32 v60, v144, v145
	v_cvt_pk_bf16_f32 v61, v146, v147
	v_cvt_pk_bf16_f32 v62, v148, v149
	v_cvt_pk_bf16_f32 v63, v150, v151
	v_add_u32_e32 v12, 0x25103000, v7
	global_store_dwordx4 v12, v[60:63], s[4:5]
	s_waitcnt lgkmcnt(0)
	s_barrier
	v_and_b32_e32 v12, 0x7f, v0
	v_lshl_add_u32 v9, v12, 1, s24
	s_and_b32 s30, s10, 2
	s_movk_i32 s23, 0x4400
	s_mov_b32 s31, 0x8800
	s_cmp_lg_u32 s30, 0
	s_cselect_b32 s31, s23, s31
	v_add_u32_e32 v9, s31, v9
	v_mov_b32_e32 v64, 0
	v_mov_b32_e32 v65, 0
	v_mov_b32_e32 v66, 0
	v_mov_b32_e32 v67, 0
	v_mov_b32_e32 v68, 0
	v_mov_b32_e32 v69, 0
	v_mov_b32_e32 v70, 0
	v_mov_b32_e32 v71, 0
	v_mov_b32_e32 v72, 0
	v_mov_b32_e32 v73, 0
	v_mov_b32_e32 v74, 0
	v_mov_b32_e32 v75, 0
	v_mov_b32_e32 v76, 0
	v_mov_b32_e32 v77, 0
	v_mov_b32_e32 v78, 0
	v_mov_b32_e32 v79, 0
	v_mov_b32_e32 v80, 0
	v_mov_b32_e32 v81, 0
	v_mov_b32_e32 v82, 0
	v_mov_b32_e32 v83, 0
	v_mov_b32_e32 v84, 0
	v_mov_b32_e32 v85, 0
	v_mov_b32_e32 v86, 0
	v_mov_b32_e32 v87, 0
	v_mov_b32_e32 v88, 0
	v_mov_b32_e32 v89, 0
	v_mov_b32_e32 v90, 0
	v_mov_b32_e32 v91, 0
	v_mov_b32_e32 v92, 0
	v_mov_b32_e32 v93, 0
	v_mov_b32_e32 v94, 0
	v_mov_b32_e32 v95, 0
	v_mov_b32_e32 v96, 0
	v_mov_b32_e32 v97, 0
	v_mov_b32_e32 v98, 0
	v_mov_b32_e32 v99, 0
	v_mov_b32_e32 v100, 0
	v_mov_b32_e32 v101, 0
	v_mov_b32_e32 v102, 0
	v_mov_b32_e32 v103, 0
	v_mov_b32_e32 v104, 0
	v_mov_b32_e32 v105, 0
	v_mov_b32_e32 v106, 0
	v_mov_b32_e32 v107, 0
	v_mov_b32_e32 v108, 0
	v_mov_b32_e32 v109, 0
	v_mov_b32_e32 v110, 0
	v_mov_b32_e32 v111, 0
	v_mov_b32_e32 v112, 0
	v_mov_b32_e32 v113, 0
	v_mov_b32_e32 v114, 0
	v_mov_b32_e32 v115, 0
	v_mov_b32_e32 v116, 0
	v_mov_b32_e32 v117, 0
	v_mov_b32_e32 v118, 0
	v_mov_b32_e32 v119, 0
	v_mov_b32_e32 v120, 0
	v_mov_b32_e32 v121, 0
	v_mov_b32_e32 v122, 0
	v_mov_b32_e32 v123, 0
	v_mov_b32_e32 v124, 0
	v_mov_b32_e32 v125, 0
	v_mov_b32_e32 v126, 0
	v_mov_b32_e32 v127, 0
	ds_read_u16_d16_hi v64, v9 offset:0
	ds_read_u16_d16_hi v65, v9 offset:272
	ds_read_u16_d16_hi v66, v9 offset:544
; #define PIN16(a, o) asm volatile("" : "+v"(a[(o)+0]), "+v"(a[(o)+1]), "+v"(a[(o)+2]), "+v"(a[(o)+3]), "+v"(a[(o)+4]), "+v"(a[(o)+5]), "+v"(a[(o)+6]), "+v"(a[(o)+7]), \
;     "+v"(a[(o)+8]), "+v"(a[(o)+9]), "+v"(a[(o)+10]), "+v"(a[(o)+11]), "+v"(a[(o)+12]), "+v"(a[(o)+13]), "+v"(a[(o)+14]), "+v"(a[(o)+15]))
; __device__ void dn_d1(const Ctx& c, int ip) {
;     ...
;         bf16x8 fki[4], fqi[4];
; #pragma unroll
;         for (int kk = 0; kk < 4; ++kk) { fki[kk] = ldfrag(dk + (size_t)(t0 + ib * 16 + r) * 1024 + h * 128 + kk * 32 + q * 8); fqi[kk] = ldfrag(dq + (size_t)(t0 + ib * 16 + r) * 1024 + h * 128 + kk * 32 + q * 8); }
;     ...
;     const int col = lt & 127; const bool isw = lt >= 128;
;     const float glast = gc_s[63];
;     {
;         const bf16_t* src = (isw ? dk : dv) + (size_t)t0 * 1024 + h * 128 + col;
;         { unsigned rw[64];
; #pragma unroll
;           for (int i = 0; i < 64; ++i) rw[i] = src[(size_t)i * 1024];
;           PIN16(rw, 0); PIN16(rw, 16); PIN16(rw, 32); PIN16(rw, 48);
; #pragma unroll
;           for (int i = 0; i < 64; ++i) x[i] = __uint_as_float(rw[i] << 16); }
	ds_read_u16_d16_hi v67, v9 offset:816
	ds_read_u16_d16_hi v68, v9 offset:1088
	ds_read_u16_d16_hi v69, v9 offset:1360
	ds_read_u16_d16_hi v70, v9 offset:1632
	ds_read_u16_d16_hi v71, v9 offset:1904
	ds_read_u16_d16_hi v72, v9 offset:2176
	ds_read_u16_d16_hi v73, v9 offset:2448
	ds_read_u16_d16_hi v74, v9 offset:2720
	ds_read_u16_d16_hi v75, v9 offset:2992
	ds_read_u16_d16_hi v76, v9 offset:3264
	ds_read_u16_d16_hi v77, v9 offset:3536
	ds_read_u16_d16_hi v78, v9 offset:3808
	ds_read_u16_d16_hi v79, v9 offset:4080
	ds_read_u16_d16_hi v80, v9 offset:4352
	ds_read_u16_d16_hi v81, v9 offset:4624
	ds_read_u16_d16_hi v82, v9 offset:4896
	ds_read_u16_d16_hi v83, v9 offset:5168
	ds_read_u16_d16_hi v84, v9 offset:5440
	ds_read_u16_d16_hi v85, v9 offset:5712
	ds_read_u16_d16_hi v86, v9 offset:5984
	ds_read_u16_d16_hi v87, v9 offset:6256
	ds_read_u16_d16_hi v88, v9 offset:6528
	ds_read_u16_d16_hi v89, v9 offset:6800
	ds_read_u16_d16_hi v90, v9 offset:7072
	ds_read_u16_d16_hi v91, v9 offset:7344
	ds_read_u16_d16_hi v92, v9 offset:7616
	ds_read_u16_d16_hi v93, v9 offset:7888
	ds_read_u16_d16_hi v94, v9 offset:8160
	ds_read_u16_d16_hi v95, v9 offset:8432
	ds_read_u16_d16_hi v96, v9 offset:8704
	ds_read_u16_d16_hi v97, v9 offset:8976
	ds_read_u16_d16_hi v98, v9 offset:9248
	ds_read_u16_d16_hi v99, v9 offset:9520
	ds_read_u16_d16_hi v100, v9 offset:9792
	ds_read_u16_d16_hi v101, v9 offset:10064
	ds_read_u16_d16_hi v102, v9 offset:10336
	ds_read_u16_d16_hi v103, v9 offset:10608
	ds_read_u16_d16_hi v104, v9 offset:10880
	ds_read_u16_d16_hi v105, v9 offset:11152
	ds_read_u16_d16_hi v106, v9 offset:11424
	ds_read_u16_d16_hi v107, v9 offset:11696
	ds_read_u16_d16_hi v108, v9 offset:11968
	ds_read_u16_d16_hi v109, v9 offset:12240
	ds_read_u16_d16_hi v110, v9 offset:12512
	ds_read_u16_d16_hi v111, v9 offset:12784
	ds_read_u16_d16_hi v112, v9 offset:13056
	ds_read_u16_d16_hi v113, v9 offset:13328
	ds_read_u16_d16_hi v114, v9 offset:13600
	ds_read_u16_d16_hi v115, v9 offset:13872
	ds_read_u16_d16_hi v116, v9 offset:14144
	ds_read_u16_d16_hi v117, v9 offset:14416
	ds_read_u16_d16_hi v118, v9 offset:14688
	ds_read_u16_d16_hi v119, v9 offset:14960
	ds_read_u16_d16_hi v120, v9 offset:15232
	ds_read_u16_d16_hi v121, v9 offset:15504
	ds_read_u16_d16_hi v122, v9 offset:15776
	ds_read_u16_d16_hi v123, v9 offset:16048
	ds_read_u16_d16_hi v124, v9 offset:16320
	ds_read_u16_d16_hi v125, v9 offset:16592
	ds_read_u16_d16_hi v126, v9 offset:16864
	ds_read_u16_d16_hi v127, v9 offset:17136
	s_lshl_b32 s22, s10, 4
	s_add_u32 s23, s22, s15
	s_lshl_b32 s23, s23, 11
	s_lshl_b32 s25, s13, 8
	s_add_u32 s23, s23, s25
	v_lshlrev_b32_e32 v12, 11, v1
	v_lshl_add_u32 v12, v2, 4, v12
	v_add_u32_e32 v12, s23, v12
	v_add_u32_e32 v12, 0x1f100000, v12
	global_load_dwordx4 v[32:35], v12, s[4:5] offset:0
	global_load_dwordx4 v[36:39], v12, s[4:5] offset:64
	global_load_dwordx4 v[40:43], v12, s[4:5] offset:128
	global_load_dwordx4 v[44:47], v12, s[4:5] offset:192
	v_mul_u32_u24_e32 v13, 272, v1
	v_lshl_add_u32 v13, v2, 4, v13
	v_add_u32_e32 v13, s24, v13
	s_mul_i32 s23, s10, 4352
	v_add_u32_e32 v14, s23, v13
	ds_read_b128 v[16:19], v14 offset:17408
	ds_read_b128 v[20:23], v14 offset:17472
	ds_read_b128 v[24:27], v14 offset:17536
	ds_read_b128 v[28:31], v14 offset:17600
	v_lshl_add_u32 v15, v2, 4, s24
	s_lshl_b32 s23, s10, 6
	v_add_u32_e32 v15, s23, v15
	ds_read_b128 v[136:139], v15 offset:52224
	ds_read_b128 v[140:143], v15 offset:52480
	v_lshl_add_u32 v15, v1, 2, s24
	v_add_u32_e32 v15, s23, v15
	ds_read_b32 v144, v15 offset:52224
	v_lshlrev_b32_e32 v145, 2, v2
	v_mul_u32_u24_e32 v147, 272, v145
	v_lshl_add_u32 v147, v1, 2, v147
	s_mul_i32 s23, s10, 4352
	s_add_u32 s23, s23, s24
	v_add_u32_e32 v147, s23, v147
	s_lshl_b32 s23, s14, 6
	s_add_u32 s23, s23, s22
	v_add_u32_e32 v148, s23, v1
	v_lshlrev_b32_e32 v148, 7, v148
	v_lshl_add_u32 v148, v2, 3, v148
	v_add_u32_e32 v148, 0x26100000, v148
	s_waitcnt vmcnt(0) lgkmcnt(0)
	s_cmp_lt_u32 s10, 0
	s_cbranch_scc1 .Ldnd_z0
	ds_read_b128 v[48:51], v13 offset:17408
	ds_read_b128 v[52:55], v13 offset:17472
	ds_read_b128 v[56:59], v13 offset:17536
	ds_read_b128 v[60:63], v13 offset:17600
	v_lshl_add_u32 v15, v1, 2, s24
	ds_read_b32 v149, v15 offset:52224
	v_lshl_add_u32 v15, v2, 4, s24
	ds_read_b128 v[152:155], v15 offset:52224
	v_mov_b32_e32 v128, 0
	v_mov_b32_e32 v132, 0
	v_mov_b32_e32 v129, 0
	v_mov_b32_e32 v133, 0
	v_mov_b32_e32 v130, 0
	v_mov_b32_e32 v134, 0
	v_mov_b32_e32 v131, 0
	v_mov_b32_e32 v135, 0
	s_waitcnt lgkmcnt(0)
; __device__ __forceinline__ u32x2 pk4(f32x4 v) { u32x2 r; r.x = pk2(v[0], v[1]); r.y = pk2(v[2], v[3]); return r; }
; __device__ __forceinline__ f32x4 mfma16(bf16x8 a, bf16x8 b, f32x4 c) { return __builtin_amdgcn_mfma_f32_16x16x32_bf16(a, b, c, 0, 0, 0); }
; __device__ void dn_d1(const Ctx& c, int ip) {
;     ...
; #pragma unroll
;         for (int jb = 0; jb < 4; ++jb) {
;             f32x4 aK = (f32x4){0.f, 0.f, 0.f, 0.f}, aA = aK;
;             if (jb <= ib) {
; #pragma unroll
;                 for (int kk = 0; kk < 4; ++kk) {
;                     const bf16x8 fkj = ldfrag(dk + (size_t)(t0 + jb * 16 + r) * 1024 + h * 128 + kk * 32 + q * 8);
;                     aK = mfma16(fki[kk], fkj, aK);
;                     aA = mfma16(fkj, fqi[kk], aA);
;                 }
; #pragma unroll
;                 for (int j = 0; j < 4; ++j) { const int i = ib * 16 + 4 * q + j, jj = jb * 16 + r;
;                     Ms[i * 68 + jj] = (i > jj) ? beta_s[i] * aK[j] * __expf(gc_s[i] - gc_s[jj]) : 0.f; }
;             }
;             { const int i = ib * 16 + r; f32x4 o;
; #pragma unroll
;               for (int j = 0; j < 4; ++j) { const int jj = jb * 16 + 4 * q + j; o[j] = (i >= jj) ? aA[j] * __expf(gc_s[i] - gc_s[jj]) : 0.f; }
;               *(u32x2*)(dAtt + (ch * 64 + i) * 64 + jb * 16 + 4 * q) = pk4(o); }
;         }
	s_nop 1
	v_mfma_f32_16x16x32_bf16 v[128:131], v[16:19], v[48:51], v[128:131]
	v_mfma_f32_16x16x32_bf16 v[132:135], v[48:51], v[32:35], v[132:135]
	v_mfma_f32_16x16x32_bf16 v[128:131], v[20:23], v[52:55], v[128:131]
	v_mfma_f32_16x16x32_bf16 v[132:135], v[52:55], v[36:39], v[132:135]
	v_mfma_f32_16x16x32_bf16 v[128:131], v[24:27], v[56:59], v[128:131]
	v_mfma_f32_16x16x32_bf16 v[132:135], v[56:59], v[40:43], v[132:135]
	v_mfma_f32_16x16x32_bf16 v[128:131], v[28:31], v[60:63], v[128:131]
	v_mfma_f32_16x16x32_bf16 v[132:135], v[60:63], v[44:47], v[132:135]
	s_lshl_b32 s23, s10, 4
	s_sub_i32 s23, s23, 0
	v_add_u32_e32 v150, s23, v145
	v_sub_f32_e32 v156, v136, v149
	v_mul_f32_e32 v156, 0x3fb8aa3b, v156
	v_exp_f32_e32 v156, v156
	v_sub_f32_e32 v157, v137, v149
	v_mul_f32_e32 v157, 0x3fb8aa3b, v157
	v_exp_f32_e32 v157, v157
	v_sub_f32_e32 v158, v138, v149
	v_mul_f32_e32 v158, 0x3fb8aa3b, v158
	v_exp_f32_e32 v158, v158
	v_sub_f32_e32 v159, v139, v149
	v_mul_f32_e32 v159, 0x3fb8aa3b, v159
	v_exp_f32_e32 v159, v159
	s_nop 7
	s_nop 7
	v_mul_f32_e32 v156, v156, v140
	v_mul_f32_e64 v156, v156, -v128
	v_add_u32_e32 v15, 0, v150
	v_cmp_gt_i32_e32 vcc, v15, v1
	s_nop 1
	v_cndmask_b32_e32 v156, 0, v156, vcc
	ds_write_b32 v147, v156 offset:0
	v_mul_f32_e32 v157, v157, v141
	v_mul_f32_e64 v157, v157, -v129
	v_add_u32_e32 v15, 1, v150
	v_cmp_gt_i32_e32 vcc, v15, v1
	s_nop 1
	v_cndmask_b32_e32 v157, 0, v157, vcc
	ds_write_b32 v147, v157 offset:272
	v_mul_f32_e32 v158, v158, v142
	v_mul_f32_e64 v158, v158, -v130
	v_add_u32_e32 v15, 2, v150
	v_cmp_gt_i32_e32 vcc, v15, v1
	s_nop 1
	v_cndmask_b32_e32 v158, 0, v158, vcc
	ds_write_b32 v147, v158 offset:544
	v_mul_f32_e32 v159, v159, v143
	v_mul_f32_e64 v159, v159, -v131
	v_add_u32_e32 v15, 3, v150
	v_cmp_gt_i32_e32 vcc, v15, v1
	s_nop 1
	v_cndmask_b32_e32 v159, 0, v159, vcc
	ds_write_b32 v147, v159 offset:816
	v_add_u32_e32 v151, s23, v1
	v_sub_f32_e32 v160, v144, v152
	v_mul_f32_e32 v160, 0x3fb8aa3b, v160
	v_exp_f32_e32 v160, v160
	v_sub_f32_e32 v161, v144, v153
	v_mul_f32_e32 v161, 0x3fb8aa3b, v161
	v_exp_f32_e32 v161, v161
	v_sub_f32_e32 v162, v144, v154
	v_mul_f32_e32 v162, 0x3fb8aa3b, v162
	v_exp_f32_e32 v162, v162
	v_sub_f32_e32 v163, v144, v155
	v_mul_f32_e32 v163, 0x3fb8aa3b, v163
	v_exp_f32_e32 v163, v163
	v_mul_f32_e32 v160, v160, v132
	v_add_u32_e32 v15, 0, v145
	v_cmp_ge_i32_e32 vcc, v151, v15
	s_nop 1
	v_cndmask_b32_e32 v160, 0, v160, vcc
	v_mul_f32_e32 v161, v161, v133
	v_add_u32_e32 v15, 1, v145
	v_cmp_ge_i32_e32 vcc, v151, v15
	s_nop 1
	v_cndmask_b32_e32 v161, 0, v161, vcc
	v_mul_f32_e32 v162, v162, v134
	v_add_u32_e32 v15, 2, v145
	v_cmp_ge_i32_e32 vcc, v151, v15
	s_nop 1
	v_cndmask_b32_e32 v162, 0, v162, vcc
	v_mul_f32_e32 v163, v163, v135
	v_add_u32_e32 v15, 3, v145
	v_cmp_ge_i32_e32 vcc, v151, v15
	s_nop 1
	v_cndmask_b32_e32 v163, 0, v163, vcc
	v_cvt_pk_bf16_f32 v164, v160, v161
	v_cvt_pk_bf16_f32 v165, v162, v163
	s_branch .Ldnd_s0
.Ldnd_z0:
	v_mov_b32_e32 v164, 0
	v_mov_b32_e32 v165, 0
.Ldnd_s0:
	global_store_dwordx2 v148, v[164:165], s[4:5] offset:0
	s_cmp_lt_u32 s10, 1
	s_cbranch_scc1 .Ldnd_z1
	ds_read_b128 v[48:51], v13 offset:21760
	ds_read_b128 v[52:55], v13 offset:21824
	ds_read_b128 v[56:59], v13 offset:21888
	ds_read_b128 v[60:63], v13 offset:21952
	v_lshl_add_u32 v15, v1, 2, s24
	ds_read_b32 v149, v15 offset:52288
	v_lshl_add_u32 v15, v2, 4, s24
	ds_read_b128 v[152:155], v15 offset:52288
	v_mov_b32_e32 v128, 0
	v_mov_b32_e32 v132, 0
	v_mov_b32_e32 v129, 0
	v_mov_b32_e32 v133, 0
	v_mov_b32_e32 v130, 0
	v_mov_b32_e32 v134, 0
	v_mov_b32_e32 v131, 0
	v_mov_b32_e32 v135, 0
	s_waitcnt lgkmcnt(0)
	s_nop 1
	v_mfma_f32_16x16x32_bf16 v[128:131], v[16:19], v[48:51], v[128:131]
	v_mfma_f32_16x16x32_bf16 v[132:135], v[48:51], v[32:35], v[132:135]
	v_mfma_f32_16x16x32_bf16 v[128:131], v[20:23], v[52:55], v[128:131]
	v_mfma_f32_16x16x32_bf16 v[132:135], v[52:55], v[36:39], v[132:135]
	v_mfma_f32_16x16x32_bf16 v[128:131], v[24:27], v[56:59], v[128:131]
	v_mfma_f32_16x16x32_bf16 v[132:135], v[56:59], v[40:43], v[132:135]
	v_mfma_f32_16x16x32_bf16 v[128:131], v[28:31], v[60:63], v[128:131]
	v_mfma_f32_16x16x32_bf16 v[132:135], v[60:63], v[44:47], v[132:135]
	s_lshl_b32 s23, s10, 4
	s_sub_i32 s23, s23, 16
	v_add_u32_e32 v150, s23, v145
	v_sub_f32_e32 v156, v136, v149
	v_mul_f32_e32 v156, 0x3fb8aa3b, v156
	v_exp_f32_e32 v156, v156
	v_sub_f32_e32 v157, v137, v149
	v_mul_f32_e32 v157, 0x3fb8aa3b, v157
	v_exp_f32_e32 v157, v157
	v_sub_f32_e32 v158, v138, v149
	v_mul_f32_e32 v158, 0x3fb8aa3b, v158
	v_exp_f32_e32 v158, v158
	v_sub_f32_e32 v159, v139, v149
	v_mul_f32_e32 v159, 0x3fb8aa3b, v159
	v_exp_f32_e32 v159, v159
	s_nop 7
	s_nop 7
	v_mul_f32_e32 v156, v156, v140
	v_mul_f32_e64 v156, v156, -v128
	v_add_u32_e32 v15, 0, v150
	v_cmp_gt_i32_e32 vcc, v15, v1
	s_nop 1
	v_cndmask_b32_e32 v156, 0, v156, vcc
	ds_write_b32 v147, v156 offset:64
	v_mul_f32_e32 v157, v157, v141
	v_mul_f32_e64 v157, v157, -v129
	v_add_u32_e32 v15, 1, v150
	v_cmp_gt_i32_e32 vcc, v15, v1
	s_nop 1
	v_cndmask_b32_e32 v157, 0, v157, vcc
	ds_write_b32 v147, v157 offset:336
	v_mul_f32_e32 v158, v158, v142
	v_mul_f32_e64 v158, v158, -v130
	v_add_u32_e32 v15, 2, v150
	v_cmp_gt_i32_e32 vcc, v15, v1
	s_nop 1
	v_cndmask_b32_e32 v158, 0, v158, vcc
	ds_write_b32 v147, v158 offset:608
	v_mul_f32_e32 v159, v159, v143
	v_mul_f32_e64 v159, v159, -v131
	v_add_u32_e32 v15, 3, v150
	v_cmp_gt_i32_e32 vcc, v15, v1
	s_nop 1
	v_cndmask_b32_e32 v159, 0, v159, vcc
	ds_write_b32 v147, v159 offset:880
	v_add_u32_e32 v151, s23, v1
	v_sub_f32_e32 v160, v144, v152
	v_mul_f32_e32 v160, 0x3fb8aa3b, v160
	v_exp_f32_e32 v160, v160
	v_sub_f32_e32 v161, v144, v153
	v_mul_f32_e32 v161, 0x3fb8aa3b, v161
	v_exp_f32_e32 v161, v161
	v_sub_f32_e32 v162, v144, v154
	v_mul_f32_e32 v162, 0x3fb8aa3b, v162
	v_exp_f32_e32 v162, v162
	v_sub_f32_e32 v163, v144, v155
	v_mul_f32_e32 v163, 0x3fb8aa3b, v163
	v_exp_f32_e32 v163, v163
	v_mul_f32_e32 v160, v160, v132
	v_add_u32_e32 v15, 0, v145
	v_cmp_ge_i32_e32 vcc, v151, v15
	s_nop 1
	v_cndmask_b32_e32 v160, 0, v160, vcc
	v_mul_f32_e32 v161, v161, v133
	v_add_u32_e32 v15, 1, v145
	v_cmp_ge_i32_e32 vcc, v151, v15
	s_nop 1
	v_cndmask_b32_e32 v161, 0, v161, vcc
	v_mul_f32_e32 v162, v162, v134
	v_add_u32_e32 v15, 2, v145
	v_cmp_ge_i32_e32 vcc, v151, v15
	s_nop 1
	v_cndmask_b32_e32 v162, 0, v162, vcc
	v_mul_f32_e32 v163, v163, v135
	v_add_u32_e32 v15, 3, v145
	v_cmp_ge_i32_e32 vcc, v151, v15
	s_nop 1
	v_cndmask_b32_e32 v163, 0, v163, vcc
	v_cvt_pk_bf16_f32 v164, v160, v161
	v_cvt_pk_bf16_f32 v165, v162, v163
	s_branch .Ldnd_s1

; __device__ __forceinline__ u32x2 pk4(f32x4 v) { u32x2 r; r.x = pk2(v[0], v[1]); r.y = pk2(v[2], v[3]); return r; }
; __device__ __forceinline__ f32x4 mfma16(bf16x8 a, bf16x8 b, f32x4 c) { return __builtin_amdgcn_mfma_f32_16x16x32_bf16(a, b, c, 0, 0, 0); }
; __device__ void dn_d1(const Ctx& c, int ip) {
;     ...
; #pragma unroll
;         for (int jb = 0; jb < 4; ++jb) {
;             f32x4 aK = (f32x4){0.f, 0.f, 0.f, 0.f}, aA = aK;
;             if (jb <= ib) {
; #pragma unroll
;                 for (int kk = 0; kk < 4; ++kk) {
;                     const bf16x8 fkj = ldfrag(dk + (size_t)(t0 + jb * 16 + r) * 1024 + h * 128 + kk * 32 + q * 8);
;                     aK = mfma16(fki[kk], fkj, aK);
;                     aA = mfma16(fkj, fqi[kk], aA);
;                 }
; #pragma unroll
;                 for (int j = 0; j < 4; ++j) { const int i = ib * 16 + 4 * q + j, jj = jb * 16 + r;
;                     Ms[i * 68 + jj] = (i > jj) ? beta_s[i] * aK[j] * __expf(gc_s[i] - gc_s[jj]) : 0.f; }
;             }
;             { const int i = ib * 16 + r; f32x4 o;
; #pragma unroll
;               for (int j = 0; j < 4; ++j) { const int jj = jb * 16 + 4 * q + j; o[j] = (i >= jj) ? aA[j] * __expf(gc_s[i] - gc_s[jj]) : 0.f; }
;               *(u32x2*)(dAtt + (ch * 64 + i) * 64 + jb * 16 + 4 * q) = pk4(o); }
;         }
.Ldnd_s1:
	global_store_dwordx2 v148, v[164:165], s[4:5] offset:32
	s_cmp_lt_u32 s10, 2
	s_cbranch_scc1 .Ldnd_z2
	ds_read_b128 v[48:51], v13 offset:26112
	ds_read_b128 v[52:55], v13 offset:26176
	ds_read_b128 v[56:59], v13 offset:26240
	ds_read_b128 v[60:63], v13 offset:26304
	v_lshl_add_u32 v15, v1, 2, s24
	ds_read_b32 v149, v15 offset:52352
	v_lshl_add_u32 v15, v2, 4, s24
	ds_read_b128 v[152:155], v15 offset:52352
	v_mov_b32_e32 v128, 0
	v_mov_b32_e32 v132, 0
	v_mov_b32_e32 v129, 0
	v_mov_b32_e32 v133, 0
	v_mov_b32_e32 v130, 0
	v_mov_b32_e32 v134, 0
	v_mov_b32_e32 v131, 0
	v_mov_b32_e32 v135, 0
	s_waitcnt lgkmcnt(0)
	s_nop 1
	v_mfma_f32_16x16x32_bf16 v[128:131], v[16:19], v[48:51], v[128:131]
	v_mfma_f32_16x16x32_bf16 v[132:135], v[48:51], v[32:35], v[132:135]
	v_mfma_f32_16x16x32_bf16 v[128:131], v[20:23], v[52:55], v[128:131]
	v_mfma_f32_16x16x32_bf16 v[132:135], v[52:55], v[36:39], v[132:135]
	v_mfma_f32_16x16x32_bf16 v[128:131], v[24:27], v[56:59], v[128:131]
	v_mfma_f32_16x16x32_bf16 v[132:135], v[56:59], v[40:43], v[132:135]
	v_mfma_f32_16x16x32_bf16 v[128:131], v[28:31], v[60:63], v[128:131]
	v_mfma_f32_16x16x32_bf16 v[132:135], v[60:63], v[44:47], v[132:135]
	s_lshl_b32 s23, s10, 4
	s_sub_i32 s23, s23, 32
	v_add_u32_e32 v150, s23, v145
	v_sub_f32_e32 v156, v136, v149
	v_mul_f32_e32 v156, 0x3fb8aa3b, v156
	v_exp_f32_e32 v156, v156
	v_sub_f32_e32 v157, v137, v149
	v_mul_f32_e32 v157, 0x3fb8aa3b, v157
	v_exp_f32_e32 v157, v157
	v_sub_f32_e32 v158, v138, v149
	v_mul_f32_e32 v158, 0x3fb8aa3b, v158
	v_exp_f32_e32 v158, v158
	v_sub_f32_e32 v159, v139, v149
	v_mul_f32_e32 v159, 0x3fb8aa3b, v159
	v_exp_f32_e32 v159, v159
	s_nop 7
	s_nop 7
	v_mul_f32_e32 v156, v156, v140
	v_mul_f32_e64 v156, v156, -v128
	v_add_u32_e32 v15, 0, v150
	v_cmp_gt_i32_e32 vcc, v15, v1
	s_nop 1
	v_cndmask_b32_e32 v156, 0, v156, vcc
	ds_write_b32 v147, v156 offset:128
	v_mul_f32_e32 v157, v157, v141
	v_mul_f32_e64 v157, v157, -v129
	v_add_u32_e32 v15, 1, v150
	v_cmp_gt_i32_e32 vcc, v15, v1
	s_nop 1
	v_cndmask_b32_e32 v157, 0, v157, vcc
	ds_write_b32 v147, v157 offset:400
	v_mul_f32_e32 v158, v158, v142
	v_mul_f32_e64 v158, v158, -v130
	v_add_u32_e32 v15, 2, v150
	v_cmp_gt_i32_e32 vcc, v15, v1
	s_nop 1
	v_cndmask_b32_e32 v158, 0, v158, vcc
	ds_write_b32 v147, v158 offset:672
	v_mul_f32_e32 v159, v159, v143
	v_mul_f32_e64 v159, v159, -v131
	v_add_u32_e32 v15, 3, v150
	v_cmp_gt_i32_e32 vcc, v15, v1
	s_nop 1
	v_cndmask_b32_e32 v159, 0, v159, vcc
	ds_write_b32 v147, v159 offset:944
	v_add_u32_e32 v151, s23, v1
	v_sub_f32_e32 v160, v144, v152
	v_mul_f32_e32 v160, 0x3fb8aa3b, v160
	v_exp_f32_e32 v160, v160
	v_sub_f32_e32 v161, v144, v153
	v_mul_f32_e32 v161, 0x3fb8aa3b, v161
	v_exp_f32_e32 v161, v161
	v_sub_f32_e32 v162, v144, v154
	v_mul_f32_e32 v162, 0x3fb8aa3b, v162
	v_exp_f32_e32 v162, v162
	v_sub_f32_e32 v163, v144, v155
	v_mul_f32_e32 v163, 0x3fb8aa3b, v163
	v_exp_f32_e32 v163, v163
	v_mul_f32_e32 v160, v160, v132
	v_add_u32_e32 v15, 0, v145
	v_cmp_ge_i32_e32 vcc, v151, v15
	s_nop 1
	v_cndmask_b32_e32 v160, 0, v160, vcc
	v_mul_f32_e32 v161, v161, v133
	v_add_u32_e32 v15, 1, v145
	v_cmp_ge_i32_e32 vcc, v151, v15
	s_nop 1
	v_cndmask_b32_e32 v161, 0, v161, vcc
	v_mul_f32_e32 v162, v162, v134
	v_add_u32_e32 v15, 2, v145
	v_cmp_ge_i32_e32 vcc, v151, v15
	s_nop 1
	v_cndmask_b32_e32 v162, 0, v162, vcc
	v_mul_f32_e32 v163, v163, v135
	v_add_u32_e32 v15, 3, v145
	v_cmp_ge_i32_e32 vcc, v151, v15
	s_nop 1
	v_cndmask_b32_e32 v163, 0, v163, vcc
	v_cvt_pk_bf16_f32 v164, v160, v161
	v_cvt_pk_bf16_f32 v165, v162, v163
	s_branch .Ldnd_s2

; __device__ __forceinline__ u32x2 pk4(f32x4 v) { u32x2 r; r.x = pk2(v[0], v[1]); r.y = pk2(v[2], v[3]); return r; }
; __device__ __forceinline__ f32x4 mfma16(bf16x8 a, bf16x8 b, f32x4 c) { return __builtin_amdgcn_mfma_f32_16x16x32_bf16(a, b, c, 0, 0, 0); }
; __device__ void dn_d1(const Ctx& c, int ip) {
;     ...
; #pragma unroll
;         for (int jb = 0; jb < 4; ++jb) {
;             f32x4 aK = (f32x4){0.f, 0.f, 0.f, 0.f}, aA = aK;
;             if (jb <= ib) {
; #pragma unroll
;                 for (int kk = 0; kk < 4; ++kk) {
;                     const bf16x8 fkj = ldfrag(dk + (size_t)(t0 + jb * 16 + r) * 1024 + h * 128 + kk * 32 + q * 8);
;                     aK = mfma16(fki[kk], fkj, aK);
;                     aA = mfma16(fkj, fqi[kk], aA);
;                 }
; #pragma unroll
;                 for (int j = 0; j < 4; ++j) { const int i = ib * 16 + 4 * q + j, jj = jb * 16 + r;
;                     Ms[i * 68 + jj] = (i > jj) ? beta_s[i] * aK[j] * __expf(gc_s[i] - gc_s[jj]) : 0.f; }
;             }
;             { const int i = ib * 16 + r; f32x4 o;
; #pragma unroll
;               for (int j = 0; j < 4; ++j) { const int jj = jb * 16 + 4 * q + j; o[j] = (i >= jj) ? aA[j] * __expf(gc_s[i] - gc_s[jj]) : 0.f; }
;               *(u32x2*)(dAtt + (ch * 64 + i) * 64 + jb * 16 + 4 * q) = pk4(o); }
;         }
.Ldnd_s2:
	global_store_dwordx2 v148, v[164:165], s[4:5] offset:64
	s_cmp_lt_u32 s10, 3
	s_cbranch_scc1 .Ldnd_z3
	ds_read_b128 v[48:51], v13 offset:30464
	ds_read_b128 v[52:55], v13 offset:30528
	ds_read_b128 v[56:59], v13 offset:30592
	ds_read_b128 v[60:63], v13 offset:30656
	v_lshl_add_u32 v15, v1, 2, s24
	ds_read_b32 v149, v15 offset:52416
	v_lshl_add_u32 v15, v2, 4, s24
	ds_read_b128 v[152:155], v15 offset:52416
	v_mov_b32_e32 v128, 0
	v_mov_b32_e32 v132, 0
	v_mov_b32_e32 v129, 0
	v_mov_b32_e32 v133, 0
	v_mov_b32_e32 v130, 0
	v_mov_b32_e32 v134, 0
	v_mov_b32_e32 v131, 0
	v_mov_b32_e32 v135, 0
	s_waitcnt lgkmcnt(0)
	s_nop 1
	v_mfma_f32_16x16x32_bf16 v[128:131], v[16:19], v[48:51], v[128:131]
	v_mfma_f32_16x16x32_bf16 v[132:135], v[48:51], v[32:35], v[132:135]
	v_mfma_f32_16x16x32_bf16 v[128:131], v[20:23], v[52:55], v[128:131]
	v_mfma_f32_16x16x32_bf16 v[132:135], v[52:55], v[36:39], v[132:135]
	v_mfma_f32_16x16x32_bf16 v[128:131], v[24:27], v[56:59], v[128:131]
	v_mfma_f32_16x16x32_bf16 v[132:135], v[56:59], v[40:43], v[132:135]
	v_mfma_f32_16x16x32_bf16 v[128:131], v[28:31], v[60:63], v[128:131]
	v_mfma_f32_16x16x32_bf16 v[132:135], v[60:63], v[44:47], v[132:135]
	s_lshl_b32 s23, s10, 4
	s_sub_i32 s23, s23, 48
	v_add_u32_e32 v150, s23, v145
	v_sub_f32_e32 v156, v136, v149
	v_mul_f32_e32 v156, 0x3fb8aa3b, v156
	v_exp_f32_e32 v156, v156
	v_sub_f32_e32 v157, v137, v149
	v_mul_f32_e32 v157, 0x3fb8aa3b, v157
	v_exp_f32_e32 v157, v157
	v_sub_f32_e32 v158, v138, v149
	v_mul_f32_e32 v158, 0x3fb8aa3b, v158
	v_exp_f32_e32 v158, v158
	v_sub_f32_e32 v159, v139, v149
	v_mul_f32_e32 v159, 0x3fb8aa3b, v159
	v_exp_f32_e32 v159, v159
	s_nop 7
	s_nop 7
	v_mul_f32_e32 v156, v156, v140
	v_mul_f32_e64 v156, v156, -v128
	v_add_u32_e32 v15, 0, v150
	v_cmp_gt_i32_e32 vcc, v15, v1
	s_nop 1
	v_cndmask_b32_e32 v156, 0, v156, vcc
	ds_write_b32 v147, v156 offset:192
	v_mul_f32_e32 v157, v157, v141
	v_mul_f32_e64 v157, v157, -v129
	v_add_u32_e32 v15, 1, v150
	v_cmp_gt_i32_e32 vcc, v15, v1
	s_nop 1
	v_cndmask_b32_e32 v157, 0, v157, vcc
	ds_write_b32 v147, v157 offset:464
	v_mul_f32_e32 v158, v158, v142
	v_mul_f32_e64 v158, v158, -v130
	v_add_u32_e32 v15, 2, v150
	v_cmp_gt_i32_e32 vcc, v15, v1
	s_nop 1
	v_cndmask_b32_e32 v158, 0, v158, vcc
	ds_write_b32 v147, v158 offset:736
	v_mul_f32_e32 v159, v159, v143
	v_mul_f32_e64 v159, v159, -v131
	v_add_u32_e32 v15, 3, v150
	v_cmp_gt_i32_e32 vcc, v15, v1
	s_nop 1
	v_cndmask_b32_e32 v159, 0, v159, vcc
	ds_write_b32 v147, v159 offset:1008
	v_add_u32_e32 v151, s23, v1
	v_sub_f32_e32 v160, v144, v152
	v_mul_f32_e32 v160, 0x3fb8aa3b, v160
	v_exp_f32_e32 v160, v160
	v_sub_f32_e32 v161, v144, v153
	v_mul_f32_e32 v161, 0x3fb8aa3b, v161
	v_exp_f32_e32 v161, v161
	v_sub_f32_e32 v162, v144, v154
	v_mul_f32_e32 v162, 0x3fb8aa3b, v162
	v_exp_f32_e32 v162, v162
	v_sub_f32_e32 v163, v144, v155
	v_mul_f32_e32 v163, 0x3fb8aa3b, v163
	v_exp_f32_e32 v163, v163
	v_mul_f32_e32 v160, v160, v132
	v_add_u32_e32 v15, 0, v145
	v_cmp_ge_i32_e32 vcc, v151, v15
	s_nop 1
	v_cndmask_b32_e32 v160, 0, v160, vcc
	v_mul_f32_e32 v161, v161, v133
	v_add_u32_e32 v15, 1, v145
	v_cmp_ge_i32_e32 vcc, v151, v15
	s_nop 1
	v_cndmask_b32_e32 v161, 0, v161, vcc
	v_mul_f32_e32 v162, v162, v134
	v_add_u32_e32 v15, 2, v145
	v_cmp_ge_i32_e32 vcc, v151, v15
	s_nop 1
	v_cndmask_b32_e32 v162, 0, v162, vcc
	v_mul_f32_e32 v163, v163, v135
	v_add_u32_e32 v15, 3, v145
	v_cmp_ge_i32_e32 vcc, v151, v15
	s_nop 1
	v_cndmask_b32_e32 v163, 0, v163, vcc
	v_cvt_pk_bf16_f32 v164, v160, v161
	v_cvt_pk_bf16_f32 v165, v162, v163
	s_branch .Ldnd_s3

; __device__ __forceinline__ unsigned pk2(float lo, float hi) { const f32v2_t v = {lo, hi}; const bf16v2_t b = __builtin_convertvector(v, bf16v2_t); return __builtin_bit_cast(unsigned, b); }
; #define PIN16(a, o) asm volatile("" : "+v"(a[(o)+0]), "+v"(a[(o)+1]), "+v"(a[(o)+2]), "+v"(a[(o)+3]), "+v"(a[(o)+4]), "+v"(a[(o)+5]), "+v"(a[(o)+6]), "+v"(a[(o)+7]), \
;     "+v"(a[(o)+8]), "+v"(a[(o)+9]), "+v"(a[(o)+10]), "+v"(a[(o)+11]), "+v"(a[(o)+12]), "+v"(a[(o)+13]), "+v"(a[(o)+14]), "+v"(a[(o)+15]))
;     template <class Tp> __device__ __forceinline__ Tp* W(size_t off) const { return (Tp*)(ws + off); }
; __device__ void dn_d1(const Ctx& c, int ip) {
;     ...
;         if (isw) {
;             bf16_t* dKdT = c.W<bf16_t>(WS_DKDT);
; #pragma unroll
;             for (int l0 = 0; l0 < 64; l0 += 8) { u32x4 a;
;                 a.x = pk2(x[l0 + 0] * __expf(glast - gc_s[l0 + 0]), x[l0 + 1] * __expf(glast - gc_s[l0 + 1])); a.y = pk2(x[l0 + 2] * __expf(glast - gc_s[l0 + 2]), x[l0 + 3] * __expf(glast - gc_s[l0 + 3]));
;                 a.z = pk2(x[l0 + 4] * __expf(glast - gc_s[l0 + 4]), x[l0 + 5] * __expf(glast - gc_s[l0 + 5])); a.w = pk2(x[l0 + 6] * __expf(glast - gc_s[l0 + 6]), x[l0 + 7] * __expf(glast - gc_s[l0 + 7]));
;                 *(u32x4*)(dKdT + (ch * 128 + col) * 64 + l0) = a; }
; #pragma unroll
;             for (int i = 0; i < 64; ++i) x[i] *= beta_s[i] * __expf(gc_s[i]);
;         } else {
;             bf16_t* dQg = c.W<bf16_t>(WS_DQG); const bf16_t* qs = dq + (size_t)t0 * 1024 + h * 128 + col;
;             unsigned qv[64];
; #pragma unroll
;             for (int i = 0; i < 64; ++i) qv[i] = qs[(size_t)i * 1024];
;             PIN16(qv, 0); PIN16(qv, 16); PIN16(qv, 32); PIN16(qv, 48);
; #pragma unroll
;             for (int i = 0; i < 64; ++i) dQg[(ch * 64 + i) * 128 + col] = f2bf(__uint_as_float(qv[i] << 16) * __expf(gc_s[i]));
; #pragma unroll
;             for (int i = 0; i < 64; ++i) x[i] *= beta_s[i];
;         }
.Ldnd_s3:
	global_store_dwordx2 v148, v[164:165], s[4:5] offset:96
	s_waitcnt lgkmcnt(0)
	s_barrier
	v_mov_b32_e32 v10, s24
	s_cmp_lg_u32 s30, 0
	s_cbranch_scc0 .Ldnd_vcol
	v_and_b32_e32 v12, 0x7f, v0
	v_lshrrev_b32_e32 v13, 4, v12
	v_and_b32_e32 v12, 15, v12
	v_lshlrev_b32_e32 v11, 11, v13
	v_lshl_add_u32 v11, v12, 4, v11
	s_lshl_b32 s22, s14, 14
	v_add_u32_e32 v11, s22, v11
	v_add_u32_e32 v11, 0x24100000, v11
	ds_read_b128 v[136:139], v10 offset:52736
	ds_read_b128 v[140:143], v10 offset:52752
	s_waitcnt lgkmcnt(0)
	v_mul_f32_e32 v136, v136, v64
	v_mul_f32_e32 v137, v137, v65
	v_mul_f32_e32 v138, v138, v66
	v_mul_f32_e32 v139, v139, v67
	v_mul_f32_e32 v140, v140, v68
	v_mul_f32_e32 v141, v141, v69
	v_mul_f32_e32 v142, v142, v70
	v_mul_f32_e32 v143, v143, v71
	v_cvt_pk_bf16_f32 v144, v136, v137
	v_cvt_pk_bf16_f32 v145, v138, v139
	v_cvt_pk_bf16_f32 v146, v140, v141
	v_cvt_pk_bf16_f32 v147, v142, v143
	global_store_dwordx4 v11, v[144:147], s[4:5] offset:0
	ds_read_b128 v[136:139], v10 offset:52768
	ds_read_b128 v[140:143], v10 offset:52784
	s_waitcnt lgkmcnt(0)
	v_mul_f32_e32 v136, v136, v72
	v_mul_f32_e32 v137, v137, v73
	v_mul_f32_e32 v138, v138, v74
	v_mul_f32_e32 v139, v139, v75
	v_mul_f32_e32 v140, v140, v76
	v_mul_f32_e32 v141, v141, v77
	v_mul_f32_e32 v142, v142, v78
	v_mul_f32_e32 v143, v143, v79
	v_cvt_pk_bf16_f32 v144, v136, v137
	v_cvt_pk_bf16_f32 v145, v138, v139
	v_cvt_pk_bf16_f32 v146, v140, v141
	v_cvt_pk_bf16_f32 v147, v142, v143
	global_store_dwordx4 v11, v[144:147], s[4:5] offset:256
	ds_read_b128 v[136:139], v10 offset:52800
	ds_read_b128 v[140:143], v10 offset:52816
	s_waitcnt lgkmcnt(0)
	v_mul_f32_e32 v136, v136, v80
	v_mul_f32_e32 v137, v137, v81
	v_mul_f32_e32 v138, v138, v82
	v_mul_f32_e32 v139, v139, v83
	v_mul_f32_e32 v140, v140, v84
	v_mul_f32_e32 v141, v141, v85
	v_mul_f32_e32 v142, v142, v86
	v_mul_f32_e32 v143, v143, v87
	v_cvt_pk_bf16_f32 v144, v136, v137
	v_cvt_pk_bf16_f32 v145, v138, v139
	v_cvt_pk_bf16_f32 v146, v140, v141
	v_cvt_pk_bf16_f32 v147, v142, v143
	global_store_dwordx4 v11, v[144:147], s[4:5] offset:512
	ds_read_b128 v[136:139], v10 offset:52832
	ds_read_b128 v[140:143], v10 offset:52848
	s_waitcnt lgkmcnt(0)
	v_mul_f32_e32 v136, v136, v88
	v_mul_f32_e32 v137, v137, v89
	v_mul_f32_e32 v138, v138, v90
	v_mul_f32_e32 v139, v139, v91
	v_mul_f32_e32 v140, v140, v92
	v_mul_f32_e32 v141, v141, v93
	v_mul_f32_e32 v142, v142, v94
	v_mul_f32_e32 v143, v143, v95
	v_cvt_pk_bf16_f32 v144, v136, v137
	v_cvt_pk_bf16_f32 v145, v138, v139
	v_cvt_pk_bf16_f32 v146, v140, v141
	v_cvt_pk_bf16_f32 v147, v142, v143
	global_store_dwordx4 v11, v[144:147], s[4:5] offset:768
	ds_read_b128 v[136:139], v10 offset:52864
	ds_read_b128 v[140:143], v10 offset:52880
	s_waitcnt lgkmcnt(0)
	v_mul_f32_e32 v136, v136, v96
	v_mul_f32_e32 v137, v137, v97
	v_mul_f32_e32 v138, v138, v98
	v_mul_f32_e32 v139, v139, v99
	v_mul_f32_e32 v140, v140, v100
	v_mul_f32_e32 v141, v141, v101
	v_mul_f32_e32 v142, v142, v102
	v_mul_f32_e32 v143, v143, v103
	v_cvt_pk_bf16_f32 v144, v136, v137
	v_cvt_pk_bf16_f32 v145, v138, v139
	v_cvt_pk_bf16_f32 v146, v140, v141
	v_cvt_pk_bf16_f32 v147, v142, v143
	global_store_dwordx4 v11, v[144:147], s[4:5] offset:1024
	ds_read_b128 v[136:139], v10 offset:52896
	ds_read_b128 v[140:143], v10 offset:52912
	s_waitcnt lgkmcnt(0)
	v_mul_f32_e32 v136, v136, v104
	v_mul_f32_e32 v137, v137, v105
	v_mul_f32_e32 v138, v138, v106
	v_mul_f32_e32 v139, v139, v107
	v_mul_f32_e32 v140, v140, v108
	v_mul_f32_e32 v141, v141, v109
	v_mul_f32_e32 v142, v142, v110
	v_mul_f32_e32 v143, v143, v111
	v_cvt_pk_bf16_f32 v144, v136, v137
	v_cvt_pk_bf16_f32 v145, v138, v139
	v_cvt_pk_bf16_f32 v146, v140, v141
	v_cvt_pk_bf16_f32 v147, v142, v143
	global_store_dwordx4 v11, v[144:147], s[4:5] offset:1280
	ds_read_b128 v[136:139], v10 offset:52928
	ds_read_b128 v[140:143], v10 offset:52944
	s_waitcnt lgkmcnt(0)
	v_mul_f32_e32 v136, v136, v112
	v_mul_f32_e32 v137, v137, v113
	v_mul_f32_e32 v138, v138, v114
	v_mul_f32_e32 v139, v139, v115
	v_mul_f32_e32 v140, v140, v116
	v_mul_f32_e32 v141, v141, v117
	v_mul_f32_e32 v142, v142, v118
	v_mul_f32_e32 v143, v143, v119
	v_cvt_pk_bf16_f32 v144, v136, v137
	v_cvt_pk_bf16_f32 v145, v138, v139
	v_cvt_pk_bf16_f32 v146, v140, v141
	v_cvt_pk_bf16_f32 v147, v142, v143
	global_store_dwordx4 v11, v[144:147], s[4:5] offset:1536
	ds_read_b128 v[136:139], v10 offset:52960
	ds_read_b128 v[140:143], v10 offset:52976
	s_waitcnt lgkmcnt(0)
	v_mul_f32_e32 v136, v136, v120
	v_mul_f32_e32 v137, v137, v121
	v_mul_f32_e32 v138, v138, v122
	v_mul_f32_e32 v139, v139, v123
	v_mul_f32_e32 v140, v140, v124
	v_mul_f32_e32 v141, v141, v125
	v_mul_f32_e32 v142, v142, v126
	v_mul_f32_e32 v143, v143, v127
	v_cvt_pk_bf16_f32 v144, v136, v137
	v_cvt_pk_bf16_f32 v145, v138, v139
	v_cvt_pk_bf16_f32 v146, v140, v141
	v_cvt_pk_bf16_f32 v147, v142, v143
	global_store_dwordx4 v11, v[144:147], s[4:5] offset:1792
	s_mov_b32 s31, 52992
	s_branch .Ldnd_scale
.Ldnd_vcol:
	s_mov_b32 s31, 52480
; #define PIN16(a, o) asm volatile("" : "+v"(a[(o)+0]), "+v"(a[(o)+1]), "+v"(a[(o)+2]), "+v"(a[(o)+3]), "+v"(a[(o)+4]), "+v"(a[(o)+5]), "+v"(a[(o)+6]), "+v"(a[(o)+7]), \
;     "+v"(a[(o)+8]), "+v"(a[(o)+9]), "+v"(a[(o)+10]), "+v"(a[(o)+11]), "+v"(a[(o)+12]), "+v"(a[(o)+13]), "+v"(a[(o)+14]), "+v"(a[(o)+15]))
; __device__ void dn_d1(const Ctx& c, int ip) {
;     ...
;             for (int i = 0; i < 64; ++i) x[i] *= beta_s[i] * __expf(gc_s[i]);
;         } else {
;             bf16_t* dQg = c.W<bf16_t>(WS_DQG); const bf16_t* qs = dq + (size_t)t0 * 1024 + h * 128 + col;
;             unsigned qv[64];
; #pragma unroll
;             for (int i = 0; i < 64; ++i) qv[i] = qs[(size_t)i * 1024];
;             PIN16(qv, 0); PIN16(qv, 16); PIN16(qv, 32); PIN16(qv, 48);
; #pragma unroll
;             for (int i = 0; i < 64; ++i) dQg[(ch * 64 + i) * 128 + col] = f2bf(__uint_as_float(qv[i] << 16) * __expf(gc_s[i]));
; #pragma unroll
;             for (int i = 0; i < 64; ++i) x[i] *= beta_s[i];
;     ...
;     SOLVE_ROW_BEGIN(1)
;     { const f32x4 m = *(const f32x4*)(mr + 0);
;       a0 -= m[0] * x[0];
;     }
;     SOLVE_ROW_END(1)
;     SOLVE_ROW_BEGIN(2)
;     { const f32x4 m = *(const f32x4*)(mr + 0);
;       a0 -= m[0] * x[0];
;       a1 -= m[1] * x[1];
;     }
;     SOLVE_ROW_END(2)
;     SOLVE_ROW_BEGIN(3)
;     { const f32x4 m = *(const f32x4*)(mr + 0);
;       a0 -= m[0] * x[0];
;       a1 -= m[1] * x[1];
;       a2 -= m[2] * x[2];
;     }
;     SOLVE_ROW_END(3)
;     SOLVE_ROW_BEGIN(4)
;     { const f32x4 m = *(const f32x4*)(mr + 0);
;       a0 -= m[0] * x[0];
;       a1 -= m[1] * x[1];
;       a2 -= m[2] * x[2];
;       a3 -= m[3] * x[3];
;     }
;     SOLVE_ROW_END(4)
;     SOLVE_ROW_BEGIN(5)
;     { const f32x4 m = *(const f32x4*)(mr + 0);
;       a0 -= m[0] * x[0];
;       a1 -= m[1] * x[1];
;       a2 -= m[2] * x[2];
;       a3 -= m[3] * x[3];
;     }
;     { const f32x4 m = *(const f32x4*)(mr + 4);
;       a0 -= m[0] * x[4];
;     }
;     SOLVE_ROW_END(5)
;     SOLVE_ROW_BEGIN(6)
;     { const f32x4 m = *(const f32x4*)(mr + 0);
;       a0 -= m[0] * x[0];
;       a1 -= m[1] * x[1];
;       a2 -= m[2] * x[2];
;       a3 -= m[3] * x[3];
;     }
;     { const f32x4 m = *(const f32x4*)(mr + 4);
;       a0 -= m[0] * x[4];
;       a1 -= m[1] * x[5];
;     }
;     SOLVE_ROW_END(6)
.Ldnd_scale:
	v_add_u32_e32 v12, s31, v10
	ds_read_b128 v[136:139], v12 offset:0
	ds_read_b128 v[140:143], v12 offset:16
	s_waitcnt lgkmcnt(0)
	v_mul_f32_e32 v64, v64, v136
	v_mul_f32_e32 v65, v65, v137
	v_mul_f32_e32 v66, v66, v138
	v_mul_f32_e32 v67, v67, v139
	v_mul_f32_e32 v68, v68, v140
	v_mul_f32_e32 v69, v69, v141
	v_mul_f32_e32 v70, v70, v142
	v_mul_f32_e32 v71, v71, v143
	ds_read_b128 v[136:139], v12 offset:32
	ds_read_b128 v[140:143], v12 offset:48
	s_waitcnt lgkmcnt(0)
	v_mul_f32_e32 v72, v72, v136
	v_mul_f32_e32 v73, v73, v137
	v_mul_f32_e32 v74, v74, v138
	v_mul_f32_e32 v75, v75, v139
	v_mul_f32_e32 v76, v76, v140
	v_mul_f32_e32 v77, v77, v141
	v_mul_f32_e32 v78, v78, v142
	v_mul_f32_e32 v79, v79, v143
	ds_read_b128 v[136:139], v12 offset:64
	ds_read_b128 v[140:143], v12 offset:80
	s_waitcnt lgkmcnt(0)
	v_mul_f32_e32 v80, v80, v136
	v_mul_f32_e32 v81, v81, v137
	v_mul_f32_e32 v82, v82, v138
	v_mul_f32_e32 v83, v83, v139
	v_mul_f32_e32 v84, v84, v140
	v_mul_f32_e32 v85, v85, v141
	v_mul_f32_e32 v86, v86, v142
	v_mul_f32_e32 v87, v87, v143
	ds_read_b128 v[136:139], v12 offset:96
	ds_read_b128 v[140:143], v12 offset:112
	s_waitcnt lgkmcnt(0)
	v_mul_f32_e32 v88, v88, v136
	v_mul_f32_e32 v89, v89, v137
	v_mul_f32_e32 v90, v90, v138
	v_mul_f32_e32 v91, v91, v139
	v_mul_f32_e32 v92, v92, v140
	v_mul_f32_e32 v93, v93, v141
	v_mul_f32_e32 v94, v94, v142
	v_mul_f32_e32 v95, v95, v143
	ds_read_b128 v[136:139], v12 offset:128
	ds_read_b128 v[140:143], v12 offset:144
	s_waitcnt lgkmcnt(0)
	v_mul_f32_e32 v96, v96, v136
	v_mul_f32_e32 v97, v97, v137
	v_mul_f32_e32 v98, v98, v138
	v_mul_f32_e32 v99, v99, v139
	v_mul_f32_e32 v100, v100, v140
	v_mul_f32_e32 v101, v101, v141
	v_mul_f32_e32 v102, v102, v142
	v_mul_f32_e32 v103, v103, v143
	ds_read_b128 v[136:139], v12 offset:160
	ds_read_b128 v[140:143], v12 offset:176
	s_waitcnt lgkmcnt(0)
	v_mul_f32_e32 v104, v104, v136
	v_mul_f32_e32 v105, v105, v137
	v_mul_f32_e32 v106, v106, v138
	v_mul_f32_e32 v107, v107, v139
	v_mul_f32_e32 v108, v108, v140
	v_mul_f32_e32 v109, v109, v141
	v_mul_f32_e32 v110, v110, v142
	v_mul_f32_e32 v111, v111, v143
	ds_read_b128 v[136:139], v12 offset:192
	ds_read_b128 v[140:143], v12 offset:208
	s_waitcnt lgkmcnt(0)
	v_mul_f32_e32 v112, v112, v136
	v_mul_f32_e32 v113, v113, v137
	v_mul_f32_e32 v114, v114, v138
	v_mul_f32_e32 v115, v115, v139
	v_mul_f32_e32 v116, v116, v140
	v_mul_f32_e32 v117, v117, v141
	v_mul_f32_e32 v118, v118, v142
	v_mul_f32_e32 v119, v119, v143
	ds_read_b128 v[136:139], v12 offset:224
	ds_read_b128 v[140:143], v12 offset:240
	s_waitcnt lgkmcnt(0)
	v_mul_f32_e32 v120, v120, v136
	v_mul_f32_e32 v121, v121, v137
	v_mul_f32_e32 v122, v122, v138
	v_mul_f32_e32 v123, v123, v139
	v_mul_f32_e32 v124, v124, v140
	v_mul_f32_e32 v125, v125, v141
	v_mul_f32_e32 v126, v126, v142
	v_mul_f32_e32 v127, v127, v143
	v_and_b32_e32 v12, 3, v3
	v_lshl_add_u32 v10, v12, 4, s24
	ds_read_b128 v[136:139], v10 offset:272
	ds_read_b128 v[140:143], v10 offset:544
	ds_read_b128 v[144:147], v10 offset:816
	ds_read_b128 v[148:151], v10 offset:1088
	ds_read_b128 v[152:155], v10 offset:1360
	ds_read_b128 v[156:159], v10 offset:1632
	s_waitcnt lgkmcnt(5)
	v_fmac_f32_dpp v65, v136, v64 quad_perm:[0,0,0,0] row_mask:0xf bank_mask:0xf
	ds_read_b128 v[160:163], v10 offset:1904
	s_waitcnt lgkmcnt(5)
	v_mov_b32_e32 v168, 0
	v_fmac_f32_dpp v66, v140, v64 quad_perm:[0,0,0,0] row_mask:0xf bank_mask:0xf
	v_fmac_f32_dpp v168, v141, v65 quad_perm:[0,0,0,0] row_mask:0xf bank_mask:0xf
	v_add_f32_e32 v66, v66, v168
	ds_read_b128 v[164:167], v10 offset:2176
	s_waitcnt lgkmcnt(5)
	v_mov_b32_e32 v168, 0
	v_mov_b32_e32 v169, 0
	v_fmac_f32_dpp v67, v144, v64 quad_perm:[0,0,0,0] row_mask:0xf bank_mask:0xf
	v_fmac_f32_dpp v168, v145, v65 quad_perm:[0,0,0,0] row_mask:0xf bank_mask:0xf
	v_fmac_f32_dpp v169, v146, v66 quad_perm:[0,0,0,0] row_mask:0xf bank_mask:0xf
	v_add_f32_e32 v67, v67, v168
	v_add_f32_e32 v67, v67, v169
	ds_read_b128 v[136:139], v10 offset:2448
	s_waitcnt lgkmcnt(5)
	v_mov_b32_e32 v168, 0
	v_mov_b32_e32 v169, 0
	v_mov_b32_e32 v170, 0
	v_fmac_f32_dpp v68, v148, v64 quad_perm:[0,0,0,0] row_mask:0xf bank_mask:0xf
	v_fmac_f32_dpp v168, v149, v65 quad_perm:[0,0,0,0] row_mask:0xf bank_mask:0xf
	v_fmac_f32_dpp v169, v150, v66 quad_perm:[0,0,0,0] row_mask:0xf bank_mask:0xf
	v_fmac_f32_dpp v170, v151, v67 quad_perm:[0,0,0,0] row_mask:0xf bank_mask:0xf
	v_add_f32_e32 v68, v68, v168
	v_add_f32_e32 v169, v169, v170
	v_add_f32_e32 v68, v68, v169
	ds_read_b128 v[140:143], v10 offset:2720
	s_waitcnt lgkmcnt(5)
	v_mov_b32_e32 v168, 0
	v_mov_b32_e32 v169, 0
	v_mov_b32_e32 v170, 0
	v_fmac_f32_dpp v69, v152, v64 quad_perm:[0,0,0,0] row_mask:0xf bank_mask:0xf
	v_fmac_f32_dpp v168, v153, v65 quad_perm:[0,0,0,0] row_mask:0xf bank_mask:0xf
	v_fmac_f32_dpp v169, v154, v66 quad_perm:[0,0,0,0] row_mask:0xf bank_mask:0xf
	v_fmac_f32_dpp v170, v155, v67 quad_perm:[0,0,0,0] row_mask:0xf bank_mask:0xf
	v_fmac_f32_dpp v69, v152, v68 quad_perm:[1,1,1,1] row_mask:0xf bank_mask:0xf
	v_add_f32_e32 v69, v69, v168
	v_add_f32_e32 v169, v169, v170
	v_add_f32_e32 v69, v69, v169
	ds_read_b128 v[144:147], v10 offset:2992
	s_waitcnt lgkmcnt(5)
	v_mov_b32_e32 v168, 0
	v_mov_b32_e32 v169, 0
	v_mov_b32_e32 v170, 0
	v_fmac_f32_dpp v70, v156, v64 quad_perm:[0,0,0,0] row_mask:0xf bank_mask:0xf
	v_fmac_f32_dpp v168, v157, v65 quad_perm:[0,0,0,0] row_mask:0xf bank_mask:0xf
	v_fmac_f32_dpp v169, v158, v66 quad_perm:[0,0,0,0] row_mask:0xf bank_mask:0xf
	v_fmac_f32_dpp v170, v159, v67 quad_perm:[0,0,0,0] row_mask:0xf bank_mask:0xf
	v_fmac_f32_dpp v70, v156, v68 quad_perm:[1,1,1,1] row_mask:0xf bank_mask:0xf
	v_fmac_f32_dpp v168, v157, v69 quad_perm:[1,1,1,1] row_mask:0xf bank_mask:0xf
	v_add_f32_e32 v70, v70, v168
	v_add_f32_e32 v169, v169, v170
	v_add_f32_e32 v70, v70, v169
	ds_read_b128 v[148:151], v10 offset:3264
	s_waitcnt lgkmcnt(5)
; __device__ void dn_d1(const Ctx& c, int ip) {
;     ...
;     SOLVE_ROW_BEGIN(10)
;     { const f32x4 m = *(const f32x4*)(mr + 0);
;       a0 -= m[0] * x[0];
;       a1 -= m[1] * x[1];
;       a2 -= m[2] * x[2];
;       a3 -= m[3] * x[3];
;     }
;     { const f32x4 m = *(const f32x4*)(mr + 4);
;       a0 -= m[0] * x[4];
;       a1 -= m[1] * x[5];
;       a2 -= m[2] * x[6];
;       a3 -= m[3] * x[7];
;     }
;     { const f32x4 m = *(const f32x4*)(mr + 8);
;       a0 -= m[0] * x[8];
;       a1 -= m[1] * x[9];
;     }
;     SOLVE_ROW_END(10)
;     SOLVE_ROW_BEGIN(11)
;     { const f32x4 m = *(const f32x4*)(mr + 0);
;       a0 -= m[0] * x[0];
;       a1 -= m[1] * x[1];
;       a2 -= m[2] * x[2];
;       a3 -= m[3] * x[3];
;     }
;     { const f32x4 m = *(const f32x4*)(mr + 4);
;       a0 -= m[0] * x[4];
;       a1 -= m[1] * x[5];
;       a2 -= m[2] * x[6];
;       a3 -= m[3] * x[7];
;     }
;     { const f32x4 m = *(const f32x4*)(mr + 8);
;       a0 -= m[0] * x[8];
;       a1 -= m[1] * x[9];
;       a2 -= m[2] * x[10];
;     }
;     SOLVE_ROW_END(11)
;     SOLVE_ROW_BEGIN(12)
;     { const f32x4 m = *(const f32x4*)(mr + 0);
;       a0 -= m[0] * x[0];
;       a1 -= m[1] * x[1];
;       a2 -= m[2] * x[2];
;       a3 -= m[3] * x[3];
;     }
;     { const f32x4 m = *(const f32x4*)(mr + 4);
;       a0 -= m[0] * x[4];
;       a1 -= m[1] * x[5];
;       a2 -= m[2] * x[6];
;       a3 -= m[3] * x[7];
;     }
;     { const f32x4 m = *(const f32x4*)(mr + 8);
;       a0 -= m[0] * x[8];
;       a1 -= m[1] * x[9];
;       a2 -= m[2] * x[10];
;       a3 -= m[3] * x[11];
;     }
;     SOLVE_ROW_END(12)
	v_mov_b32_e32 v168, 0
	v_mov_b32_e32 v169, 0
	v_mov_b32_e32 v170, 0
	v_fmac_f32_dpp v71, v160, v64 quad_perm:[0,0,0,0] row_mask:0xf bank_mask:0xf
	v_fmac_f32_dpp v168, v161, v65 quad_perm:[0,0,0,0] row_mask:0xf bank_mask:0xf
	v_fmac_f32_dpp v169, v162, v66 quad_perm:[0,0,0,0] row_mask:0xf bank_mask:0xf
	v_fmac_f32_dpp v170, v163, v67 quad_perm:[0,0,0,0] row_mask:0xf bank_mask:0xf
	v_fmac_f32_dpp v71, v160, v68 quad_perm:[1,1,1,1] row_mask:0xf bank_mask:0xf
	v_fmac_f32_dpp v168, v161, v69 quad_perm:[1,1,1,1] row_mask:0xf bank_mask:0xf
	v_fmac_f32_dpp v169, v162, v70 quad_perm:[1,1,1,1] row_mask:0xf bank_mask:0xf
	v_add_f32_e32 v71, v71, v168
	v_add_f32_e32 v169, v169, v170
	v_add_f32_e32 v71, v71, v169
	ds_read_b128 v[152:155], v10 offset:3536
	s_waitcnt lgkmcnt(5)
	v_mov_b32_e32 v168, 0
	v_mov_b32_e32 v169, 0
	v_mov_b32_e32 v170, 0
	v_fmac_f32_dpp v72, v164, v64 quad_perm:[0,0,0,0] row_mask:0xf bank_mask:0xf
	v_fmac_f32_dpp v168, v165, v65 quad_perm:[0,0,0,0] row_mask:0xf bank_mask:0xf
	v_fmac_f32_dpp v169, v166, v66 quad_perm:[0,0,0,0] row_mask:0xf bank_mask:0xf
	v_fmac_f32_dpp v170, v167, v67 quad_perm:[0,0,0,0] row_mask:0xf bank_mask:0xf
	v_fmac_f32_dpp v72, v164, v68 quad_perm:[1,1,1,1] row_mask:0xf bank_mask:0xf
	v_fmac_f32_dpp v168, v165, v69 quad_perm:[1,1,1,1] row_mask:0xf bank_mask:0xf
	v_fmac_f32_dpp v169, v166, v70 quad_perm:[1,1,1,1] row_mask:0xf bank_mask:0xf
	v_fmac_f32_dpp v170, v167, v71 quad_perm:[1,1,1,1] row_mask:0xf bank_mask:0xf
	v_add_f32_e32 v72, v72, v168
	v_add_f32_e32 v169, v169, v170
	v_add_f32_e32 v72, v72, v169
	ds_read_b128 v[156:159], v10 offset:3808
	s_waitcnt lgkmcnt(5)
	v_mov_b32_e32 v168, 0
	v_mov_b32_e32 v169, 0
	v_mov_b32_e32 v170, 0
	v_fmac_f32_dpp v73, v136, v64 quad_perm:[0,0,0,0] row_mask:0xf bank_mask:0xf
	v_fmac_f32_dpp v168, v137, v65 quad_perm:[0,0,0,0] row_mask:0xf bank_mask:0xf
	v_fmac_f32_dpp v169, v138, v66 quad_perm:[0,0,0,0] row_mask:0xf bank_mask:0xf
	v_fmac_f32_dpp v170, v139, v67 quad_perm:[0,0,0,0] row_mask:0xf bank_mask:0xf
	v_fmac_f32_dpp v73, v136, v68 quad_perm:[1,1,1,1] row_mask:0xf bank_mask:0xf
	v_fmac_f32_dpp v168, v137, v69 quad_perm:[1,1,1,1] row_mask:0xf bank_mask:0xf
	v_fmac_f32_dpp v169, v138, v70 quad_perm:[1,1,1,1] row_mask:0xf bank_mask:0xf
	v_fmac_f32_dpp v170, v139, v71 quad_perm:[1,1,1,1] row_mask:0xf bank_mask:0xf
	v_fmac_f32_dpp v73, v136, v72 quad_perm:[2,2,2,2] row_mask:0xf bank_mask:0xf
	v_add_f32_e32 v73, v73, v168
	v_add_f32_e32 v169, v169, v170
	v_add_f32_e32 v73, v73, v169
	ds_read_b128 v[160:163], v10 offset:4080
	s_waitcnt lgkmcnt(5)
	v_mov_b32_e32 v168, 0
	v_mov_b32_e32 v169, 0
	v_mov_b32_e32 v170, 0
	v_fmac_f32_dpp v74, v140, v64 quad_perm:[0,0,0,0] row_mask:0xf bank_mask:0xf
	v_fmac_f32_dpp v168, v141, v65 quad_perm:[0,0,0,0] row_mask:0xf bank_mask:0xf
	v_fmac_f32_dpp v169, v142, v66 quad_perm:[0,0,0,0] row_mask:0xf bank_mask:0xf
	v_fmac_f32_dpp v170, v143, v67 quad_perm:[0,0,0,0] row_mask:0xf bank_mask:0xf
	v_fmac_f32_dpp v74, v140, v68 quad_perm:[1,1,1,1] row_mask:0xf bank_mask:0xf
	v_fmac_f32_dpp v168, v141, v69 quad_perm:[1,1,1,1] row_mask:0xf bank_mask:0xf
	v_fmac_f32_dpp v169, v142, v70 quad_perm:[1,1,1,1] row_mask:0xf bank_mask:0xf
	v_fmac_f32_dpp v170, v143, v71 quad_perm:[1,1,1,1] row_mask:0xf bank_mask:0xf
	v_fmac_f32_dpp v74, v140, v72 quad_perm:[2,2,2,2] row_mask:0xf bank_mask:0xf
	v_fmac_f32_dpp v168, v141, v73 quad_perm:[2,2,2,2] row_mask:0xf bank_mask:0xf
	v_add_f32_e32 v74, v74, v168
	v_add_f32_e32 v169, v169, v170
	v_add_f32_e32 v74, v74, v169
	ds_read_b128 v[164:167], v10 offset:4352
	s_waitcnt lgkmcnt(5)
	v_mov_b32_e32 v168, 0
	v_mov_b32_e32 v169, 0
	v_mov_b32_e32 v170, 0
	v_fmac_f32_dpp v75, v144, v64 quad_perm:[0,0,0,0] row_mask:0xf bank_mask:0xf
	v_fmac_f32_dpp v168, v145, v65 quad_perm:[0,0,0,0] row_mask:0xf bank_mask:0xf
	v_fmac_f32_dpp v169, v146, v66 quad_perm:[0,0,0,0] row_mask:0xf bank_mask:0xf
	v_fmac_f32_dpp v170, v147, v67 quad_perm:[0,0,0,0] row_mask:0xf bank_mask:0xf
	v_fmac_f32_dpp v75, v144, v68 quad_perm:[1,1,1,1] row_mask:0xf bank_mask:0xf
	v_fmac_f32_dpp v168, v145, v69 quad_perm:[1,1,1,1] row_mask:0xf bank_mask:0xf
	v_fmac_f32_dpp v169, v146, v70 quad_perm:[1,1,1,1] row_mask:0xf bank_mask:0xf
	v_fmac_f32_dpp v170, v147, v71 quad_perm:[1,1,1,1] row_mask:0xf bank_mask:0xf
	v_fmac_f32_dpp v75, v144, v72 quad_perm:[2,2,2,2] row_mask:0xf bank_mask:0xf
	v_fmac_f32_dpp v168, v145, v73 quad_perm:[2,2,2,2] row_mask:0xf bank_mask:0xf
	v_fmac_f32_dpp v169, v146, v74 quad_perm:[2,2,2,2] row_mask:0xf bank_mask:0xf
	v_add_f32_e32 v75, v75, v168
	v_add_f32_e32 v169, v169, v170
	v_add_f32_e32 v75, v75, v169
	ds_read_b128 v[136:139], v10 offset:4624
	s_waitcnt lgkmcnt(5)
	v_mov_b32_e32 v168, 0
	v_mov_b32_e32 v169, 0
	v_mov_b32_e32 v170, 0
	v_fmac_f32_dpp v76, v148, v64 quad_perm:[0,0,0,0] row_mask:0xf bank_mask:0xf
	v_fmac_f32_dpp v168, v149, v65 quad_perm:[0,0,0,0] row_mask:0xf bank_mask:0xf
	v_fmac_f32_dpp v169, v150, v66 quad_perm:[0,0,0,0] row_mask:0xf bank_mask:0xf
	v_fmac_f32_dpp v170, v151, v67 quad_perm:[0,0,0,0] row_mask:0xf bank_mask:0xf
	v_fmac_f32_dpp v76, v148, v68 quad_perm:[1,1,1,1] row_mask:0xf bank_mask:0xf
	v_fmac_f32_dpp v168, v149, v69 quad_perm:[1,1,1,1] row_mask:0xf bank_mask:0xf
	v_fmac_f32_dpp v169, v150, v70 quad_perm:[1,1,1,1] row_mask:0xf bank_mask:0xf
	v_fmac_f32_dpp v170, v151, v71 quad_perm:[1,1,1,1] row_mask:0xf bank_mask:0xf
	v_fmac_f32_dpp v76, v148, v72 quad_perm:[2,2,2,2] row_mask:0xf bank_mask:0xf
	v_fmac_f32_dpp v168, v149, v73 quad_perm:[2,2,2,2] row_mask:0xf bank_mask:0xf
	v_fmac_f32_dpp v169, v150, v74 quad_perm:[2,2,2,2] row_mask:0xf bank_mask:0xf
	v_fmac_f32_dpp v170, v151, v75 quad_perm:[2,2,2,2] row_mask:0xf bank_mask:0xf
	v_add_f32_e32 v76, v76, v168
	v_add_f32_e32 v169, v169, v170
	v_add_f32_e32 v76, v76, v169
	ds_read_b128 v[140:143], v10 offset:4688
	s_waitcnt lgkmcnt(5)
; __device__ void dn_d1(const Ctx& c, int ip) {
;     ...
;     SOLVE_ROW_BEGIN(15)
;     { const f32x4 m = *(const f32x4*)(mr + 0);
;       a0 -= m[0] * x[0];
;       a1 -= m[1] * x[1];
;       a2 -= m[2] * x[2];
;       a3 -= m[3] * x[3];
;     }
;     { const f32x4 m = *(const f32x4*)(mr + 4);
;       a0 -= m[0] * x[4];
;       a1 -= m[1] * x[5];
;       a2 -= m[2] * x[6];
;       a3 -= m[3] * x[7];
;     }
;     { const f32x4 m = *(const f32x4*)(mr + 8);
;       a0 -= m[0] * x[8];
;       a1 -= m[1] * x[9];
;       a2 -= m[2] * x[10];
;       a3 -= m[3] * x[11];
;     }
;     { const f32x4 m = *(const f32x4*)(mr + 12);
;       a0 -= m[0] * x[12];
;       a1 -= m[1] * x[13];
;       a2 -= m[2] * x[14];
;     }
;     SOLVE_ROW_END(15)
;     SOLVE_ROW_BEGIN(16)
;     { const f32x4 m = *(const f32x4*)(mr + 0);
;       a0 -= m[0] * x[0];
;       a1 -= m[1] * x[1];
;       a2 -= m[2] * x[2];
;       a3 -= m[3] * x[3];
;     }
;     { const f32x4 m = *(const f32x4*)(mr + 4);
;       a0 -= m[0] * x[4];
;       a1 -= m[1] * x[5];
;       a2 -= m[2] * x[6];
;       a3 -= m[3] * x[7];
;     }
;     { const f32x4 m = *(const f32x4*)(mr + 8);
;       a0 -= m[0] * x[8];
;       a1 -= m[1] * x[9];
;       a2 -= m[2] * x[10];
;       a3 -= m[3] * x[11];
;     }
;     { const f32x4 m = *(const f32x4*)(mr + 12);
;       a0 -= m[0] * x[12];
;       a1 -= m[1] * x[13];
;       a2 -= m[2] * x[14];
;       a3 -= m[3] * x[15];
;     }
;     SOLVE_ROW_END(16)
	v_mov_b32_e32 v168, 0
	v_mov_b32_e32 v169, 0
	v_mov_b32_e32 v170, 0
	v_fmac_f32_dpp v77, v152, v64 quad_perm:[0,0,0,0] row_mask:0xf bank_mask:0xf
	v_fmac_f32_dpp v168, v153, v65 quad_perm:[0,0,0,0] row_mask:0xf bank_mask:0xf
	v_fmac_f32_dpp v169, v154, v66 quad_perm:[0,0,0,0] row_mask:0xf bank_mask:0xf
	v_fmac_f32_dpp v170, v155, v67 quad_perm:[0,0,0,0] row_mask:0xf bank_mask:0xf
	v_fmac_f32_dpp v77, v152, v68 quad_perm:[1,1,1,1] row_mask:0xf bank_mask:0xf
	v_fmac_f32_dpp v168, v153, v69 quad_perm:[1,1,1,1] row_mask:0xf bank_mask:0xf
	v_fmac_f32_dpp v169, v154, v70 quad_perm:[1,1,1,1] row_mask:0xf bank_mask:0xf
	v_fmac_f32_dpp v170, v155, v71 quad_perm:[1,1,1,1] row_mask:0xf bank_mask:0xf
	v_fmac_f32_dpp v77, v152, v72 quad_perm:[2,2,2,2] row_mask:0xf bank_mask:0xf
	v_fmac_f32_dpp v168, v153, v73 quad_perm:[2,2,2,2] row_mask:0xf bank_mask:0xf
	v_fmac_f32_dpp v169, v154, v74 quad_perm:[2,2,2,2] row_mask:0xf bank_mask:0xf
	v_fmac_f32_dpp v170, v155, v75 quad_perm:[2,2,2,2] row_mask:0xf bank_mask:0xf
	v_fmac_f32_dpp v77, v152, v76 quad_perm:[3,3,3,3] row_mask:0xf bank_mask:0xf
	v_add_f32_e32 v77, v77, v168
	v_add_f32_e32 v169, v169, v170
	v_add_f32_e32 v77, v77, v169
	ds_read_b128 v[144:147], v10 offset:4896
	s_waitcnt lgkmcnt(5)
	v_mov_b32_e32 v168, 0
	v_mov_b32_e32 v169, 0
	v_mov_b32_e32 v170, 0
	v_fmac_f32_dpp v78, v156, v64 quad_perm:[0,0,0,0] row_mask:0xf bank_mask:0xf
	v_fmac_f32_dpp v168, v157, v65 quad_perm:[0,0,0,0] row_mask:0xf bank_mask:0xf
	v_fmac_f32_dpp v169, v158, v66 quad_perm:[0,0,0,0] row_mask:0xf bank_mask:0xf
	v_fmac_f32_dpp v170, v159, v67 quad_perm:[0,0,0,0] row_mask:0xf bank_mask:0xf
	v_fmac_f32_dpp v78, v156, v68 quad_perm:[1,1,1,1] row_mask:0xf bank_mask:0xf
	v_fmac_f32_dpp v168, v157, v69 quad_perm:[1,1,1,1] row_mask:0xf bank_mask:0xf
	v_fmac_f32_dpp v169, v158, v70 quad_perm:[1,1,1,1] row_mask:0xf bank_mask:0xf
	v_fmac_f32_dpp v170, v159, v71 quad_perm:[1,1,1,1] row_mask:0xf bank_mask:0xf
	v_fmac_f32_dpp v78, v156, v72 quad_perm:[2,2,2,2] row_mask:0xf bank_mask:0xf
	v_fmac_f32_dpp v168, v157, v73 quad_perm:[2,2,2,2] row_mask:0xf bank_mask:0xf
	v_fmac_f32_dpp v169, v158, v74 quad_perm:[2,2,2,2] row_mask:0xf bank_mask:0xf
	v_fmac_f32_dpp v170, v159, v75 quad_perm:[2,2,2,2] row_mask:0xf bank_mask:0xf
	v_fmac_f32_dpp v78, v156, v76 quad_perm:[3,3,3,3] row_mask:0xf bank_mask:0xf
	v_fmac_f32_dpp v168, v157, v77 quad_perm:[3,3,3,3] row_mask:0xf bank_mask:0xf
	v_add_f32_e32 v78, v78, v168
	v_add_f32_e32 v169, v169, v170
	v_add_f32_e32 v78, v78, v169
	ds_read_b128 v[148:151], v10 offset:4960
	s_waitcnt lgkmcnt(5)
	v_mov_b32_e32 v168, 0
	v_mov_b32_e32 v169, 0
	v_mov_b32_e32 v170, 0
	v_fmac_f32_dpp v79, v160, v64 quad_perm:[0,0,0,0] row_mask:0xf bank_mask:0xf
	v_fmac_f32_dpp v168, v161, v65 quad_perm:[0,0,0,0] row_mask:0xf bank_mask:0xf
	v_fmac_f32_dpp v169, v162, v66 quad_perm:[0,0,0,0] row_mask:0xf bank_mask:0xf
	v_fmac_f32_dpp v170, v163, v67 quad_perm:[0,0,0,0] row_mask:0xf bank_mask:0xf
	v_fmac_f32_dpp v79, v160, v68 quad_perm:[1,1,1,1] row_mask:0xf bank_mask:0xf
	v_fmac_f32_dpp v168, v161, v69 quad_perm:[1,1,1,1] row_mask:0xf bank_mask:0xf
	v_fmac_f32_dpp v169, v162, v70 quad_perm:[1,1,1,1] row_mask:0xf bank_mask:0xf
	v_fmac_f32_dpp v170, v163, v71 quad_perm:[1,1,1,1] row_mask:0xf bank_mask:0xf
	v_fmac_f32_dpp v79, v160, v72 quad_perm:[2,2,2,2] row_mask:0xf bank_mask:0xf
	v_fmac_f32_dpp v168, v161, v73 quad_perm:[2,2,2,2] row_mask:0xf bank_mask:0xf
	v_fmac_f32_dpp v169, v162, v74 quad_perm:[2,2,2,2] row_mask:0xf bank_mask:0xf
	v_fmac_f32_dpp v170, v163, v75 quad_perm:[2,2,2,2] row_mask:0xf bank_mask:0xf
	v_fmac_f32_dpp v79, v160, v76 quad_perm:[3,3,3,3] row_mask:0xf bank_mask:0xf
	v_fmac_f32_dpp v168, v161, v77 quad_perm:[3,3,3,3] row_mask:0xf bank_mask:0xf
	v_fmac_f32_dpp v169, v162, v78 quad_perm:[3,3,3,3] row_mask:0xf bank_mask:0xf
	v_add_f32_e32 v79, v79, v168
	v_add_f32_e32 v169, v169, v170
	v_add_f32_e32 v79, v79, v169
	ds_read_b128 v[152:155], v10 offset:5168
	s_waitcnt lgkmcnt(5)
	v_mov_b32_e32 v168, 0
	v_mov_b32_e32 v169, 0
	v_mov_b32_e32 v170, 0
	v_fmac_f32_dpp v80, v164, v64 quad_perm:[0,0,0,0] row_mask:0xf bank_mask:0xf
	v_fmac_f32_dpp v168, v165, v65 quad_perm:[0,0,0,0] row_mask:0xf bank_mask:0xf
	v_fmac_f32_dpp v169, v166, v66 quad_perm:[0,0,0,0] row_mask:0xf bank_mask:0xf
	v_fmac_f32_dpp v170, v167, v67 quad_perm:[0,0,0,0] row_mask:0xf bank_mask:0xf
	v_fmac_f32_dpp v80, v164, v68 quad_perm:[1,1,1,1] row_mask:0xf bank_mask:0xf
	v_fmac_f32_dpp v168, v165, v69 quad_perm:[1,1,1,1] row_mask:0xf bank_mask:0xf
	v_fmac_f32_dpp v169, v166, v70 quad_perm:[1,1,1,1] row_mask:0xf bank_mask:0xf
	v_fmac_f32_dpp v170, v167, v71 quad_perm:[1,1,1,1] row_mask:0xf bank_mask:0xf
	v_fmac_f32_dpp v80, v164, v72 quad_perm:[2,2,2,2] row_mask:0xf bank_mask:0xf
	v_fmac_f32_dpp v168, v165, v73 quad_perm:[2,2,2,2] row_mask:0xf bank_mask:0xf
	v_fmac_f32_dpp v169, v166, v74 quad_perm:[2,2,2,2] row_mask:0xf bank_mask:0xf
	v_fmac_f32_dpp v170, v167, v75 quad_perm:[2,2,2,2] row_mask:0xf bank_mask:0xf
	v_fmac_f32_dpp v80, v164, v76 quad_perm:[3,3,3,3] row_mask:0xf bank_mask:0xf
	v_fmac_f32_dpp v168, v165, v77 quad_perm:[3,3,3,3] row_mask:0xf bank_mask:0xf
	v_fmac_f32_dpp v169, v166, v78 quad_perm:[3,3,3,3] row_mask:0xf bank_mask:0xf
	v_fmac_f32_dpp v170, v167, v79 quad_perm:[3,3,3,3] row_mask:0xf bank_mask:0xf
	v_add_f32_e32 v80, v80, v168
	v_add_f32_e32 v169, v169, v170
	v_add_f32_e32 v80, v80, v169
	ds_read_b128 v[156:159], v10 offset:5232
	s_waitcnt lgkmcnt(5)
; __device__ void dn_d1(const Ctx& c, int ip) {
;     ...
;     { const f32x4 m = *(const f32x4*)(mr + 0);
;       a0 -= m[0] * x[0];
;       a1 -= m[1] * x[1];
;       a2 -= m[2] * x[2];
;       a3 -= m[3] * x[3];
;     }
;     { const f32x4 m = *(const f32x4*)(mr + 4);
;       a0 -= m[0] * x[4];
;       a1 -= m[1] * x[5];
;       a2 -= m[2] * x[6];
;       a3 -= m[3] * x[7];
;     }
;     { const f32x4 m = *(const f32x4*)(mr + 8);
;       a0 -= m[0] * x[8];
;       a1 -= m[1] * x[9];
;       a2 -= m[2] * x[10];
;       a3 -= m[3] * x[11];
;     }
;     { const f32x4 m = *(const f32x4*)(mr + 12);
;       a0 -= m[0] * x[12];
;       a1 -= m[1] * x[13];
;       a2 -= m[2] * x[14];
;       a3 -= m[3] * x[15];
;     }
;     { const f32x4 m = *(const f32x4*)(mr + 16);
;       a0 -= m[0] * x[16];
;       a1 -= m[1] * x[17];
;     }
;     SOLVE_ROW_END(18)
;     SOLVE_ROW_BEGIN(19)
;     { const f32x4 m = *(const f32x4*)(mr + 0);
;       a0 -= m[0] * x[0];
;       a1 -= m[1] * x[1];
;       a2 -= m[2] * x[2];
;       a3 -= m[3] * x[3];
;     }
;     { const f32x4 m = *(const f32x4*)(mr + 4);
;       a0 -= m[0] * x[4];
;       a1 -= m[1] * x[5];
;       a2 -= m[2] * x[6];
;       a3 -= m[3] * x[7];
;     }
;     { const f32x4 m = *(const f32x4*)(mr + 8);
;       a0 -= m[0] * x[8];
;       a1 -= m[1] * x[9];
;       a2 -= m[2] * x[10];
;       a3 -= m[3] * x[11];
;     }
;     { const f32x4 m = *(const f32x4*)(mr + 12);
;       a0 -= m[0] * x[12];
;       a1 -= m[1] * x[13];
;       a2 -= m[2] * x[14];
;       a3 -= m[3] * x[15];
;     }
;     { const f32x4 m = *(const f32x4*)(mr + 16);
;       a0 -= m[0] * x[16];
;       a1 -= m[1] * x[17];
;       a2 -= m[2] * x[18];
;     }
;     SOLVE_ROW_END(19)
	v_mov_b32_e32 v168, 0
	v_mov_b32_e32 v169, 0
	v_mov_b32_e32 v170, 0
	v_fmac_f32_dpp v81, v136, v64 quad_perm:[0,0,0,0] row_mask:0xf bank_mask:0xf
	v_fmac_f32_dpp v168, v137, v65 quad_perm:[0,0,0,0] row_mask:0xf bank_mask:0xf
	v_fmac_f32_dpp v169, v138, v66 quad_perm:[0,0,0,0] row_mask:0xf bank_mask:0xf
	v_fmac_f32_dpp v170, v139, v67 quad_perm:[0,0,0,0] row_mask:0xf bank_mask:0xf
	v_fmac_f32_dpp v81, v136, v68 quad_perm:[1,1,1,1] row_mask:0xf bank_mask:0xf
	v_fmac_f32_dpp v168, v137, v69 quad_perm:[1,1,1,1] row_mask:0xf bank_mask:0xf
	v_fmac_f32_dpp v169, v138, v70 quad_perm:[1,1,1,1] row_mask:0xf bank_mask:0xf
	v_fmac_f32_dpp v170, v139, v71 quad_perm:[1,1,1,1] row_mask:0xf bank_mask:0xf
	v_fmac_f32_dpp v81, v136, v72 quad_perm:[2,2,2,2] row_mask:0xf bank_mask:0xf
	v_fmac_f32_dpp v168, v137, v73 quad_perm:[2,2,2,2] row_mask:0xf bank_mask:0xf
	v_fmac_f32_dpp v169, v138, v74 quad_perm:[2,2,2,2] row_mask:0xf bank_mask:0xf
	v_fmac_f32_dpp v170, v139, v75 quad_perm:[2,2,2,2] row_mask:0xf bank_mask:0xf
	v_fmac_f32_dpp v81, v136, v76 quad_perm:[3,3,3,3] row_mask:0xf bank_mask:0xf
	v_fmac_f32_dpp v168, v137, v77 quad_perm:[3,3,3,3] row_mask:0xf bank_mask:0xf
	v_fmac_f32_dpp v169, v138, v78 quad_perm:[3,3,3,3] row_mask:0xf bank_mask:0xf
	v_fmac_f32_dpp v170, v139, v79 quad_perm:[3,3,3,3] row_mask:0xf bank_mask:0xf
	ds_read_b128 v[160:163], v10 offset:5440
	s_waitcnt lgkmcnt(5)
	v_fmac_f32_dpp v81, v140, v80 quad_perm:[0,0,0,0] row_mask:0xf bank_mask:0xf
	v_add_f32_e32 v81, v81, v168
	v_add_f32_e32 v169, v169, v170
	v_add_f32_e32 v81, v81, v169
	ds_read_b128 v[164:167], v10 offset:5504
	s_waitcnt lgkmcnt(5)
	v_mov_b32_e32 v168, 0
	v_mov_b32_e32 v169, 0
	v_mov_b32_e32 v170, 0
	v_fmac_f32_dpp v82, v144, v64 quad_perm:[0,0,0,0] row_mask:0xf bank_mask:0xf
	v_fmac_f32_dpp v168, v145, v65 quad_perm:[0,0,0,0] row_mask:0xf bank_mask:0xf
	v_fmac_f32_dpp v169, v146, v66 quad_perm:[0,0,0,0] row_mask:0xf bank_mask:0xf
	v_fmac_f32_dpp v170, v147, v67 quad_perm:[0,0,0,0] row_mask:0xf bank_mask:0xf
	v_fmac_f32_dpp v82, v144, v68 quad_perm:[1,1,1,1] row_mask:0xf bank_mask:0xf
	v_fmac_f32_dpp v168, v145, v69 quad_perm:[1,1,1,1] row_mask:0xf bank_mask:0xf
	v_fmac_f32_dpp v169, v146, v70 quad_perm:[1,1,1,1] row_mask:0xf bank_mask:0xf
	v_fmac_f32_dpp v170, v147, v71 quad_perm:[1,1,1,1] row_mask:0xf bank_mask:0xf
	v_fmac_f32_dpp v82, v144, v72 quad_perm:[2,2,2,2] row_mask:0xf bank_mask:0xf
	v_fmac_f32_dpp v168, v145, v73 quad_perm:[2,2,2,2] row_mask:0xf bank_mask:0xf
	v_fmac_f32_dpp v169, v146, v74 quad_perm:[2,2,2,2] row_mask:0xf bank_mask:0xf
	v_fmac_f32_dpp v170, v147, v75 quad_perm:[2,2,2,2] row_mask:0xf bank_mask:0xf
	v_fmac_f32_dpp v82, v144, v76 quad_perm:[3,3,3,3] row_mask:0xf bank_mask:0xf
	v_fmac_f32_dpp v168, v145, v77 quad_perm:[3,3,3,3] row_mask:0xf bank_mask:0xf
	v_fmac_f32_dpp v169, v146, v78 quad_perm:[3,3,3,3] row_mask:0xf bank_mask:0xf
	v_fmac_f32_dpp v170, v147, v79 quad_perm:[3,3,3,3] row_mask:0xf bank_mask:0xf
	ds_read_b128 v[136:139], v10 offset:5712
	s_waitcnt lgkmcnt(5)
	v_fmac_f32_dpp v82, v148, v80 quad_perm:[0,0,0,0] row_mask:0xf bank_mask:0xf
	v_fmac_f32_dpp v168, v149, v81 quad_perm:[0,0,0,0] row_mask:0xf bank_mask:0xf
	v_add_f32_e32 v82, v82, v168
	v_add_f32_e32 v169, v169, v170
	v_add_f32_e32 v82, v82, v169
	ds_read_b128 v[140:143], v10 offset:5776
	s_waitcnt lgkmcnt(5)
	v_mov_b32_e32 v168, 0
	v_mov_b32_e32 v169, 0
	v_mov_b32_e32 v170, 0
	v_fmac_f32_dpp v83, v152, v64 quad_perm:[0,0,0,0] row_mask:0xf bank_mask:0xf
	v_fmac_f32_dpp v168, v153, v65 quad_perm:[0,0,0,0] row_mask:0xf bank_mask:0xf
	v_fmac_f32_dpp v169, v154, v66 quad_perm:[0,0,0,0] row_mask:0xf bank_mask:0xf
	v_fmac_f32_dpp v170, v155, v67 quad_perm:[0,0,0,0] row_mask:0xf bank_mask:0xf
	v_fmac_f32_dpp v83, v152, v68 quad_perm:[1,1,1,1] row_mask:0xf bank_mask:0xf
	v_fmac_f32_dpp v168, v153, v69 quad_perm:[1,1,1,1] row_mask:0xf bank_mask:0xf
	v_fmac_f32_dpp v169, v154, v70 quad_perm:[1,1,1,1] row_mask:0xf bank_mask:0xf
	v_fmac_f32_dpp v170, v155, v71 quad_perm:[1,1,1,1] row_mask:0xf bank_mask:0xf
	v_fmac_f32_dpp v83, v152, v72 quad_perm:[2,2,2,2] row_mask:0xf bank_mask:0xf
	v_fmac_f32_dpp v168, v153, v73 quad_perm:[2,2,2,2] row_mask:0xf bank_mask:0xf
	v_fmac_f32_dpp v169, v154, v74 quad_perm:[2,2,2,2] row_mask:0xf bank_mask:0xf
	v_fmac_f32_dpp v170, v155, v75 quad_perm:[2,2,2,2] row_mask:0xf bank_mask:0xf
	v_fmac_f32_dpp v83, v152, v76 quad_perm:[3,3,3,3] row_mask:0xf bank_mask:0xf
	v_fmac_f32_dpp v168, v153, v77 quad_perm:[3,3,3,3] row_mask:0xf bank_mask:0xf
	v_fmac_f32_dpp v169, v154, v78 quad_perm:[3,3,3,3] row_mask:0xf bank_mask:0xf
	v_fmac_f32_dpp v170, v155, v79 quad_perm:[3,3,3,3] row_mask:0xf bank_mask:0xf
	ds_read_b128 v[144:147], v10 offset:5984
	s_waitcnt lgkmcnt(5)
	v_fmac_f32_dpp v83, v156, v80 quad_perm:[0,0,0,0] row_mask:0xf bank_mask:0xf
	v_fmac_f32_dpp v168, v157, v81 quad_perm:[0,0,0,0] row_mask:0xf bank_mask:0xf
	v_fmac_f32_dpp v169, v158, v82 quad_perm:[0,0,0,0] row_mask:0xf bank_mask:0xf
	v_add_f32_e32 v83, v83, v168
	v_add_f32_e32 v169, v169, v170
	v_add_f32_e32 v83, v83, v169
	ds_read_b128 v[148:151], v10 offset:6048
	s_waitcnt lgkmcnt(5)
; __device__ void dn_d1(const Ctx& c, int ip) {
;     ...
;       a3 -= m[3] * x[7];
;     }
;     { const f32x4 m = *(const f32x4*)(mr + 8);
;       a0 -= m[0] * x[8];
;       a1 -= m[1] * x[9];
;       a2 -= m[2] * x[10];
;       a3 -= m[3] * x[11];
;     }
;     { const f32x4 m = *(const f32x4*)(mr + 12);
;       a0 -= m[0] * x[12];
;       a1 -= m[1] * x[13];
;       a2 -= m[2] * x[14];
;       a3 -= m[3] * x[15];
;     }
;     { const f32x4 m = *(const f32x4*)(mr + 16);
;       a0 -= m[0] * x[16];
;       a1 -= m[1] * x[17];
;       a2 -= m[2] * x[18];
;       a3 -= m[3] * x[19];
;     }
;     { const f32x4 m = *(const f32x4*)(mr + 20);
;       a0 -= m[0] * x[20];
;     }
;     SOLVE_ROW_END(21)
;     SOLVE_ROW_BEGIN(22)
;     { const f32x4 m = *(const f32x4*)(mr + 0);
;       a0 -= m[0] * x[0];
;       a1 -= m[1] * x[1];
;       a2 -= m[2] * x[2];
;       a3 -= m[3] * x[3];
;     }
;     { const f32x4 m = *(const f32x4*)(mr + 4);
;       a0 -= m[0] * x[4];
;       a1 -= m[1] * x[5];
;       a2 -= m[2] * x[6];
;       a3 -= m[3] * x[7];
;     }
;     { const f32x4 m = *(const f32x4*)(mr + 8);
;       a0 -= m[0] * x[8];
;       a1 -= m[1] * x[9];
;       a2 -= m[2] * x[10];
;       a3 -= m[3] * x[11];
;     }
;     { const f32x4 m = *(const f32x4*)(mr + 12);
;       a0 -= m[0] * x[12];
;       a1 -= m[1] * x[13];
;       a2 -= m[2] * x[14];
;       a3 -= m[3] * x[15];
;     }
;     { const f32x4 m = *(const f32x4*)(mr + 16);
;       a0 -= m[0] * x[16];
;       a1 -= m[1] * x[17];
;       a2 -= m[2] * x[18];
;       a3 -= m[3] * x[19];
;     }
;     { const f32x4 m = *(const f32x4*)(mr + 20);
;       a0 -= m[0] * x[20];
;       a1 -= m[1] * x[21];
;     }
;     SOLVE_ROW_END(22)
	v_mov_b32_e32 v168, 0
	v_mov_b32_e32 v169, 0
	v_mov_b32_e32 v170, 0
	v_fmac_f32_dpp v84, v160, v64 quad_perm:[0,0,0,0] row_mask:0xf bank_mask:0xf
	v_fmac_f32_dpp v168, v161, v65 quad_perm:[0,0,0,0] row_mask:0xf bank_mask:0xf
	v_fmac_f32_dpp v169, v162, v66 quad_perm:[0,0,0,0] row_mask:0xf bank_mask:0xf
	v_fmac_f32_dpp v170, v163, v67 quad_perm:[0,0,0,0] row_mask:0xf bank_mask:0xf
	v_fmac_f32_dpp v84, v160, v68 quad_perm:[1,1,1,1] row_mask:0xf bank_mask:0xf
	v_fmac_f32_dpp v168, v161, v69 quad_perm:[1,1,1,1] row_mask:0xf bank_mask:0xf
	v_fmac_f32_dpp v169, v162, v70 quad_perm:[1,1,1,1] row_mask:0xf bank_mask:0xf
	v_fmac_f32_dpp v170, v163, v71 quad_perm:[1,1,1,1] row_mask:0xf bank_mask:0xf
	v_fmac_f32_dpp v84, v160, v72 quad_perm:[2,2,2,2] row_mask:0xf bank_mask:0xf
	v_fmac_f32_dpp v168, v161, v73 quad_perm:[2,2,2,2] row_mask:0xf bank_mask:0xf
	v_fmac_f32_dpp v169, v162, v74 quad_perm:[2,2,2,2] row_mask:0xf bank_mask:0xf
	v_fmac_f32_dpp v170, v163, v75 quad_perm:[2,2,2,2] row_mask:0xf bank_mask:0xf
	v_fmac_f32_dpp v84, v160, v76 quad_perm:[3,3,3,3] row_mask:0xf bank_mask:0xf
	v_fmac_f32_dpp v168, v161, v77 quad_perm:[3,3,3,3] row_mask:0xf bank_mask:0xf
	v_fmac_f32_dpp v169, v162, v78 quad_perm:[3,3,3,3] row_mask:0xf bank_mask:0xf
	v_fmac_f32_dpp v170, v163, v79 quad_perm:[3,3,3,3] row_mask:0xf bank_mask:0xf
	ds_read_b128 v[152:155], v10 offset:6256
	s_waitcnt lgkmcnt(5)
	v_fmac_f32_dpp v84, v164, v80 quad_perm:[0,0,0,0] row_mask:0xf bank_mask:0xf
	v_fmac_f32_dpp v168, v165, v81 quad_perm:[0,0,0,0] row_mask:0xf bank_mask:0xf
	v_fmac_f32_dpp v169, v166, v82 quad_perm:[0,0,0,0] row_mask:0xf bank_mask:0xf
	v_fmac_f32_dpp v170, v167, v83 quad_perm:[0,0,0,0] row_mask:0xf bank_mask:0xf
	v_add_f32_e32 v84, v84, v168
	v_add_f32_e32 v169, v169, v170
	v_add_f32_e32 v84, v84, v169
	ds_read_b128 v[156:159], v10 offset:6320
	s_waitcnt lgkmcnt(5)
	v_mov_b32_e32 v168, 0
	v_mov_b32_e32 v169, 0
	v_mov_b32_e32 v170, 0
	v_fmac_f32_dpp v85, v136, v64 quad_perm:[0,0,0,0] row_mask:0xf bank_mask:0xf
	v_fmac_f32_dpp v168, v137, v65 quad_perm:[0,0,0,0] row_mask:0xf bank_mask:0xf
	v_fmac_f32_dpp v169, v138, v66 quad_perm:[0,0,0,0] row_mask:0xf bank_mask:0xf
	v_fmac_f32_dpp v170, v139, v67 quad_perm:[0,0,0,0] row_mask:0xf bank_mask:0xf
	v_fmac_f32_dpp v85, v136, v68 quad_perm:[1,1,1,1] row_mask:0xf bank_mask:0xf
	v_fmac_f32_dpp v168, v137, v69 quad_perm:[1,1,1,1] row_mask:0xf bank_mask:0xf
	v_fmac_f32_dpp v169, v138, v70 quad_perm:[1,1,1,1] row_mask:0xf bank_mask:0xf
	v_fmac_f32_dpp v170, v139, v71 quad_perm:[1,1,1,1] row_mask:0xf bank_mask:0xf
	v_fmac_f32_dpp v85, v136, v72 quad_perm:[2,2,2,2] row_mask:0xf bank_mask:0xf
	v_fmac_f32_dpp v168, v137, v73 quad_perm:[2,2,2,2] row_mask:0xf bank_mask:0xf
	v_fmac_f32_dpp v169, v138, v74 quad_perm:[2,2,2,2] row_mask:0xf bank_mask:0xf
	v_fmac_f32_dpp v170, v139, v75 quad_perm:[2,2,2,2] row_mask:0xf bank_mask:0xf
	v_fmac_f32_dpp v85, v136, v76 quad_perm:[3,3,3,3] row_mask:0xf bank_mask:0xf
	v_fmac_f32_dpp v168, v137, v77 quad_perm:[3,3,3,3] row_mask:0xf bank_mask:0xf
	v_fmac_f32_dpp v169, v138, v78 quad_perm:[3,3,3,3] row_mask:0xf bank_mask:0xf
	v_fmac_f32_dpp v170, v139, v79 quad_perm:[3,3,3,3] row_mask:0xf bank_mask:0xf
	ds_read_b128 v[160:163], v10 offset:6528
	s_waitcnt lgkmcnt(5)
	v_fmac_f32_dpp v85, v140, v80 quad_perm:[0,0,0,0] row_mask:0xf bank_mask:0xf
	v_fmac_f32_dpp v168, v141, v81 quad_perm:[0,0,0,0] row_mask:0xf bank_mask:0xf
	v_fmac_f32_dpp v169, v142, v82 quad_perm:[0,0,0,0] row_mask:0xf bank_mask:0xf
	v_fmac_f32_dpp v170, v143, v83 quad_perm:[0,0,0,0] row_mask:0xf bank_mask:0xf
	v_fmac_f32_dpp v85, v140, v84 quad_perm:[1,1,1,1] row_mask:0xf bank_mask:0xf
	v_add_f32_e32 v85, v85, v168
	v_add_f32_e32 v169, v169, v170
	v_add_f32_e32 v85, v85, v169
	ds_read_b128 v[164:167], v10 offset:6592
	s_waitcnt lgkmcnt(5)
	v_mov_b32_e32 v168, 0
	v_mov_b32_e32 v169, 0
	v_mov_b32_e32 v170, 0
	v_fmac_f32_dpp v86, v144, v64 quad_perm:[0,0,0,0] row_mask:0xf bank_mask:0xf
	v_fmac_f32_dpp v168, v145, v65 quad_perm:[0,0,0,0] row_mask:0xf bank_mask:0xf
	v_fmac_f32_dpp v169, v146, v66 quad_perm:[0,0,0,0] row_mask:0xf bank_mask:0xf
	v_fmac_f32_dpp v170, v147, v67 quad_perm:[0,0,0,0] row_mask:0xf bank_mask:0xf
	v_fmac_f32_dpp v86, v144, v68 quad_perm:[1,1,1,1] row_mask:0xf bank_mask:0xf
	v_fmac_f32_dpp v168, v145, v69 quad_perm:[1,1,1,1] row_mask:0xf bank_mask:0xf
	v_fmac_f32_dpp v169, v146, v70 quad_perm:[1,1,1,1] row_mask:0xf bank_mask:0xf
	v_fmac_f32_dpp v170, v147, v71 quad_perm:[1,1,1,1] row_mask:0xf bank_mask:0xf
	v_fmac_f32_dpp v86, v144, v72 quad_perm:[2,2,2,2] row_mask:0xf bank_mask:0xf
	v_fmac_f32_dpp v168, v145, v73 quad_perm:[2,2,2,2] row_mask:0xf bank_mask:0xf
	v_fmac_f32_dpp v169, v146, v74 quad_perm:[2,2,2,2] row_mask:0xf bank_mask:0xf
	v_fmac_f32_dpp v170, v147, v75 quad_perm:[2,2,2,2] row_mask:0xf bank_mask:0xf
	v_fmac_f32_dpp v86, v144, v76 quad_perm:[3,3,3,3] row_mask:0xf bank_mask:0xf
	v_fmac_f32_dpp v168, v145, v77 quad_perm:[3,3,3,3] row_mask:0xf bank_mask:0xf
	v_fmac_f32_dpp v169, v146, v78 quad_perm:[3,3,3,3] row_mask:0xf bank_mask:0xf
	v_fmac_f32_dpp v170, v147, v79 quad_perm:[3,3,3,3] row_mask:0xf bank_mask:0xf
	ds_read_b128 v[136:139], v10 offset:6800
	s_waitcnt lgkmcnt(5)
	v_fmac_f32_dpp v86, v148, v80 quad_perm:[0,0,0,0] row_mask:0xf bank_mask:0xf
	v_fmac_f32_dpp v168, v149, v81 quad_perm:[0,0,0,0] row_mask:0xf bank_mask:0xf
	v_fmac_f32_dpp v169, v150, v82 quad_perm:[0,0,0,0] row_mask:0xf bank_mask:0xf
	v_fmac_f32_dpp v170, v151, v83 quad_perm:[0,0,0,0] row_mask:0xf bank_mask:0xf
	v_fmac_f32_dpp v86, v148, v84 quad_perm:[1,1,1,1] row_mask:0xf bank_mask:0xf
	v_fmac_f32_dpp v168, v149, v85 quad_perm:[1,1,1,1] row_mask:0xf bank_mask:0xf
	v_add_f32_e32 v86, v86, v168
	v_add_f32_e32 v169, v169, v170
	v_add_f32_e32 v86, v86, v169
	ds_read_b128 v[140:143], v10 offset:6864
	s_waitcnt lgkmcnt(5)
; __device__ void dn_d1(const Ctx& c, int ip) {
;     ...
;     SOLVE_ROW_BEGIN(24)
;     { const f32x4 m = *(const f32x4*)(mr + 0);
;       a0 -= m[0] * x[0];
;       a1 -= m[1] * x[1];
;       a2 -= m[2] * x[2];
;       a3 -= m[3] * x[3];
;     }
;     { const f32x4 m = *(const f32x4*)(mr + 4);
;       a0 -= m[0] * x[4];
;       a1 -= m[1] * x[5];
;       a2 -= m[2] * x[6];
;       a3 -= m[3] * x[7];
;     }
;     { const f32x4 m = *(const f32x4*)(mr + 8);
;       a0 -= m[0] * x[8];
;       a1 -= m[1] * x[9];
;       a2 -= m[2] * x[10];
;       a3 -= m[3] * x[11];
;     }
;     { const f32x4 m = *(const f32x4*)(mr + 12);
;       a0 -= m[0] * x[12];
;       a1 -= m[1] * x[13];
;       a2 -= m[2] * x[14];
;       a3 -= m[3] * x[15];
;     }
;     { const f32x4 m = *(const f32x4*)(mr + 16);
;       a0 -= m[0] * x[16];
;       a1 -= m[1] * x[17];
;       a2 -= m[2] * x[18];
;       a3 -= m[3] * x[19];
;     }
;     { const f32x4 m = *(const f32x4*)(mr + 20);
;       a0 -= m[0] * x[20];
;       a1 -= m[1] * x[21];
;       a2 -= m[2] * x[22];
;       a3 -= m[3] * x[23];
;     }
;     SOLVE_ROW_END(24)
;     SOLVE_ROW_BEGIN(25)
;     { const f32x4 m = *(const f32x4*)(mr + 0);
;       a0 -= m[0] * x[0];
;       a1 -= m[1] * x[1];
;       a2 -= m[2] * x[2];
;       a3 -= m[3] * x[3];
;     }
;     { const f32x4 m = *(const f32x4*)(mr + 4);
;       a0 -= m[0] * x[4];
;       a1 -= m[1] * x[5];
;       a2 -= m[2] * x[6];
;       a3 -= m[3] * x[7];
;     }
;     { const f32x4 m = *(const f32x4*)(mr + 8);
;       a0 -= m[0] * x[8];
;       a1 -= m[1] * x[9];
;       a2 -= m[2] * x[10];
;       a3 -= m[3] * x[11];
;     }
;     { const f32x4 m = *(const f32x4*)(mr + 12);
;       a0 -= m[0] * x[12];
;       a1 -= m[1] * x[13];
	v_mov_b32_e32 v168, 0
	v_mov_b32_e32 v169, 0
	v_mov_b32_e32 v170, 0
	v_fmac_f32_dpp v87, v152, v64 quad_perm:[0,0,0,0] row_mask:0xf bank_mask:0xf
	v_fmac_f32_dpp v168, v153, v65 quad_perm:[0,0,0,0] row_mask:0xf bank_mask:0xf
	v_fmac_f32_dpp v169, v154, v66 quad_perm:[0,0,0,0] row_mask:0xf bank_mask:0xf
	v_fmac_f32_dpp v170, v155, v67 quad_perm:[0,0,0,0] row_mask:0xf bank_mask:0xf
	v_fmac_f32_dpp v87, v152, v68 quad_perm:[1,1,1,1] row_mask:0xf bank_mask:0xf
	v_fmac_f32_dpp v168, v153, v69 quad_perm:[1,1,1,1] row_mask:0xf bank_mask:0xf
	v_fmac_f32_dpp v169, v154, v70 quad_perm:[1,1,1,1] row_mask:0xf bank_mask:0xf
	v_fmac_f32_dpp v170, v155, v71 quad_perm:[1,1,1,1] row_mask:0xf bank_mask:0xf
	v_fmac_f32_dpp v87, v152, v72 quad_perm:[2,2,2,2] row_mask:0xf bank_mask:0xf
	v_fmac_f32_dpp v168, v153, v73 quad_perm:[2,2,2,2] row_mask:0xf bank_mask:0xf
	v_fmac_f32_dpp v169, v154, v74 quad_perm:[2,2,2,2] row_mask:0xf bank_mask:0xf
	v_fmac_f32_dpp v170, v155, v75 quad_perm:[2,2,2,2] row_mask:0xf bank_mask:0xf
	v_fmac_f32_dpp v87, v152, v76 quad_perm:[3,3,3,3] row_mask:0xf bank_mask:0xf
	v_fmac_f32_dpp v168, v153, v77 quad_perm:[3,3,3,3] row_mask:0xf bank_mask:0xf
	v_fmac_f32_dpp v169, v154, v78 quad_perm:[3,3,3,3] row_mask:0xf bank_mask:0xf
	v_fmac_f32_dpp v170, v155, v79 quad_perm:[3,3,3,3] row_mask:0xf bank_mask:0xf
	ds_read_b128 v[144:147], v10 offset:7072
	s_waitcnt lgkmcnt(5)
	v_fmac_f32_dpp v87, v156, v80 quad_perm:[0,0,0,0] row_mask:0xf bank_mask:0xf
	v_fmac_f32_dpp v168, v157, v81 quad_perm:[0,0,0,0] row_mask:0xf bank_mask:0xf
	v_fmac_f32_dpp v169, v158, v82 quad_perm:[0,0,0,0] row_mask:0xf bank_mask:0xf
	v_fmac_f32_dpp v170, v159, v83 quad_perm:[0,0,0,0] row_mask:0xf bank_mask:0xf
	v_fmac_f32_dpp v87, v156, v84 quad_perm:[1,1,1,1] row_mask:0xf bank_mask:0xf
	v_fmac_f32_dpp v168, v157, v85 quad_perm:[1,1,1,1] row_mask:0xf bank_mask:0xf
	v_fmac_f32_dpp v169, v158, v86 quad_perm:[1,1,1,1] row_mask:0xf bank_mask:0xf
	v_add_f32_e32 v87, v87, v168
	v_add_f32_e32 v169, v169, v170
	v_add_f32_e32 v87, v87, v169
	ds_read_b128 v[148:151], v10 offset:7136
	s_waitcnt lgkmcnt(5)
	v_mov_b32_e32 v168, 0
	v_mov_b32_e32 v169, 0
	v_mov_b32_e32 v170, 0
	v_fmac_f32_dpp v88, v160, v64 quad_perm:[0,0,0,0] row_mask:0xf bank_mask:0xf
	v_fmac_f32_dpp v168, v161, v65 quad_perm:[0,0,0,0] row_mask:0xf bank_mask:0xf
	v_fmac_f32_dpp v169, v162, v66 quad_perm:[0,0,0,0] row_mask:0xf bank_mask:0xf
	v_fmac_f32_dpp v170, v163, v67 quad_perm:[0,0,0,0] row_mask:0xf bank_mask:0xf
	v_fmac_f32_dpp v88, v160, v68 quad_perm:[1,1,1,1] row_mask:0xf bank_mask:0xf
	v_fmac_f32_dpp v168, v161, v69 quad_perm:[1,1,1,1] row_mask:0xf bank_mask:0xf
	v_fmac_f32_dpp v169, v162, v70 quad_perm:[1,1,1,1] row_mask:0xf bank_mask:0xf
	v_fmac_f32_dpp v170, v163, v71 quad_perm:[1,1,1,1] row_mask:0xf bank_mask:0xf
	v_fmac_f32_dpp v88, v160, v72 quad_perm:[2,2,2,2] row_mask:0xf bank_mask:0xf
	v_fmac_f32_dpp v168, v161, v73 quad_perm:[2,2,2,2] row_mask:0xf bank_mask:0xf
	v_fmac_f32_dpp v169, v162, v74 quad_perm:[2,2,2,2] row_mask:0xf bank_mask:0xf
	v_fmac_f32_dpp v170, v163, v75 quad_perm:[2,2,2,2] row_mask:0xf bank_mask:0xf
	v_fmac_f32_dpp v88, v160, v76 quad_perm:[3,3,3,3] row_mask:0xf bank_mask:0xf
	v_fmac_f32_dpp v168, v161, v77 quad_perm:[3,3,3,3] row_mask:0xf bank_mask:0xf
	v_fmac_f32_dpp v169, v162, v78 quad_perm:[3,3,3,3] row_mask:0xf bank_mask:0xf
	v_fmac_f32_dpp v170, v163, v79 quad_perm:[3,3,3,3] row_mask:0xf bank_mask:0xf
	ds_read_b128 v[152:155], v10 offset:7344
	s_waitcnt lgkmcnt(5)
	v_fmac_f32_dpp v88, v164, v80 quad_perm:[0,0,0,0] row_mask:0xf bank_mask:0xf
	v_fmac_f32_dpp v168, v165, v81 quad_perm:[0,0,0,0] row_mask:0xf bank_mask:0xf
	v_fmac_f32_dpp v169, v166, v82 quad_perm:[0,0,0,0] row_mask:0xf bank_mask:0xf
	v_fmac_f32_dpp v170, v167, v83 quad_perm:[0,0,0,0] row_mask:0xf bank_mask:0xf
	v_fmac_f32_dpp v88, v164, v84 quad_perm:[1,1,1,1] row_mask:0xf bank_mask:0xf
	v_fmac_f32_dpp v168, v165, v85 quad_perm:[1,1,1,1] row_mask:0xf bank_mask:0xf
	v_fmac_f32_dpp v169, v166, v86 quad_perm:[1,1,1,1] row_mask:0xf bank_mask:0xf
	v_fmac_f32_dpp v170, v167, v87 quad_perm:[1,1,1,1] row_mask:0xf bank_mask:0xf
	v_add_f32_e32 v88, v88, v168
	v_add_f32_e32 v169, v169, v170
	v_add_f32_e32 v88, v88, v169
	ds_read_b128 v[156:159], v10 offset:7408
	s_waitcnt lgkmcnt(5)
	v_mov_b32_e32 v168, 0
	v_mov_b32_e32 v169, 0
	v_mov_b32_e32 v170, 0
	v_fmac_f32_dpp v89, v136, v64 quad_perm:[0,0,0,0] row_mask:0xf bank_mask:0xf
	v_fmac_f32_dpp v168, v137, v65 quad_perm:[0,0,0,0] row_mask:0xf bank_mask:0xf
	v_fmac_f32_dpp v169, v138, v66 quad_perm:[0,0,0,0] row_mask:0xf bank_mask:0xf
	v_fmac_f32_dpp v170, v139, v67 quad_perm:[0,0,0,0] row_mask:0xf bank_mask:0xf
	v_fmac_f32_dpp v89, v136, v68 quad_perm:[1,1,1,1] row_mask:0xf bank_mask:0xf
	v_fmac_f32_dpp v168, v137, v69 quad_perm:[1,1,1,1] row_mask:0xf bank_mask:0xf
	v_fmac_f32_dpp v169, v138, v70 quad_perm:[1,1,1,1] row_mask:0xf bank_mask:0xf
	v_fmac_f32_dpp v170, v139, v71 quad_perm:[1,1,1,1] row_mask:0xf bank_mask:0xf
	v_fmac_f32_dpp v89, v136, v72 quad_perm:[2,2,2,2] row_mask:0xf bank_mask:0xf
	v_fmac_f32_dpp v168, v137, v73 quad_perm:[2,2,2,2] row_mask:0xf bank_mask:0xf
	v_fmac_f32_dpp v169, v138, v74 quad_perm:[2,2,2,2] row_mask:0xf bank_mask:0xf
	v_fmac_f32_dpp v170, v139, v75 quad_perm:[2,2,2,2] row_mask:0xf bank_mask:0xf
	v_fmac_f32_dpp v89, v136, v76 quad_perm:[3,3,3,3] row_mask:0xf bank_mask:0xf
	v_fmac_f32_dpp v168, v137, v77 quad_perm:[3,3,3,3] row_mask:0xf bank_mask:0xf
	v_fmac_f32_dpp v169, v138, v78 quad_perm:[3,3,3,3] row_mask:0xf bank_mask:0xf
	v_fmac_f32_dpp v170, v139, v79 quad_perm:[3,3,3,3] row_mask:0xf bank_mask:0xf
	ds_read_b128 v[160:163], v10 offset:7616
	s_waitcnt lgkmcnt(5)
; __device__ void dn_d1(const Ctx& c, int ip) {
;     ...
;     { const f32x4 m = *(const f32x4*)(mr + 16);
;       a0 -= m[0] * x[16];
;       a1 -= m[1] * x[17];
;       a2 -= m[2] * x[18];
;       a3 -= m[3] * x[19];
;     }
;     { const f32x4 m = *(const f32x4*)(mr + 20);
;       a0 -= m[0] * x[20];
;       a1 -= m[1] * x[21];
;       a2 -= m[2] * x[22];
;       a3 -= m[3] * x[23];
;     }
;     { const f32x4 m = *(const f32x4*)(mr + 24);
;       a0 -= m[0] * x[24];
;       a1 -= m[1] * x[25];
;     }
;     SOLVE_ROW_END(26)
;     SOLVE_ROW_BEGIN(27)
;     { const f32x4 m = *(const f32x4*)(mr + 0);
;       a0 -= m[0] * x[0];
;       a1 -= m[1] * x[1];
;       a2 -= m[2] * x[2];
;       a3 -= m[3] * x[3];
;     }
;     { const f32x4 m = *(const f32x4*)(mr + 4);
;       a0 -= m[0] * x[4];
;       a1 -= m[1] * x[5];
;       a2 -= m[2] * x[6];
;       a3 -= m[3] * x[7];
;     }
;     { const f32x4 m = *(const f32x4*)(mr + 8);
;       a0 -= m[0] * x[8];
;       a1 -= m[1] * x[9];
;       a2 -= m[2] * x[10];
;       a3 -= m[3] * x[11];
;     }
;     { const f32x4 m = *(const f32x4*)(mr + 12);
;       a0 -= m[0] * x[12];
;       a1 -= m[1] * x[13];
;       a2 -= m[2] * x[14];
;       a3 -= m[3] * x[15];
;     }
;     { const f32x4 m = *(const f32x4*)(mr + 16);
;       a0 -= m[0] * x[16];
;       a1 -= m[1] * x[17];
;       a2 -= m[2] * x[18];
;       a3 -= m[3] * x[19];
;     }
;     { const f32x4 m = *(const f32x4*)(mr + 20);
;       a0 -= m[0] * x[20];
;       a1 -= m[1] * x[21];
;       a2 -= m[2] * x[22];
;       a3 -= m[3] * x[23];
;     }
;     { const f32x4 m = *(const f32x4*)(mr + 24);
;       a0 -= m[0] * x[24];
;       a1 -= m[1] * x[25];
;       a2 -= m[2] * x[26];
;     }
;     SOLVE_ROW_END(27)
	v_fmac_f32_dpp v89, v140, v80 quad_perm:[0,0,0,0] row_mask:0xf bank_mask:0xf
	v_fmac_f32_dpp v168, v141, v81 quad_perm:[0,0,0,0] row_mask:0xf bank_mask:0xf
	v_fmac_f32_dpp v169, v142, v82 quad_perm:[0,0,0,0] row_mask:0xf bank_mask:0xf
	v_fmac_f32_dpp v170, v143, v83 quad_perm:[0,0,0,0] row_mask:0xf bank_mask:0xf
	v_fmac_f32_dpp v89, v140, v84 quad_perm:[1,1,1,1] row_mask:0xf bank_mask:0xf
	v_fmac_f32_dpp v168, v141, v85 quad_perm:[1,1,1,1] row_mask:0xf bank_mask:0xf
	v_fmac_f32_dpp v169, v142, v86 quad_perm:[1,1,1,1] row_mask:0xf bank_mask:0xf
	v_fmac_f32_dpp v170, v143, v87 quad_perm:[1,1,1,1] row_mask:0xf bank_mask:0xf
	v_fmac_f32_dpp v89, v140, v88 quad_perm:[2,2,2,2] row_mask:0xf bank_mask:0xf
	v_add_f32_e32 v89, v89, v168
	v_add_f32_e32 v169, v169, v170
	v_add_f32_e32 v89, v89, v169
	ds_read_b128 v[164:167], v10 offset:7680
	s_waitcnt lgkmcnt(5)
	v_mov_b32_e32 v168, 0
	v_mov_b32_e32 v169, 0
	v_mov_b32_e32 v170, 0
	v_fmac_f32_dpp v90, v144, v64 quad_perm:[0,0,0,0] row_mask:0xf bank_mask:0xf
	v_fmac_f32_dpp v168, v145, v65 quad_perm:[0,0,0,0] row_mask:0xf bank_mask:0xf
	v_fmac_f32_dpp v169, v146, v66 quad_perm:[0,0,0,0] row_mask:0xf bank_mask:0xf
	v_fmac_f32_dpp v170, v147, v67 quad_perm:[0,0,0,0] row_mask:0xf bank_mask:0xf
	v_fmac_f32_dpp v90, v144, v68 quad_perm:[1,1,1,1] row_mask:0xf bank_mask:0xf
	v_fmac_f32_dpp v168, v145, v69 quad_perm:[1,1,1,1] row_mask:0xf bank_mask:0xf
	v_fmac_f32_dpp v169, v146, v70 quad_perm:[1,1,1,1] row_mask:0xf bank_mask:0xf
	v_fmac_f32_dpp v170, v147, v71 quad_perm:[1,1,1,1] row_mask:0xf bank_mask:0xf
	v_fmac_f32_dpp v90, v144, v72 quad_perm:[2,2,2,2] row_mask:0xf bank_mask:0xf
	v_fmac_f32_dpp v168, v145, v73 quad_perm:[2,2,2,2] row_mask:0xf bank_mask:0xf
	v_fmac_f32_dpp v169, v146, v74 quad_perm:[2,2,2,2] row_mask:0xf bank_mask:0xf
	v_fmac_f32_dpp v170, v147, v75 quad_perm:[2,2,2,2] row_mask:0xf bank_mask:0xf
	v_fmac_f32_dpp v90, v144, v76 quad_perm:[3,3,3,3] row_mask:0xf bank_mask:0xf
	v_fmac_f32_dpp v168, v145, v77 quad_perm:[3,3,3,3] row_mask:0xf bank_mask:0xf
	v_fmac_f32_dpp v169, v146, v78 quad_perm:[3,3,3,3] row_mask:0xf bank_mask:0xf
	v_fmac_f32_dpp v170, v147, v79 quad_perm:[3,3,3,3] row_mask:0xf bank_mask:0xf
	ds_read_b128 v[136:139], v10 offset:7888
	s_waitcnt lgkmcnt(5)
	v_fmac_f32_dpp v90, v148, v80 quad_perm:[0,0,0,0] row_mask:0xf bank_mask:0xf
	v_fmac_f32_dpp v168, v149, v81 quad_perm:[0,0,0,0] row_mask:0xf bank_mask:0xf
	v_fmac_f32_dpp v169, v150, v82 quad_perm:[0,0,0,0] row_mask:0xf bank_mask:0xf
	v_fmac_f32_dpp v170, v151, v83 quad_perm:[0,0,0,0] row_mask:0xf bank_mask:0xf
	v_fmac_f32_dpp v90, v148, v84 quad_perm:[1,1,1,1] row_mask:0xf bank_mask:0xf
	v_fmac_f32_dpp v168, v149, v85 quad_perm:[1,1,1,1] row_mask:0xf bank_mask:0xf
	v_fmac_f32_dpp v169, v150, v86 quad_perm:[1,1,1,1] row_mask:0xf bank_mask:0xf
	v_fmac_f32_dpp v170, v151, v87 quad_perm:[1,1,1,1] row_mask:0xf bank_mask:0xf
	v_fmac_f32_dpp v90, v148, v88 quad_perm:[2,2,2,2] row_mask:0xf bank_mask:0xf
	v_fmac_f32_dpp v168, v149, v89 quad_perm:[2,2,2,2] row_mask:0xf bank_mask:0xf
	v_add_f32_e32 v90, v90, v168
	v_add_f32_e32 v169, v169, v170
	v_add_f32_e32 v90, v90, v169
	ds_read_b128 v[140:143], v10 offset:7952
	s_waitcnt lgkmcnt(5)
	v_mov_b32_e32 v168, 0
	v_mov_b32_e32 v169, 0
	v_mov_b32_e32 v170, 0
	v_fmac_f32_dpp v91, v152, v64 quad_perm:[0,0,0,0] row_mask:0xf bank_mask:0xf
	v_fmac_f32_dpp v168, v153, v65 quad_perm:[0,0,0,0] row_mask:0xf bank_mask:0xf
	v_fmac_f32_dpp v169, v154, v66 quad_perm:[0,0,0,0] row_mask:0xf bank_mask:0xf
	v_fmac_f32_dpp v170, v155, v67 quad_perm:[0,0,0,0] row_mask:0xf bank_mask:0xf
	v_fmac_f32_dpp v91, v152, v68 quad_perm:[1,1,1,1] row_mask:0xf bank_mask:0xf
	v_fmac_f32_dpp v168, v153, v69 quad_perm:[1,1,1,1] row_mask:0xf bank_mask:0xf
	v_fmac_f32_dpp v169, v154, v70 quad_perm:[1,1,1,1] row_mask:0xf bank_mask:0xf
	v_fmac_f32_dpp v170, v155, v71 quad_perm:[1,1,1,1] row_mask:0xf bank_mask:0xf
	v_fmac_f32_dpp v91, v152, v72 quad_perm:[2,2,2,2] row_mask:0xf bank_mask:0xf
	v_fmac_f32_dpp v168, v153, v73 quad_perm:[2,2,2,2] row_mask:0xf bank_mask:0xf
	v_fmac_f32_dpp v169, v154, v74 quad_perm:[2,2,2,2] row_mask:0xf bank_mask:0xf
	v_fmac_f32_dpp v170, v155, v75 quad_perm:[2,2,2,2] row_mask:0xf bank_mask:0xf
	v_fmac_f32_dpp v91, v152, v76 quad_perm:[3,3,3,3] row_mask:0xf bank_mask:0xf
	v_fmac_f32_dpp v168, v153, v77 quad_perm:[3,3,3,3] row_mask:0xf bank_mask:0xf
	v_fmac_f32_dpp v169, v154, v78 quad_perm:[3,3,3,3] row_mask:0xf bank_mask:0xf
	v_fmac_f32_dpp v170, v155, v79 quad_perm:[3,3,3,3] row_mask:0xf bank_mask:0xf
	ds_read_b128 v[144:147], v10 offset:8160
	s_waitcnt lgkmcnt(5)
	v_fmac_f32_dpp v91, v156, v80 quad_perm:[0,0,0,0] row_mask:0xf bank_mask:0xf
	v_fmac_f32_dpp v168, v157, v81 quad_perm:[0,0,0,0] row_mask:0xf bank_mask:0xf
	v_fmac_f32_dpp v169, v158, v82 quad_perm:[0,0,0,0] row_mask:0xf bank_mask:0xf
	v_fmac_f32_dpp v170, v159, v83 quad_perm:[0,0,0,0] row_mask:0xf bank_mask:0xf
	v_fmac_f32_dpp v91, v156, v84 quad_perm:[1,1,1,1] row_mask:0xf bank_mask:0xf
	v_fmac_f32_dpp v168, v157, v85 quad_perm:[1,1,1,1] row_mask:0xf bank_mask:0xf
	v_fmac_f32_dpp v169, v158, v86 quad_perm:[1,1,1,1] row_mask:0xf bank_mask:0xf
	v_fmac_f32_dpp v170, v159, v87 quad_perm:[1,1,1,1] row_mask:0xf bank_mask:0xf
	v_fmac_f32_dpp v91, v156, v88 quad_perm:[2,2,2,2] row_mask:0xf bank_mask:0xf
	v_fmac_f32_dpp v168, v157, v89 quad_perm:[2,2,2,2] row_mask:0xf bank_mask:0xf
	v_fmac_f32_dpp v169, v158, v90 quad_perm:[2,2,2,2] row_mask:0xf bank_mask:0xf
	v_add_f32_e32 v91, v91, v168
	v_add_f32_e32 v169, v169, v170
	v_add_f32_e32 v91, v91, v169
	ds_read_b128 v[148:151], v10 offset:8224
	s_waitcnt lgkmcnt(5)
; __device__ void dn_d1(const Ctx& c, int ip) {
;     ...
;     { const f32x4 m = *(const f32x4*)(mr + 20);
;       a0 -= m[0] * x[20];
;       a1 -= m[1] * x[21];
;       a2 -= m[2] * x[22];
;       a3 -= m[3] * x[23];
;     }
;     { const f32x4 m = *(const f32x4*)(mr + 24);
;       a0 -= m[0] * x[24];
;       a1 -= m[1] * x[25];
;       a2 -= m[2] * x[26];
;       a3 -= m[3] * x[27];
;     }
;     SOLVE_ROW_END(28)
;     SOLVE_ROW_BEGIN(29)
;     { const f32x4 m = *(const f32x4*)(mr + 0);
;       a0 -= m[0] * x[0];
;       a1 -= m[1] * x[1];
;       a2 -= m[2] * x[2];
;       a3 -= m[3] * x[3];
;     }
;     { const f32x4 m = *(const f32x4*)(mr + 4);
;       a0 -= m[0] * x[4];
;       a1 -= m[1] * x[5];
;       a2 -= m[2] * x[6];
;       a3 -= m[3] * x[7];
;     }
;     { const f32x4 m = *(const f32x4*)(mr + 8);
;       a0 -= m[0] * x[8];
;       a1 -= m[1] * x[9];
;       a2 -= m[2] * x[10];
;       a3 -= m[3] * x[11];
;     }
;     { const f32x4 m = *(const f32x4*)(mr + 12);
;       a0 -= m[0] * x[12];
;       a1 -= m[1] * x[13];
;       a2 -= m[2] * x[14];
;       a3 -= m[3] * x[15];
;     }
;     { const f32x4 m = *(const f32x4*)(mr + 16);
;       a0 -= m[0] * x[16];
;       a1 -= m[1] * x[17];
;       a2 -= m[2] * x[18];
;       a3 -= m[3] * x[19];
;     }
;     { const f32x4 m = *(const f32x4*)(mr + 20);
;       a0 -= m[0] * x[20];
;       a1 -= m[1] * x[21];
;       a2 -= m[2] * x[22];
;       a3 -= m[3] * x[23];
;     }
;     { const f32x4 m = *(const f32x4*)(mr + 24);
;       a0 -= m[0] * x[24];
;       a1 -= m[1] * x[25];
;       a2 -= m[2] * x[26];
;       a3 -= m[3] * x[27];
;     }
;     { const f32x4 m = *(const f32x4*)(mr + 28);
;       a0 -= m[0] * x[28];
;     }
;     SOLVE_ROW_END(29)
	v_mov_b32_e32 v168, 0
	v_mov_b32_e32 v169, 0
	v_mov_b32_e32 v170, 0
	v_fmac_f32_dpp v92, v160, v64 quad_perm:[0,0,0,0] row_mask:0xf bank_mask:0xf
	v_fmac_f32_dpp v168, v161, v65 quad_perm:[0,0,0,0] row_mask:0xf bank_mask:0xf
	v_fmac_f32_dpp v169, v162, v66 quad_perm:[0,0,0,0] row_mask:0xf bank_mask:0xf
	v_fmac_f32_dpp v170, v163, v67 quad_perm:[0,0,0,0] row_mask:0xf bank_mask:0xf
	v_fmac_f32_dpp v92, v160, v68 quad_perm:[1,1,1,1] row_mask:0xf bank_mask:0xf
	v_fmac_f32_dpp v168, v161, v69 quad_perm:[1,1,1,1] row_mask:0xf bank_mask:0xf
	v_fmac_f32_dpp v169, v162, v70 quad_perm:[1,1,1,1] row_mask:0xf bank_mask:0xf
	v_fmac_f32_dpp v170, v163, v71 quad_perm:[1,1,1,1] row_mask:0xf bank_mask:0xf
	v_fmac_f32_dpp v92, v160, v72 quad_perm:[2,2,2,2] row_mask:0xf bank_mask:0xf
	v_fmac_f32_dpp v168, v161, v73 quad_perm:[2,2,2,2] row_mask:0xf bank_mask:0xf
	v_fmac_f32_dpp v169, v162, v74 quad_perm:[2,2,2,2] row_mask:0xf bank_mask:0xf
	v_fmac_f32_dpp v170, v163, v75 quad_perm:[2,2,2,2] row_mask:0xf bank_mask:0xf
	v_fmac_f32_dpp v92, v160, v76 quad_perm:[3,3,3,3] row_mask:0xf bank_mask:0xf
	v_fmac_f32_dpp v168, v161, v77 quad_perm:[3,3,3,3] row_mask:0xf bank_mask:0xf
	v_fmac_f32_dpp v169, v162, v78 quad_perm:[3,3,3,3] row_mask:0xf bank_mask:0xf
	v_fmac_f32_dpp v170, v163, v79 quad_perm:[3,3,3,3] row_mask:0xf bank_mask:0xf
	ds_read_b128 v[152:155], v10 offset:8432
	s_waitcnt lgkmcnt(5)
	v_fmac_f32_dpp v92, v164, v80 quad_perm:[0,0,0,0] row_mask:0xf bank_mask:0xf
	v_fmac_f32_dpp v168, v165, v81 quad_perm:[0,0,0,0] row_mask:0xf bank_mask:0xf
	v_fmac_f32_dpp v169, v166, v82 quad_perm:[0,0,0,0] row_mask:0xf bank_mask:0xf
	v_fmac_f32_dpp v170, v167, v83 quad_perm:[0,0,0,0] row_mask:0xf bank_mask:0xf
	v_fmac_f32_dpp v92, v164, v84 quad_perm:[1,1,1,1] row_mask:0xf bank_mask:0xf
	v_fmac_f32_dpp v168, v165, v85 quad_perm:[1,1,1,1] row_mask:0xf bank_mask:0xf
	v_fmac_f32_dpp v169, v166, v86 quad_perm:[1,1,1,1] row_mask:0xf bank_mask:0xf
	v_fmac_f32_dpp v170, v167, v87 quad_perm:[1,1,1,1] row_mask:0xf bank_mask:0xf
	v_fmac_f32_dpp v92, v164, v88 quad_perm:[2,2,2,2] row_mask:0xf bank_mask:0xf
	v_fmac_f32_dpp v168, v165, v89 quad_perm:[2,2,2,2] row_mask:0xf bank_mask:0xf
	v_fmac_f32_dpp v169, v166, v90 quad_perm:[2,2,2,2] row_mask:0xf bank_mask:0xf
	v_fmac_f32_dpp v170, v167, v91 quad_perm:[2,2,2,2] row_mask:0xf bank_mask:0xf
	v_add_f32_e32 v92, v92, v168
	v_add_f32_e32 v169, v169, v170
	v_add_f32_e32 v92, v92, v169
	ds_read_b128 v[156:159], v10 offset:8496
	s_waitcnt lgkmcnt(5)
	v_mov_b32_e32 v168, 0
	v_mov_b32_e32 v169, 0
	v_mov_b32_e32 v170, 0
	v_fmac_f32_dpp v93, v136, v64 quad_perm:[0,0,0,0] row_mask:0xf bank_mask:0xf
	v_fmac_f32_dpp v168, v137, v65 quad_perm:[0,0,0,0] row_mask:0xf bank_mask:0xf
	v_fmac_f32_dpp v169, v138, v66 quad_perm:[0,0,0,0] row_mask:0xf bank_mask:0xf
	v_fmac_f32_dpp v170, v139, v67 quad_perm:[0,0,0,0] row_mask:0xf bank_mask:0xf
	v_fmac_f32_dpp v93, v136, v68 quad_perm:[1,1,1,1] row_mask:0xf bank_mask:0xf
	v_fmac_f32_dpp v168, v137, v69 quad_perm:[1,1,1,1] row_mask:0xf bank_mask:0xf
	v_fmac_f32_dpp v169, v138, v70 quad_perm:[1,1,1,1] row_mask:0xf bank_mask:0xf
	v_fmac_f32_dpp v170, v139, v71 quad_perm:[1,1,1,1] row_mask:0xf bank_mask:0xf
	v_fmac_f32_dpp v93, v136, v72 quad_perm:[2,2,2,2] row_mask:0xf bank_mask:0xf
	v_fmac_f32_dpp v168, v137, v73 quad_perm:[2,2,2,2] row_mask:0xf bank_mask:0xf
	v_fmac_f32_dpp v169, v138, v74 quad_perm:[2,2,2,2] row_mask:0xf bank_mask:0xf
	v_fmac_f32_dpp v170, v139, v75 quad_perm:[2,2,2,2] row_mask:0xf bank_mask:0xf
	v_fmac_f32_dpp v93, v136, v76 quad_perm:[3,3,3,3] row_mask:0xf bank_mask:0xf
	v_fmac_f32_dpp v168, v137, v77 quad_perm:[3,3,3,3] row_mask:0xf bank_mask:0xf
	v_fmac_f32_dpp v169, v138, v78 quad_perm:[3,3,3,3] row_mask:0xf bank_mask:0xf
	v_fmac_f32_dpp v170, v139, v79 quad_perm:[3,3,3,3] row_mask:0xf bank_mask:0xf
	ds_read_b128 v[160:163], v10 offset:8704
	s_waitcnt lgkmcnt(5)
	v_fmac_f32_dpp v93, v140, v80 quad_perm:[0,0,0,0] row_mask:0xf bank_mask:0xf
	v_fmac_f32_dpp v168, v141, v81 quad_perm:[0,0,0,0] row_mask:0xf bank_mask:0xf
	v_fmac_f32_dpp v169, v142, v82 quad_perm:[0,0,0,0] row_mask:0xf bank_mask:0xf
	v_fmac_f32_dpp v170, v143, v83 quad_perm:[0,0,0,0] row_mask:0xf bank_mask:0xf
	v_fmac_f32_dpp v93, v140, v84 quad_perm:[1,1,1,1] row_mask:0xf bank_mask:0xf
	v_fmac_f32_dpp v168, v141, v85 quad_perm:[1,1,1,1] row_mask:0xf bank_mask:0xf
	v_fmac_f32_dpp v169, v142, v86 quad_perm:[1,1,1,1] row_mask:0xf bank_mask:0xf
	v_fmac_f32_dpp v170, v143, v87 quad_perm:[1,1,1,1] row_mask:0xf bank_mask:0xf
	v_fmac_f32_dpp v93, v140, v88 quad_perm:[2,2,2,2] row_mask:0xf bank_mask:0xf
	v_fmac_f32_dpp v168, v141, v89 quad_perm:[2,2,2,2] row_mask:0xf bank_mask:0xf
	v_fmac_f32_dpp v169, v142, v90 quad_perm:[2,2,2,2] row_mask:0xf bank_mask:0xf
	v_fmac_f32_dpp v170, v143, v91 quad_perm:[2,2,2,2] row_mask:0xf bank_mask:0xf
	v_fmac_f32_dpp v93, v140, v92 quad_perm:[3,3,3,3] row_mask:0xf bank_mask:0xf
	v_add_f32_e32 v93, v93, v168
	v_add_f32_e32 v169, v169, v170
	v_add_f32_e32 v93, v93, v169
	ds_read_b128 v[164:167], v10 offset:8768
	s_waitcnt lgkmcnt(5)
; __device__ void dn_d1(const Ctx& c, int ip) {
;     ...
;     { const f32x4 m = *(const f32x4*)(mr + 24);
;       a0 -= m[0] * x[24];
;       a1 -= m[1] * x[25];
;       a2 -= m[2] * x[26];
;       a3 -= m[3] * x[27];
;     }
;     { const f32x4 m = *(const f32x4*)(mr + 28);
;       a0 -= m[0] * x[28];
;       a1 -= m[1] * x[29];
;     }
;     SOLVE_ROW_END(30)
;     SOLVE_ROW_BEGIN(31)
;     { const f32x4 m = *(const f32x4*)(mr + 0);
;       a0 -= m[0] * x[0];
;       a1 -= m[1] * x[1];
;       a2 -= m[2] * x[2];
;       a3 -= m[3] * x[3];
;     }
;     { const f32x4 m = *(const f32x4*)(mr + 4);
;       a0 -= m[0] * x[4];
;       a1 -= m[1] * x[5];
;       a2 -= m[2] * x[6];
;       a3 -= m[3] * x[7];
;     }
;     { const f32x4 m = *(const f32x4*)(mr + 8);
;       a0 -= m[0] * x[8];
;       a1 -= m[1] * x[9];
;       a2 -= m[2] * x[10];
;       a3 -= m[3] * x[11];
;     }
;     { const f32x4 m = *(const f32x4*)(mr + 12);
;       a0 -= m[0] * x[12];
;       a1 -= m[1] * x[13];
;       a2 -= m[2] * x[14];
;       a3 -= m[3] * x[15];
;     }
;     { const f32x4 m = *(const f32x4*)(mr + 16);
;       a0 -= m[0] * x[16];
;       a1 -= m[1] * x[17];
;       a2 -= m[2] * x[18];
;       a3 -= m[3] * x[19];
;     }
;     { const f32x4 m = *(const f32x4*)(mr + 20);
;       a0 -= m[0] * x[20];
;       a1 -= m[1] * x[21];
;       a2 -= m[2] * x[22];
;       a3 -= m[3] * x[23];
;     }
;     { const f32x4 m = *(const f32x4*)(mr + 24);
;       a0 -= m[0] * x[24];
;       a1 -= m[1] * x[25];
;       a2 -= m[2] * x[26];
;       a3 -= m[3] * x[27];
;     }
;     { const f32x4 m = *(const f32x4*)(mr + 28);
;       a0 -= m[0] * x[28];
;       a1 -= m[1] * x[29];
;       a2 -= m[2] * x[30];
;     }
;     SOLVE_ROW_END(31)
	v_mov_b32_e32 v168, 0
	v_mov_b32_e32 v169, 0
	v_mov_b32_e32 v170, 0
	v_fmac_f32_dpp v94, v144, v64 quad_perm:[0,0,0,0] row_mask:0xf bank_mask:0xf
	v_fmac_f32_dpp v168, v145, v65 quad_perm:[0,0,0,0] row_mask:0xf bank_mask:0xf
	v_fmac_f32_dpp v169, v146, v66 quad_perm:[0,0,0,0] row_mask:0xf bank_mask:0xf
	v_fmac_f32_dpp v170, v147, v67 quad_perm:[0,0,0,0] row_mask:0xf bank_mask:0xf
	v_fmac_f32_dpp v94, v144, v68 quad_perm:[1,1,1,1] row_mask:0xf bank_mask:0xf
	v_fmac_f32_dpp v168, v145, v69 quad_perm:[1,1,1,1] row_mask:0xf bank_mask:0xf
	v_fmac_f32_dpp v169, v146, v70 quad_perm:[1,1,1,1] row_mask:0xf bank_mask:0xf
	v_fmac_f32_dpp v170, v147, v71 quad_perm:[1,1,1,1] row_mask:0xf bank_mask:0xf
	v_fmac_f32_dpp v94, v144, v72 quad_perm:[2,2,2,2] row_mask:0xf bank_mask:0xf
	v_fmac_f32_dpp v168, v145, v73 quad_perm:[2,2,2,2] row_mask:0xf bank_mask:0xf
	v_fmac_f32_dpp v169, v146, v74 quad_perm:[2,2,2,2] row_mask:0xf bank_mask:0xf
	v_fmac_f32_dpp v170, v147, v75 quad_perm:[2,2,2,2] row_mask:0xf bank_mask:0xf
	v_fmac_f32_dpp v94, v144, v76 quad_perm:[3,3,3,3] row_mask:0xf bank_mask:0xf
	v_fmac_f32_dpp v168, v145, v77 quad_perm:[3,3,3,3] row_mask:0xf bank_mask:0xf
	v_fmac_f32_dpp v169, v146, v78 quad_perm:[3,3,3,3] row_mask:0xf bank_mask:0xf
	v_fmac_f32_dpp v170, v147, v79 quad_perm:[3,3,3,3] row_mask:0xf bank_mask:0xf
	ds_read_b128 v[136:139], v10 offset:8976
	s_waitcnt lgkmcnt(5)
	v_fmac_f32_dpp v94, v148, v80 quad_perm:[0,0,0,0] row_mask:0xf bank_mask:0xf
	v_fmac_f32_dpp v168, v149, v81 quad_perm:[0,0,0,0] row_mask:0xf bank_mask:0xf
	v_fmac_f32_dpp v169, v150, v82 quad_perm:[0,0,0,0] row_mask:0xf bank_mask:0xf
	v_fmac_f32_dpp v170, v151, v83 quad_perm:[0,0,0,0] row_mask:0xf bank_mask:0xf
	v_fmac_f32_dpp v94, v148, v84 quad_perm:[1,1,1,1] row_mask:0xf bank_mask:0xf
	v_fmac_f32_dpp v168, v149, v85 quad_perm:[1,1,1,1] row_mask:0xf bank_mask:0xf
	v_fmac_f32_dpp v169, v150, v86 quad_perm:[1,1,1,1] row_mask:0xf bank_mask:0xf
	v_fmac_f32_dpp v170, v151, v87 quad_perm:[1,1,1,1] row_mask:0xf bank_mask:0xf
	v_fmac_f32_dpp v94, v148, v88 quad_perm:[2,2,2,2] row_mask:0xf bank_mask:0xf
	v_fmac_f32_dpp v168, v149, v89 quad_perm:[2,2,2,2] row_mask:0xf bank_mask:0xf
	v_fmac_f32_dpp v169, v150, v90 quad_perm:[2,2,2,2] row_mask:0xf bank_mask:0xf
	v_fmac_f32_dpp v170, v151, v91 quad_perm:[2,2,2,2] row_mask:0xf bank_mask:0xf
	v_fmac_f32_dpp v94, v148, v92 quad_perm:[3,3,3,3] row_mask:0xf bank_mask:0xf
	v_fmac_f32_dpp v168, v149, v93 quad_perm:[3,3,3,3] row_mask:0xf bank_mask:0xf
	v_add_f32_e32 v94, v94, v168
	v_add_f32_e32 v169, v169, v170
	v_add_f32_e32 v94, v94, v169
	ds_read_b128 v[140:143], v10 offset:9040
	s_waitcnt lgkmcnt(5)
	v_mov_b32_e32 v168, 0
	v_mov_b32_e32 v169, 0
	v_mov_b32_e32 v170, 0
	v_fmac_f32_dpp v95, v152, v64 quad_perm:[0,0,0,0] row_mask:0xf bank_mask:0xf
	v_fmac_f32_dpp v168, v153, v65 quad_perm:[0,0,0,0] row_mask:0xf bank_mask:0xf
	v_fmac_f32_dpp v169, v154, v66 quad_perm:[0,0,0,0] row_mask:0xf bank_mask:0xf
	v_fmac_f32_dpp v170, v155, v67 quad_perm:[0,0,0,0] row_mask:0xf bank_mask:0xf
	v_fmac_f32_dpp v95, v152, v68 quad_perm:[1,1,1,1] row_mask:0xf bank_mask:0xf
	v_fmac_f32_dpp v168, v153, v69 quad_perm:[1,1,1,1] row_mask:0xf bank_mask:0xf
	v_fmac_f32_dpp v169, v154, v70 quad_perm:[1,1,1,1] row_mask:0xf bank_mask:0xf
	v_fmac_f32_dpp v170, v155, v71 quad_perm:[1,1,1,1] row_mask:0xf bank_mask:0xf
	v_fmac_f32_dpp v95, v152, v72 quad_perm:[2,2,2,2] row_mask:0xf bank_mask:0xf
	v_fmac_f32_dpp v168, v153, v73 quad_perm:[2,2,2,2] row_mask:0xf bank_mask:0xf
	v_fmac_f32_dpp v169, v154, v74 quad_perm:[2,2,2,2] row_mask:0xf bank_mask:0xf
	v_fmac_f32_dpp v170, v155, v75 quad_perm:[2,2,2,2] row_mask:0xf bank_mask:0xf
	v_fmac_f32_dpp v95, v152, v76 quad_perm:[3,3,3,3] row_mask:0xf bank_mask:0xf
	v_fmac_f32_dpp v168, v153, v77 quad_perm:[3,3,3,3] row_mask:0xf bank_mask:0xf
	v_fmac_f32_dpp v169, v154, v78 quad_perm:[3,3,3,3] row_mask:0xf bank_mask:0xf
	v_fmac_f32_dpp v170, v155, v79 quad_perm:[3,3,3,3] row_mask:0xf bank_mask:0xf
	ds_read_b128 v[144:147], v10 offset:9104
	s_waitcnt lgkmcnt(5)
	v_fmac_f32_dpp v95, v156, v80 quad_perm:[0,0,0,0] row_mask:0xf bank_mask:0xf
	v_fmac_f32_dpp v168, v157, v81 quad_perm:[0,0,0,0] row_mask:0xf bank_mask:0xf
	v_fmac_f32_dpp v169, v158, v82 quad_perm:[0,0,0,0] row_mask:0xf bank_mask:0xf
	v_fmac_f32_dpp v170, v159, v83 quad_perm:[0,0,0,0] row_mask:0xf bank_mask:0xf
	v_fmac_f32_dpp v95, v156, v84 quad_perm:[1,1,1,1] row_mask:0xf bank_mask:0xf
	v_fmac_f32_dpp v168, v157, v85 quad_perm:[1,1,1,1] row_mask:0xf bank_mask:0xf
	v_fmac_f32_dpp v169, v158, v86 quad_perm:[1,1,1,1] row_mask:0xf bank_mask:0xf
	v_fmac_f32_dpp v170, v159, v87 quad_perm:[1,1,1,1] row_mask:0xf bank_mask:0xf
	v_fmac_f32_dpp v95, v156, v88 quad_perm:[2,2,2,2] row_mask:0xf bank_mask:0xf
	v_fmac_f32_dpp v168, v157, v89 quad_perm:[2,2,2,2] row_mask:0xf bank_mask:0xf
	v_fmac_f32_dpp v169, v158, v90 quad_perm:[2,2,2,2] row_mask:0xf bank_mask:0xf
	v_fmac_f32_dpp v170, v159, v91 quad_perm:[2,2,2,2] row_mask:0xf bank_mask:0xf
	v_fmac_f32_dpp v95, v156, v92 quad_perm:[3,3,3,3] row_mask:0xf bank_mask:0xf
	v_fmac_f32_dpp v168, v157, v93 quad_perm:[3,3,3,3] row_mask:0xf bank_mask:0xf
	v_fmac_f32_dpp v169, v158, v94 quad_perm:[3,3,3,3] row_mask:0xf bank_mask:0xf
	v_add_f32_e32 v95, v95, v168
	v_add_f32_e32 v169, v169, v170
	v_add_f32_e32 v95, v95, v169
	ds_read_b128 v[148:151], v10 offset:9248
	s_waitcnt lgkmcnt(5)
; __device__ void dn_d1(const Ctx& c, int ip) {
;     ...
;     { const f32x4 m = *(const f32x4*)(mr + 28);
;       a0 -= m[0] * x[28];
;       a1 -= m[1] * x[29];
;       a2 -= m[2] * x[30];
;       a3 -= m[3] * x[31];
;     }
;     SOLVE_ROW_END(32)
;     SOLVE_ROW_BEGIN(33)
;     { const f32x4 m = *(const f32x4*)(mr + 0);
;       a0 -= m[0] * x[0];
;       a1 -= m[1] * x[1];
;       a2 -= m[2] * x[2];
;       a3 -= m[3] * x[3];
;     }
;     { const f32x4 m = *(const f32x4*)(mr + 4);
;       a0 -= m[0] * x[4];
;       a1 -= m[1] * x[5];
;       a2 -= m[2] * x[6];
;       a3 -= m[3] * x[7];
;     }
;     { const f32x4 m = *(const f32x4*)(mr + 8);
;       a0 -= m[0] * x[8];
;       a1 -= m[1] * x[9];
;       a2 -= m[2] * x[10];
;       a3 -= m[3] * x[11];
;     }
;     { const f32x4 m = *(const f32x4*)(mr + 12);
;       a0 -= m[0] * x[12];
;       a1 -= m[1] * x[13];
;       a2 -= m[2] * x[14];
;       a3 -= m[3] * x[15];
;     }
;     { const f32x4 m = *(const f32x4*)(mr + 16);
;       a0 -= m[0] * x[16];
;       a1 -= m[1] * x[17];
;       a2 -= m[2] * x[18];
;       a3 -= m[3] * x[19];
;     }
;     { const f32x4 m = *(const f32x4*)(mr + 20);
;       a0 -= m[0] * x[20];
;       a1 -= m[1] * x[21];
;       a2 -= m[2] * x[22];
;       a3 -= m[3] * x[23];
;     }
;     { const f32x4 m = *(const f32x4*)(mr + 24);
;       a0 -= m[0] * x[24];
;       a1 -= m[1] * x[25];
;       a2 -= m[2] * x[26];
;       a3 -= m[3] * x[27];
;     }
;     { const f32x4 m = *(const f32x4*)(mr + 28);
;       a0 -= m[0] * x[28];
;       a1 -= m[1] * x[29];
;       a2 -= m[2] * x[30];
;       a3 -= m[3] * x[31];
;     }
;     { const f32x4 m = *(const f32x4*)(mr + 32);
;       a0 -= m[0] * x[32];
;     }
;     SOLVE_ROW_END(33)
	v_mov_b32_e32 v168, 0
	v_mov_b32_e32 v169, 0
	v_mov_b32_e32 v170, 0
	v_fmac_f32_dpp v96, v160, v64 quad_perm:[0,0,0,0] row_mask:0xf bank_mask:0xf
	v_fmac_f32_dpp v168, v161, v65 quad_perm:[0,0,0,0] row_mask:0xf bank_mask:0xf
	v_fmac_f32_dpp v169, v162, v66 quad_perm:[0,0,0,0] row_mask:0xf bank_mask:0xf
	v_fmac_f32_dpp v170, v163, v67 quad_perm:[0,0,0,0] row_mask:0xf bank_mask:0xf
	v_fmac_f32_dpp v96, v160, v68 quad_perm:[1,1,1,1] row_mask:0xf bank_mask:0xf
	v_fmac_f32_dpp v168, v161, v69 quad_perm:[1,1,1,1] row_mask:0xf bank_mask:0xf
	v_fmac_f32_dpp v169, v162, v70 quad_perm:[1,1,1,1] row_mask:0xf bank_mask:0xf
	v_fmac_f32_dpp v170, v163, v71 quad_perm:[1,1,1,1] row_mask:0xf bank_mask:0xf
	v_fmac_f32_dpp v96, v160, v72 quad_perm:[2,2,2,2] row_mask:0xf bank_mask:0xf
	v_fmac_f32_dpp v168, v161, v73 quad_perm:[2,2,2,2] row_mask:0xf bank_mask:0xf
	v_fmac_f32_dpp v169, v162, v74 quad_perm:[2,2,2,2] row_mask:0xf bank_mask:0xf
	v_fmac_f32_dpp v170, v163, v75 quad_perm:[2,2,2,2] row_mask:0xf bank_mask:0xf
	v_fmac_f32_dpp v96, v160, v76 quad_perm:[3,3,3,3] row_mask:0xf bank_mask:0xf
	v_fmac_f32_dpp v168, v161, v77 quad_perm:[3,3,3,3] row_mask:0xf bank_mask:0xf
	v_fmac_f32_dpp v169, v162, v78 quad_perm:[3,3,3,3] row_mask:0xf bank_mask:0xf
	v_fmac_f32_dpp v170, v163, v79 quad_perm:[3,3,3,3] row_mask:0xf bank_mask:0xf
	ds_read_b128 v[152:155], v10 offset:9312
	s_waitcnt lgkmcnt(5)
	v_fmac_f32_dpp v96, v164, v80 quad_perm:[0,0,0,0] row_mask:0xf bank_mask:0xf
	v_fmac_f32_dpp v168, v165, v81 quad_perm:[0,0,0,0] row_mask:0xf bank_mask:0xf
	v_fmac_f32_dpp v169, v166, v82 quad_perm:[0,0,0,0] row_mask:0xf bank_mask:0xf
	v_fmac_f32_dpp v170, v167, v83 quad_perm:[0,0,0,0] row_mask:0xf bank_mask:0xf
	v_fmac_f32_dpp v96, v164, v84 quad_perm:[1,1,1,1] row_mask:0xf bank_mask:0xf
	v_fmac_f32_dpp v168, v165, v85 quad_perm:[1,1,1,1] row_mask:0xf bank_mask:0xf
	v_fmac_f32_dpp v169, v166, v86 quad_perm:[1,1,1,1] row_mask:0xf bank_mask:0xf
	v_fmac_f32_dpp v170, v167, v87 quad_perm:[1,1,1,1] row_mask:0xf bank_mask:0xf
	v_fmac_f32_dpp v96, v164, v88 quad_perm:[2,2,2,2] row_mask:0xf bank_mask:0xf
	v_fmac_f32_dpp v168, v165, v89 quad_perm:[2,2,2,2] row_mask:0xf bank_mask:0xf
	v_fmac_f32_dpp v169, v166, v90 quad_perm:[2,2,2,2] row_mask:0xf bank_mask:0xf
	v_fmac_f32_dpp v170, v167, v91 quad_perm:[2,2,2,2] row_mask:0xf bank_mask:0xf
	v_fmac_f32_dpp v96, v164, v92 quad_perm:[3,3,3,3] row_mask:0xf bank_mask:0xf
	v_fmac_f32_dpp v168, v165, v93 quad_perm:[3,3,3,3] row_mask:0xf bank_mask:0xf
	v_fmac_f32_dpp v169, v166, v94 quad_perm:[3,3,3,3] row_mask:0xf bank_mask:0xf
	v_fmac_f32_dpp v170, v167, v95 quad_perm:[3,3,3,3] row_mask:0xf bank_mask:0xf
	v_add_f32_e32 v96, v96, v168
	v_add_f32_e32 v169, v169, v170
	v_add_f32_e32 v96, v96, v169
	ds_read_b128 v[156:159], v10 offset:9376
	s_waitcnt lgkmcnt(5)
	v_mov_b32_e32 v168, 0
	v_mov_b32_e32 v169, 0
	v_mov_b32_e32 v170, 0
	v_fmac_f32_dpp v97, v136, v64 quad_perm:[0,0,0,0] row_mask:0xf bank_mask:0xf
	v_fmac_f32_dpp v168, v137, v65 quad_perm:[0,0,0,0] row_mask:0xf bank_mask:0xf
	v_fmac_f32_dpp v169, v138, v66 quad_perm:[0,0,0,0] row_mask:0xf bank_mask:0xf
	v_fmac_f32_dpp v170, v139, v67 quad_perm:[0,0,0,0] row_mask:0xf bank_mask:0xf
	v_fmac_f32_dpp v97, v136, v68 quad_perm:[1,1,1,1] row_mask:0xf bank_mask:0xf
	v_fmac_f32_dpp v168, v137, v69 quad_perm:[1,1,1,1] row_mask:0xf bank_mask:0xf
	v_fmac_f32_dpp v169, v138, v70 quad_perm:[1,1,1,1] row_mask:0xf bank_mask:0xf
	v_fmac_f32_dpp v170, v139, v71 quad_perm:[1,1,1,1] row_mask:0xf bank_mask:0xf
	v_fmac_f32_dpp v97, v136, v72 quad_perm:[2,2,2,2] row_mask:0xf bank_mask:0xf
	v_fmac_f32_dpp v168, v137, v73 quad_perm:[2,2,2,2] row_mask:0xf bank_mask:0xf
	v_fmac_f32_dpp v169, v138, v74 quad_perm:[2,2,2,2] row_mask:0xf bank_mask:0xf
	v_fmac_f32_dpp v170, v139, v75 quad_perm:[2,2,2,2] row_mask:0xf bank_mask:0xf
	v_fmac_f32_dpp v97, v136, v76 quad_perm:[3,3,3,3] row_mask:0xf bank_mask:0xf
	v_fmac_f32_dpp v168, v137, v77 quad_perm:[3,3,3,3] row_mask:0xf bank_mask:0xf
	v_fmac_f32_dpp v169, v138, v78 quad_perm:[3,3,3,3] row_mask:0xf bank_mask:0xf
	v_fmac_f32_dpp v170, v139, v79 quad_perm:[3,3,3,3] row_mask:0xf bank_mask:0xf
	ds_read_b128 v[160:163], v10 offset:9520
	s_waitcnt lgkmcnt(5)
	v_fmac_f32_dpp v97, v140, v80 quad_perm:[0,0,0,0] row_mask:0xf bank_mask:0xf
	v_fmac_f32_dpp v168, v141, v81 quad_perm:[0,0,0,0] row_mask:0xf bank_mask:0xf
	v_fmac_f32_dpp v169, v142, v82 quad_perm:[0,0,0,0] row_mask:0xf bank_mask:0xf
	v_fmac_f32_dpp v170, v143, v83 quad_perm:[0,0,0,0] row_mask:0xf bank_mask:0xf
	v_fmac_f32_dpp v97, v140, v84 quad_perm:[1,1,1,1] row_mask:0xf bank_mask:0xf
	v_fmac_f32_dpp v168, v141, v85 quad_perm:[1,1,1,1] row_mask:0xf bank_mask:0xf
	v_fmac_f32_dpp v169, v142, v86 quad_perm:[1,1,1,1] row_mask:0xf bank_mask:0xf
	v_fmac_f32_dpp v170, v143, v87 quad_perm:[1,1,1,1] row_mask:0xf bank_mask:0xf
	v_fmac_f32_dpp v97, v140, v88 quad_perm:[2,2,2,2] row_mask:0xf bank_mask:0xf
	v_fmac_f32_dpp v168, v141, v89 quad_perm:[2,2,2,2] row_mask:0xf bank_mask:0xf
	v_fmac_f32_dpp v169, v142, v90 quad_perm:[2,2,2,2] row_mask:0xf bank_mask:0xf
	v_fmac_f32_dpp v170, v143, v91 quad_perm:[2,2,2,2] row_mask:0xf bank_mask:0xf
	v_fmac_f32_dpp v97, v140, v92 quad_perm:[3,3,3,3] row_mask:0xf bank_mask:0xf
	v_fmac_f32_dpp v168, v141, v93 quad_perm:[3,3,3,3] row_mask:0xf bank_mask:0xf
	v_fmac_f32_dpp v169, v142, v94 quad_perm:[3,3,3,3] row_mask:0xf bank_mask:0xf
	v_fmac_f32_dpp v170, v143, v95 quad_perm:[3,3,3,3] row_mask:0xf bank_mask:0xf
	ds_read_b128 v[164:167], v10 offset:9584
	s_waitcnt lgkmcnt(5)
; __device__ void dn_d1(const Ctx& c, int ip) {
;     ...
;     { const f32x4 m = *(const f32x4*)(mr + 32);
;       a0 -= m[0] * x[32];
;       a1 -= m[1] * x[33];
;     }
;     SOLVE_ROW_END(34)
;     SOLVE_ROW_BEGIN(35)
;     { const f32x4 m = *(const f32x4*)(mr + 0);
;       a0 -= m[0] * x[0];
;       a1 -= m[1] * x[1];
;       a2 -= m[2] * x[2];
;       a3 -= m[3] * x[3];
;     }
;     { const f32x4 m = *(const f32x4*)(mr + 4);
;       a0 -= m[0] * x[4];
;       a1 -= m[1] * x[5];
;       a2 -= m[2] * x[6];
;       a3 -= m[3] * x[7];
;     }
;     { const f32x4 m = *(const f32x4*)(mr + 8);
;       a0 -= m[0] * x[8];
;       a1 -= m[1] * x[9];
;       a2 -= m[2] * x[10];
;       a3 -= m[3] * x[11];
;     }
;     { const f32x4 m = *(const f32x4*)(mr + 12);
;       a0 -= m[0] * x[12];
;       a1 -= m[1] * x[13];
;       a2 -= m[2] * x[14];
;       a3 -= m[3] * x[15];
;     }
;     { const f32x4 m = *(const f32x4*)(mr + 16);
;       a0 -= m[0] * x[16];
;       a1 -= m[1] * x[17];
;       a2 -= m[2] * x[18];
;       a3 -= m[3] * x[19];
;     }
;     { const f32x4 m = *(const f32x4*)(mr + 20);
;       a0 -= m[0] * x[20];
;       a1 -= m[1] * x[21];
;       a2 -= m[2] * x[22];
;       a3 -= m[3] * x[23];
;     }
;     { const f32x4 m = *(const f32x4*)(mr + 24);
;       a0 -= m[0] * x[24];
;       a1 -= m[1] * x[25];
;       a2 -= m[2] * x[26];
;       a3 -= m[3] * x[27];
;     }
;     { const f32x4 m = *(const f32x4*)(mr + 28);
;       a0 -= m[0] * x[28];
;       a1 -= m[1] * x[29];
;       a2 -= m[2] * x[30];
;       a3 -= m[3] * x[31];
;     }
;     { const f32x4 m = *(const f32x4*)(mr + 32);
;       a0 -= m[0] * x[32];
;       a1 -= m[1] * x[33];
;       a2 -= m[2] * x[34];
;     }
;     SOLVE_ROW_END(35)
	v_fmac_f32_dpp v97, v144, v96 quad_perm:[0,0,0,0] row_mask:0xf bank_mask:0xf
	v_add_f32_e32 v97, v97, v168
	v_add_f32_e32 v169, v169, v170
	v_add_f32_e32 v97, v97, v169
	ds_read_b128 v[136:139], v10 offset:9648
	s_waitcnt lgkmcnt(5)
	v_mov_b32_e32 v168, 0
	v_mov_b32_e32 v169, 0
	v_mov_b32_e32 v170, 0
	v_fmac_f32_dpp v98, v148, v64 quad_perm:[0,0,0,0] row_mask:0xf bank_mask:0xf
	v_fmac_f32_dpp v168, v149, v65 quad_perm:[0,0,0,0] row_mask:0xf bank_mask:0xf
	v_fmac_f32_dpp v169, v150, v66 quad_perm:[0,0,0,0] row_mask:0xf bank_mask:0xf
	v_fmac_f32_dpp v170, v151, v67 quad_perm:[0,0,0,0] row_mask:0xf bank_mask:0xf
	v_fmac_f32_dpp v98, v148, v68 quad_perm:[1,1,1,1] row_mask:0xf bank_mask:0xf
	v_fmac_f32_dpp v168, v149, v69 quad_perm:[1,1,1,1] row_mask:0xf bank_mask:0xf
	v_fmac_f32_dpp v169, v150, v70 quad_perm:[1,1,1,1] row_mask:0xf bank_mask:0xf
	v_fmac_f32_dpp v170, v151, v71 quad_perm:[1,1,1,1] row_mask:0xf bank_mask:0xf
	v_fmac_f32_dpp v98, v148, v72 quad_perm:[2,2,2,2] row_mask:0xf bank_mask:0xf
	v_fmac_f32_dpp v168, v149, v73 quad_perm:[2,2,2,2] row_mask:0xf bank_mask:0xf
	v_fmac_f32_dpp v169, v150, v74 quad_perm:[2,2,2,2] row_mask:0xf bank_mask:0xf
	v_fmac_f32_dpp v170, v151, v75 quad_perm:[2,2,2,2] row_mask:0xf bank_mask:0xf
	v_fmac_f32_dpp v98, v148, v76 quad_perm:[3,3,3,3] row_mask:0xf bank_mask:0xf
	v_fmac_f32_dpp v168, v149, v77 quad_perm:[3,3,3,3] row_mask:0xf bank_mask:0xf
	v_fmac_f32_dpp v169, v150, v78 quad_perm:[3,3,3,3] row_mask:0xf bank_mask:0xf
	v_fmac_f32_dpp v170, v151, v79 quad_perm:[3,3,3,3] row_mask:0xf bank_mask:0xf
	ds_read_b128 v[140:143], v10 offset:9792
	s_waitcnt lgkmcnt(5)
	v_fmac_f32_dpp v98, v152, v80 quad_perm:[0,0,0,0] row_mask:0xf bank_mask:0xf
	v_fmac_f32_dpp v168, v153, v81 quad_perm:[0,0,0,0] row_mask:0xf bank_mask:0xf
	v_fmac_f32_dpp v169, v154, v82 quad_perm:[0,0,0,0] row_mask:0xf bank_mask:0xf
	v_fmac_f32_dpp v170, v155, v83 quad_perm:[0,0,0,0] row_mask:0xf bank_mask:0xf
	v_fmac_f32_dpp v98, v152, v84 quad_perm:[1,1,1,1] row_mask:0xf bank_mask:0xf
	v_fmac_f32_dpp v168, v153, v85 quad_perm:[1,1,1,1] row_mask:0xf bank_mask:0xf
	v_fmac_f32_dpp v169, v154, v86 quad_perm:[1,1,1,1] row_mask:0xf bank_mask:0xf
	v_fmac_f32_dpp v170, v155, v87 quad_perm:[1,1,1,1] row_mask:0xf bank_mask:0xf
	v_fmac_f32_dpp v98, v152, v88 quad_perm:[2,2,2,2] row_mask:0xf bank_mask:0xf
	v_fmac_f32_dpp v168, v153, v89 quad_perm:[2,2,2,2] row_mask:0xf bank_mask:0xf
	v_fmac_f32_dpp v169, v154, v90 quad_perm:[2,2,2,2] row_mask:0xf bank_mask:0xf
	v_fmac_f32_dpp v170, v155, v91 quad_perm:[2,2,2,2] row_mask:0xf bank_mask:0xf
	v_fmac_f32_dpp v98, v152, v92 quad_perm:[3,3,3,3] row_mask:0xf bank_mask:0xf
	v_fmac_f32_dpp v168, v153, v93 quad_perm:[3,3,3,3] row_mask:0xf bank_mask:0xf
	v_fmac_f32_dpp v169, v154, v94 quad_perm:[3,3,3,3] row_mask:0xf bank_mask:0xf
	v_fmac_f32_dpp v170, v155, v95 quad_perm:[3,3,3,3] row_mask:0xf bank_mask:0xf
	ds_read_b128 v[144:147], v10 offset:9856
	s_waitcnt lgkmcnt(5)
	v_fmac_f32_dpp v98, v156, v96 quad_perm:[0,0,0,0] row_mask:0xf bank_mask:0xf
	v_fmac_f32_dpp v168, v157, v97 quad_perm:[0,0,0,0] row_mask:0xf bank_mask:0xf
	v_add_f32_e32 v98, v98, v168
	v_add_f32_e32 v169, v169, v170
	v_add_f32_e32 v98, v98, v169
	ds_read_b128 v[148:151], v10 offset:9920
	s_waitcnt lgkmcnt(5)
	v_mov_b32_e32 v168, 0
	v_mov_b32_e32 v169, 0
	v_mov_b32_e32 v170, 0
	v_fmac_f32_dpp v99, v160, v64 quad_perm:[0,0,0,0] row_mask:0xf bank_mask:0xf
	v_fmac_f32_dpp v168, v161, v65 quad_perm:[0,0,0,0] row_mask:0xf bank_mask:0xf
	v_fmac_f32_dpp v169, v162, v66 quad_perm:[0,0,0,0] row_mask:0xf bank_mask:0xf
	v_fmac_f32_dpp v170, v163, v67 quad_perm:[0,0,0,0] row_mask:0xf bank_mask:0xf
	v_fmac_f32_dpp v99, v160, v68 quad_perm:[1,1,1,1] row_mask:0xf bank_mask:0xf
	v_fmac_f32_dpp v168, v161, v69 quad_perm:[1,1,1,1] row_mask:0xf bank_mask:0xf
	v_fmac_f32_dpp v169, v162, v70 quad_perm:[1,1,1,1] row_mask:0xf bank_mask:0xf
	v_fmac_f32_dpp v170, v163, v71 quad_perm:[1,1,1,1] row_mask:0xf bank_mask:0xf
	v_fmac_f32_dpp v99, v160, v72 quad_perm:[2,2,2,2] row_mask:0xf bank_mask:0xf
	v_fmac_f32_dpp v168, v161, v73 quad_perm:[2,2,2,2] row_mask:0xf bank_mask:0xf
	v_fmac_f32_dpp v169, v162, v74 quad_perm:[2,2,2,2] row_mask:0xf bank_mask:0xf
	v_fmac_f32_dpp v170, v163, v75 quad_perm:[2,2,2,2] row_mask:0xf bank_mask:0xf
	v_fmac_f32_dpp v99, v160, v76 quad_perm:[3,3,3,3] row_mask:0xf bank_mask:0xf
	v_fmac_f32_dpp v168, v161, v77 quad_perm:[3,3,3,3] row_mask:0xf bank_mask:0xf
	v_fmac_f32_dpp v169, v162, v78 quad_perm:[3,3,3,3] row_mask:0xf bank_mask:0xf
	v_fmac_f32_dpp v170, v163, v79 quad_perm:[3,3,3,3] row_mask:0xf bank_mask:0xf
	ds_read_b128 v[152:155], v10 offset:10064
	s_waitcnt lgkmcnt(5)
	v_fmac_f32_dpp v99, v164, v80 quad_perm:[0,0,0,0] row_mask:0xf bank_mask:0xf
	v_fmac_f32_dpp v168, v165, v81 quad_perm:[0,0,0,0] row_mask:0xf bank_mask:0xf
	v_fmac_f32_dpp v169, v166, v82 quad_perm:[0,0,0,0] row_mask:0xf bank_mask:0xf
	v_fmac_f32_dpp v170, v167, v83 quad_perm:[0,0,0,0] row_mask:0xf bank_mask:0xf
	v_fmac_f32_dpp v99, v164, v84 quad_perm:[1,1,1,1] row_mask:0xf bank_mask:0xf
	v_fmac_f32_dpp v168, v165, v85 quad_perm:[1,1,1,1] row_mask:0xf bank_mask:0xf
	v_fmac_f32_dpp v169, v166, v86 quad_perm:[1,1,1,1] row_mask:0xf bank_mask:0xf
	v_fmac_f32_dpp v170, v167, v87 quad_perm:[1,1,1,1] row_mask:0xf bank_mask:0xf
	v_fmac_f32_dpp v99, v164, v88 quad_perm:[2,2,2,2] row_mask:0xf bank_mask:0xf
	v_fmac_f32_dpp v168, v165, v89 quad_perm:[2,2,2,2] row_mask:0xf bank_mask:0xf
	v_fmac_f32_dpp v169, v166, v90 quad_perm:[2,2,2,2] row_mask:0xf bank_mask:0xf
	v_fmac_f32_dpp v170, v167, v91 quad_perm:[2,2,2,2] row_mask:0xf bank_mask:0xf
	v_fmac_f32_dpp v99, v164, v92 quad_perm:[3,3,3,3] row_mask:0xf bank_mask:0xf
	v_fmac_f32_dpp v168, v165, v93 quad_perm:[3,3,3,3] row_mask:0xf bank_mask:0xf
	v_fmac_f32_dpp v169, v166, v94 quad_perm:[3,3,3,3] row_mask:0xf bank_mask:0xf
	v_fmac_f32_dpp v170, v167, v95 quad_perm:[3,3,3,3] row_mask:0xf bank_mask:0xf
	ds_read_b128 v[156:159], v10 offset:10128
	s_waitcnt lgkmcnt(5)
; __device__ void dn_d1(const Ctx& c, int ip) {
;     ...
;     SOLVE_ROW_BEGIN(36)
;     { const f32x4 m = *(const f32x4*)(mr + 0);
;       a0 -= m[0] * x[0];
;       a1 -= m[1] * x[1];
;       a2 -= m[2] * x[2];
;       a3 -= m[3] * x[3];
;     }
;     { const f32x4 m = *(const f32x4*)(mr + 4);
;       a0 -= m[0] * x[4];
;       a1 -= m[1] * x[5];
;       a2 -= m[2] * x[6];
;       a3 -= m[3] * x[7];
;     }
;     { const f32x4 m = *(const f32x4*)(mr + 8);
;       a0 -= m[0] * x[8];
;       a1 -= m[1] * x[9];
;       a2 -= m[2] * x[10];
;       a3 -= m[3] * x[11];
;     }
;     { const f32x4 m = *(const f32x4*)(mr + 12);
;       a0 -= m[0] * x[12];
;       a1 -= m[1] * x[13];
;       a2 -= m[2] * x[14];
;       a3 -= m[3] * x[15];
;     }
;     { const f32x4 m = *(const f32x4*)(mr + 16);
;       a0 -= m[0] * x[16];
;       a1 -= m[1] * x[17];
;       a2 -= m[2] * x[18];
;       a3 -= m[3] * x[19];
;     }
;     { const f32x4 m = *(const f32x4*)(mr + 20);
;       a0 -= m[0] * x[20];
;       a1 -= m[1] * x[21];
;       a2 -= m[2] * x[22];
;       a3 -= m[3] * x[23];
;     }
;     { const f32x4 m = *(const f32x4*)(mr + 24);
;       a0 -= m[0] * x[24];
;       a1 -= m[1] * x[25];
;       a2 -= m[2] * x[26];
;       a3 -= m[3] * x[27];
;     }
;     { const f32x4 m = *(const f32x4*)(mr + 28);
;       a0 -= m[0] * x[28];
;       a1 -= m[1] * x[29];
;       a2 -= m[2] * x[30];
;       a3 -= m[3] * x[31];
;     }
;     { const f32x4 m = *(const f32x4*)(mr + 32);
;       a0 -= m[0] * x[32];
;       a1 -= m[1] * x[33];
;       a2 -= m[2] * x[34];
;       a3 -= m[3] * x[35];
;     }
;     SOLVE_ROW_END(36)
	v_fmac_f32_dpp v99, v136, v96 quad_perm:[0,0,0,0] row_mask:0xf bank_mask:0xf
	v_fmac_f32_dpp v168, v137, v97 quad_perm:[0,0,0,0] row_mask:0xf bank_mask:0xf
	v_fmac_f32_dpp v169, v138, v98 quad_perm:[0,0,0,0] row_mask:0xf bank_mask:0xf
	v_add_f32_e32 v99, v99, v168
	v_add_f32_e32 v169, v169, v170
	v_add_f32_e32 v99, v99, v169
	ds_read_b128 v[160:163], v10 offset:10192
	s_waitcnt lgkmcnt(5)
	v_mov_b32_e32 v168, 0
	v_mov_b32_e32 v169, 0
	v_mov_b32_e32 v170, 0
	v_fmac_f32_dpp v100, v140, v64 quad_perm:[0,0,0,0] row_mask:0xf bank_mask:0xf
	v_fmac_f32_dpp v168, v141, v65 quad_perm:[0,0,0,0] row_mask:0xf bank_mask:0xf
	v_fmac_f32_dpp v169, v142, v66 quad_perm:[0,0,0,0] row_mask:0xf bank_mask:0xf
	v_fmac_f32_dpp v170, v143, v67 quad_perm:[0,0,0,0] row_mask:0xf bank_mask:0xf
	v_fmac_f32_dpp v100, v140, v68 quad_perm:[1,1,1,1] row_mask:0xf bank_mask:0xf
	v_fmac_f32_dpp v168, v141, v69 quad_perm:[1,1,1,1] row_mask:0xf bank_mask:0xf
	v_fmac_f32_dpp v169, v142, v70 quad_perm:[1,1,1,1] row_mask:0xf bank_mask:0xf
	v_fmac_f32_dpp v170, v143, v71 quad_perm:[1,1,1,1] row_mask:0xf bank_mask:0xf
	v_fmac_f32_dpp v100, v140, v72 quad_perm:[2,2,2,2] row_mask:0xf bank_mask:0xf
	v_fmac_f32_dpp v168, v141, v73 quad_perm:[2,2,2,2] row_mask:0xf bank_mask:0xf
	v_fmac_f32_dpp v169, v142, v74 quad_perm:[2,2,2,2] row_mask:0xf bank_mask:0xf
	v_fmac_f32_dpp v170, v143, v75 quad_perm:[2,2,2,2] row_mask:0xf bank_mask:0xf
	v_fmac_f32_dpp v100, v140, v76 quad_perm:[3,3,3,3] row_mask:0xf bank_mask:0xf
	v_fmac_f32_dpp v168, v141, v77 quad_perm:[3,3,3,3] row_mask:0xf bank_mask:0xf
	v_fmac_f32_dpp v169, v142, v78 quad_perm:[3,3,3,3] row_mask:0xf bank_mask:0xf
	v_fmac_f32_dpp v170, v143, v79 quad_perm:[3,3,3,3] row_mask:0xf bank_mask:0xf
	ds_read_b128 v[164:167], v10 offset:10336
	s_waitcnt lgkmcnt(5)
	v_fmac_f32_dpp v100, v144, v80 quad_perm:[0,0,0,0] row_mask:0xf bank_mask:0xf
	v_fmac_f32_dpp v168, v145, v81 quad_perm:[0,0,0,0] row_mask:0xf bank_mask:0xf
	v_fmac_f32_dpp v169, v146, v82 quad_perm:[0,0,0,0] row_mask:0xf bank_mask:0xf
	v_fmac_f32_dpp v170, v147, v83 quad_perm:[0,0,0,0] row_mask:0xf bank_mask:0xf
	v_fmac_f32_dpp v100, v144, v84 quad_perm:[1,1,1,1] row_mask:0xf bank_mask:0xf
	v_fmac_f32_dpp v168, v145, v85 quad_perm:[1,1,1,1] row_mask:0xf bank_mask:0xf
	v_fmac_f32_dpp v169, v146, v86 quad_perm:[1,1,1,1] row_mask:0xf bank_mask:0xf
	v_fmac_f32_dpp v170, v147, v87 quad_perm:[1,1,1,1] row_mask:0xf bank_mask:0xf
	v_fmac_f32_dpp v100, v144, v88 quad_perm:[2,2,2,2] row_mask:0xf bank_mask:0xf
	v_fmac_f32_dpp v168, v145, v89 quad_perm:[2,2,2,2] row_mask:0xf bank_mask:0xf
	v_fmac_f32_dpp v169, v146, v90 quad_perm:[2,2,2,2] row_mask:0xf bank_mask:0xf
	v_fmac_f32_dpp v170, v147, v91 quad_perm:[2,2,2,2] row_mask:0xf bank_mask:0xf
	v_fmac_f32_dpp v100, v144, v92 quad_perm:[3,3,3,3] row_mask:0xf bank_mask:0xf
	v_fmac_f32_dpp v168, v145, v93 quad_perm:[3,3,3,3] row_mask:0xf bank_mask:0xf
	v_fmac_f32_dpp v169, v146, v94 quad_perm:[3,3,3,3] row_mask:0xf bank_mask:0xf
	v_fmac_f32_dpp v170, v147, v95 quad_perm:[3,3,3,3] row_mask:0xf bank_mask:0xf
	ds_read_b128 v[136:139], v10 offset:10400
	s_waitcnt lgkmcnt(5)
	v_fmac_f32_dpp v100, v148, v96 quad_perm:[0,0,0,0] row_mask:0xf bank_mask:0xf
	v_fmac_f32_dpp v168, v149, v97 quad_perm:[0,0,0,0] row_mask:0xf bank_mask:0xf
	v_fmac_f32_dpp v169, v150, v98 quad_perm:[0,0,0,0] row_mask:0xf bank_mask:0xf
	v_fmac_f32_dpp v170, v151, v99 quad_perm:[0,0,0,0] row_mask:0xf bank_mask:0xf
	v_add_f32_e32 v100, v100, v168
	v_add_f32_e32 v169, v169, v170
	v_add_f32_e32 v100, v100, v169
	ds_read_b128 v[140:143], v10 offset:10464
	s_waitcnt lgkmcnt(5)
	v_mov_b32_e32 v168, 0
	v_mov_b32_e32 v169, 0
	v_mov_b32_e32 v170, 0
	v_fmac_f32_dpp v101, v152, v64 quad_perm:[0,0,0,0] row_mask:0xf bank_mask:0xf
	v_fmac_f32_dpp v168, v153, v65 quad_perm:[0,0,0,0] row_mask:0xf bank_mask:0xf
	v_fmac_f32_dpp v169, v154, v66 quad_perm:[0,0,0,0] row_mask:0xf bank_mask:0xf
	v_fmac_f32_dpp v170, v155, v67 quad_perm:[0,0,0,0] row_mask:0xf bank_mask:0xf
	v_fmac_f32_dpp v101, v152, v68 quad_perm:[1,1,1,1] row_mask:0xf bank_mask:0xf
	v_fmac_f32_dpp v168, v153, v69 quad_perm:[1,1,1,1] row_mask:0xf bank_mask:0xf
	v_fmac_f32_dpp v169, v154, v70 quad_perm:[1,1,1,1] row_mask:0xf bank_mask:0xf
	v_fmac_f32_dpp v170, v155, v71 quad_perm:[1,1,1,1] row_mask:0xf bank_mask:0xf
	v_fmac_f32_dpp v101, v152, v72 quad_perm:[2,2,2,2] row_mask:0xf bank_mask:0xf
	v_fmac_f32_dpp v168, v153, v73 quad_perm:[2,2,2,2] row_mask:0xf bank_mask:0xf
	v_fmac_f32_dpp v169, v154, v74 quad_perm:[2,2,2,2] row_mask:0xf bank_mask:0xf
	v_fmac_f32_dpp v170, v155, v75 quad_perm:[2,2,2,2] row_mask:0xf bank_mask:0xf
	v_fmac_f32_dpp v101, v152, v76 quad_perm:[3,3,3,3] row_mask:0xf bank_mask:0xf
	v_fmac_f32_dpp v168, v153, v77 quad_perm:[3,3,3,3] row_mask:0xf bank_mask:0xf
	v_fmac_f32_dpp v169, v154, v78 quad_perm:[3,3,3,3] row_mask:0xf bank_mask:0xf
	v_fmac_f32_dpp v170, v155, v79 quad_perm:[3,3,3,3] row_mask:0xf bank_mask:0xf
	ds_read_b128 v[144:147], v10 offset:10608
	s_waitcnt lgkmcnt(5)
; __device__ void dn_d1(const Ctx& c, int ip) {
;     ...
;     SOLVE_ROW_BEGIN(38)
;     { const f32x4 m = *(const f32x4*)(mr + 0);
;       a0 -= m[0] * x[0];
;       a1 -= m[1] * x[1];
;       a2 -= m[2] * x[2];
;       a3 -= m[3] * x[3];
;     }
;     { const f32x4 m = *(const f32x4*)(mr + 4);
;       a0 -= m[0] * x[4];
;       a1 -= m[1] * x[5];
;       a2 -= m[2] * x[6];
;       a3 -= m[3] * x[7];
;     }
;     { const f32x4 m = *(const f32x4*)(mr + 8);
;       a0 -= m[0] * x[8];
;       a1 -= m[1] * x[9];
;       a2 -= m[2] * x[10];
;       a3 -= m[3] * x[11];
;     }
;     { const f32x4 m = *(const f32x4*)(mr + 12);
;       a0 -= m[0] * x[12];
;       a1 -= m[1] * x[13];
;       a2 -= m[2] * x[14];
;       a3 -= m[3] * x[15];
;     }
;     { const f32x4 m = *(const f32x4*)(mr + 16);
;       a0 -= m[0] * x[16];
;       a1 -= m[1] * x[17];
;       a2 -= m[2] * x[18];
;       a3 -= m[3] * x[19];
;     }
;     { const f32x4 m = *(const f32x4*)(mr + 20);
;       a0 -= m[0] * x[20];
;       a1 -= m[1] * x[21];
;       a2 -= m[2] * x[22];
;       a3 -= m[3] * x[23];
;     }
;     { const f32x4 m = *(const f32x4*)(mr + 24);
;       a0 -= m[0] * x[24];
;       a1 -= m[1] * x[25];
;       a2 -= m[2] * x[26];
;       a3 -= m[3] * x[27];
;     }
;     { const f32x4 m = *(const f32x4*)(mr + 28);
;       a0 -= m[0] * x[28];
;       a1 -= m[1] * x[29];
;       a2 -= m[2] * x[30];
;       a3 -= m[3] * x[31];
;     }
;     { const f32x4 m = *(const f32x4*)(mr + 32);
;       a0 -= m[0] * x[32];
;       a1 -= m[1] * x[33];
;       a2 -= m[2] * x[34];
;       a3 -= m[3] * x[35];
;     }
;     { const f32x4 m = *(const f32x4*)(mr + 36);
;       a0 -= m[0] * x[36];
;       a1 -= m[1] * x[37];
;     }
;     SOLVE_ROW_END(38)
	v_fmac_f32_dpp v101, v156, v80 quad_perm:[0,0,0,0] row_mask:0xf bank_mask:0xf
	v_fmac_f32_dpp v168, v157, v81 quad_perm:[0,0,0,0] row_mask:0xf bank_mask:0xf
	v_fmac_f32_dpp v169, v158, v82 quad_perm:[0,0,0,0] row_mask:0xf bank_mask:0xf
	v_fmac_f32_dpp v170, v159, v83 quad_perm:[0,0,0,0] row_mask:0xf bank_mask:0xf
	v_fmac_f32_dpp v101, v156, v84 quad_perm:[1,1,1,1] row_mask:0xf bank_mask:0xf
	v_fmac_f32_dpp v168, v157, v85 quad_perm:[1,1,1,1] row_mask:0xf bank_mask:0xf
	v_fmac_f32_dpp v169, v158, v86 quad_perm:[1,1,1,1] row_mask:0xf bank_mask:0xf
	v_fmac_f32_dpp v170, v159, v87 quad_perm:[1,1,1,1] row_mask:0xf bank_mask:0xf
	v_fmac_f32_dpp v101, v156, v88 quad_perm:[2,2,2,2] row_mask:0xf bank_mask:0xf
	v_fmac_f32_dpp v168, v157, v89 quad_perm:[2,2,2,2] row_mask:0xf bank_mask:0xf
	v_fmac_f32_dpp v169, v158, v90 quad_perm:[2,2,2,2] row_mask:0xf bank_mask:0xf
	v_fmac_f32_dpp v170, v159, v91 quad_perm:[2,2,2,2] row_mask:0xf bank_mask:0xf
	v_fmac_f32_dpp v101, v156, v92 quad_perm:[3,3,3,3] row_mask:0xf bank_mask:0xf
	v_fmac_f32_dpp v168, v157, v93 quad_perm:[3,3,3,3] row_mask:0xf bank_mask:0xf
	v_fmac_f32_dpp v169, v158, v94 quad_perm:[3,3,3,3] row_mask:0xf bank_mask:0xf
	v_fmac_f32_dpp v170, v159, v95 quad_perm:[3,3,3,3] row_mask:0xf bank_mask:0xf
	ds_read_b128 v[148:151], v10 offset:10672
	s_waitcnt lgkmcnt(5)
	v_fmac_f32_dpp v101, v160, v96 quad_perm:[0,0,0,0] row_mask:0xf bank_mask:0xf
	v_fmac_f32_dpp v168, v161, v97 quad_perm:[0,0,0,0] row_mask:0xf bank_mask:0xf
	v_fmac_f32_dpp v169, v162, v98 quad_perm:[0,0,0,0] row_mask:0xf bank_mask:0xf
	v_fmac_f32_dpp v170, v163, v99 quad_perm:[0,0,0,0] row_mask:0xf bank_mask:0xf
	v_fmac_f32_dpp v101, v160, v100 quad_perm:[1,1,1,1] row_mask:0xf bank_mask:0xf
	v_add_f32_e32 v101, v101, v168
	v_add_f32_e32 v169, v169, v170
	v_add_f32_e32 v101, v101, v169
	ds_read_b128 v[152:155], v10 offset:10736
	s_waitcnt lgkmcnt(5)
	v_mov_b32_e32 v168, 0
	v_mov_b32_e32 v169, 0
	v_mov_b32_e32 v170, 0
	v_fmac_f32_dpp v102, v164, v64 quad_perm:[0,0,0,0] row_mask:0xf bank_mask:0xf
	v_fmac_f32_dpp v168, v165, v65 quad_perm:[0,0,0,0] row_mask:0xf bank_mask:0xf
	v_fmac_f32_dpp v169, v166, v66 quad_perm:[0,0,0,0] row_mask:0xf bank_mask:0xf
	v_fmac_f32_dpp v170, v167, v67 quad_perm:[0,0,0,0] row_mask:0xf bank_mask:0xf
	v_fmac_f32_dpp v102, v164, v68 quad_perm:[1,1,1,1] row_mask:0xf bank_mask:0xf
	v_fmac_f32_dpp v168, v165, v69 quad_perm:[1,1,1,1] row_mask:0xf bank_mask:0xf
	v_fmac_f32_dpp v169, v166, v70 quad_perm:[1,1,1,1] row_mask:0xf bank_mask:0xf
	v_fmac_f32_dpp v170, v167, v71 quad_perm:[1,1,1,1] row_mask:0xf bank_mask:0xf
	v_fmac_f32_dpp v102, v164, v72 quad_perm:[2,2,2,2] row_mask:0xf bank_mask:0xf
	v_fmac_f32_dpp v168, v165, v73 quad_perm:[2,2,2,2] row_mask:0xf bank_mask:0xf
	v_fmac_f32_dpp v169, v166, v74 quad_perm:[2,2,2,2] row_mask:0xf bank_mask:0xf
	v_fmac_f32_dpp v170, v167, v75 quad_perm:[2,2,2,2] row_mask:0xf bank_mask:0xf
	v_fmac_f32_dpp v102, v164, v76 quad_perm:[3,3,3,3] row_mask:0xf bank_mask:0xf
	v_fmac_f32_dpp v168, v165, v77 quad_perm:[3,3,3,3] row_mask:0xf bank_mask:0xf
	v_fmac_f32_dpp v169, v166, v78 quad_perm:[3,3,3,3] row_mask:0xf bank_mask:0xf
	v_fmac_f32_dpp v170, v167, v79 quad_perm:[3,3,3,3] row_mask:0xf bank_mask:0xf
	ds_read_b128 v[156:159], v10 offset:10880
	s_waitcnt lgkmcnt(5)
	v_fmac_f32_dpp v102, v136, v80 quad_perm:[0,0,0,0] row_mask:0xf bank_mask:0xf
	v_fmac_f32_dpp v168, v137, v81 quad_perm:[0,0,0,0] row_mask:0xf bank_mask:0xf
	v_fmac_f32_dpp v169, v138, v82 quad_perm:[0,0,0,0] row_mask:0xf bank_mask:0xf
	v_fmac_f32_dpp v170, v139, v83 quad_perm:[0,0,0,0] row_mask:0xf bank_mask:0xf
	v_fmac_f32_dpp v102, v136, v84 quad_perm:[1,1,1,1] row_mask:0xf bank_mask:0xf
	v_fmac_f32_dpp v168, v137, v85 quad_perm:[1,1,1,1] row_mask:0xf bank_mask:0xf
	v_fmac_f32_dpp v169, v138, v86 quad_perm:[1,1,1,1] row_mask:0xf bank_mask:0xf
	v_fmac_f32_dpp v170, v139, v87 quad_perm:[1,1,1,1] row_mask:0xf bank_mask:0xf
	v_fmac_f32_dpp v102, v136, v88 quad_perm:[2,2,2,2] row_mask:0xf bank_mask:0xf
	v_fmac_f32_dpp v168, v137, v89 quad_perm:[2,2,2,2] row_mask:0xf bank_mask:0xf
	v_fmac_f32_dpp v169, v138, v90 quad_perm:[2,2,2,2] row_mask:0xf bank_mask:0xf
	v_fmac_f32_dpp v170, v139, v91 quad_perm:[2,2,2,2] row_mask:0xf bank_mask:0xf
	v_fmac_f32_dpp v102, v136, v92 quad_perm:[3,3,3,3] row_mask:0xf bank_mask:0xf
	v_fmac_f32_dpp v168, v137, v93 quad_perm:[3,3,3,3] row_mask:0xf bank_mask:0xf
	v_fmac_f32_dpp v169, v138, v94 quad_perm:[3,3,3,3] row_mask:0xf bank_mask:0xf
	v_fmac_f32_dpp v170, v139, v95 quad_perm:[3,3,3,3] row_mask:0xf bank_mask:0xf
	ds_read_b128 v[160:163], v10 offset:10944
	s_waitcnt lgkmcnt(5)
	v_fmac_f32_dpp v102, v140, v96 quad_perm:[0,0,0,0] row_mask:0xf bank_mask:0xf
	v_fmac_f32_dpp v168, v141, v97 quad_perm:[0,0,0,0] row_mask:0xf bank_mask:0xf
	v_fmac_f32_dpp v169, v142, v98 quad_perm:[0,0,0,0] row_mask:0xf bank_mask:0xf
	v_fmac_f32_dpp v170, v143, v99 quad_perm:[0,0,0,0] row_mask:0xf bank_mask:0xf
	v_fmac_f32_dpp v102, v140, v100 quad_perm:[1,1,1,1] row_mask:0xf bank_mask:0xf
	v_fmac_f32_dpp v168, v141, v101 quad_perm:[1,1,1,1] row_mask:0xf bank_mask:0xf
	v_add_f32_e32 v102, v102, v168
	v_add_f32_e32 v169, v169, v170
	v_add_f32_e32 v102, v102, v169
	ds_read_b128 v[164:167], v10 offset:11008
	s_waitcnt lgkmcnt(5)
; __device__ void dn_d1(const Ctx& c, int ip) {
;     ...
;     SOLVE_ROW_BEGIN(40)
;     { const f32x4 m = *(const f32x4*)(mr + 0);
;       a0 -= m[0] * x[0];
;       a1 -= m[1] * x[1];
;       a2 -= m[2] * x[2];
;       a3 -= m[3] * x[3];
;     }
;     { const f32x4 m = *(const f32x4*)(mr + 4);
;       a0 -= m[0] * x[4];
;       a1 -= m[1] * x[5];
;       a2 -= m[2] * x[6];
;       a3 -= m[3] * x[7];
;     }
;     { const f32x4 m = *(const f32x4*)(mr + 8);
;       a0 -= m[0] * x[8];
;       a1 -= m[1] * x[9];
;       a2 -= m[2] * x[10];
;       a3 -= m[3] * x[11];
;     }
;     { const f32x4 m = *(const f32x4*)(mr + 12);
;       a0 -= m[0] * x[12];
;       a1 -= m[1] * x[13];
;       a2 -= m[2] * x[14];
;       a3 -= m[3] * x[15];
;     }
;     { const f32x4 m = *(const f32x4*)(mr + 16);
;       a0 -= m[0] * x[16];
;       a1 -= m[1] * x[17];
;       a2 -= m[2] * x[18];
;       a3 -= m[3] * x[19];
;     }
;     { const f32x4 m = *(const f32x4*)(mr + 20);
;       a0 -= m[0] * x[20];
;       a1 -= m[1] * x[21];
;       a2 -= m[2] * x[22];
;       a3 -= m[3] * x[23];
;     }
;     { const f32x4 m = *(const f32x4*)(mr + 24);
;       a0 -= m[0] * x[24];
;       a1 -= m[1] * x[25];
;       a2 -= m[2] * x[26];
;       a3 -= m[3] * x[27];
;     }
;     { const f32x4 m = *(const f32x4*)(mr + 28);
;       a0 -= m[0] * x[28];
;       a1 -= m[1] * x[29];
;       a2 -= m[2] * x[30];
;       a3 -= m[3] * x[31];
;     }
;     { const f32x4 m = *(const f32x4*)(mr + 32);
;       a0 -= m[0] * x[32];
;       a1 -= m[1] * x[33];
;       a2 -= m[2] * x[34];
;       a3 -= m[3] * x[35];
;     }
;     { const f32x4 m = *(const f32x4*)(mr + 36);
;       a0 -= m[0] * x[36];
;       a1 -= m[1] * x[37];
;       a2 -= m[2] * x[38];
;       a3 -= m[3] * x[39];
	v_mov_b32_e32 v168, 0
	v_mov_b32_e32 v169, 0
	v_mov_b32_e32 v170, 0
	v_fmac_f32_dpp v103, v144, v64 quad_perm:[0,0,0,0] row_mask:0xf bank_mask:0xf
	v_fmac_f32_dpp v168, v145, v65 quad_perm:[0,0,0,0] row_mask:0xf bank_mask:0xf
	v_fmac_f32_dpp v169, v146, v66 quad_perm:[0,0,0,0] row_mask:0xf bank_mask:0xf
	v_fmac_f32_dpp v170, v147, v67 quad_perm:[0,0,0,0] row_mask:0xf bank_mask:0xf
	v_fmac_f32_dpp v103, v144, v68 quad_perm:[1,1,1,1] row_mask:0xf bank_mask:0xf
	v_fmac_f32_dpp v168, v145, v69 quad_perm:[1,1,1,1] row_mask:0xf bank_mask:0xf
	v_fmac_f32_dpp v169, v146, v70 quad_perm:[1,1,1,1] row_mask:0xf bank_mask:0xf
	v_fmac_f32_dpp v170, v147, v71 quad_perm:[1,1,1,1] row_mask:0xf bank_mask:0xf
	v_fmac_f32_dpp v103, v144, v72 quad_perm:[2,2,2,2] row_mask:0xf bank_mask:0xf
	v_fmac_f32_dpp v168, v145, v73 quad_perm:[2,2,2,2] row_mask:0xf bank_mask:0xf
	v_fmac_f32_dpp v169, v146, v74 quad_perm:[2,2,2,2] row_mask:0xf bank_mask:0xf
	v_fmac_f32_dpp v170, v147, v75 quad_perm:[2,2,2,2] row_mask:0xf bank_mask:0xf
	v_fmac_f32_dpp v103, v144, v76 quad_perm:[3,3,3,3] row_mask:0xf bank_mask:0xf
	v_fmac_f32_dpp v168, v145, v77 quad_perm:[3,3,3,3] row_mask:0xf bank_mask:0xf
	v_fmac_f32_dpp v169, v146, v78 quad_perm:[3,3,3,3] row_mask:0xf bank_mask:0xf
	v_fmac_f32_dpp v170, v147, v79 quad_perm:[3,3,3,3] row_mask:0xf bank_mask:0xf
	ds_read_b128 v[136:139], v10 offset:11152
	s_waitcnt lgkmcnt(5)
	v_fmac_f32_dpp v103, v148, v80 quad_perm:[0,0,0,0] row_mask:0xf bank_mask:0xf
	v_fmac_f32_dpp v168, v149, v81 quad_perm:[0,0,0,0] row_mask:0xf bank_mask:0xf
	v_fmac_f32_dpp v169, v150, v82 quad_perm:[0,0,0,0] row_mask:0xf bank_mask:0xf
	v_fmac_f32_dpp v170, v151, v83 quad_perm:[0,0,0,0] row_mask:0xf bank_mask:0xf
	v_fmac_f32_dpp v103, v148, v84 quad_perm:[1,1,1,1] row_mask:0xf bank_mask:0xf
	v_fmac_f32_dpp v168, v149, v85 quad_perm:[1,1,1,1] row_mask:0xf bank_mask:0xf
	v_fmac_f32_dpp v169, v150, v86 quad_perm:[1,1,1,1] row_mask:0xf bank_mask:0xf
	v_fmac_f32_dpp v170, v151, v87 quad_perm:[1,1,1,1] row_mask:0xf bank_mask:0xf
	v_fmac_f32_dpp v103, v148, v88 quad_perm:[2,2,2,2] row_mask:0xf bank_mask:0xf
	v_fmac_f32_dpp v168, v149, v89 quad_perm:[2,2,2,2] row_mask:0xf bank_mask:0xf
	v_fmac_f32_dpp v169, v150, v90 quad_perm:[2,2,2,2] row_mask:0xf bank_mask:0xf
	v_fmac_f32_dpp v170, v151, v91 quad_perm:[2,2,2,2] row_mask:0xf bank_mask:0xf
	v_fmac_f32_dpp v103, v148, v92 quad_perm:[3,3,3,3] row_mask:0xf bank_mask:0xf
	v_fmac_f32_dpp v168, v149, v93 quad_perm:[3,3,3,3] row_mask:0xf bank_mask:0xf
	v_fmac_f32_dpp v169, v150, v94 quad_perm:[3,3,3,3] row_mask:0xf bank_mask:0xf
	v_fmac_f32_dpp v170, v151, v95 quad_perm:[3,3,3,3] row_mask:0xf bank_mask:0xf
	ds_read_b128 v[140:143], v10 offset:11216
	s_waitcnt lgkmcnt(5)
	v_fmac_f32_dpp v103, v152, v96 quad_perm:[0,0,0,0] row_mask:0xf bank_mask:0xf
	v_fmac_f32_dpp v168, v153, v97 quad_perm:[0,0,0,0] row_mask:0xf bank_mask:0xf
	v_fmac_f32_dpp v169, v154, v98 quad_perm:[0,0,0,0] row_mask:0xf bank_mask:0xf
	v_fmac_f32_dpp v170, v155, v99 quad_perm:[0,0,0,0] row_mask:0xf bank_mask:0xf
	v_fmac_f32_dpp v103, v152, v100 quad_perm:[1,1,1,1] row_mask:0xf bank_mask:0xf
	v_fmac_f32_dpp v168, v153, v101 quad_perm:[1,1,1,1] row_mask:0xf bank_mask:0xf
	v_fmac_f32_dpp v169, v154, v102 quad_perm:[1,1,1,1] row_mask:0xf bank_mask:0xf
	v_add_f32_e32 v103, v103, v168
	v_add_f32_e32 v169, v169, v170
	v_add_f32_e32 v103, v103, v169
	ds_read_b128 v[144:147], v10 offset:11280
	s_waitcnt lgkmcnt(5)
	v_mov_b32_e32 v168, 0
	v_mov_b32_e32 v169, 0
	v_mov_b32_e32 v170, 0
	v_fmac_f32_dpp v104, v156, v64 quad_perm:[0,0,0,0] row_mask:0xf bank_mask:0xf
	v_fmac_f32_dpp v168, v157, v65 quad_perm:[0,0,0,0] row_mask:0xf bank_mask:0xf
	v_fmac_f32_dpp v169, v158, v66 quad_perm:[0,0,0,0] row_mask:0xf bank_mask:0xf
	v_fmac_f32_dpp v170, v159, v67 quad_perm:[0,0,0,0] row_mask:0xf bank_mask:0xf
	v_fmac_f32_dpp v104, v156, v68 quad_perm:[1,1,1,1] row_mask:0xf bank_mask:0xf
	v_fmac_f32_dpp v168, v157, v69 quad_perm:[1,1,1,1] row_mask:0xf bank_mask:0xf
	v_fmac_f32_dpp v169, v158, v70 quad_perm:[1,1,1,1] row_mask:0xf bank_mask:0xf
	v_fmac_f32_dpp v170, v159, v71 quad_perm:[1,1,1,1] row_mask:0xf bank_mask:0xf
	v_fmac_f32_dpp v104, v156, v72 quad_perm:[2,2,2,2] row_mask:0xf bank_mask:0xf
	v_fmac_f32_dpp v168, v157, v73 quad_perm:[2,2,2,2] row_mask:0xf bank_mask:0xf
	v_fmac_f32_dpp v169, v158, v74 quad_perm:[2,2,2,2] row_mask:0xf bank_mask:0xf
	v_fmac_f32_dpp v170, v159, v75 quad_perm:[2,2,2,2] row_mask:0xf bank_mask:0xf
	v_fmac_f32_dpp v104, v156, v76 quad_perm:[3,3,3,3] row_mask:0xf bank_mask:0xf
	v_fmac_f32_dpp v168, v157, v77 quad_perm:[3,3,3,3] row_mask:0xf bank_mask:0xf
	v_fmac_f32_dpp v169, v158, v78 quad_perm:[3,3,3,3] row_mask:0xf bank_mask:0xf
	v_fmac_f32_dpp v170, v159, v79 quad_perm:[3,3,3,3] row_mask:0xf bank_mask:0xf
	ds_read_b128 v[148:151], v10 offset:11424
	s_waitcnt lgkmcnt(5)
	v_fmac_f32_dpp v104, v160, v80 quad_perm:[0,0,0,0] row_mask:0xf bank_mask:0xf
	v_fmac_f32_dpp v168, v161, v81 quad_perm:[0,0,0,0] row_mask:0xf bank_mask:0xf
	v_fmac_f32_dpp v169, v162, v82 quad_perm:[0,0,0,0] row_mask:0xf bank_mask:0xf
	v_fmac_f32_dpp v170, v163, v83 quad_perm:[0,0,0,0] row_mask:0xf bank_mask:0xf
	v_fmac_f32_dpp v104, v160, v84 quad_perm:[1,1,1,1] row_mask:0xf bank_mask:0xf
	v_fmac_f32_dpp v168, v161, v85 quad_perm:[1,1,1,1] row_mask:0xf bank_mask:0xf
	v_fmac_f32_dpp v169, v162, v86 quad_perm:[1,1,1,1] row_mask:0xf bank_mask:0xf
	v_fmac_f32_dpp v170, v163, v87 quad_perm:[1,1,1,1] row_mask:0xf bank_mask:0xf
	v_fmac_f32_dpp v104, v160, v88 quad_perm:[2,2,2,2] row_mask:0xf bank_mask:0xf
	v_fmac_f32_dpp v168, v161, v89 quad_perm:[2,2,2,2] row_mask:0xf bank_mask:0xf
	v_fmac_f32_dpp v169, v162, v90 quad_perm:[2,2,2,2] row_mask:0xf bank_mask:0xf
	v_fmac_f32_dpp v170, v163, v91 quad_perm:[2,2,2,2] row_mask:0xf bank_mask:0xf
	v_fmac_f32_dpp v104, v160, v92 quad_perm:[3,3,3,3] row_mask:0xf bank_mask:0xf
	v_fmac_f32_dpp v168, v161, v93 quad_perm:[3,3,3,3] row_mask:0xf bank_mask:0xf
	v_fmac_f32_dpp v169, v162, v94 quad_perm:[3,3,3,3] row_mask:0xf bank_mask:0xf
	v_fmac_f32_dpp v170, v163, v95 quad_perm:[3,3,3,3] row_mask:0xf bank_mask:0xf
	ds_read_b128 v[152:155], v10 offset:11488
	s_waitcnt lgkmcnt(5)
; __device__ void dn_d1(const Ctx& c, int ip) {
;     ...
;       a3 -= m[3] * x[3];
;     }
;     { const f32x4 m = *(const f32x4*)(mr + 4);
;       a0 -= m[0] * x[4];
;       a1 -= m[1] * x[5];
;       a2 -= m[2] * x[6];
;       a3 -= m[3] * x[7];
;     }
;     { const f32x4 m = *(const f32x4*)(mr + 8);
;       a0 -= m[0] * x[8];
;       a1 -= m[1] * x[9];
;       a2 -= m[2] * x[10];
;       a3 -= m[3] * x[11];
;     }
;     { const f32x4 m = *(const f32x4*)(mr + 12);
;       a0 -= m[0] * x[12];
;       a1 -= m[1] * x[13];
;       a2 -= m[2] * x[14];
;       a3 -= m[3] * x[15];
;     }
;     { const f32x4 m = *(const f32x4*)(mr + 16);
;       a0 -= m[0] * x[16];
;       a1 -= m[1] * x[17];
;       a2 -= m[2] * x[18];
;       a3 -= m[3] * x[19];
;     }
;     { const f32x4 m = *(const f32x4*)(mr + 20);
;       a0 -= m[0] * x[20];
;       a1 -= m[1] * x[21];
;       a2 -= m[2] * x[22];
;       a3 -= m[3] * x[23];
;     }
;     { const f32x4 m = *(const f32x4*)(mr + 24);
;       a0 -= m[0] * x[24];
;       a1 -= m[1] * x[25];
;       a2 -= m[2] * x[26];
;       a3 -= m[3] * x[27];
;     }
;     { const f32x4 m = *(const f32x4*)(mr + 28);
;       a0 -= m[0] * x[28];
;       a1 -= m[1] * x[29];
;       a2 -= m[2] * x[30];
;       a3 -= m[3] * x[31];
;     }
;     { const f32x4 m = *(const f32x4*)(mr + 32);
;       a0 -= m[0] * x[32];
;       a1 -= m[1] * x[33];
;       a2 -= m[2] * x[34];
;       a3 -= m[3] * x[35];
;     }
;     { const f32x4 m = *(const f32x4*)(mr + 36);
;       a0 -= m[0] * x[36];
;       a1 -= m[1] * x[37];
;       a2 -= m[2] * x[38];
;       a3 -= m[3] * x[39];
;     }
;     { const f32x4 m = *(const f32x4*)(mr + 40);
;       a0 -= m[0] * x[40];
;     }
;     SOLVE_ROW_END(41)
	v_fmac_f32_dpp v104, v164, v96 quad_perm:[0,0,0,0] row_mask:0xf bank_mask:0xf
	v_fmac_f32_dpp v168, v165, v97 quad_perm:[0,0,0,0] row_mask:0xf bank_mask:0xf
	v_fmac_f32_dpp v169, v166, v98 quad_perm:[0,0,0,0] row_mask:0xf bank_mask:0xf
	v_fmac_f32_dpp v170, v167, v99 quad_perm:[0,0,0,0] row_mask:0xf bank_mask:0xf
	v_fmac_f32_dpp v104, v164, v100 quad_perm:[1,1,1,1] row_mask:0xf bank_mask:0xf
	v_fmac_f32_dpp v168, v165, v101 quad_perm:[1,1,1,1] row_mask:0xf bank_mask:0xf
	v_fmac_f32_dpp v169, v166, v102 quad_perm:[1,1,1,1] row_mask:0xf bank_mask:0xf
	v_fmac_f32_dpp v170, v167, v103 quad_perm:[1,1,1,1] row_mask:0xf bank_mask:0xf
	v_add_f32_e32 v104, v104, v168
	v_add_f32_e32 v169, v169, v170
	v_add_f32_e32 v104, v104, v169
	ds_read_b128 v[156:159], v10 offset:11552
	s_waitcnt lgkmcnt(5)
	v_mov_b32_e32 v168, 0
	v_mov_b32_e32 v169, 0
	v_mov_b32_e32 v170, 0
	v_fmac_f32_dpp v105, v136, v64 quad_perm:[0,0,0,0] row_mask:0xf bank_mask:0xf
	v_fmac_f32_dpp v168, v137, v65 quad_perm:[0,0,0,0] row_mask:0xf bank_mask:0xf
	v_fmac_f32_dpp v169, v138, v66 quad_perm:[0,0,0,0] row_mask:0xf bank_mask:0xf
	v_fmac_f32_dpp v170, v139, v67 quad_perm:[0,0,0,0] row_mask:0xf bank_mask:0xf
	v_fmac_f32_dpp v105, v136, v68 quad_perm:[1,1,1,1] row_mask:0xf bank_mask:0xf
	v_fmac_f32_dpp v168, v137, v69 quad_perm:[1,1,1,1] row_mask:0xf bank_mask:0xf
	v_fmac_f32_dpp v169, v138, v70 quad_perm:[1,1,1,1] row_mask:0xf bank_mask:0xf
	v_fmac_f32_dpp v170, v139, v71 quad_perm:[1,1,1,1] row_mask:0xf bank_mask:0xf
	v_fmac_f32_dpp v105, v136, v72 quad_perm:[2,2,2,2] row_mask:0xf bank_mask:0xf
	v_fmac_f32_dpp v168, v137, v73 quad_perm:[2,2,2,2] row_mask:0xf bank_mask:0xf
	v_fmac_f32_dpp v169, v138, v74 quad_perm:[2,2,2,2] row_mask:0xf bank_mask:0xf
	v_fmac_f32_dpp v170, v139, v75 quad_perm:[2,2,2,2] row_mask:0xf bank_mask:0xf
	v_fmac_f32_dpp v105, v136, v76 quad_perm:[3,3,3,3] row_mask:0xf bank_mask:0xf
	v_fmac_f32_dpp v168, v137, v77 quad_perm:[3,3,3,3] row_mask:0xf bank_mask:0xf
	v_fmac_f32_dpp v169, v138, v78 quad_perm:[3,3,3,3] row_mask:0xf bank_mask:0xf
	v_fmac_f32_dpp v170, v139, v79 quad_perm:[3,3,3,3] row_mask:0xf bank_mask:0xf
	ds_read_b128 v[160:163], v10 offset:11696
	s_waitcnt lgkmcnt(5)
	v_fmac_f32_dpp v105, v140, v80 quad_perm:[0,0,0,0] row_mask:0xf bank_mask:0xf
	v_fmac_f32_dpp v168, v141, v81 quad_perm:[0,0,0,0] row_mask:0xf bank_mask:0xf
	v_fmac_f32_dpp v169, v142, v82 quad_perm:[0,0,0,0] row_mask:0xf bank_mask:0xf
	v_fmac_f32_dpp v170, v143, v83 quad_perm:[0,0,0,0] row_mask:0xf bank_mask:0xf
	v_fmac_f32_dpp v105, v140, v84 quad_perm:[1,1,1,1] row_mask:0xf bank_mask:0xf
	v_fmac_f32_dpp v168, v141, v85 quad_perm:[1,1,1,1] row_mask:0xf bank_mask:0xf
	v_fmac_f32_dpp v169, v142, v86 quad_perm:[1,1,1,1] row_mask:0xf bank_mask:0xf
	v_fmac_f32_dpp v170, v143, v87 quad_perm:[1,1,1,1] row_mask:0xf bank_mask:0xf
	v_fmac_f32_dpp v105, v140, v88 quad_perm:[2,2,2,2] row_mask:0xf bank_mask:0xf
	v_fmac_f32_dpp v168, v141, v89 quad_perm:[2,2,2,2] row_mask:0xf bank_mask:0xf
	v_fmac_f32_dpp v169, v142, v90 quad_perm:[2,2,2,2] row_mask:0xf bank_mask:0xf
	v_fmac_f32_dpp v170, v143, v91 quad_perm:[2,2,2,2] row_mask:0xf bank_mask:0xf
	v_fmac_f32_dpp v105, v140, v92 quad_perm:[3,3,3,3] row_mask:0xf bank_mask:0xf
	v_fmac_f32_dpp v168, v141, v93 quad_perm:[3,3,3,3] row_mask:0xf bank_mask:0xf
	v_fmac_f32_dpp v169, v142, v94 quad_perm:[3,3,3,3] row_mask:0xf bank_mask:0xf
	v_fmac_f32_dpp v170, v143, v95 quad_perm:[3,3,3,3] row_mask:0xf bank_mask:0xf
	ds_read_b128 v[164:167], v10 offset:11760
	s_waitcnt lgkmcnt(5)
	v_fmac_f32_dpp v105, v144, v96 quad_perm:[0,0,0,0] row_mask:0xf bank_mask:0xf
	v_fmac_f32_dpp v168, v145, v97 quad_perm:[0,0,0,0] row_mask:0xf bank_mask:0xf
	v_fmac_f32_dpp v169, v146, v98 quad_perm:[0,0,0,0] row_mask:0xf bank_mask:0xf
	v_fmac_f32_dpp v170, v147, v99 quad_perm:[0,0,0,0] row_mask:0xf bank_mask:0xf
	v_fmac_f32_dpp v105, v144, v100 quad_perm:[1,1,1,1] row_mask:0xf bank_mask:0xf
	v_fmac_f32_dpp v168, v145, v101 quad_perm:[1,1,1,1] row_mask:0xf bank_mask:0xf
	v_fmac_f32_dpp v169, v146, v102 quad_perm:[1,1,1,1] row_mask:0xf bank_mask:0xf
	v_fmac_f32_dpp v170, v147, v103 quad_perm:[1,1,1,1] row_mask:0xf bank_mask:0xf
	v_fmac_f32_dpp v105, v144, v104 quad_perm:[2,2,2,2] row_mask:0xf bank_mask:0xf
	v_add_f32_e32 v105, v105, v168
	v_add_f32_e32 v169, v169, v170
	v_add_f32_e32 v105, v105, v169
	ds_read_b128 v[136:139], v10 offset:11824
	s_waitcnt lgkmcnt(5)
	v_mov_b32_e32 v168, 0
	v_mov_b32_e32 v169, 0
	v_mov_b32_e32 v170, 0
	v_fmac_f32_dpp v106, v148, v64 quad_perm:[0,0,0,0] row_mask:0xf bank_mask:0xf
	v_fmac_f32_dpp v168, v149, v65 quad_perm:[0,0,0,0] row_mask:0xf bank_mask:0xf
	v_fmac_f32_dpp v169, v150, v66 quad_perm:[0,0,0,0] row_mask:0xf bank_mask:0xf
	v_fmac_f32_dpp v170, v151, v67 quad_perm:[0,0,0,0] row_mask:0xf bank_mask:0xf
	v_fmac_f32_dpp v106, v148, v68 quad_perm:[1,1,1,1] row_mask:0xf bank_mask:0xf
	v_fmac_f32_dpp v168, v149, v69 quad_perm:[1,1,1,1] row_mask:0xf bank_mask:0xf
	v_fmac_f32_dpp v169, v150, v70 quad_perm:[1,1,1,1] row_mask:0xf bank_mask:0xf
	v_fmac_f32_dpp v170, v151, v71 quad_perm:[1,1,1,1] row_mask:0xf bank_mask:0xf
	v_fmac_f32_dpp v106, v148, v72 quad_perm:[2,2,2,2] row_mask:0xf bank_mask:0xf
	v_fmac_f32_dpp v168, v149, v73 quad_perm:[2,2,2,2] row_mask:0xf bank_mask:0xf
	v_fmac_f32_dpp v169, v150, v74 quad_perm:[2,2,2,2] row_mask:0xf bank_mask:0xf
	v_fmac_f32_dpp v170, v151, v75 quad_perm:[2,2,2,2] row_mask:0xf bank_mask:0xf
	v_fmac_f32_dpp v106, v148, v76 quad_perm:[3,3,3,3] row_mask:0xf bank_mask:0xf
	v_fmac_f32_dpp v168, v149, v77 quad_perm:[3,3,3,3] row_mask:0xf bank_mask:0xf
	v_fmac_f32_dpp v169, v150, v78 quad_perm:[3,3,3,3] row_mask:0xf bank_mask:0xf
	v_fmac_f32_dpp v170, v151, v79 quad_perm:[3,3,3,3] row_mask:0xf bank_mask:0xf
	ds_read_b128 v[140:143], v10 offset:11968
	s_waitcnt lgkmcnt(5)
; __device__ void dn_d1(const Ctx& c, int ip) {
;     ...
;     SOLVE_ROW_BEGIN(43)
;     { const f32x4 m = *(const f32x4*)(mr + 0);
;       a0 -= m[0] * x[0];
;       a1 -= m[1] * x[1];
;       a2 -= m[2] * x[2];
;       a3 -= m[3] * x[3];
;     }
;     { const f32x4 m = *(const f32x4*)(mr + 4);
;       a0 -= m[0] * x[4];
;       a1 -= m[1] * x[5];
;       a2 -= m[2] * x[6];
;       a3 -= m[3] * x[7];
;     }
;     { const f32x4 m = *(const f32x4*)(mr + 8);
;       a0 -= m[0] * x[8];
;       a1 -= m[1] * x[9];
;       a2 -= m[2] * x[10];
;       a3 -= m[3] * x[11];
;     }
;     { const f32x4 m = *(const f32x4*)(mr + 12);
;       a0 -= m[0] * x[12];
;       a1 -= m[1] * x[13];
;       a2 -= m[2] * x[14];
;       a3 -= m[3] * x[15];
;     }
;     { const f32x4 m = *(const f32x4*)(mr + 16);
;       a0 -= m[0] * x[16];
;       a1 -= m[1] * x[17];
;       a2 -= m[2] * x[18];
;       a3 -= m[3] * x[19];
;     }
;     { const f32x4 m = *(const f32x4*)(mr + 20);
;       a0 -= m[0] * x[20];
;       a1 -= m[1] * x[21];
;       a2 -= m[2] * x[22];
;       a3 -= m[3] * x[23];
;     }
;     { const f32x4 m = *(const f32x4*)(mr + 24);
;       a0 -= m[0] * x[24];
;       a1 -= m[1] * x[25];
;       a2 -= m[2] * x[26];
;       a3 -= m[3] * x[27];
;     }
;     { const f32x4 m = *(const f32x4*)(mr + 28);
;       a0 -= m[0] * x[28];
;       a1 -= m[1] * x[29];
;       a2 -= m[2] * x[30];
;       a3 -= m[3] * x[31];
;     }
;     { const f32x4 m = *(const f32x4*)(mr + 32);
;       a0 -= m[0] * x[32];
;       a1 -= m[1] * x[33];
;       a2 -= m[2] * x[34];
;       a3 -= m[3] * x[35];
;     }
;     { const f32x4 m = *(const f32x4*)(mr + 36);
;       a0 -= m[0] * x[36];
;       a1 -= m[1] * x[37];
;       a2 -= m[2] * x[38];
;       a3 -= m[3] * x[39];
	v_fmac_f32_dpp v106, v152, v80 quad_perm:[0,0,0,0] row_mask:0xf bank_mask:0xf
	v_fmac_f32_dpp v168, v153, v81 quad_perm:[0,0,0,0] row_mask:0xf bank_mask:0xf
	v_fmac_f32_dpp v169, v154, v82 quad_perm:[0,0,0,0] row_mask:0xf bank_mask:0xf
	v_fmac_f32_dpp v170, v155, v83 quad_perm:[0,0,0,0] row_mask:0xf bank_mask:0xf
	v_fmac_f32_dpp v106, v152, v84 quad_perm:[1,1,1,1] row_mask:0xf bank_mask:0xf
	v_fmac_f32_dpp v168, v153, v85 quad_perm:[1,1,1,1] row_mask:0xf bank_mask:0xf
	v_fmac_f32_dpp v169, v154, v86 quad_perm:[1,1,1,1] row_mask:0xf bank_mask:0xf
	v_fmac_f32_dpp v170, v155, v87 quad_perm:[1,1,1,1] row_mask:0xf bank_mask:0xf
	v_fmac_f32_dpp v106, v152, v88 quad_perm:[2,2,2,2] row_mask:0xf bank_mask:0xf
	v_fmac_f32_dpp v168, v153, v89 quad_perm:[2,2,2,2] row_mask:0xf bank_mask:0xf
	v_fmac_f32_dpp v169, v154, v90 quad_perm:[2,2,2,2] row_mask:0xf bank_mask:0xf
	v_fmac_f32_dpp v170, v155, v91 quad_perm:[2,2,2,2] row_mask:0xf bank_mask:0xf
	v_fmac_f32_dpp v106, v152, v92 quad_perm:[3,3,3,3] row_mask:0xf bank_mask:0xf
	v_fmac_f32_dpp v168, v153, v93 quad_perm:[3,3,3,3] row_mask:0xf bank_mask:0xf
	v_fmac_f32_dpp v169, v154, v94 quad_perm:[3,3,3,3] row_mask:0xf bank_mask:0xf
	v_fmac_f32_dpp v170, v155, v95 quad_perm:[3,3,3,3] row_mask:0xf bank_mask:0xf
	ds_read_b128 v[144:147], v10 offset:12032
	s_waitcnt lgkmcnt(5)
	v_fmac_f32_dpp v106, v156, v96 quad_perm:[0,0,0,0] row_mask:0xf bank_mask:0xf
	v_fmac_f32_dpp v168, v157, v97 quad_perm:[0,0,0,0] row_mask:0xf bank_mask:0xf
	v_fmac_f32_dpp v169, v158, v98 quad_perm:[0,0,0,0] row_mask:0xf bank_mask:0xf
	v_fmac_f32_dpp v170, v159, v99 quad_perm:[0,0,0,0] row_mask:0xf bank_mask:0xf
	v_fmac_f32_dpp v106, v156, v100 quad_perm:[1,1,1,1] row_mask:0xf bank_mask:0xf
	v_fmac_f32_dpp v168, v157, v101 quad_perm:[1,1,1,1] row_mask:0xf bank_mask:0xf
	v_fmac_f32_dpp v169, v158, v102 quad_perm:[1,1,1,1] row_mask:0xf bank_mask:0xf
	v_fmac_f32_dpp v170, v159, v103 quad_perm:[1,1,1,1] row_mask:0xf bank_mask:0xf
	v_fmac_f32_dpp v106, v156, v104 quad_perm:[2,2,2,2] row_mask:0xf bank_mask:0xf
	v_fmac_f32_dpp v168, v157, v105 quad_perm:[2,2,2,2] row_mask:0xf bank_mask:0xf
	v_add_f32_e32 v106, v106, v168
	v_add_f32_e32 v169, v169, v170
	v_add_f32_e32 v106, v106, v169
	ds_read_b128 v[148:151], v10 offset:12096
	s_waitcnt lgkmcnt(5)
	v_mov_b32_e32 v168, 0
	v_mov_b32_e32 v169, 0
	v_mov_b32_e32 v170, 0
	v_fmac_f32_dpp v107, v160, v64 quad_perm:[0,0,0,0] row_mask:0xf bank_mask:0xf
	v_fmac_f32_dpp v168, v161, v65 quad_perm:[0,0,0,0] row_mask:0xf bank_mask:0xf
	v_fmac_f32_dpp v169, v162, v66 quad_perm:[0,0,0,0] row_mask:0xf bank_mask:0xf
	v_fmac_f32_dpp v170, v163, v67 quad_perm:[0,0,0,0] row_mask:0xf bank_mask:0xf
	v_fmac_f32_dpp v107, v160, v68 quad_perm:[1,1,1,1] row_mask:0xf bank_mask:0xf
	v_fmac_f32_dpp v168, v161, v69 quad_perm:[1,1,1,1] row_mask:0xf bank_mask:0xf
	v_fmac_f32_dpp v169, v162, v70 quad_perm:[1,1,1,1] row_mask:0xf bank_mask:0xf
	v_fmac_f32_dpp v170, v163, v71 quad_perm:[1,1,1,1] row_mask:0xf bank_mask:0xf
	v_fmac_f32_dpp v107, v160, v72 quad_perm:[2,2,2,2] row_mask:0xf bank_mask:0xf
	v_fmac_f32_dpp v168, v161, v73 quad_perm:[2,2,2,2] row_mask:0xf bank_mask:0xf
	v_fmac_f32_dpp v169, v162, v74 quad_perm:[2,2,2,2] row_mask:0xf bank_mask:0xf
	v_fmac_f32_dpp v170, v163, v75 quad_perm:[2,2,2,2] row_mask:0xf bank_mask:0xf
	v_fmac_f32_dpp v107, v160, v76 quad_perm:[3,3,3,3] row_mask:0xf bank_mask:0xf
	v_fmac_f32_dpp v168, v161, v77 quad_perm:[3,3,3,3] row_mask:0xf bank_mask:0xf
	v_fmac_f32_dpp v169, v162, v78 quad_perm:[3,3,3,3] row_mask:0xf bank_mask:0xf
	v_fmac_f32_dpp v170, v163, v79 quad_perm:[3,3,3,3] row_mask:0xf bank_mask:0xf
	ds_read_b128 v[152:155], v10 offset:12240
	s_waitcnt lgkmcnt(5)
	v_fmac_f32_dpp v107, v164, v80 quad_perm:[0,0,0,0] row_mask:0xf bank_mask:0xf
	v_fmac_f32_dpp v168, v165, v81 quad_perm:[0,0,0,0] row_mask:0xf bank_mask:0xf
	v_fmac_f32_dpp v169, v166, v82 quad_perm:[0,0,0,0] row_mask:0xf bank_mask:0xf
	v_fmac_f32_dpp v170, v167, v83 quad_perm:[0,0,0,0] row_mask:0xf bank_mask:0xf
	v_fmac_f32_dpp v107, v164, v84 quad_perm:[1,1,1,1] row_mask:0xf bank_mask:0xf
	v_fmac_f32_dpp v168, v165, v85 quad_perm:[1,1,1,1] row_mask:0xf bank_mask:0xf
	v_fmac_f32_dpp v169, v166, v86 quad_perm:[1,1,1,1] row_mask:0xf bank_mask:0xf
	v_fmac_f32_dpp v170, v167, v87 quad_perm:[1,1,1,1] row_mask:0xf bank_mask:0xf
	v_fmac_f32_dpp v107, v164, v88 quad_perm:[2,2,2,2] row_mask:0xf bank_mask:0xf
	v_fmac_f32_dpp v168, v165, v89 quad_perm:[2,2,2,2] row_mask:0xf bank_mask:0xf
	v_fmac_f32_dpp v169, v166, v90 quad_perm:[2,2,2,2] row_mask:0xf bank_mask:0xf
	v_fmac_f32_dpp v170, v167, v91 quad_perm:[2,2,2,2] row_mask:0xf bank_mask:0xf
	v_fmac_f32_dpp v107, v164, v92 quad_perm:[3,3,3,3] row_mask:0xf bank_mask:0xf
	v_fmac_f32_dpp v168, v165, v93 quad_perm:[3,3,3,3] row_mask:0xf bank_mask:0xf
	v_fmac_f32_dpp v169, v166, v94 quad_perm:[3,3,3,3] row_mask:0xf bank_mask:0xf
	v_fmac_f32_dpp v170, v167, v95 quad_perm:[3,3,3,3] row_mask:0xf bank_mask:0xf
	ds_read_b128 v[156:159], v10 offset:12304
	s_waitcnt lgkmcnt(5)
	v_fmac_f32_dpp v107, v136, v96 quad_perm:[0,0,0,0] row_mask:0xf bank_mask:0xf
	v_fmac_f32_dpp v168, v137, v97 quad_perm:[0,0,0,0] row_mask:0xf bank_mask:0xf
	v_fmac_f32_dpp v169, v138, v98 quad_perm:[0,0,0,0] row_mask:0xf bank_mask:0xf
	v_fmac_f32_dpp v170, v139, v99 quad_perm:[0,0,0,0] row_mask:0xf bank_mask:0xf
	v_fmac_f32_dpp v107, v136, v100 quad_perm:[1,1,1,1] row_mask:0xf bank_mask:0xf
	v_fmac_f32_dpp v168, v137, v101 quad_perm:[1,1,1,1] row_mask:0xf bank_mask:0xf
	v_fmac_f32_dpp v169, v138, v102 quad_perm:[1,1,1,1] row_mask:0xf bank_mask:0xf
	v_fmac_f32_dpp v170, v139, v103 quad_perm:[1,1,1,1] row_mask:0xf bank_mask:0xf
	v_fmac_f32_dpp v107, v136, v104 quad_perm:[2,2,2,2] row_mask:0xf bank_mask:0xf
	v_fmac_f32_dpp v168, v137, v105 quad_perm:[2,2,2,2] row_mask:0xf bank_mask:0xf
	v_fmac_f32_dpp v169, v138, v106 quad_perm:[2,2,2,2] row_mask:0xf bank_mask:0xf
	v_add_f32_e32 v107, v107, v168
	v_add_f32_e32 v169, v169, v170
	v_add_f32_e32 v107, v107, v169
	ds_read_b128 v[160:163], v10 offset:12368
	s_waitcnt lgkmcnt(5)
; __device__ void dn_d1(const Ctx& c, int ip) {
;     ...
;     SOLVE_ROW_BEGIN(44)
;     { const f32x4 m = *(const f32x4*)(mr + 0);
;       a0 -= m[0] * x[0];
;       a1 -= m[1] * x[1];
;       a2 -= m[2] * x[2];
;       a3 -= m[3] * x[3];
;     }
;     { const f32x4 m = *(const f32x4*)(mr + 4);
;       a0 -= m[0] * x[4];
;       a1 -= m[1] * x[5];
;       a2 -= m[2] * x[6];
;       a3 -= m[3] * x[7];
;     }
;     { const f32x4 m = *(const f32x4*)(mr + 8);
;       a0 -= m[0] * x[8];
;       a1 -= m[1] * x[9];
;       a2 -= m[2] * x[10];
;       a3 -= m[3] * x[11];
;     }
;     { const f32x4 m = *(const f32x4*)(mr + 12);
;       a0 -= m[0] * x[12];
;       a1 -= m[1] * x[13];
;       a2 -= m[2] * x[14];
;       a3 -= m[3] * x[15];
;     }
;     { const f32x4 m = *(const f32x4*)(mr + 16);
;       a0 -= m[0] * x[16];
;       a1 -= m[1] * x[17];
;       a2 -= m[2] * x[18];
;       a3 -= m[3] * x[19];
;     }
;     { const f32x4 m = *(const f32x4*)(mr + 20);
;       a0 -= m[0] * x[20];
;       a1 -= m[1] * x[21];
;       a2 -= m[2] * x[22];
;       a3 -= m[3] * x[23];
;     }
;     { const f32x4 m = *(const f32x4*)(mr + 24);
;       a0 -= m[0] * x[24];
;       a1 -= m[1] * x[25];
;       a2 -= m[2] * x[26];
;       a3 -= m[3] * x[27];
;     }
;     { const f32x4 m = *(const f32x4*)(mr + 28);
;       a0 -= m[0] * x[28];
;       a1 -= m[1] * x[29];
;       a2 -= m[2] * x[30];
;       a3 -= m[3] * x[31];
;     }
;     { const f32x4 m = *(const f32x4*)(mr + 32);
;       a0 -= m[0] * x[32];
;       a1 -= m[1] * x[33];
;       a2 -= m[2] * x[34];
;       a3 -= m[3] * x[35];
;     }
;     { const f32x4 m = *(const f32x4*)(mr + 36);
;       a0 -= m[0] * x[36];
;       a1 -= m[1] * x[37];
;       a2 -= m[2] * x[38];
;       a3 -= m[3] * x[39];
	v_mov_b32_e32 v168, 0
	v_mov_b32_e32 v169, 0
	v_mov_b32_e32 v170, 0
	v_fmac_f32_dpp v108, v140, v64 quad_perm:[0,0,0,0] row_mask:0xf bank_mask:0xf
	v_fmac_f32_dpp v168, v141, v65 quad_perm:[0,0,0,0] row_mask:0xf bank_mask:0xf
	v_fmac_f32_dpp v169, v142, v66 quad_perm:[0,0,0,0] row_mask:0xf bank_mask:0xf
	v_fmac_f32_dpp v170, v143, v67 quad_perm:[0,0,0,0] row_mask:0xf bank_mask:0xf
	v_fmac_f32_dpp v108, v140, v68 quad_perm:[1,1,1,1] row_mask:0xf bank_mask:0xf
	v_fmac_f32_dpp v168, v141, v69 quad_perm:[1,1,1,1] row_mask:0xf bank_mask:0xf
	v_fmac_f32_dpp v169, v142, v70 quad_perm:[1,1,1,1] row_mask:0xf bank_mask:0xf
	v_fmac_f32_dpp v170, v143, v71 quad_perm:[1,1,1,1] row_mask:0xf bank_mask:0xf
	v_fmac_f32_dpp v108, v140, v72 quad_perm:[2,2,2,2] row_mask:0xf bank_mask:0xf
	v_fmac_f32_dpp v168, v141, v73 quad_perm:[2,2,2,2] row_mask:0xf bank_mask:0xf
	v_fmac_f32_dpp v169, v142, v74 quad_perm:[2,2,2,2] row_mask:0xf bank_mask:0xf
	v_fmac_f32_dpp v170, v143, v75 quad_perm:[2,2,2,2] row_mask:0xf bank_mask:0xf
	v_fmac_f32_dpp v108, v140, v76 quad_perm:[3,3,3,3] row_mask:0xf bank_mask:0xf
	v_fmac_f32_dpp v168, v141, v77 quad_perm:[3,3,3,3] row_mask:0xf bank_mask:0xf
	v_fmac_f32_dpp v169, v142, v78 quad_perm:[3,3,3,3] row_mask:0xf bank_mask:0xf
	v_fmac_f32_dpp v170, v143, v79 quad_perm:[3,3,3,3] row_mask:0xf bank_mask:0xf
	ds_read_b128 v[164:167], v10 offset:12512
	s_waitcnt lgkmcnt(5)
	v_fmac_f32_dpp v108, v144, v80 quad_perm:[0,0,0,0] row_mask:0xf bank_mask:0xf
	v_fmac_f32_dpp v168, v145, v81 quad_perm:[0,0,0,0] row_mask:0xf bank_mask:0xf
	v_fmac_f32_dpp v169, v146, v82 quad_perm:[0,0,0,0] row_mask:0xf bank_mask:0xf
	v_fmac_f32_dpp v170, v147, v83 quad_perm:[0,0,0,0] row_mask:0xf bank_mask:0xf
	v_fmac_f32_dpp v108, v144, v84 quad_perm:[1,1,1,1] row_mask:0xf bank_mask:0xf
	v_fmac_f32_dpp v168, v145, v85 quad_perm:[1,1,1,1] row_mask:0xf bank_mask:0xf
	v_fmac_f32_dpp v169, v146, v86 quad_perm:[1,1,1,1] row_mask:0xf bank_mask:0xf
	v_fmac_f32_dpp v170, v147, v87 quad_perm:[1,1,1,1] row_mask:0xf bank_mask:0xf
	v_fmac_f32_dpp v108, v144, v88 quad_perm:[2,2,2,2] row_mask:0xf bank_mask:0xf
	v_fmac_f32_dpp v168, v145, v89 quad_perm:[2,2,2,2] row_mask:0xf bank_mask:0xf
	v_fmac_f32_dpp v169, v146, v90 quad_perm:[2,2,2,2] row_mask:0xf bank_mask:0xf
	v_fmac_f32_dpp v170, v147, v91 quad_perm:[2,2,2,2] row_mask:0xf bank_mask:0xf
	v_fmac_f32_dpp v108, v144, v92 quad_perm:[3,3,3,3] row_mask:0xf bank_mask:0xf
	v_fmac_f32_dpp v168, v145, v93 quad_perm:[3,3,3,3] row_mask:0xf bank_mask:0xf
	v_fmac_f32_dpp v169, v146, v94 quad_perm:[3,3,3,3] row_mask:0xf bank_mask:0xf
	v_fmac_f32_dpp v170, v147, v95 quad_perm:[3,3,3,3] row_mask:0xf bank_mask:0xf
	ds_read_b128 v[136:139], v10 offset:12576
	s_waitcnt lgkmcnt(5)
	v_fmac_f32_dpp v108, v148, v96 quad_perm:[0,0,0,0] row_mask:0xf bank_mask:0xf
	v_fmac_f32_dpp v168, v149, v97 quad_perm:[0,0,0,0] row_mask:0xf bank_mask:0xf
	v_fmac_f32_dpp v169, v150, v98 quad_perm:[0,0,0,0] row_mask:0xf bank_mask:0xf
	v_fmac_f32_dpp v170, v151, v99 quad_perm:[0,0,0,0] row_mask:0xf bank_mask:0xf
	v_fmac_f32_dpp v108, v148, v100 quad_perm:[1,1,1,1] row_mask:0xf bank_mask:0xf
	v_fmac_f32_dpp v168, v149, v101 quad_perm:[1,1,1,1] row_mask:0xf bank_mask:0xf
	v_fmac_f32_dpp v169, v150, v102 quad_perm:[1,1,1,1] row_mask:0xf bank_mask:0xf
	v_fmac_f32_dpp v170, v151, v103 quad_perm:[1,1,1,1] row_mask:0xf bank_mask:0xf
	v_fmac_f32_dpp v108, v148, v104 quad_perm:[2,2,2,2] row_mask:0xf bank_mask:0xf
	v_fmac_f32_dpp v168, v149, v105 quad_perm:[2,2,2,2] row_mask:0xf bank_mask:0xf
	v_fmac_f32_dpp v169, v150, v106 quad_perm:[2,2,2,2] row_mask:0xf bank_mask:0xf
	v_fmac_f32_dpp v170, v151, v107 quad_perm:[2,2,2,2] row_mask:0xf bank_mask:0xf
	v_add_f32_e32 v108, v108, v168
	v_add_f32_e32 v169, v169, v170
	v_add_f32_e32 v108, v108, v169
	ds_read_b128 v[140:143], v10 offset:12640
	s_waitcnt lgkmcnt(5)
	v_mov_b32_e32 v168, 0
	v_mov_b32_e32 v169, 0
	v_mov_b32_e32 v170, 0
	v_fmac_f32_dpp v109, v152, v64 quad_perm:[0,0,0,0] row_mask:0xf bank_mask:0xf
	v_fmac_f32_dpp v168, v153, v65 quad_perm:[0,0,0,0] row_mask:0xf bank_mask:0xf
	v_fmac_f32_dpp v169, v154, v66 quad_perm:[0,0,0,0] row_mask:0xf bank_mask:0xf
	v_fmac_f32_dpp v170, v155, v67 quad_perm:[0,0,0,0] row_mask:0xf bank_mask:0xf
	v_fmac_f32_dpp v109, v152, v68 quad_perm:[1,1,1,1] row_mask:0xf bank_mask:0xf
	v_fmac_f32_dpp v168, v153, v69 quad_perm:[1,1,1,1] row_mask:0xf bank_mask:0xf
	v_fmac_f32_dpp v169, v154, v70 quad_perm:[1,1,1,1] row_mask:0xf bank_mask:0xf
	v_fmac_f32_dpp v170, v155, v71 quad_perm:[1,1,1,1] row_mask:0xf bank_mask:0xf
	v_fmac_f32_dpp v109, v152, v72 quad_perm:[2,2,2,2] row_mask:0xf bank_mask:0xf
	v_fmac_f32_dpp v168, v153, v73 quad_perm:[2,2,2,2] row_mask:0xf bank_mask:0xf
	v_fmac_f32_dpp v169, v154, v74 quad_perm:[2,2,2,2] row_mask:0xf bank_mask:0xf
	v_fmac_f32_dpp v170, v155, v75 quad_perm:[2,2,2,2] row_mask:0xf bank_mask:0xf
	v_fmac_f32_dpp v109, v152, v76 quad_perm:[3,3,3,3] row_mask:0xf bank_mask:0xf
	v_fmac_f32_dpp v168, v153, v77 quad_perm:[3,3,3,3] row_mask:0xf bank_mask:0xf
	v_fmac_f32_dpp v169, v154, v78 quad_perm:[3,3,3,3] row_mask:0xf bank_mask:0xf
	v_fmac_f32_dpp v170, v155, v79 quad_perm:[3,3,3,3] row_mask:0xf bank_mask:0xf
	ds_read_b128 v[144:147], v10 offset:12784
	s_waitcnt lgkmcnt(5)
; __device__ void dn_d1(const Ctx& c, int ip) {
;     ...
;       a3 -= m[3] * x[7];
;     }
;     { const f32x4 m = *(const f32x4*)(mr + 8);
;       a0 -= m[0] * x[8];
;       a1 -= m[1] * x[9];
;       a2 -= m[2] * x[10];
;       a3 -= m[3] * x[11];
;     }
;     { const f32x4 m = *(const f32x4*)(mr + 12);
;       a0 -= m[0] * x[12];
;       a1 -= m[1] * x[13];
;       a2 -= m[2] * x[14];
;       a3 -= m[3] * x[15];
;     }
;     { const f32x4 m = *(const f32x4*)(mr + 16);
;       a0 -= m[0] * x[16];
;       a1 -= m[1] * x[17];
;       a2 -= m[2] * x[18];
;       a3 -= m[3] * x[19];
;     }
;     { const f32x4 m = *(const f32x4*)(mr + 20);
;       a0 -= m[0] * x[20];
;       a1 -= m[1] * x[21];
;       a2 -= m[2] * x[22];
;       a3 -= m[3] * x[23];
;     }
;     { const f32x4 m = *(const f32x4*)(mr + 24);
;       a0 -= m[0] * x[24];
;       a1 -= m[1] * x[25];
;       a2 -= m[2] * x[26];
;       a3 -= m[3] * x[27];
;     }
;     { const f32x4 m = *(const f32x4*)(mr + 28);
;       a0 -= m[0] * x[28];
;       a1 -= m[1] * x[29];
;       a2 -= m[2] * x[30];
;       a3 -= m[3] * x[31];
;     }
;     { const f32x4 m = *(const f32x4*)(mr + 32);
;       a0 -= m[0] * x[32];
;       a1 -= m[1] * x[33];
;       a2 -= m[2] * x[34];
;       a3 -= m[3] * x[35];
;     }
;     { const f32x4 m = *(const f32x4*)(mr + 36);
;       a0 -= m[0] * x[36];
;       a1 -= m[1] * x[37];
;       a2 -= m[2] * x[38];
;       a3 -= m[3] * x[39];
;     }
;     { const f32x4 m = *(const f32x4*)(mr + 40);
;       a0 -= m[0] * x[40];
;       a1 -= m[1] * x[41];
;       a2 -= m[2] * x[42];
;       a3 -= m[3] * x[43];
;     }
;     { const f32x4 m = *(const f32x4*)(mr + 44);
;       a0 -= m[0] * x[44];
;     }
;     SOLVE_ROW_END(45)
	v_fmac_f32_dpp v109, v156, v80 quad_perm:[0,0,0,0] row_mask:0xf bank_mask:0xf
	v_fmac_f32_dpp v168, v157, v81 quad_perm:[0,0,0,0] row_mask:0xf bank_mask:0xf
	v_fmac_f32_dpp v169, v158, v82 quad_perm:[0,0,0,0] row_mask:0xf bank_mask:0xf
	v_fmac_f32_dpp v170, v159, v83 quad_perm:[0,0,0,0] row_mask:0xf bank_mask:0xf
	v_fmac_f32_dpp v109, v156, v84 quad_perm:[1,1,1,1] row_mask:0xf bank_mask:0xf
	v_fmac_f32_dpp v168, v157, v85 quad_perm:[1,1,1,1] row_mask:0xf bank_mask:0xf
	v_fmac_f32_dpp v169, v158, v86 quad_perm:[1,1,1,1] row_mask:0xf bank_mask:0xf
	v_fmac_f32_dpp v170, v159, v87 quad_perm:[1,1,1,1] row_mask:0xf bank_mask:0xf
	v_fmac_f32_dpp v109, v156, v88 quad_perm:[2,2,2,2] row_mask:0xf bank_mask:0xf
	v_fmac_f32_dpp v168, v157, v89 quad_perm:[2,2,2,2] row_mask:0xf bank_mask:0xf
	v_fmac_f32_dpp v169, v158, v90 quad_perm:[2,2,2,2] row_mask:0xf bank_mask:0xf
	v_fmac_f32_dpp v170, v159, v91 quad_perm:[2,2,2,2] row_mask:0xf bank_mask:0xf
	v_fmac_f32_dpp v109, v156, v92 quad_perm:[3,3,3,3] row_mask:0xf bank_mask:0xf
	v_fmac_f32_dpp v168, v157, v93 quad_perm:[3,3,3,3] row_mask:0xf bank_mask:0xf
	v_fmac_f32_dpp v169, v158, v94 quad_perm:[3,3,3,3] row_mask:0xf bank_mask:0xf
	v_fmac_f32_dpp v170, v159, v95 quad_perm:[3,3,3,3] row_mask:0xf bank_mask:0xf
	ds_read_b128 v[148:151], v10 offset:12848
	s_waitcnt lgkmcnt(5)
	v_fmac_f32_dpp v109, v160, v96 quad_perm:[0,0,0,0] row_mask:0xf bank_mask:0xf
	v_fmac_f32_dpp v168, v161, v97 quad_perm:[0,0,0,0] row_mask:0xf bank_mask:0xf
	v_fmac_f32_dpp v169, v162, v98 quad_perm:[0,0,0,0] row_mask:0xf bank_mask:0xf
	v_fmac_f32_dpp v170, v163, v99 quad_perm:[0,0,0,0] row_mask:0xf bank_mask:0xf
	v_fmac_f32_dpp v109, v160, v100 quad_perm:[1,1,1,1] row_mask:0xf bank_mask:0xf
	v_fmac_f32_dpp v168, v161, v101 quad_perm:[1,1,1,1] row_mask:0xf bank_mask:0xf
	v_fmac_f32_dpp v169, v162, v102 quad_perm:[1,1,1,1] row_mask:0xf bank_mask:0xf
	v_fmac_f32_dpp v170, v163, v103 quad_perm:[1,1,1,1] row_mask:0xf bank_mask:0xf
	v_fmac_f32_dpp v109, v160, v104 quad_perm:[2,2,2,2] row_mask:0xf bank_mask:0xf
	v_fmac_f32_dpp v168, v161, v105 quad_perm:[2,2,2,2] row_mask:0xf bank_mask:0xf
	v_fmac_f32_dpp v169, v162, v106 quad_perm:[2,2,2,2] row_mask:0xf bank_mask:0xf
	v_fmac_f32_dpp v170, v163, v107 quad_perm:[2,2,2,2] row_mask:0xf bank_mask:0xf
	v_fmac_f32_dpp v109, v160, v108 quad_perm:[3,3,3,3] row_mask:0xf bank_mask:0xf
	v_add_f32_e32 v109, v109, v168
	v_add_f32_e32 v169, v169, v170
	v_add_f32_e32 v109, v109, v169
	ds_read_b128 v[152:155], v10 offset:12912
	s_waitcnt lgkmcnt(5)
	v_mov_b32_e32 v168, 0
	v_mov_b32_e32 v169, 0
	v_mov_b32_e32 v170, 0
	v_fmac_f32_dpp v110, v164, v64 quad_perm:[0,0,0,0] row_mask:0xf bank_mask:0xf
	v_fmac_f32_dpp v168, v165, v65 quad_perm:[0,0,0,0] row_mask:0xf bank_mask:0xf
	v_fmac_f32_dpp v169, v166, v66 quad_perm:[0,0,0,0] row_mask:0xf bank_mask:0xf
	v_fmac_f32_dpp v170, v167, v67 quad_perm:[0,0,0,0] row_mask:0xf bank_mask:0xf
	v_fmac_f32_dpp v110, v164, v68 quad_perm:[1,1,1,1] row_mask:0xf bank_mask:0xf
	v_fmac_f32_dpp v168, v165, v69 quad_perm:[1,1,1,1] row_mask:0xf bank_mask:0xf
	v_fmac_f32_dpp v169, v166, v70 quad_perm:[1,1,1,1] row_mask:0xf bank_mask:0xf
	v_fmac_f32_dpp v170, v167, v71 quad_perm:[1,1,1,1] row_mask:0xf bank_mask:0xf
	v_fmac_f32_dpp v110, v164, v72 quad_perm:[2,2,2,2] row_mask:0xf bank_mask:0xf
	v_fmac_f32_dpp v168, v165, v73 quad_perm:[2,2,2,2] row_mask:0xf bank_mask:0xf
	v_fmac_f32_dpp v169, v166, v74 quad_perm:[2,2,2,2] row_mask:0xf bank_mask:0xf
	v_fmac_f32_dpp v170, v167, v75 quad_perm:[2,2,2,2] row_mask:0xf bank_mask:0xf
	v_fmac_f32_dpp v110, v164, v76 quad_perm:[3,3,3,3] row_mask:0xf bank_mask:0xf
	v_fmac_f32_dpp v168, v165, v77 quad_perm:[3,3,3,3] row_mask:0xf bank_mask:0xf
	v_fmac_f32_dpp v169, v166, v78 quad_perm:[3,3,3,3] row_mask:0xf bank_mask:0xf
	v_fmac_f32_dpp v170, v167, v79 quad_perm:[3,3,3,3] row_mask:0xf bank_mask:0xf
	ds_read_b128 v[156:159], v10 offset:13056
	s_waitcnt lgkmcnt(5)
	v_fmac_f32_dpp v110, v136, v80 quad_perm:[0,0,0,0] row_mask:0xf bank_mask:0xf
	v_fmac_f32_dpp v168, v137, v81 quad_perm:[0,0,0,0] row_mask:0xf bank_mask:0xf
	v_fmac_f32_dpp v169, v138, v82 quad_perm:[0,0,0,0] row_mask:0xf bank_mask:0xf
	v_fmac_f32_dpp v170, v139, v83 quad_perm:[0,0,0,0] row_mask:0xf bank_mask:0xf
	v_fmac_f32_dpp v110, v136, v84 quad_perm:[1,1,1,1] row_mask:0xf bank_mask:0xf
	v_fmac_f32_dpp v168, v137, v85 quad_perm:[1,1,1,1] row_mask:0xf bank_mask:0xf
	v_fmac_f32_dpp v169, v138, v86 quad_perm:[1,1,1,1] row_mask:0xf bank_mask:0xf
	v_fmac_f32_dpp v170, v139, v87 quad_perm:[1,1,1,1] row_mask:0xf bank_mask:0xf
	v_fmac_f32_dpp v110, v136, v88 quad_perm:[2,2,2,2] row_mask:0xf bank_mask:0xf
	v_fmac_f32_dpp v168, v137, v89 quad_perm:[2,2,2,2] row_mask:0xf bank_mask:0xf
	v_fmac_f32_dpp v169, v138, v90 quad_perm:[2,2,2,2] row_mask:0xf bank_mask:0xf
	v_fmac_f32_dpp v170, v139, v91 quad_perm:[2,2,2,2] row_mask:0xf bank_mask:0xf
	v_fmac_f32_dpp v110, v136, v92 quad_perm:[3,3,3,3] row_mask:0xf bank_mask:0xf
	v_fmac_f32_dpp v168, v137, v93 quad_perm:[3,3,3,3] row_mask:0xf bank_mask:0xf
	v_fmac_f32_dpp v169, v138, v94 quad_perm:[3,3,3,3] row_mask:0xf bank_mask:0xf
	v_fmac_f32_dpp v170, v139, v95 quad_perm:[3,3,3,3] row_mask:0xf bank_mask:0xf
	ds_read_b128 v[160:163], v10 offset:13120
	s_waitcnt lgkmcnt(5)
; __device__ void dn_d1(const Ctx& c, int ip) {
;     ...
;     { const f32x4 m = *(const f32x4*)(mr + 8);
;       a0 -= m[0] * x[8];
;       a1 -= m[1] * x[9];
;       a2 -= m[2] * x[10];
;       a3 -= m[3] * x[11];
;     }
;     { const f32x4 m = *(const f32x4*)(mr + 12);
;       a0 -= m[0] * x[12];
;       a1 -= m[1] * x[13];
;       a2 -= m[2] * x[14];
;       a3 -= m[3] * x[15];
;     }
;     { const f32x4 m = *(const f32x4*)(mr + 16);
;       a0 -= m[0] * x[16];
;       a1 -= m[1] * x[17];
;       a2 -= m[2] * x[18];
;       a3 -= m[3] * x[19];
;     }
;     { const f32x4 m = *(const f32x4*)(mr + 20);
;       a0 -= m[0] * x[20];
;       a1 -= m[1] * x[21];
;       a2 -= m[2] * x[22];
;       a3 -= m[3] * x[23];
;     }
;     { const f32x4 m = *(const f32x4*)(mr + 24);
;       a0 -= m[0] * x[24];
;       a1 -= m[1] * x[25];
;       a2 -= m[2] * x[26];
;       a3 -= m[3] * x[27];
;     }
;     { const f32x4 m = *(const f32x4*)(mr + 28);
;       a0 -= m[0] * x[28];
;       a1 -= m[1] * x[29];
;       a2 -= m[2] * x[30];
;       a3 -= m[3] * x[31];
;     }
;     { const f32x4 m = *(const f32x4*)(mr + 32);
;       a0 -= m[0] * x[32];
;       a1 -= m[1] * x[33];
;       a2 -= m[2] * x[34];
;       a3 -= m[3] * x[35];
;     }
;     { const f32x4 m = *(const f32x4*)(mr + 36);
;       a0 -= m[0] * x[36];
;       a1 -= m[1] * x[37];
;       a2 -= m[2] * x[38];
;       a3 -= m[3] * x[39];
;     }
;     { const f32x4 m = *(const f32x4*)(mr + 40);
;       a0 -= m[0] * x[40];
;       a1 -= m[1] * x[41];
;       a2 -= m[2] * x[42];
;       a3 -= m[3] * x[43];
;     }
;     { const f32x4 m = *(const f32x4*)(mr + 44);
;       a0 -= m[0] * x[44];
;       a1 -= m[1] * x[45];
;       a2 -= m[2] * x[46];
;     }
;     SOLVE_ROW_END(47)
	v_fmac_f32_dpp v110, v140, v96 quad_perm:[0,0,0,0] row_mask:0xf bank_mask:0xf
	v_fmac_f32_dpp v168, v141, v97 quad_perm:[0,0,0,0] row_mask:0xf bank_mask:0xf
	v_fmac_f32_dpp v169, v142, v98 quad_perm:[0,0,0,0] row_mask:0xf bank_mask:0xf
	v_fmac_f32_dpp v170, v143, v99 quad_perm:[0,0,0,0] row_mask:0xf bank_mask:0xf
	v_fmac_f32_dpp v110, v140, v100 quad_perm:[1,1,1,1] row_mask:0xf bank_mask:0xf
	v_fmac_f32_dpp v168, v141, v101 quad_perm:[1,1,1,1] row_mask:0xf bank_mask:0xf
	v_fmac_f32_dpp v169, v142, v102 quad_perm:[1,1,1,1] row_mask:0xf bank_mask:0xf
	v_fmac_f32_dpp v170, v143, v103 quad_perm:[1,1,1,1] row_mask:0xf bank_mask:0xf
	v_fmac_f32_dpp v110, v140, v104 quad_perm:[2,2,2,2] row_mask:0xf bank_mask:0xf
	v_fmac_f32_dpp v168, v141, v105 quad_perm:[2,2,2,2] row_mask:0xf bank_mask:0xf
	v_fmac_f32_dpp v169, v142, v106 quad_perm:[2,2,2,2] row_mask:0xf bank_mask:0xf
	v_fmac_f32_dpp v170, v143, v107 quad_perm:[2,2,2,2] row_mask:0xf bank_mask:0xf
	v_fmac_f32_dpp v110, v140, v108 quad_perm:[3,3,3,3] row_mask:0xf bank_mask:0xf
	v_fmac_f32_dpp v168, v141, v109 quad_perm:[3,3,3,3] row_mask:0xf bank_mask:0xf
	v_add_f32_e32 v110, v110, v168
	v_add_f32_e32 v169, v169, v170
	v_add_f32_e32 v110, v110, v169
	ds_read_b128 v[164:167], v10 offset:13184
	s_waitcnt lgkmcnt(5)
	v_mov_b32_e32 v168, 0
	v_mov_b32_e32 v169, 0
	v_mov_b32_e32 v170, 0
	v_fmac_f32_dpp v111, v144, v64 quad_perm:[0,0,0,0] row_mask:0xf bank_mask:0xf
	v_fmac_f32_dpp v168, v145, v65 quad_perm:[0,0,0,0] row_mask:0xf bank_mask:0xf
	v_fmac_f32_dpp v169, v146, v66 quad_perm:[0,0,0,0] row_mask:0xf bank_mask:0xf
	v_fmac_f32_dpp v170, v147, v67 quad_perm:[0,0,0,0] row_mask:0xf bank_mask:0xf
	v_fmac_f32_dpp v111, v144, v68 quad_perm:[1,1,1,1] row_mask:0xf bank_mask:0xf
	v_fmac_f32_dpp v168, v145, v69 quad_perm:[1,1,1,1] row_mask:0xf bank_mask:0xf
	v_fmac_f32_dpp v169, v146, v70 quad_perm:[1,1,1,1] row_mask:0xf bank_mask:0xf
	v_fmac_f32_dpp v170, v147, v71 quad_perm:[1,1,1,1] row_mask:0xf bank_mask:0xf
	v_fmac_f32_dpp v111, v144, v72 quad_perm:[2,2,2,2] row_mask:0xf bank_mask:0xf
	v_fmac_f32_dpp v168, v145, v73 quad_perm:[2,2,2,2] row_mask:0xf bank_mask:0xf
	v_fmac_f32_dpp v169, v146, v74 quad_perm:[2,2,2,2] row_mask:0xf bank_mask:0xf
	v_fmac_f32_dpp v170, v147, v75 quad_perm:[2,2,2,2] row_mask:0xf bank_mask:0xf
	v_fmac_f32_dpp v111, v144, v76 quad_perm:[3,3,3,3] row_mask:0xf bank_mask:0xf
	v_fmac_f32_dpp v168, v145, v77 quad_perm:[3,3,3,3] row_mask:0xf bank_mask:0xf
	v_fmac_f32_dpp v169, v146, v78 quad_perm:[3,3,3,3] row_mask:0xf bank_mask:0xf
	v_fmac_f32_dpp v170, v147, v79 quad_perm:[3,3,3,3] row_mask:0xf bank_mask:0xf
	ds_read_b128 v[136:139], v10 offset:13328
	s_waitcnt lgkmcnt(5)
	v_fmac_f32_dpp v111, v148, v80 quad_perm:[0,0,0,0] row_mask:0xf bank_mask:0xf
	v_fmac_f32_dpp v168, v149, v81 quad_perm:[0,0,0,0] row_mask:0xf bank_mask:0xf
	v_fmac_f32_dpp v169, v150, v82 quad_perm:[0,0,0,0] row_mask:0xf bank_mask:0xf
	v_fmac_f32_dpp v170, v151, v83 quad_perm:[0,0,0,0] row_mask:0xf bank_mask:0xf
	v_fmac_f32_dpp v111, v148, v84 quad_perm:[1,1,1,1] row_mask:0xf bank_mask:0xf
	v_fmac_f32_dpp v168, v149, v85 quad_perm:[1,1,1,1] row_mask:0xf bank_mask:0xf
	v_fmac_f32_dpp v169, v150, v86 quad_perm:[1,1,1,1] row_mask:0xf bank_mask:0xf
	v_fmac_f32_dpp v170, v151, v87 quad_perm:[1,1,1,1] row_mask:0xf bank_mask:0xf
	v_fmac_f32_dpp v111, v148, v88 quad_perm:[2,2,2,2] row_mask:0xf bank_mask:0xf
	v_fmac_f32_dpp v168, v149, v89 quad_perm:[2,2,2,2] row_mask:0xf bank_mask:0xf
	v_fmac_f32_dpp v169, v150, v90 quad_perm:[2,2,2,2] row_mask:0xf bank_mask:0xf
	v_fmac_f32_dpp v170, v151, v91 quad_perm:[2,2,2,2] row_mask:0xf bank_mask:0xf
	v_fmac_f32_dpp v111, v148, v92 quad_perm:[3,3,3,3] row_mask:0xf bank_mask:0xf
	v_fmac_f32_dpp v168, v149, v93 quad_perm:[3,3,3,3] row_mask:0xf bank_mask:0xf
	v_fmac_f32_dpp v169, v150, v94 quad_perm:[3,3,3,3] row_mask:0xf bank_mask:0xf
	v_fmac_f32_dpp v170, v151, v95 quad_perm:[3,3,3,3] row_mask:0xf bank_mask:0xf
	ds_read_b128 v[140:143], v10 offset:13392
	s_waitcnt lgkmcnt(5)
	v_fmac_f32_dpp v111, v152, v96 quad_perm:[0,0,0,0] row_mask:0xf bank_mask:0xf
	v_fmac_f32_dpp v168, v153, v97 quad_perm:[0,0,0,0] row_mask:0xf bank_mask:0xf
	v_fmac_f32_dpp v169, v154, v98 quad_perm:[0,0,0,0] row_mask:0xf bank_mask:0xf
	v_fmac_f32_dpp v170, v155, v99 quad_perm:[0,0,0,0] row_mask:0xf bank_mask:0xf
	v_fmac_f32_dpp v111, v152, v100 quad_perm:[1,1,1,1] row_mask:0xf bank_mask:0xf
	v_fmac_f32_dpp v168, v153, v101 quad_perm:[1,1,1,1] row_mask:0xf bank_mask:0xf
	v_fmac_f32_dpp v169, v154, v102 quad_perm:[1,1,1,1] row_mask:0xf bank_mask:0xf
	v_fmac_f32_dpp v170, v155, v103 quad_perm:[1,1,1,1] row_mask:0xf bank_mask:0xf
	v_fmac_f32_dpp v111, v152, v104 quad_perm:[2,2,2,2] row_mask:0xf bank_mask:0xf
	v_fmac_f32_dpp v168, v153, v105 quad_perm:[2,2,2,2] row_mask:0xf bank_mask:0xf
	v_fmac_f32_dpp v169, v154, v106 quad_perm:[2,2,2,2] row_mask:0xf bank_mask:0xf
	v_fmac_f32_dpp v170, v155, v107 quad_perm:[2,2,2,2] row_mask:0xf bank_mask:0xf
	v_fmac_f32_dpp v111, v152, v108 quad_perm:[3,3,3,3] row_mask:0xf bank_mask:0xf
	v_fmac_f32_dpp v168, v153, v109 quad_perm:[3,3,3,3] row_mask:0xf bank_mask:0xf
	v_fmac_f32_dpp v169, v154, v110 quad_perm:[3,3,3,3] row_mask:0xf bank_mask:0xf
	v_add_f32_e32 v111, v111, v168
	v_add_f32_e32 v169, v169, v170
	v_add_f32_e32 v111, v111, v169
	ds_read_b128 v[144:147], v10 offset:13456
	s_waitcnt lgkmcnt(5)
; __device__ void dn_d1(const Ctx& c, int ip) {
;     ...
;       a0 -= m[0] * x[8];
;       a1 -= m[1] * x[9];
;       a2 -= m[2] * x[10];
;       a3 -= m[3] * x[11];
;     }
;     { const f32x4 m = *(const f32x4*)(mr + 12);
;       a0 -= m[0] * x[12];
;       a1 -= m[1] * x[13];
;       a2 -= m[2] * x[14];
;       a3 -= m[3] * x[15];
;     }
;     { const f32x4 m = *(const f32x4*)(mr + 16);
;       a0 -= m[0] * x[16];
;       a1 -= m[1] * x[17];
;       a2 -= m[2] * x[18];
;       a3 -= m[3] * x[19];
;     }
;     { const f32x4 m = *(const f32x4*)(mr + 20);
;       a0 -= m[0] * x[20];
;       a1 -= m[1] * x[21];
;       a2 -= m[2] * x[22];
;       a3 -= m[3] * x[23];
;     }
;     { const f32x4 m = *(const f32x4*)(mr + 24);
;       a0 -= m[0] * x[24];
;       a1 -= m[1] * x[25];
;       a2 -= m[2] * x[26];
;       a3 -= m[3] * x[27];
;     }
;     { const f32x4 m = *(const f32x4*)(mr + 28);
;       a0 -= m[0] * x[28];
;       a1 -= m[1] * x[29];
;       a2 -= m[2] * x[30];
;       a3 -= m[3] * x[31];
;     }
;     { const f32x4 m = *(const f32x4*)(mr + 32);
;       a0 -= m[0] * x[32];
;       a1 -= m[1] * x[33];
;       a2 -= m[2] * x[34];
;       a3 -= m[3] * x[35];
;     }
;     { const f32x4 m = *(const f32x4*)(mr + 36);
;       a0 -= m[0] * x[36];
;       a1 -= m[1] * x[37];
;       a2 -= m[2] * x[38];
;       a3 -= m[3] * x[39];
;     }
;     { const f32x4 m = *(const f32x4*)(mr + 40);
;       a0 -= m[0] * x[40];
;       a1 -= m[1] * x[41];
;       a2 -= m[2] * x[42];
;       a3 -= m[3] * x[43];
;     }
;     { const f32x4 m = *(const f32x4*)(mr + 44);
;       a0 -= m[0] * x[44];
;       a1 -= m[1] * x[45];
;       a2 -= m[2] * x[46];
;       a3 -= m[3] * x[47];
;     }
;     SOLVE_ROW_END(48)
	v_mov_b32_e32 v168, 0
	v_mov_b32_e32 v169, 0
	v_mov_b32_e32 v170, 0
	v_fmac_f32_dpp v112, v156, v64 quad_perm:[0,0,0,0] row_mask:0xf bank_mask:0xf
	v_fmac_f32_dpp v168, v157, v65 quad_perm:[0,0,0,0] row_mask:0xf bank_mask:0xf
	v_fmac_f32_dpp v169, v158, v66 quad_perm:[0,0,0,0] row_mask:0xf bank_mask:0xf
	v_fmac_f32_dpp v170, v159, v67 quad_perm:[0,0,0,0] row_mask:0xf bank_mask:0xf
	v_fmac_f32_dpp v112, v156, v68 quad_perm:[1,1,1,1] row_mask:0xf bank_mask:0xf
	v_fmac_f32_dpp v168, v157, v69 quad_perm:[1,1,1,1] row_mask:0xf bank_mask:0xf
	v_fmac_f32_dpp v169, v158, v70 quad_perm:[1,1,1,1] row_mask:0xf bank_mask:0xf
	v_fmac_f32_dpp v170, v159, v71 quad_perm:[1,1,1,1] row_mask:0xf bank_mask:0xf
	v_fmac_f32_dpp v112, v156, v72 quad_perm:[2,2,2,2] row_mask:0xf bank_mask:0xf
	v_fmac_f32_dpp v168, v157, v73 quad_perm:[2,2,2,2] row_mask:0xf bank_mask:0xf
	v_fmac_f32_dpp v169, v158, v74 quad_perm:[2,2,2,2] row_mask:0xf bank_mask:0xf
	v_fmac_f32_dpp v170, v159, v75 quad_perm:[2,2,2,2] row_mask:0xf bank_mask:0xf
	v_fmac_f32_dpp v112, v156, v76 quad_perm:[3,3,3,3] row_mask:0xf bank_mask:0xf
	v_fmac_f32_dpp v168, v157, v77 quad_perm:[3,3,3,3] row_mask:0xf bank_mask:0xf
	v_fmac_f32_dpp v169, v158, v78 quad_perm:[3,3,3,3] row_mask:0xf bank_mask:0xf
	v_fmac_f32_dpp v170, v159, v79 quad_perm:[3,3,3,3] row_mask:0xf bank_mask:0xf
	ds_read_b128 v[148:151], v10 offset:13520
	s_waitcnt lgkmcnt(5)
	v_fmac_f32_dpp v112, v160, v80 quad_perm:[0,0,0,0] row_mask:0xf bank_mask:0xf
	v_fmac_f32_dpp v168, v161, v81 quad_perm:[0,0,0,0] row_mask:0xf bank_mask:0xf
	v_fmac_f32_dpp v169, v162, v82 quad_perm:[0,0,0,0] row_mask:0xf bank_mask:0xf
	v_fmac_f32_dpp v170, v163, v83 quad_perm:[0,0,0,0] row_mask:0xf bank_mask:0xf
	v_fmac_f32_dpp v112, v160, v84 quad_perm:[1,1,1,1] row_mask:0xf bank_mask:0xf
	v_fmac_f32_dpp v168, v161, v85 quad_perm:[1,1,1,1] row_mask:0xf bank_mask:0xf
	v_fmac_f32_dpp v169, v162, v86 quad_perm:[1,1,1,1] row_mask:0xf bank_mask:0xf
	v_fmac_f32_dpp v170, v163, v87 quad_perm:[1,1,1,1] row_mask:0xf bank_mask:0xf
	v_fmac_f32_dpp v112, v160, v88 quad_perm:[2,2,2,2] row_mask:0xf bank_mask:0xf
	v_fmac_f32_dpp v168, v161, v89 quad_perm:[2,2,2,2] row_mask:0xf bank_mask:0xf
	v_fmac_f32_dpp v169, v162, v90 quad_perm:[2,2,2,2] row_mask:0xf bank_mask:0xf
	v_fmac_f32_dpp v170, v163, v91 quad_perm:[2,2,2,2] row_mask:0xf bank_mask:0xf
	v_fmac_f32_dpp v112, v160, v92 quad_perm:[3,3,3,3] row_mask:0xf bank_mask:0xf
	v_fmac_f32_dpp v168, v161, v93 quad_perm:[3,3,3,3] row_mask:0xf bank_mask:0xf
	v_fmac_f32_dpp v169, v162, v94 quad_perm:[3,3,3,3] row_mask:0xf bank_mask:0xf
	v_fmac_f32_dpp v170, v163, v95 quad_perm:[3,3,3,3] row_mask:0xf bank_mask:0xf
	ds_read_b128 v[152:155], v10 offset:13600
	s_waitcnt lgkmcnt(5)
	v_fmac_f32_dpp v112, v164, v96 quad_perm:[0,0,0,0] row_mask:0xf bank_mask:0xf
	v_fmac_f32_dpp v168, v165, v97 quad_perm:[0,0,0,0] row_mask:0xf bank_mask:0xf
	v_fmac_f32_dpp v169, v166, v98 quad_perm:[0,0,0,0] row_mask:0xf bank_mask:0xf
	v_fmac_f32_dpp v170, v167, v99 quad_perm:[0,0,0,0] row_mask:0xf bank_mask:0xf
	v_fmac_f32_dpp v112, v164, v100 quad_perm:[1,1,1,1] row_mask:0xf bank_mask:0xf
	v_fmac_f32_dpp v168, v165, v101 quad_perm:[1,1,1,1] row_mask:0xf bank_mask:0xf
	v_fmac_f32_dpp v169, v166, v102 quad_perm:[1,1,1,1] row_mask:0xf bank_mask:0xf
	v_fmac_f32_dpp v170, v167, v103 quad_perm:[1,1,1,1] row_mask:0xf bank_mask:0xf
	v_fmac_f32_dpp v112, v164, v104 quad_perm:[2,2,2,2] row_mask:0xf bank_mask:0xf
	v_fmac_f32_dpp v168, v165, v105 quad_perm:[2,2,2,2] row_mask:0xf bank_mask:0xf
	v_fmac_f32_dpp v169, v166, v106 quad_perm:[2,2,2,2] row_mask:0xf bank_mask:0xf
	v_fmac_f32_dpp v170, v167, v107 quad_perm:[2,2,2,2] row_mask:0xf bank_mask:0xf
	v_fmac_f32_dpp v112, v164, v108 quad_perm:[3,3,3,3] row_mask:0xf bank_mask:0xf
	v_fmac_f32_dpp v168, v165, v109 quad_perm:[3,3,3,3] row_mask:0xf bank_mask:0xf
	v_fmac_f32_dpp v169, v166, v110 quad_perm:[3,3,3,3] row_mask:0xf bank_mask:0xf
	v_fmac_f32_dpp v170, v167, v111 quad_perm:[3,3,3,3] row_mask:0xf bank_mask:0xf
	v_add_f32_e32 v112, v112, v168
	v_add_f32_e32 v169, v169, v170
	v_add_f32_e32 v112, v112, v169
	ds_read_b128 v[156:159], v10 offset:13664
	s_waitcnt lgkmcnt(5)
	v_mov_b32_e32 v168, 0
	v_mov_b32_e32 v169, 0
	v_mov_b32_e32 v170, 0
	v_fmac_f32_dpp v113, v136, v64 quad_perm:[0,0,0,0] row_mask:0xf bank_mask:0xf
	v_fmac_f32_dpp v168, v137, v65 quad_perm:[0,0,0,0] row_mask:0xf bank_mask:0xf
	v_fmac_f32_dpp v169, v138, v66 quad_perm:[0,0,0,0] row_mask:0xf bank_mask:0xf
	v_fmac_f32_dpp v170, v139, v67 quad_perm:[0,0,0,0] row_mask:0xf bank_mask:0xf
	v_fmac_f32_dpp v113, v136, v68 quad_perm:[1,1,1,1] row_mask:0xf bank_mask:0xf
	v_fmac_f32_dpp v168, v137, v69 quad_perm:[1,1,1,1] row_mask:0xf bank_mask:0xf
	v_fmac_f32_dpp v169, v138, v70 quad_perm:[1,1,1,1] row_mask:0xf bank_mask:0xf
	v_fmac_f32_dpp v170, v139, v71 quad_perm:[1,1,1,1] row_mask:0xf bank_mask:0xf
	v_fmac_f32_dpp v113, v136, v72 quad_perm:[2,2,2,2] row_mask:0xf bank_mask:0xf
	v_fmac_f32_dpp v168, v137, v73 quad_perm:[2,2,2,2] row_mask:0xf bank_mask:0xf
	v_fmac_f32_dpp v169, v138, v74 quad_perm:[2,2,2,2] row_mask:0xf bank_mask:0xf
	v_fmac_f32_dpp v170, v139, v75 quad_perm:[2,2,2,2] row_mask:0xf bank_mask:0xf
	v_fmac_f32_dpp v113, v136, v76 quad_perm:[3,3,3,3] row_mask:0xf bank_mask:0xf
	v_fmac_f32_dpp v168, v137, v77 quad_perm:[3,3,3,3] row_mask:0xf bank_mask:0xf
	v_fmac_f32_dpp v169, v138, v78 quad_perm:[3,3,3,3] row_mask:0xf bank_mask:0xf
	v_fmac_f32_dpp v170, v139, v79 quad_perm:[3,3,3,3] row_mask:0xf bank_mask:0xf
	ds_read_b128 v[160:163], v10 offset:13728
	s_waitcnt lgkmcnt(5)
; __device__ void dn_d1(const Ctx& c, int ip) {
;     ...
;     { const f32x4 m = *(const f32x4*)(mr + 48);
;       a0 -= m[0] * x[48];
;     }
;     SOLVE_ROW_END(49)
;     SOLVE_ROW_BEGIN(50)
;     { const f32x4 m = *(const f32x4*)(mr + 0);
;       a0 -= m[0] * x[0];
;       a1 -= m[1] * x[1];
;       a2 -= m[2] * x[2];
;       a3 -= m[3] * x[3];
;     }
;     { const f32x4 m = *(const f32x4*)(mr + 4);
;       a0 -= m[0] * x[4];
;       a1 -= m[1] * x[5];
;       a2 -= m[2] * x[6];
;       a3 -= m[3] * x[7];
;     }
;     { const f32x4 m = *(const f32x4*)(mr + 8);
;       a0 -= m[0] * x[8];
;       a1 -= m[1] * x[9];
;       a2 -= m[2] * x[10];
;       a3 -= m[3] * x[11];
;     }
;     { const f32x4 m = *(const f32x4*)(mr + 12);
;       a0 -= m[0] * x[12];
;       a1 -= m[1] * x[13];
;       a2 -= m[2] * x[14];
;       a3 -= m[3] * x[15];
;     }
;     { const f32x4 m = *(const f32x4*)(mr + 16);
;       a0 -= m[0] * x[16];
;       a1 -= m[1] * x[17];
;       a2 -= m[2] * x[18];
;       a3 -= m[3] * x[19];
;     }
;     { const f32x4 m = *(const f32x4*)(mr + 20);
;       a0 -= m[0] * x[20];
;       a1 -= m[1] * x[21];
;       a2 -= m[2] * x[22];
;       a3 -= m[3] * x[23];
;     }
;     { const f32x4 m = *(const f32x4*)(mr + 24);
;       a0 -= m[0] * x[24];
;       a1 -= m[1] * x[25];
;       a2 -= m[2] * x[26];
;       a3 -= m[3] * x[27];
;     }
;     { const f32x4 m = *(const f32x4*)(mr + 28);
;       a0 -= m[0] * x[28];
;       a1 -= m[1] * x[29];
;       a2 -= m[2] * x[30];
;       a3 -= m[3] * x[31];
;     }
;     { const f32x4 m = *(const f32x4*)(mr + 32);
;       a0 -= m[0] * x[32];
;       a1 -= m[1] * x[33];
;       a2 -= m[2] * x[34];
;       a3 -= m[3] * x[35];
;     }
;     { const f32x4 m = *(const f32x4*)(mr + 36);
	v_fmac_f32_dpp v113, v140, v80 quad_perm:[0,0,0,0] row_mask:0xf bank_mask:0xf
	v_fmac_f32_dpp v168, v141, v81 quad_perm:[0,0,0,0] row_mask:0xf bank_mask:0xf
	v_fmac_f32_dpp v169, v142, v82 quad_perm:[0,0,0,0] row_mask:0xf bank_mask:0xf
	v_fmac_f32_dpp v170, v143, v83 quad_perm:[0,0,0,0] row_mask:0xf bank_mask:0xf
	v_fmac_f32_dpp v113, v140, v84 quad_perm:[1,1,1,1] row_mask:0xf bank_mask:0xf
	v_fmac_f32_dpp v168, v141, v85 quad_perm:[1,1,1,1] row_mask:0xf bank_mask:0xf
	v_fmac_f32_dpp v169, v142, v86 quad_perm:[1,1,1,1] row_mask:0xf bank_mask:0xf
	v_fmac_f32_dpp v170, v143, v87 quad_perm:[1,1,1,1] row_mask:0xf bank_mask:0xf
	v_fmac_f32_dpp v113, v140, v88 quad_perm:[2,2,2,2] row_mask:0xf bank_mask:0xf
	v_fmac_f32_dpp v168, v141, v89 quad_perm:[2,2,2,2] row_mask:0xf bank_mask:0xf
	v_fmac_f32_dpp v169, v142, v90 quad_perm:[2,2,2,2] row_mask:0xf bank_mask:0xf
	v_fmac_f32_dpp v170, v143, v91 quad_perm:[2,2,2,2] row_mask:0xf bank_mask:0xf
	v_fmac_f32_dpp v113, v140, v92 quad_perm:[3,3,3,3] row_mask:0xf bank_mask:0xf
	v_fmac_f32_dpp v168, v141, v93 quad_perm:[3,3,3,3] row_mask:0xf bank_mask:0xf
	v_fmac_f32_dpp v169, v142, v94 quad_perm:[3,3,3,3] row_mask:0xf bank_mask:0xf
	v_fmac_f32_dpp v170, v143, v95 quad_perm:[3,3,3,3] row_mask:0xf bank_mask:0xf
	ds_read_b128 v[164:167], v10 offset:13792
	s_waitcnt lgkmcnt(5)
	v_fmac_f32_dpp v113, v144, v96 quad_perm:[0,0,0,0] row_mask:0xf bank_mask:0xf
	v_fmac_f32_dpp v168, v145, v97 quad_perm:[0,0,0,0] row_mask:0xf bank_mask:0xf
	v_fmac_f32_dpp v169, v146, v98 quad_perm:[0,0,0,0] row_mask:0xf bank_mask:0xf
	v_fmac_f32_dpp v170, v147, v99 quad_perm:[0,0,0,0] row_mask:0xf bank_mask:0xf
	v_fmac_f32_dpp v113, v144, v100 quad_perm:[1,1,1,1] row_mask:0xf bank_mask:0xf
	v_fmac_f32_dpp v168, v145, v101 quad_perm:[1,1,1,1] row_mask:0xf bank_mask:0xf
	v_fmac_f32_dpp v169, v146, v102 quad_perm:[1,1,1,1] row_mask:0xf bank_mask:0xf
	v_fmac_f32_dpp v170, v147, v103 quad_perm:[1,1,1,1] row_mask:0xf bank_mask:0xf
	v_fmac_f32_dpp v113, v144, v104 quad_perm:[2,2,2,2] row_mask:0xf bank_mask:0xf
	v_fmac_f32_dpp v168, v145, v105 quad_perm:[2,2,2,2] row_mask:0xf bank_mask:0xf
	v_fmac_f32_dpp v169, v146, v106 quad_perm:[2,2,2,2] row_mask:0xf bank_mask:0xf
	v_fmac_f32_dpp v170, v147, v107 quad_perm:[2,2,2,2] row_mask:0xf bank_mask:0xf
	v_fmac_f32_dpp v113, v144, v108 quad_perm:[3,3,3,3] row_mask:0xf bank_mask:0xf
	v_fmac_f32_dpp v168, v145, v109 quad_perm:[3,3,3,3] row_mask:0xf bank_mask:0xf
	v_fmac_f32_dpp v169, v146, v110 quad_perm:[3,3,3,3] row_mask:0xf bank_mask:0xf
	v_fmac_f32_dpp v170, v147, v111 quad_perm:[3,3,3,3] row_mask:0xf bank_mask:0xf
	ds_read_b128 v[136:139], v10 offset:13872
	s_waitcnt lgkmcnt(5)
	v_fmac_f32_dpp v113, v148, v112 quad_perm:[0,0,0,0] row_mask:0xf bank_mask:0xf
	v_add_f32_e32 v113, v113, v168
	v_add_f32_e32 v169, v169, v170
	v_add_f32_e32 v113, v113, v169
	ds_read_b128 v[140:143], v10 offset:13936
	s_waitcnt lgkmcnt(5)
	v_mov_b32_e32 v168, 0
	v_mov_b32_e32 v169, 0
	v_mov_b32_e32 v170, 0
	v_fmac_f32_dpp v114, v152, v64 quad_perm:[0,0,0,0] row_mask:0xf bank_mask:0xf
	v_fmac_f32_dpp v168, v153, v65 quad_perm:[0,0,0,0] row_mask:0xf bank_mask:0xf
	v_fmac_f32_dpp v169, v154, v66 quad_perm:[0,0,0,0] row_mask:0xf bank_mask:0xf
	v_fmac_f32_dpp v170, v155, v67 quad_perm:[0,0,0,0] row_mask:0xf bank_mask:0xf
	v_fmac_f32_dpp v114, v152, v68 quad_perm:[1,1,1,1] row_mask:0xf bank_mask:0xf
	v_fmac_f32_dpp v168, v153, v69 quad_perm:[1,1,1,1] row_mask:0xf bank_mask:0xf
	v_fmac_f32_dpp v169, v154, v70 quad_perm:[1,1,1,1] row_mask:0xf bank_mask:0xf
	v_fmac_f32_dpp v170, v155, v71 quad_perm:[1,1,1,1] row_mask:0xf bank_mask:0xf
	v_fmac_f32_dpp v114, v152, v72 quad_perm:[2,2,2,2] row_mask:0xf bank_mask:0xf
	v_fmac_f32_dpp v168, v153, v73 quad_perm:[2,2,2,2] row_mask:0xf bank_mask:0xf
	v_fmac_f32_dpp v169, v154, v74 quad_perm:[2,2,2,2] row_mask:0xf bank_mask:0xf
	v_fmac_f32_dpp v170, v155, v75 quad_perm:[2,2,2,2] row_mask:0xf bank_mask:0xf
	v_fmac_f32_dpp v114, v152, v76 quad_perm:[3,3,3,3] row_mask:0xf bank_mask:0xf
	v_fmac_f32_dpp v168, v153, v77 quad_perm:[3,3,3,3] row_mask:0xf bank_mask:0xf
	v_fmac_f32_dpp v169, v154, v78 quad_perm:[3,3,3,3] row_mask:0xf bank_mask:0xf
	v_fmac_f32_dpp v170, v155, v79 quad_perm:[3,3,3,3] row_mask:0xf bank_mask:0xf
	ds_read_b128 v[144:147], v10 offset:14000
	s_waitcnt lgkmcnt(5)
	v_fmac_f32_dpp v114, v156, v80 quad_perm:[0,0,0,0] row_mask:0xf bank_mask:0xf
	v_fmac_f32_dpp v168, v157, v81 quad_perm:[0,0,0,0] row_mask:0xf bank_mask:0xf
	v_fmac_f32_dpp v169, v158, v82 quad_perm:[0,0,0,0] row_mask:0xf bank_mask:0xf
	v_fmac_f32_dpp v170, v159, v83 quad_perm:[0,0,0,0] row_mask:0xf bank_mask:0xf
	v_fmac_f32_dpp v114, v156, v84 quad_perm:[1,1,1,1] row_mask:0xf bank_mask:0xf
	v_fmac_f32_dpp v168, v157, v85 quad_perm:[1,1,1,1] row_mask:0xf bank_mask:0xf
	v_fmac_f32_dpp v169, v158, v86 quad_perm:[1,1,1,1] row_mask:0xf bank_mask:0xf
	v_fmac_f32_dpp v170, v159, v87 quad_perm:[1,1,1,1] row_mask:0xf bank_mask:0xf
	v_fmac_f32_dpp v114, v156, v88 quad_perm:[2,2,2,2] row_mask:0xf bank_mask:0xf
	v_fmac_f32_dpp v168, v157, v89 quad_perm:[2,2,2,2] row_mask:0xf bank_mask:0xf
	v_fmac_f32_dpp v169, v158, v90 quad_perm:[2,2,2,2] row_mask:0xf bank_mask:0xf
	v_fmac_f32_dpp v170, v159, v91 quad_perm:[2,2,2,2] row_mask:0xf bank_mask:0xf
	v_fmac_f32_dpp v114, v156, v92 quad_perm:[3,3,3,3] row_mask:0xf bank_mask:0xf
	v_fmac_f32_dpp v168, v157, v93 quad_perm:[3,3,3,3] row_mask:0xf bank_mask:0xf
	v_fmac_f32_dpp v169, v158, v94 quad_perm:[3,3,3,3] row_mask:0xf bank_mask:0xf
	v_fmac_f32_dpp v170, v159, v95 quad_perm:[3,3,3,3] row_mask:0xf bank_mask:0xf
	ds_read_b128 v[148:151], v10 offset:14064
	s_waitcnt lgkmcnt(5)
; __device__ void dn_d1(const Ctx& c, int ip) {
;     ...
;     }
;     { const f32x4 m = *(const f32x4*)(mr + 44);
;       a0 -= m[0] * x[44];
;       a1 -= m[1] * x[45];
;       a2 -= m[2] * x[46];
;       a3 -= m[3] * x[47];
;     }
;     { const f32x4 m = *(const f32x4*)(mr + 48);
;       a0 -= m[0] * x[48];
;       a1 -= m[1] * x[49];
;     }
;     SOLVE_ROW_END(50)
;     SOLVE_ROW_BEGIN(51)
;     { const f32x4 m = *(const f32x4*)(mr + 0);
;       a0 -= m[0] * x[0];
;       a1 -= m[1] * x[1];
;       a2 -= m[2] * x[2];
;       a3 -= m[3] * x[3];
;     }
;     { const f32x4 m = *(const f32x4*)(mr + 4);
;       a0 -= m[0] * x[4];
;       a1 -= m[1] * x[5];
;       a2 -= m[2] * x[6];
;       a3 -= m[3] * x[7];
;     }
;     { const f32x4 m = *(const f32x4*)(mr + 8);
;       a0 -= m[0] * x[8];
;       a1 -= m[1] * x[9];
;       a2 -= m[2] * x[10];
;       a3 -= m[3] * x[11];
;     }
;     { const f32x4 m = *(const f32x4*)(mr + 12);
;       a0 -= m[0] * x[12];
;       a1 -= m[1] * x[13];
;       a2 -= m[2] * x[14];
;       a3 -= m[3] * x[15];
;     }
;     { const f32x4 m = *(const f32x4*)(mr + 16);
;       a0 -= m[0] * x[16];
;       a1 -= m[1] * x[17];
;       a2 -= m[2] * x[18];
;       a3 -= m[3] * x[19];
;     }
;     { const f32x4 m = *(const f32x4*)(mr + 20);
;       a0 -= m[0] * x[20];
;       a1 -= m[1] * x[21];
;       a2 -= m[2] * x[22];
;       a3 -= m[3] * x[23];
;     }
;     { const f32x4 m = *(const f32x4*)(mr + 24);
;       a0 -= m[0] * x[24];
;       a1 -= m[1] * x[25];
;       a2 -= m[2] * x[26];
;       a3 -= m[3] * x[27];
;     }
;     { const f32x4 m = *(const f32x4*)(mr + 28);
;       a0 -= m[0] * x[28];
;       a1 -= m[1] * x[29];
;       a2 -= m[2] * x[30];
;       a3 -= m[3] * x[31];
	v_fmac_f32_dpp v114, v160, v96 quad_perm:[0,0,0,0] row_mask:0xf bank_mask:0xf
	v_fmac_f32_dpp v168, v161, v97 quad_perm:[0,0,0,0] row_mask:0xf bank_mask:0xf
	v_fmac_f32_dpp v169, v162, v98 quad_perm:[0,0,0,0] row_mask:0xf bank_mask:0xf
	v_fmac_f32_dpp v170, v163, v99 quad_perm:[0,0,0,0] row_mask:0xf bank_mask:0xf
	v_fmac_f32_dpp v114, v160, v100 quad_perm:[1,1,1,1] row_mask:0xf bank_mask:0xf
	v_fmac_f32_dpp v168, v161, v101 quad_perm:[1,1,1,1] row_mask:0xf bank_mask:0xf
	v_fmac_f32_dpp v169, v162, v102 quad_perm:[1,1,1,1] row_mask:0xf bank_mask:0xf
	v_fmac_f32_dpp v170, v163, v103 quad_perm:[1,1,1,1] row_mask:0xf bank_mask:0xf
	v_fmac_f32_dpp v114, v160, v104 quad_perm:[2,2,2,2] row_mask:0xf bank_mask:0xf
	v_fmac_f32_dpp v168, v161, v105 quad_perm:[2,2,2,2] row_mask:0xf bank_mask:0xf
	v_fmac_f32_dpp v169, v162, v106 quad_perm:[2,2,2,2] row_mask:0xf bank_mask:0xf
	v_fmac_f32_dpp v170, v163, v107 quad_perm:[2,2,2,2] row_mask:0xf bank_mask:0xf
	v_fmac_f32_dpp v114, v160, v108 quad_perm:[3,3,3,3] row_mask:0xf bank_mask:0xf
	v_fmac_f32_dpp v168, v161, v109 quad_perm:[3,3,3,3] row_mask:0xf bank_mask:0xf
	v_fmac_f32_dpp v169, v162, v110 quad_perm:[3,3,3,3] row_mask:0xf bank_mask:0xf
	v_fmac_f32_dpp v170, v163, v111 quad_perm:[3,3,3,3] row_mask:0xf bank_mask:0xf
	ds_read_b128 v[152:155], v10 offset:14144
	s_waitcnt lgkmcnt(5)
	v_fmac_f32_dpp v114, v164, v112 quad_perm:[0,0,0,0] row_mask:0xf bank_mask:0xf
	v_fmac_f32_dpp v168, v165, v113 quad_perm:[0,0,0,0] row_mask:0xf bank_mask:0xf
	v_add_f32_e32 v114, v114, v168
	v_add_f32_e32 v169, v169, v170
	v_add_f32_e32 v114, v114, v169
	ds_read_b128 v[156:159], v10 offset:14208
	s_waitcnt lgkmcnt(5)
	v_mov_b32_e32 v168, 0
	v_mov_b32_e32 v169, 0
	v_mov_b32_e32 v170, 0
	v_fmac_f32_dpp v115, v136, v64 quad_perm:[0,0,0,0] row_mask:0xf bank_mask:0xf
	v_fmac_f32_dpp v168, v137, v65 quad_perm:[0,0,0,0] row_mask:0xf bank_mask:0xf
	v_fmac_f32_dpp v169, v138, v66 quad_perm:[0,0,0,0] row_mask:0xf bank_mask:0xf
	v_fmac_f32_dpp v170, v139, v67 quad_perm:[0,0,0,0] row_mask:0xf bank_mask:0xf
	v_fmac_f32_dpp v115, v136, v68 quad_perm:[1,1,1,1] row_mask:0xf bank_mask:0xf
	v_fmac_f32_dpp v168, v137, v69 quad_perm:[1,1,1,1] row_mask:0xf bank_mask:0xf
	v_fmac_f32_dpp v169, v138, v70 quad_perm:[1,1,1,1] row_mask:0xf bank_mask:0xf
	v_fmac_f32_dpp v170, v139, v71 quad_perm:[1,1,1,1] row_mask:0xf bank_mask:0xf
	v_fmac_f32_dpp v115, v136, v72 quad_perm:[2,2,2,2] row_mask:0xf bank_mask:0xf
	v_fmac_f32_dpp v168, v137, v73 quad_perm:[2,2,2,2] row_mask:0xf bank_mask:0xf
	v_fmac_f32_dpp v169, v138, v74 quad_perm:[2,2,2,2] row_mask:0xf bank_mask:0xf
	v_fmac_f32_dpp v170, v139, v75 quad_perm:[2,2,2,2] row_mask:0xf bank_mask:0xf
	v_fmac_f32_dpp v115, v136, v76 quad_perm:[3,3,3,3] row_mask:0xf bank_mask:0xf
	v_fmac_f32_dpp v168, v137, v77 quad_perm:[3,3,3,3] row_mask:0xf bank_mask:0xf
	v_fmac_f32_dpp v169, v138, v78 quad_perm:[3,3,3,3] row_mask:0xf bank_mask:0xf
	v_fmac_f32_dpp v170, v139, v79 quad_perm:[3,3,3,3] row_mask:0xf bank_mask:0xf
	ds_read_b128 v[160:163], v10 offset:14272
	s_waitcnt lgkmcnt(5)
	v_fmac_f32_dpp v115, v140, v80 quad_perm:[0,0,0,0] row_mask:0xf bank_mask:0xf
	v_fmac_f32_dpp v168, v141, v81 quad_perm:[0,0,0,0] row_mask:0xf bank_mask:0xf
	v_fmac_f32_dpp v169, v142, v82 quad_perm:[0,0,0,0] row_mask:0xf bank_mask:0xf
	v_fmac_f32_dpp v170, v143, v83 quad_perm:[0,0,0,0] row_mask:0xf bank_mask:0xf
	v_fmac_f32_dpp v115, v140, v84 quad_perm:[1,1,1,1] row_mask:0xf bank_mask:0xf
	v_fmac_f32_dpp v168, v141, v85 quad_perm:[1,1,1,1] row_mask:0xf bank_mask:0xf
	v_fmac_f32_dpp v169, v142, v86 quad_perm:[1,1,1,1] row_mask:0xf bank_mask:0xf
	v_fmac_f32_dpp v170, v143, v87 quad_perm:[1,1,1,1] row_mask:0xf bank_mask:0xf
	v_fmac_f32_dpp v115, v140, v88 quad_perm:[2,2,2,2] row_mask:0xf bank_mask:0xf
	v_fmac_f32_dpp v168, v141, v89 quad_perm:[2,2,2,2] row_mask:0xf bank_mask:0xf
	v_fmac_f32_dpp v169, v142, v90 quad_perm:[2,2,2,2] row_mask:0xf bank_mask:0xf
	v_fmac_f32_dpp v170, v143, v91 quad_perm:[2,2,2,2] row_mask:0xf bank_mask:0xf
	v_fmac_f32_dpp v115, v140, v92 quad_perm:[3,3,3,3] row_mask:0xf bank_mask:0xf
	v_fmac_f32_dpp v168, v141, v93 quad_perm:[3,3,3,3] row_mask:0xf bank_mask:0xf
	v_fmac_f32_dpp v169, v142, v94 quad_perm:[3,3,3,3] row_mask:0xf bank_mask:0xf
	v_fmac_f32_dpp v170, v143, v95 quad_perm:[3,3,3,3] row_mask:0xf bank_mask:0xf
	ds_read_b128 v[164:167], v10 offset:14336
	s_waitcnt lgkmcnt(5)
	v_fmac_f32_dpp v115, v144, v96 quad_perm:[0,0,0,0] row_mask:0xf bank_mask:0xf
	v_fmac_f32_dpp v168, v145, v97 quad_perm:[0,0,0,0] row_mask:0xf bank_mask:0xf
	v_fmac_f32_dpp v169, v146, v98 quad_perm:[0,0,0,0] row_mask:0xf bank_mask:0xf
	v_fmac_f32_dpp v170, v147, v99 quad_perm:[0,0,0,0] row_mask:0xf bank_mask:0xf
	v_fmac_f32_dpp v115, v144, v100 quad_perm:[1,1,1,1] row_mask:0xf bank_mask:0xf
	v_fmac_f32_dpp v168, v145, v101 quad_perm:[1,1,1,1] row_mask:0xf bank_mask:0xf
	v_fmac_f32_dpp v169, v146, v102 quad_perm:[1,1,1,1] row_mask:0xf bank_mask:0xf
	v_fmac_f32_dpp v170, v147, v103 quad_perm:[1,1,1,1] row_mask:0xf bank_mask:0xf
	v_fmac_f32_dpp v115, v144, v104 quad_perm:[2,2,2,2] row_mask:0xf bank_mask:0xf
	v_fmac_f32_dpp v168, v145, v105 quad_perm:[2,2,2,2] row_mask:0xf bank_mask:0xf
	v_fmac_f32_dpp v169, v146, v106 quad_perm:[2,2,2,2] row_mask:0xf bank_mask:0xf
	v_fmac_f32_dpp v170, v147, v107 quad_perm:[2,2,2,2] row_mask:0xf bank_mask:0xf
	v_fmac_f32_dpp v115, v144, v108 quad_perm:[3,3,3,3] row_mask:0xf bank_mask:0xf
	v_fmac_f32_dpp v168, v145, v109 quad_perm:[3,3,3,3] row_mask:0xf bank_mask:0xf
	v_fmac_f32_dpp v169, v146, v110 quad_perm:[3,3,3,3] row_mask:0xf bank_mask:0xf
	v_fmac_f32_dpp v170, v147, v111 quad_perm:[3,3,3,3] row_mask:0xf bank_mask:0xf
	ds_read_b128 v[136:139], v10 offset:14416
	s_waitcnt lgkmcnt(5)
; __device__ void dn_d1(const Ctx& c, int ip) {
;     ...
;       a0 -= m[0] * x[44];
;       a1 -= m[1] * x[45];
;       a2 -= m[2] * x[46];
;       a3 -= m[3] * x[47];
;     }
;     { const f32x4 m = *(const f32x4*)(mr + 48);
;       a0 -= m[0] * x[48];
;       a1 -= m[1] * x[49];
;       a2 -= m[2] * x[50];
;     }
;     SOLVE_ROW_END(51)
;     SOLVE_ROW_BEGIN(52)
;     { const f32x4 m = *(const f32x4*)(mr + 0);
;       a0 -= m[0] * x[0];
;       a1 -= m[1] * x[1];
;       a2 -= m[2] * x[2];
;       a3 -= m[3] * x[3];
;     }
;     { const f32x4 m = *(const f32x4*)(mr + 4);
;       a0 -= m[0] * x[4];
;       a1 -= m[1] * x[5];
;       a2 -= m[2] * x[6];
;       a3 -= m[3] * x[7];
;     }
;     { const f32x4 m = *(const f32x4*)(mr + 8);
;       a0 -= m[0] * x[8];
;       a1 -= m[1] * x[9];
;       a2 -= m[2] * x[10];
;       a3 -= m[3] * x[11];
;     }
;     { const f32x4 m = *(const f32x4*)(mr + 12);
;       a0 -= m[0] * x[12];
;       a1 -= m[1] * x[13];
;       a2 -= m[2] * x[14];
;       a3 -= m[3] * x[15];
;     }
;     { const f32x4 m = *(const f32x4*)(mr + 16);
;       a0 -= m[0] * x[16];
;       a1 -= m[1] * x[17];
;       a2 -= m[2] * x[18];
;       a3 -= m[3] * x[19];
;     }
;     { const f32x4 m = *(const f32x4*)(mr + 20);
;       a0 -= m[0] * x[20];
;       a1 -= m[1] * x[21];
;       a2 -= m[2] * x[22];
;       a3 -= m[3] * x[23];
;     }
;     { const f32x4 m = *(const f32x4*)(mr + 24);
;       a0 -= m[0] * x[24];
;       a1 -= m[1] * x[25];
;       a2 -= m[2] * x[26];
;       a3 -= m[3] * x[27];
;     }
;     { const f32x4 m = *(const f32x4*)(mr + 28);
;       a0 -= m[0] * x[28];
;       a1 -= m[1] * x[29];
;       a2 -= m[2] * x[30];
;       a3 -= m[3] * x[31];
;     }
	v_fmac_f32_dpp v115, v148, v112 quad_perm:[0,0,0,0] row_mask:0xf bank_mask:0xf
	v_fmac_f32_dpp v168, v149, v113 quad_perm:[0,0,0,0] row_mask:0xf bank_mask:0xf
	v_fmac_f32_dpp v169, v150, v114 quad_perm:[0,0,0,0] row_mask:0xf bank_mask:0xf
	v_add_f32_e32 v115, v115, v168
	v_add_f32_e32 v169, v169, v170
	v_add_f32_e32 v115, v115, v169
	ds_read_b128 v[140:143], v10 offset:14480
	s_waitcnt lgkmcnt(5)
	v_mov_b32_e32 v168, 0
	v_mov_b32_e32 v169, 0
	v_mov_b32_e32 v170, 0
	v_fmac_f32_dpp v116, v152, v64 quad_perm:[0,0,0,0] row_mask:0xf bank_mask:0xf
	v_fmac_f32_dpp v168, v153, v65 quad_perm:[0,0,0,0] row_mask:0xf bank_mask:0xf
	v_fmac_f32_dpp v169, v154, v66 quad_perm:[0,0,0,0] row_mask:0xf bank_mask:0xf
	v_fmac_f32_dpp v170, v155, v67 quad_perm:[0,0,0,0] row_mask:0xf bank_mask:0xf
	v_fmac_f32_dpp v116, v152, v68 quad_perm:[1,1,1,1] row_mask:0xf bank_mask:0xf
	v_fmac_f32_dpp v168, v153, v69 quad_perm:[1,1,1,1] row_mask:0xf bank_mask:0xf
	v_fmac_f32_dpp v169, v154, v70 quad_perm:[1,1,1,1] row_mask:0xf bank_mask:0xf
	v_fmac_f32_dpp v170, v155, v71 quad_perm:[1,1,1,1] row_mask:0xf bank_mask:0xf
	v_fmac_f32_dpp v116, v152, v72 quad_perm:[2,2,2,2] row_mask:0xf bank_mask:0xf
	v_fmac_f32_dpp v168, v153, v73 quad_perm:[2,2,2,2] row_mask:0xf bank_mask:0xf
	v_fmac_f32_dpp v169, v154, v74 quad_perm:[2,2,2,2] row_mask:0xf bank_mask:0xf
	v_fmac_f32_dpp v170, v155, v75 quad_perm:[2,2,2,2] row_mask:0xf bank_mask:0xf
	v_fmac_f32_dpp v116, v152, v76 quad_perm:[3,3,3,3] row_mask:0xf bank_mask:0xf
	v_fmac_f32_dpp v168, v153, v77 quad_perm:[3,3,3,3] row_mask:0xf bank_mask:0xf
	v_fmac_f32_dpp v169, v154, v78 quad_perm:[3,3,3,3] row_mask:0xf bank_mask:0xf
	v_fmac_f32_dpp v170, v155, v79 quad_perm:[3,3,3,3] row_mask:0xf bank_mask:0xf
	ds_read_b128 v[144:147], v10 offset:14544
	s_waitcnt lgkmcnt(5)
	v_fmac_f32_dpp v116, v156, v80 quad_perm:[0,0,0,0] row_mask:0xf bank_mask:0xf
	v_fmac_f32_dpp v168, v157, v81 quad_perm:[0,0,0,0] row_mask:0xf bank_mask:0xf
	v_fmac_f32_dpp v169, v158, v82 quad_perm:[0,0,0,0] row_mask:0xf bank_mask:0xf
	v_fmac_f32_dpp v170, v159, v83 quad_perm:[0,0,0,0] row_mask:0xf bank_mask:0xf
	v_fmac_f32_dpp v116, v156, v84 quad_perm:[1,1,1,1] row_mask:0xf bank_mask:0xf
	v_fmac_f32_dpp v168, v157, v85 quad_perm:[1,1,1,1] row_mask:0xf bank_mask:0xf
	v_fmac_f32_dpp v169, v158, v86 quad_perm:[1,1,1,1] row_mask:0xf bank_mask:0xf
	v_fmac_f32_dpp v170, v159, v87 quad_perm:[1,1,1,1] row_mask:0xf bank_mask:0xf
	v_fmac_f32_dpp v116, v156, v88 quad_perm:[2,2,2,2] row_mask:0xf bank_mask:0xf
	v_fmac_f32_dpp v168, v157, v89 quad_perm:[2,2,2,2] row_mask:0xf bank_mask:0xf
	v_fmac_f32_dpp v169, v158, v90 quad_perm:[2,2,2,2] row_mask:0xf bank_mask:0xf
	v_fmac_f32_dpp v170, v159, v91 quad_perm:[2,2,2,2] row_mask:0xf bank_mask:0xf
	v_fmac_f32_dpp v116, v156, v92 quad_perm:[3,3,3,3] row_mask:0xf bank_mask:0xf
	v_fmac_f32_dpp v168, v157, v93 quad_perm:[3,3,3,3] row_mask:0xf bank_mask:0xf
	v_fmac_f32_dpp v169, v158, v94 quad_perm:[3,3,3,3] row_mask:0xf bank_mask:0xf
	v_fmac_f32_dpp v170, v159, v95 quad_perm:[3,3,3,3] row_mask:0xf bank_mask:0xf
	ds_read_b128 v[148:151], v10 offset:14608
	s_waitcnt lgkmcnt(5)
	v_fmac_f32_dpp v116, v160, v96 quad_perm:[0,0,0,0] row_mask:0xf bank_mask:0xf
	v_fmac_f32_dpp v168, v161, v97 quad_perm:[0,0,0,0] row_mask:0xf bank_mask:0xf
	v_fmac_f32_dpp v169, v162, v98 quad_perm:[0,0,0,0] row_mask:0xf bank_mask:0xf
	v_fmac_f32_dpp v170, v163, v99 quad_perm:[0,0,0,0] row_mask:0xf bank_mask:0xf
	v_fmac_f32_dpp v116, v160, v100 quad_perm:[1,1,1,1] row_mask:0xf bank_mask:0xf
	v_fmac_f32_dpp v168, v161, v101 quad_perm:[1,1,1,1] row_mask:0xf bank_mask:0xf
	v_fmac_f32_dpp v169, v162, v102 quad_perm:[1,1,1,1] row_mask:0xf bank_mask:0xf
	v_fmac_f32_dpp v170, v163, v103 quad_perm:[1,1,1,1] row_mask:0xf bank_mask:0xf
	v_fmac_f32_dpp v116, v160, v104 quad_perm:[2,2,2,2] row_mask:0xf bank_mask:0xf
	v_fmac_f32_dpp v168, v161, v105 quad_perm:[2,2,2,2] row_mask:0xf bank_mask:0xf
	v_fmac_f32_dpp v169, v162, v106 quad_perm:[2,2,2,2] row_mask:0xf bank_mask:0xf
	v_fmac_f32_dpp v170, v163, v107 quad_perm:[2,2,2,2] row_mask:0xf bank_mask:0xf
	v_fmac_f32_dpp v116, v160, v108 quad_perm:[3,3,3,3] row_mask:0xf bank_mask:0xf
	v_fmac_f32_dpp v168, v161, v109 quad_perm:[3,3,3,3] row_mask:0xf bank_mask:0xf
	v_fmac_f32_dpp v169, v162, v110 quad_perm:[3,3,3,3] row_mask:0xf bank_mask:0xf
	v_fmac_f32_dpp v170, v163, v111 quad_perm:[3,3,3,3] row_mask:0xf bank_mask:0xf
	ds_read_b128 v[152:155], v10 offset:14688
	s_waitcnt lgkmcnt(5)
	v_fmac_f32_dpp v116, v164, v112 quad_perm:[0,0,0,0] row_mask:0xf bank_mask:0xf
	v_fmac_f32_dpp v168, v165, v113 quad_perm:[0,0,0,0] row_mask:0xf bank_mask:0xf
	v_fmac_f32_dpp v169, v166, v114 quad_perm:[0,0,0,0] row_mask:0xf bank_mask:0xf
	v_fmac_f32_dpp v170, v167, v115 quad_perm:[0,0,0,0] row_mask:0xf bank_mask:0xf
	v_add_f32_e32 v116, v116, v168
	v_add_f32_e32 v169, v169, v170
	v_add_f32_e32 v116, v116, v169
	ds_read_b128 v[156:159], v10 offset:14752
	s_waitcnt lgkmcnt(5)
; __device__ void dn_d1(const Ctx& c, int ip) {
;     ...
;     SOLVE_ROW_BEGIN(53)
;     { const f32x4 m = *(const f32x4*)(mr + 0);
;       a0 -= m[0] * x[0];
;       a1 -= m[1] * x[1];
;       a2 -= m[2] * x[2];
;       a3 -= m[3] * x[3];
;     }
;     { const f32x4 m = *(const f32x4*)(mr + 4);
;       a0 -= m[0] * x[4];
;       a1 -= m[1] * x[5];
;       a2 -= m[2] * x[6];
;       a3 -= m[3] * x[7];
;     }
;     { const f32x4 m = *(const f32x4*)(mr + 8);
;       a0 -= m[0] * x[8];
;       a1 -= m[1] * x[9];
;       a2 -= m[2] * x[10];
;       a3 -= m[3] * x[11];
;     }
;     { const f32x4 m = *(const f32x4*)(mr + 12);
;       a0 -= m[0] * x[12];
;       a1 -= m[1] * x[13];
;       a2 -= m[2] * x[14];
;       a3 -= m[3] * x[15];
;     }
;     { const f32x4 m = *(const f32x4*)(mr + 16);
;       a0 -= m[0] * x[16];
;       a1 -= m[1] * x[17];
;       a2 -= m[2] * x[18];
;       a3 -= m[3] * x[19];
;     }
;     { const f32x4 m = *(const f32x4*)(mr + 20);
;       a0 -= m[0] * x[20];
;       a1 -= m[1] * x[21];
;       a2 -= m[2] * x[22];
;       a3 -= m[3] * x[23];
;     }
;     { const f32x4 m = *(const f32x4*)(mr + 24);
;       a0 -= m[0] * x[24];
;       a1 -= m[1] * x[25];
;       a2 -= m[2] * x[26];
;       a3 -= m[3] * x[27];
;     }
;     { const f32x4 m = *(const f32x4*)(mr + 28);
;       a0 -= m[0] * x[28];
;       a1 -= m[1] * x[29];
;       a2 -= m[2] * x[30];
;       a3 -= m[3] * x[31];
;     }
;     { const f32x4 m = *(const f32x4*)(mr + 32);
;       a0 -= m[0] * x[32];
;       a1 -= m[1] * x[33];
;       a2 -= m[2] * x[34];
;       a3 -= m[3] * x[35];
;     }
;     { const f32x4 m = *(const f32x4*)(mr + 36);
;       a0 -= m[0] * x[36];
;       a1 -= m[1] * x[37];
;       a2 -= m[2] * x[38];
;       a3 -= m[3] * x[39];
	v_mov_b32_e32 v168, 0
	v_mov_b32_e32 v169, 0
	v_mov_b32_e32 v170, 0
	v_fmac_f32_dpp v117, v136, v64 quad_perm:[0,0,0,0] row_mask:0xf bank_mask:0xf
	v_fmac_f32_dpp v168, v137, v65 quad_perm:[0,0,0,0] row_mask:0xf bank_mask:0xf
	v_fmac_f32_dpp v169, v138, v66 quad_perm:[0,0,0,0] row_mask:0xf bank_mask:0xf
	v_fmac_f32_dpp v170, v139, v67 quad_perm:[0,0,0,0] row_mask:0xf bank_mask:0xf
	v_fmac_f32_dpp v117, v136, v68 quad_perm:[1,1,1,1] row_mask:0xf bank_mask:0xf
	v_fmac_f32_dpp v168, v137, v69 quad_perm:[1,1,1,1] row_mask:0xf bank_mask:0xf
	v_fmac_f32_dpp v169, v138, v70 quad_perm:[1,1,1,1] row_mask:0xf bank_mask:0xf
	v_fmac_f32_dpp v170, v139, v71 quad_perm:[1,1,1,1] row_mask:0xf bank_mask:0xf
	v_fmac_f32_dpp v117, v136, v72 quad_perm:[2,2,2,2] row_mask:0xf bank_mask:0xf
	v_fmac_f32_dpp v168, v137, v73 quad_perm:[2,2,2,2] row_mask:0xf bank_mask:0xf
	v_fmac_f32_dpp v169, v138, v74 quad_perm:[2,2,2,2] row_mask:0xf bank_mask:0xf
	v_fmac_f32_dpp v170, v139, v75 quad_perm:[2,2,2,2] row_mask:0xf bank_mask:0xf
	v_fmac_f32_dpp v117, v136, v76 quad_perm:[3,3,3,3] row_mask:0xf bank_mask:0xf
	v_fmac_f32_dpp v168, v137, v77 quad_perm:[3,3,3,3] row_mask:0xf bank_mask:0xf
	v_fmac_f32_dpp v169, v138, v78 quad_perm:[3,3,3,3] row_mask:0xf bank_mask:0xf
	v_fmac_f32_dpp v170, v139, v79 quad_perm:[3,3,3,3] row_mask:0xf bank_mask:0xf
	ds_read_b128 v[160:163], v10 offset:14816
	s_waitcnt lgkmcnt(5)
	v_fmac_f32_dpp v117, v140, v80 quad_perm:[0,0,0,0] row_mask:0xf bank_mask:0xf
	v_fmac_f32_dpp v168, v141, v81 quad_perm:[0,0,0,0] row_mask:0xf bank_mask:0xf
	v_fmac_f32_dpp v169, v142, v82 quad_perm:[0,0,0,0] row_mask:0xf bank_mask:0xf
	v_fmac_f32_dpp v170, v143, v83 quad_perm:[0,0,0,0] row_mask:0xf bank_mask:0xf
	v_fmac_f32_dpp v117, v140, v84 quad_perm:[1,1,1,1] row_mask:0xf bank_mask:0xf
	v_fmac_f32_dpp v168, v141, v85 quad_perm:[1,1,1,1] row_mask:0xf bank_mask:0xf
	v_fmac_f32_dpp v169, v142, v86 quad_perm:[1,1,1,1] row_mask:0xf bank_mask:0xf
	v_fmac_f32_dpp v170, v143, v87 quad_perm:[1,1,1,1] row_mask:0xf bank_mask:0xf
	v_fmac_f32_dpp v117, v140, v88 quad_perm:[2,2,2,2] row_mask:0xf bank_mask:0xf
	v_fmac_f32_dpp v168, v141, v89 quad_perm:[2,2,2,2] row_mask:0xf bank_mask:0xf
	v_fmac_f32_dpp v169, v142, v90 quad_perm:[2,2,2,2] row_mask:0xf bank_mask:0xf
	v_fmac_f32_dpp v170, v143, v91 quad_perm:[2,2,2,2] row_mask:0xf bank_mask:0xf
	v_fmac_f32_dpp v117, v140, v92 quad_perm:[3,3,3,3] row_mask:0xf bank_mask:0xf
	v_fmac_f32_dpp v168, v141, v93 quad_perm:[3,3,3,3] row_mask:0xf bank_mask:0xf
	v_fmac_f32_dpp v169, v142, v94 quad_perm:[3,3,3,3] row_mask:0xf bank_mask:0xf
	v_fmac_f32_dpp v170, v143, v95 quad_perm:[3,3,3,3] row_mask:0xf bank_mask:0xf
	ds_read_b128 v[164:167], v10 offset:14880
	s_waitcnt lgkmcnt(5)
	v_fmac_f32_dpp v117, v144, v96 quad_perm:[0,0,0,0] row_mask:0xf bank_mask:0xf
	v_fmac_f32_dpp v168, v145, v97 quad_perm:[0,0,0,0] row_mask:0xf bank_mask:0xf
	v_fmac_f32_dpp v169, v146, v98 quad_perm:[0,0,0,0] row_mask:0xf bank_mask:0xf
	v_fmac_f32_dpp v170, v147, v99 quad_perm:[0,0,0,0] row_mask:0xf bank_mask:0xf
	v_fmac_f32_dpp v117, v144, v100 quad_perm:[1,1,1,1] row_mask:0xf bank_mask:0xf
	v_fmac_f32_dpp v168, v145, v101 quad_perm:[1,1,1,1] row_mask:0xf bank_mask:0xf
	v_fmac_f32_dpp v169, v146, v102 quad_perm:[1,1,1,1] row_mask:0xf bank_mask:0xf
	v_fmac_f32_dpp v170, v147, v103 quad_perm:[1,1,1,1] row_mask:0xf bank_mask:0xf
	v_fmac_f32_dpp v117, v144, v104 quad_perm:[2,2,2,2] row_mask:0xf bank_mask:0xf
	v_fmac_f32_dpp v168, v145, v105 quad_perm:[2,2,2,2] row_mask:0xf bank_mask:0xf
	v_fmac_f32_dpp v169, v146, v106 quad_perm:[2,2,2,2] row_mask:0xf bank_mask:0xf
	v_fmac_f32_dpp v170, v147, v107 quad_perm:[2,2,2,2] row_mask:0xf bank_mask:0xf
	v_fmac_f32_dpp v117, v144, v108 quad_perm:[3,3,3,3] row_mask:0xf bank_mask:0xf
	v_fmac_f32_dpp v168, v145, v109 quad_perm:[3,3,3,3] row_mask:0xf bank_mask:0xf
	v_fmac_f32_dpp v169, v146, v110 quad_perm:[3,3,3,3] row_mask:0xf bank_mask:0xf
	v_fmac_f32_dpp v170, v147, v111 quad_perm:[3,3,3,3] row_mask:0xf bank_mask:0xf
	ds_read_b128 v[136:139], v10 offset:14960
	s_waitcnt lgkmcnt(5)
	v_fmac_f32_dpp v117, v148, v112 quad_perm:[0,0,0,0] row_mask:0xf bank_mask:0xf
	v_fmac_f32_dpp v168, v149, v113 quad_perm:[0,0,0,0] row_mask:0xf bank_mask:0xf
	v_fmac_f32_dpp v169, v150, v114 quad_perm:[0,0,0,0] row_mask:0xf bank_mask:0xf
	v_fmac_f32_dpp v170, v151, v115 quad_perm:[0,0,0,0] row_mask:0xf bank_mask:0xf
	v_fmac_f32_dpp v117, v148, v116 quad_perm:[1,1,1,1] row_mask:0xf bank_mask:0xf
	v_add_f32_e32 v117, v117, v168
	v_add_f32_e32 v169, v169, v170
	v_add_f32_e32 v117, v117, v169
	ds_read_b128 v[140:143], v10 offset:15024
	s_waitcnt lgkmcnt(5)
	v_mov_b32_e32 v168, 0
	v_mov_b32_e32 v169, 0
	v_mov_b32_e32 v170, 0
	v_fmac_f32_dpp v118, v152, v64 quad_perm:[0,0,0,0] row_mask:0xf bank_mask:0xf
	v_fmac_f32_dpp v168, v153, v65 quad_perm:[0,0,0,0] row_mask:0xf bank_mask:0xf
	v_fmac_f32_dpp v169, v154, v66 quad_perm:[0,0,0,0] row_mask:0xf bank_mask:0xf
	v_fmac_f32_dpp v170, v155, v67 quad_perm:[0,0,0,0] row_mask:0xf bank_mask:0xf
	v_fmac_f32_dpp v118, v152, v68 quad_perm:[1,1,1,1] row_mask:0xf bank_mask:0xf
	v_fmac_f32_dpp v168, v153, v69 quad_perm:[1,1,1,1] row_mask:0xf bank_mask:0xf
	v_fmac_f32_dpp v169, v154, v70 quad_perm:[1,1,1,1] row_mask:0xf bank_mask:0xf
	v_fmac_f32_dpp v170, v155, v71 quad_perm:[1,1,1,1] row_mask:0xf bank_mask:0xf
	v_fmac_f32_dpp v118, v152, v72 quad_perm:[2,2,2,2] row_mask:0xf bank_mask:0xf
	v_fmac_f32_dpp v168, v153, v73 quad_perm:[2,2,2,2] row_mask:0xf bank_mask:0xf
	v_fmac_f32_dpp v169, v154, v74 quad_perm:[2,2,2,2] row_mask:0xf bank_mask:0xf
	v_fmac_f32_dpp v170, v155, v75 quad_perm:[2,2,2,2] row_mask:0xf bank_mask:0xf
	v_fmac_f32_dpp v118, v152, v76 quad_perm:[3,3,3,3] row_mask:0xf bank_mask:0xf
	v_fmac_f32_dpp v168, v153, v77 quad_perm:[3,3,3,3] row_mask:0xf bank_mask:0xf
	v_fmac_f32_dpp v169, v154, v78 quad_perm:[3,3,3,3] row_mask:0xf bank_mask:0xf
	v_fmac_f32_dpp v170, v155, v79 quad_perm:[3,3,3,3] row_mask:0xf bank_mask:0xf
	ds_read_b128 v[144:147], v10 offset:15088
	s_waitcnt lgkmcnt(5)
; __device__ void dn_d1(const Ctx& c, int ip) {
;     ...
;     SOLVE_ROW_BEGIN(54)
;     { const f32x4 m = *(const f32x4*)(mr + 0);
;       a0 -= m[0] * x[0];
;       a1 -= m[1] * x[1];
;       a2 -= m[2] * x[2];
;       a3 -= m[3] * x[3];
;     }
;     { const f32x4 m = *(const f32x4*)(mr + 4);
;       a0 -= m[0] * x[4];
;       a1 -= m[1] * x[5];
;       a2 -= m[2] * x[6];
;       a3 -= m[3] * x[7];
;     }
;     { const f32x4 m = *(const f32x4*)(mr + 8);
;       a0 -= m[0] * x[8];
;       a1 -= m[1] * x[9];
;       a2 -= m[2] * x[10];
;       a3 -= m[3] * x[11];
;     }
;     { const f32x4 m = *(const f32x4*)(mr + 12);
;       a0 -= m[0] * x[12];
;       a1 -= m[1] * x[13];
;       a2 -= m[2] * x[14];
;       a3 -= m[3] * x[15];
;     }
;     { const f32x4 m = *(const f32x4*)(mr + 16);
;       a0 -= m[0] * x[16];
;       a1 -= m[1] * x[17];
;       a2 -= m[2] * x[18];
;       a3 -= m[3] * x[19];
;     }
;     { const f32x4 m = *(const f32x4*)(mr + 20);
;       a0 -= m[0] * x[20];
;       a1 -= m[1] * x[21];
;       a2 -= m[2] * x[22];
;       a3 -= m[3] * x[23];
;     }
;     { const f32x4 m = *(const f32x4*)(mr + 24);
;       a0 -= m[0] * x[24];
;       a1 -= m[1] * x[25];
;       a2 -= m[2] * x[26];
;       a3 -= m[3] * x[27];
;     }
;     { const f32x4 m = *(const f32x4*)(mr + 28);
;       a0 -= m[0] * x[28];
;       a1 -= m[1] * x[29];
;       a2 -= m[2] * x[30];
;       a3 -= m[3] * x[31];
;     }
;     { const f32x4 m = *(const f32x4*)(mr + 32);
;       a0 -= m[0] * x[32];
;       a1 -= m[1] * x[33];
;       a2 -= m[2] * x[34];
;       a3 -= m[3] * x[35];
;     }
;     { const f32x4 m = *(const f32x4*)(mr + 36);
;       a0 -= m[0] * x[36];
;       a1 -= m[1] * x[37];
;       a2 -= m[2] * x[38];
;       a3 -= m[3] * x[39];
	v_fmac_f32_dpp v118, v156, v80 quad_perm:[0,0,0,0] row_mask:0xf bank_mask:0xf
	v_fmac_f32_dpp v168, v157, v81 quad_perm:[0,0,0,0] row_mask:0xf bank_mask:0xf
	v_fmac_f32_dpp v169, v158, v82 quad_perm:[0,0,0,0] row_mask:0xf bank_mask:0xf
	v_fmac_f32_dpp v170, v159, v83 quad_perm:[0,0,0,0] row_mask:0xf bank_mask:0xf
	v_fmac_f32_dpp v118, v156, v84 quad_perm:[1,1,1,1] row_mask:0xf bank_mask:0xf
	v_fmac_f32_dpp v168, v157, v85 quad_perm:[1,1,1,1] row_mask:0xf bank_mask:0xf
	v_fmac_f32_dpp v169, v158, v86 quad_perm:[1,1,1,1] row_mask:0xf bank_mask:0xf
	v_fmac_f32_dpp v170, v159, v87 quad_perm:[1,1,1,1] row_mask:0xf bank_mask:0xf
	v_fmac_f32_dpp v118, v156, v88 quad_perm:[2,2,2,2] row_mask:0xf bank_mask:0xf
	v_fmac_f32_dpp v168, v157, v89 quad_perm:[2,2,2,2] row_mask:0xf bank_mask:0xf
	v_fmac_f32_dpp v169, v158, v90 quad_perm:[2,2,2,2] row_mask:0xf bank_mask:0xf
	v_fmac_f32_dpp v170, v159, v91 quad_perm:[2,2,2,2] row_mask:0xf bank_mask:0xf
	v_fmac_f32_dpp v118, v156, v92 quad_perm:[3,3,3,3] row_mask:0xf bank_mask:0xf
	v_fmac_f32_dpp v168, v157, v93 quad_perm:[3,3,3,3] row_mask:0xf bank_mask:0xf
	v_fmac_f32_dpp v169, v158, v94 quad_perm:[3,3,3,3] row_mask:0xf bank_mask:0xf
	v_fmac_f32_dpp v170, v159, v95 quad_perm:[3,3,3,3] row_mask:0xf bank_mask:0xf
	ds_read_b128 v[148:151], v10 offset:15152
	s_waitcnt lgkmcnt(5)
	v_fmac_f32_dpp v118, v160, v96 quad_perm:[0,0,0,0] row_mask:0xf bank_mask:0xf
	v_fmac_f32_dpp v168, v161, v97 quad_perm:[0,0,0,0] row_mask:0xf bank_mask:0xf
	v_fmac_f32_dpp v169, v162, v98 quad_perm:[0,0,0,0] row_mask:0xf bank_mask:0xf
	v_fmac_f32_dpp v170, v163, v99 quad_perm:[0,0,0,0] row_mask:0xf bank_mask:0xf
	v_fmac_f32_dpp v118, v160, v100 quad_perm:[1,1,1,1] row_mask:0xf bank_mask:0xf
	v_fmac_f32_dpp v168, v161, v101 quad_perm:[1,1,1,1] row_mask:0xf bank_mask:0xf
	v_fmac_f32_dpp v169, v162, v102 quad_perm:[1,1,1,1] row_mask:0xf bank_mask:0xf
	v_fmac_f32_dpp v170, v163, v103 quad_perm:[1,1,1,1] row_mask:0xf bank_mask:0xf
	v_fmac_f32_dpp v118, v160, v104 quad_perm:[2,2,2,2] row_mask:0xf bank_mask:0xf
	v_fmac_f32_dpp v168, v161, v105 quad_perm:[2,2,2,2] row_mask:0xf bank_mask:0xf
	v_fmac_f32_dpp v169, v162, v106 quad_perm:[2,2,2,2] row_mask:0xf bank_mask:0xf
	v_fmac_f32_dpp v170, v163, v107 quad_perm:[2,2,2,2] row_mask:0xf bank_mask:0xf
	v_fmac_f32_dpp v118, v160, v108 quad_perm:[3,3,3,3] row_mask:0xf bank_mask:0xf
	v_fmac_f32_dpp v168, v161, v109 quad_perm:[3,3,3,3] row_mask:0xf bank_mask:0xf
	v_fmac_f32_dpp v169, v162, v110 quad_perm:[3,3,3,3] row_mask:0xf bank_mask:0xf
	v_fmac_f32_dpp v170, v163, v111 quad_perm:[3,3,3,3] row_mask:0xf bank_mask:0xf
	ds_read_b128 v[152:155], v10 offset:15232
	s_waitcnt lgkmcnt(5)
	v_fmac_f32_dpp v118, v164, v112 quad_perm:[0,0,0,0] row_mask:0xf bank_mask:0xf
	v_fmac_f32_dpp v168, v165, v113 quad_perm:[0,0,0,0] row_mask:0xf bank_mask:0xf
	v_fmac_f32_dpp v169, v166, v114 quad_perm:[0,0,0,0] row_mask:0xf bank_mask:0xf
	v_fmac_f32_dpp v170, v167, v115 quad_perm:[0,0,0,0] row_mask:0xf bank_mask:0xf
	v_fmac_f32_dpp v118, v164, v116 quad_perm:[1,1,1,1] row_mask:0xf bank_mask:0xf
	v_fmac_f32_dpp v168, v165, v117 quad_perm:[1,1,1,1] row_mask:0xf bank_mask:0xf
	v_add_f32_e32 v118, v118, v168
	v_add_f32_e32 v169, v169, v170
	v_add_f32_e32 v118, v118, v169
	ds_read_b128 v[156:159], v10 offset:15296
	s_waitcnt lgkmcnt(5)
	v_mov_b32_e32 v168, 0
	v_mov_b32_e32 v169, 0
	v_mov_b32_e32 v170, 0
	v_fmac_f32_dpp v119, v136, v64 quad_perm:[0,0,0,0] row_mask:0xf bank_mask:0xf
	v_fmac_f32_dpp v168, v137, v65 quad_perm:[0,0,0,0] row_mask:0xf bank_mask:0xf
	v_fmac_f32_dpp v169, v138, v66 quad_perm:[0,0,0,0] row_mask:0xf bank_mask:0xf
	v_fmac_f32_dpp v170, v139, v67 quad_perm:[0,0,0,0] row_mask:0xf bank_mask:0xf
	v_fmac_f32_dpp v119, v136, v68 quad_perm:[1,1,1,1] row_mask:0xf bank_mask:0xf
	v_fmac_f32_dpp v168, v137, v69 quad_perm:[1,1,1,1] row_mask:0xf bank_mask:0xf
	v_fmac_f32_dpp v169, v138, v70 quad_perm:[1,1,1,1] row_mask:0xf bank_mask:0xf
	v_fmac_f32_dpp v170, v139, v71 quad_perm:[1,1,1,1] row_mask:0xf bank_mask:0xf
	v_fmac_f32_dpp v119, v136, v72 quad_perm:[2,2,2,2] row_mask:0xf bank_mask:0xf
	v_fmac_f32_dpp v168, v137, v73 quad_perm:[2,2,2,2] row_mask:0xf bank_mask:0xf
	v_fmac_f32_dpp v169, v138, v74 quad_perm:[2,2,2,2] row_mask:0xf bank_mask:0xf
	v_fmac_f32_dpp v170, v139, v75 quad_perm:[2,2,2,2] row_mask:0xf bank_mask:0xf
	v_fmac_f32_dpp v119, v136, v76 quad_perm:[3,3,3,3] row_mask:0xf bank_mask:0xf
	v_fmac_f32_dpp v168, v137, v77 quad_perm:[3,3,3,3] row_mask:0xf bank_mask:0xf
	v_fmac_f32_dpp v169, v138, v78 quad_perm:[3,3,3,3] row_mask:0xf bank_mask:0xf
	v_fmac_f32_dpp v170, v139, v79 quad_perm:[3,3,3,3] row_mask:0xf bank_mask:0xf
	ds_read_b128 v[160:163], v10 offset:15360
	s_waitcnt lgkmcnt(5)
	v_fmac_f32_dpp v119, v140, v80 quad_perm:[0,0,0,0] row_mask:0xf bank_mask:0xf
	v_fmac_f32_dpp v168, v141, v81 quad_perm:[0,0,0,0] row_mask:0xf bank_mask:0xf
	v_fmac_f32_dpp v169, v142, v82 quad_perm:[0,0,0,0] row_mask:0xf bank_mask:0xf
	v_fmac_f32_dpp v170, v143, v83 quad_perm:[0,0,0,0] row_mask:0xf bank_mask:0xf
	v_fmac_f32_dpp v119, v140, v84 quad_perm:[1,1,1,1] row_mask:0xf bank_mask:0xf
	v_fmac_f32_dpp v168, v141, v85 quad_perm:[1,1,1,1] row_mask:0xf bank_mask:0xf
	v_fmac_f32_dpp v169, v142, v86 quad_perm:[1,1,1,1] row_mask:0xf bank_mask:0xf
	v_fmac_f32_dpp v170, v143, v87 quad_perm:[1,1,1,1] row_mask:0xf bank_mask:0xf
	v_fmac_f32_dpp v119, v140, v88 quad_perm:[2,2,2,2] row_mask:0xf bank_mask:0xf
	v_fmac_f32_dpp v168, v141, v89 quad_perm:[2,2,2,2] row_mask:0xf bank_mask:0xf
	v_fmac_f32_dpp v169, v142, v90 quad_perm:[2,2,2,2] row_mask:0xf bank_mask:0xf
	v_fmac_f32_dpp v170, v143, v91 quad_perm:[2,2,2,2] row_mask:0xf bank_mask:0xf
	v_fmac_f32_dpp v119, v140, v92 quad_perm:[3,3,3,3] row_mask:0xf bank_mask:0xf
	v_fmac_f32_dpp v168, v141, v93 quad_perm:[3,3,3,3] row_mask:0xf bank_mask:0xf
	v_fmac_f32_dpp v169, v142, v94 quad_perm:[3,3,3,3] row_mask:0xf bank_mask:0xf
	v_fmac_f32_dpp v170, v143, v95 quad_perm:[3,3,3,3] row_mask:0xf bank_mask:0xf
	ds_read_b128 v[164:167], v10 offset:15424
	s_waitcnt lgkmcnt(5)
; __device__ void dn_d1(const Ctx& c, int ip) {
;     ...
;       a2 -= m[2] * x[14];
;       a3 -= m[3] * x[15];
;     }
;     { const f32x4 m = *(const f32x4*)(mr + 16);
;       a0 -= m[0] * x[16];
;       a1 -= m[1] * x[17];
;       a2 -= m[2] * x[18];
;       a3 -= m[3] * x[19];
;     }
;     { const f32x4 m = *(const f32x4*)(mr + 20);
;       a0 -= m[0] * x[20];
;       a1 -= m[1] * x[21];
;       a2 -= m[2] * x[22];
;       a3 -= m[3] * x[23];
;     }
;     { const f32x4 m = *(const f32x4*)(mr + 24);
;       a0 -= m[0] * x[24];
;       a1 -= m[1] * x[25];
;       a2 -= m[2] * x[26];
;       a3 -= m[3] * x[27];
;     }
;     { const f32x4 m = *(const f32x4*)(mr + 28);
;       a0 -= m[0] * x[28];
;       a1 -= m[1] * x[29];
;       a2 -= m[2] * x[30];
;       a3 -= m[3] * x[31];
;     }
;     { const f32x4 m = *(const f32x4*)(mr + 32);
;       a0 -= m[0] * x[32];
;       a1 -= m[1] * x[33];
;       a2 -= m[2] * x[34];
;       a3 -= m[3] * x[35];
;     }
;     { const f32x4 m = *(const f32x4*)(mr + 36);
;       a0 -= m[0] * x[36];
;       a1 -= m[1] * x[37];
;       a2 -= m[2] * x[38];
;       a3 -= m[3] * x[39];
;     }
;     { const f32x4 m = *(const f32x4*)(mr + 40);
;       a0 -= m[0] * x[40];
;       a1 -= m[1] * x[41];
;       a2 -= m[2] * x[42];
;       a3 -= m[3] * x[43];
;     }
;     { const f32x4 m = *(const f32x4*)(mr + 44);
;       a0 -= m[0] * x[44];
;       a1 -= m[1] * x[45];
;       a2 -= m[2] * x[46];
;       a3 -= m[3] * x[47];
;     }
;     { const f32x4 m = *(const f32x4*)(mr + 48);
;       a0 -= m[0] * x[48];
;       a1 -= m[1] * x[49];
;       a2 -= m[2] * x[50];
;       a3 -= m[3] * x[51];
;     }
;     { const f32x4 m = *(const f32x4*)(mr + 52);
;       a0 -= m[0] * x[52];
;       a1 -= m[1] * x[53];
	v_fmac_f32_dpp v119, v144, v96 quad_perm:[0,0,0,0] row_mask:0xf bank_mask:0xf
	v_fmac_f32_dpp v168, v145, v97 quad_perm:[0,0,0,0] row_mask:0xf bank_mask:0xf
	v_fmac_f32_dpp v169, v146, v98 quad_perm:[0,0,0,0] row_mask:0xf bank_mask:0xf
	v_fmac_f32_dpp v170, v147, v99 quad_perm:[0,0,0,0] row_mask:0xf bank_mask:0xf
	v_fmac_f32_dpp v119, v144, v100 quad_perm:[1,1,1,1] row_mask:0xf bank_mask:0xf
	v_fmac_f32_dpp v168, v145, v101 quad_perm:[1,1,1,1] row_mask:0xf bank_mask:0xf
	v_fmac_f32_dpp v169, v146, v102 quad_perm:[1,1,1,1] row_mask:0xf bank_mask:0xf
	v_fmac_f32_dpp v170, v147, v103 quad_perm:[1,1,1,1] row_mask:0xf bank_mask:0xf
	v_fmac_f32_dpp v119, v144, v104 quad_perm:[2,2,2,2] row_mask:0xf bank_mask:0xf
	v_fmac_f32_dpp v168, v145, v105 quad_perm:[2,2,2,2] row_mask:0xf bank_mask:0xf
	v_fmac_f32_dpp v169, v146, v106 quad_perm:[2,2,2,2] row_mask:0xf bank_mask:0xf
	v_fmac_f32_dpp v170, v147, v107 quad_perm:[2,2,2,2] row_mask:0xf bank_mask:0xf
	v_fmac_f32_dpp v119, v144, v108 quad_perm:[3,3,3,3] row_mask:0xf bank_mask:0xf
	v_fmac_f32_dpp v168, v145, v109 quad_perm:[3,3,3,3] row_mask:0xf bank_mask:0xf
	v_fmac_f32_dpp v169, v146, v110 quad_perm:[3,3,3,3] row_mask:0xf bank_mask:0xf
	v_fmac_f32_dpp v170, v147, v111 quad_perm:[3,3,3,3] row_mask:0xf bank_mask:0xf
	ds_read_b128 v[136:139], v10 offset:15504
	s_waitcnt lgkmcnt(5)
	v_fmac_f32_dpp v119, v148, v112 quad_perm:[0,0,0,0] row_mask:0xf bank_mask:0xf
	v_fmac_f32_dpp v168, v149, v113 quad_perm:[0,0,0,0] row_mask:0xf bank_mask:0xf
	v_fmac_f32_dpp v169, v150, v114 quad_perm:[0,0,0,0] row_mask:0xf bank_mask:0xf
	v_fmac_f32_dpp v170, v151, v115 quad_perm:[0,0,0,0] row_mask:0xf bank_mask:0xf
	v_fmac_f32_dpp v119, v148, v116 quad_perm:[1,1,1,1] row_mask:0xf bank_mask:0xf
	v_fmac_f32_dpp v168, v149, v117 quad_perm:[1,1,1,1] row_mask:0xf bank_mask:0xf
	v_fmac_f32_dpp v169, v150, v118 quad_perm:[1,1,1,1] row_mask:0xf bank_mask:0xf
	v_add_f32_e32 v119, v119, v168
	v_add_f32_e32 v169, v169, v170
	v_add_f32_e32 v119, v119, v169
	ds_read_b128 v[140:143], v10 offset:15568
	s_waitcnt lgkmcnt(5)
	v_mov_b32_e32 v168, 0
	v_mov_b32_e32 v169, 0
	v_mov_b32_e32 v170, 0
	v_fmac_f32_dpp v120, v152, v64 quad_perm:[0,0,0,0] row_mask:0xf bank_mask:0xf
	v_fmac_f32_dpp v168, v153, v65 quad_perm:[0,0,0,0] row_mask:0xf bank_mask:0xf
	v_fmac_f32_dpp v169, v154, v66 quad_perm:[0,0,0,0] row_mask:0xf bank_mask:0xf
	v_fmac_f32_dpp v170, v155, v67 quad_perm:[0,0,0,0] row_mask:0xf bank_mask:0xf
	v_fmac_f32_dpp v120, v152, v68 quad_perm:[1,1,1,1] row_mask:0xf bank_mask:0xf
	v_fmac_f32_dpp v168, v153, v69 quad_perm:[1,1,1,1] row_mask:0xf bank_mask:0xf
	v_fmac_f32_dpp v169, v154, v70 quad_perm:[1,1,1,1] row_mask:0xf bank_mask:0xf
	v_fmac_f32_dpp v170, v155, v71 quad_perm:[1,1,1,1] row_mask:0xf bank_mask:0xf
	v_fmac_f32_dpp v120, v152, v72 quad_perm:[2,2,2,2] row_mask:0xf bank_mask:0xf
	v_fmac_f32_dpp v168, v153, v73 quad_perm:[2,2,2,2] row_mask:0xf bank_mask:0xf
	v_fmac_f32_dpp v169, v154, v74 quad_perm:[2,2,2,2] row_mask:0xf bank_mask:0xf
	v_fmac_f32_dpp v170, v155, v75 quad_perm:[2,2,2,2] row_mask:0xf bank_mask:0xf
	v_fmac_f32_dpp v120, v152, v76 quad_perm:[3,3,3,3] row_mask:0xf bank_mask:0xf
	v_fmac_f32_dpp v168, v153, v77 quad_perm:[3,3,3,3] row_mask:0xf bank_mask:0xf
	v_fmac_f32_dpp v169, v154, v78 quad_perm:[3,3,3,3] row_mask:0xf bank_mask:0xf
	v_fmac_f32_dpp v170, v155, v79 quad_perm:[3,3,3,3] row_mask:0xf bank_mask:0xf
	ds_read_b128 v[144:147], v10 offset:15632
	s_waitcnt lgkmcnt(5)
	v_fmac_f32_dpp v120, v156, v80 quad_perm:[0,0,0,0] row_mask:0xf bank_mask:0xf
	v_fmac_f32_dpp v168, v157, v81 quad_perm:[0,0,0,0] row_mask:0xf bank_mask:0xf
	v_fmac_f32_dpp v169, v158, v82 quad_perm:[0,0,0,0] row_mask:0xf bank_mask:0xf
	v_fmac_f32_dpp v170, v159, v83 quad_perm:[0,0,0,0] row_mask:0xf bank_mask:0xf
	v_fmac_f32_dpp v120, v156, v84 quad_perm:[1,1,1,1] row_mask:0xf bank_mask:0xf
	v_fmac_f32_dpp v168, v157, v85 quad_perm:[1,1,1,1] row_mask:0xf bank_mask:0xf
	v_fmac_f32_dpp v169, v158, v86 quad_perm:[1,1,1,1] row_mask:0xf bank_mask:0xf
	v_fmac_f32_dpp v170, v159, v87 quad_perm:[1,1,1,1] row_mask:0xf bank_mask:0xf
	v_fmac_f32_dpp v120, v156, v88 quad_perm:[2,2,2,2] row_mask:0xf bank_mask:0xf
	v_fmac_f32_dpp v168, v157, v89 quad_perm:[2,2,2,2] row_mask:0xf bank_mask:0xf
	v_fmac_f32_dpp v169, v158, v90 quad_perm:[2,2,2,2] row_mask:0xf bank_mask:0xf
	v_fmac_f32_dpp v170, v159, v91 quad_perm:[2,2,2,2] row_mask:0xf bank_mask:0xf
	v_fmac_f32_dpp v120, v156, v92 quad_perm:[3,3,3,3] row_mask:0xf bank_mask:0xf
	v_fmac_f32_dpp v168, v157, v93 quad_perm:[3,3,3,3] row_mask:0xf bank_mask:0xf
	v_fmac_f32_dpp v169, v158, v94 quad_perm:[3,3,3,3] row_mask:0xf bank_mask:0xf
	v_fmac_f32_dpp v170, v159, v95 quad_perm:[3,3,3,3] row_mask:0xf bank_mask:0xf
	ds_read_b128 v[148:151], v10 offset:15696
	s_waitcnt lgkmcnt(5)
	v_fmac_f32_dpp v120, v160, v96 quad_perm:[0,0,0,0] row_mask:0xf bank_mask:0xf
	v_fmac_f32_dpp v168, v161, v97 quad_perm:[0,0,0,0] row_mask:0xf bank_mask:0xf
	v_fmac_f32_dpp v169, v162, v98 quad_perm:[0,0,0,0] row_mask:0xf bank_mask:0xf
	v_fmac_f32_dpp v170, v163, v99 quad_perm:[0,0,0,0] row_mask:0xf bank_mask:0xf
	v_fmac_f32_dpp v120, v160, v100 quad_perm:[1,1,1,1] row_mask:0xf bank_mask:0xf
	v_fmac_f32_dpp v168, v161, v101 quad_perm:[1,1,1,1] row_mask:0xf bank_mask:0xf
	v_fmac_f32_dpp v169, v162, v102 quad_perm:[1,1,1,1] row_mask:0xf bank_mask:0xf
	v_fmac_f32_dpp v170, v163, v103 quad_perm:[1,1,1,1] row_mask:0xf bank_mask:0xf
	v_fmac_f32_dpp v120, v160, v104 quad_perm:[2,2,2,2] row_mask:0xf bank_mask:0xf
	v_fmac_f32_dpp v168, v161, v105 quad_perm:[2,2,2,2] row_mask:0xf bank_mask:0xf
	v_fmac_f32_dpp v169, v162, v106 quad_perm:[2,2,2,2] row_mask:0xf bank_mask:0xf
	v_fmac_f32_dpp v170, v163, v107 quad_perm:[2,2,2,2] row_mask:0xf bank_mask:0xf
	v_fmac_f32_dpp v120, v160, v108 quad_perm:[3,3,3,3] row_mask:0xf bank_mask:0xf
	v_fmac_f32_dpp v168, v161, v109 quad_perm:[3,3,3,3] row_mask:0xf bank_mask:0xf
	v_fmac_f32_dpp v169, v162, v110 quad_perm:[3,3,3,3] row_mask:0xf bank_mask:0xf
	v_fmac_f32_dpp v170, v163, v111 quad_perm:[3,3,3,3] row_mask:0xf bank_mask:0xf
	ds_read_b128 v[152:155], v10 offset:15776
	s_waitcnt lgkmcnt(5)
; __device__ void dn_d1(const Ctx& c, int ip) {
;     ...
;       a1 -= m[1] * x[13];
;       a2 -= m[2] * x[14];
;       a3 -= m[3] * x[15];
;     }
;     { const f32x4 m = *(const f32x4*)(mr + 16);
;       a0 -= m[0] * x[16];
;       a1 -= m[1] * x[17];
;       a2 -= m[2] * x[18];
;       a3 -= m[3] * x[19];
;     }
;     { const f32x4 m = *(const f32x4*)(mr + 20);
;       a0 -= m[0] * x[20];
;       a1 -= m[1] * x[21];
;       a2 -= m[2] * x[22];
;       a3 -= m[3] * x[23];
;     }
;     { const f32x4 m = *(const f32x4*)(mr + 24);
;       a0 -= m[0] * x[24];
;       a1 -= m[1] * x[25];
;       a2 -= m[2] * x[26];
;       a3 -= m[3] * x[27];
;     }
;     { const f32x4 m = *(const f32x4*)(mr + 28);
;       a0 -= m[0] * x[28];
;       a1 -= m[1] * x[29];
;       a2 -= m[2] * x[30];
;       a3 -= m[3] * x[31];
;     }
;     { const f32x4 m = *(const f32x4*)(mr + 32);
;       a0 -= m[0] * x[32];
;       a1 -= m[1] * x[33];
;       a2 -= m[2] * x[34];
;       a3 -= m[3] * x[35];
;     }
;     { const f32x4 m = *(const f32x4*)(mr + 36);
;       a0 -= m[0] * x[36];
;       a1 -= m[1] * x[37];
;       a2 -= m[2] * x[38];
;       a3 -= m[3] * x[39];
;     }
;     { const f32x4 m = *(const f32x4*)(mr + 40);
;       a0 -= m[0] * x[40];
;       a1 -= m[1] * x[41];
;       a2 -= m[2] * x[42];
;       a3 -= m[3] * x[43];
;     }
;     { const f32x4 m = *(const f32x4*)(mr + 44);
;       a0 -= m[0] * x[44];
;       a1 -= m[1] * x[45];
;       a2 -= m[2] * x[46];
;       a3 -= m[3] * x[47];
;     }
;     { const f32x4 m = *(const f32x4*)(mr + 48);
;       a0 -= m[0] * x[48];
;       a1 -= m[1] * x[49];
;       a2 -= m[2] * x[50];
;       a3 -= m[3] * x[51];
;     }
;     { const f32x4 m = *(const f32x4*)(mr + 52);
;       a0 -= m[0] * x[52];
	v_fmac_f32_dpp v120, v164, v112 quad_perm:[0,0,0,0] row_mask:0xf bank_mask:0xf
	v_fmac_f32_dpp v168, v165, v113 quad_perm:[0,0,0,0] row_mask:0xf bank_mask:0xf
	v_fmac_f32_dpp v169, v166, v114 quad_perm:[0,0,0,0] row_mask:0xf bank_mask:0xf
	v_fmac_f32_dpp v170, v167, v115 quad_perm:[0,0,0,0] row_mask:0xf bank_mask:0xf
	v_fmac_f32_dpp v120, v164, v116 quad_perm:[1,1,1,1] row_mask:0xf bank_mask:0xf
	v_fmac_f32_dpp v168, v165, v117 quad_perm:[1,1,1,1] row_mask:0xf bank_mask:0xf
	v_fmac_f32_dpp v169, v166, v118 quad_perm:[1,1,1,1] row_mask:0xf bank_mask:0xf
	v_fmac_f32_dpp v170, v167, v119 quad_perm:[1,1,1,1] row_mask:0xf bank_mask:0xf
	v_add_f32_e32 v120, v120, v168
	v_add_f32_e32 v169, v169, v170
	v_add_f32_e32 v120, v120, v169
	ds_read_b128 v[156:159], v10 offset:15840
	s_waitcnt lgkmcnt(5)
	v_mov_b32_e32 v168, 0
	v_mov_b32_e32 v169, 0
	v_mov_b32_e32 v170, 0
	v_fmac_f32_dpp v121, v136, v64 quad_perm:[0,0,0,0] row_mask:0xf bank_mask:0xf
	v_fmac_f32_dpp v168, v137, v65 quad_perm:[0,0,0,0] row_mask:0xf bank_mask:0xf
	v_fmac_f32_dpp v169, v138, v66 quad_perm:[0,0,0,0] row_mask:0xf bank_mask:0xf
	v_fmac_f32_dpp v170, v139, v67 quad_perm:[0,0,0,0] row_mask:0xf bank_mask:0xf
	v_fmac_f32_dpp v121, v136, v68 quad_perm:[1,1,1,1] row_mask:0xf bank_mask:0xf
	v_fmac_f32_dpp v168, v137, v69 quad_perm:[1,1,1,1] row_mask:0xf bank_mask:0xf
	v_fmac_f32_dpp v169, v138, v70 quad_perm:[1,1,1,1] row_mask:0xf bank_mask:0xf
	v_fmac_f32_dpp v170, v139, v71 quad_perm:[1,1,1,1] row_mask:0xf bank_mask:0xf
	v_fmac_f32_dpp v121, v136, v72 quad_perm:[2,2,2,2] row_mask:0xf bank_mask:0xf
	v_fmac_f32_dpp v168, v137, v73 quad_perm:[2,2,2,2] row_mask:0xf bank_mask:0xf
	v_fmac_f32_dpp v169, v138, v74 quad_perm:[2,2,2,2] row_mask:0xf bank_mask:0xf
	v_fmac_f32_dpp v170, v139, v75 quad_perm:[2,2,2,2] row_mask:0xf bank_mask:0xf
	v_fmac_f32_dpp v121, v136, v76 quad_perm:[3,3,3,3] row_mask:0xf bank_mask:0xf
	v_fmac_f32_dpp v168, v137, v77 quad_perm:[3,3,3,3] row_mask:0xf bank_mask:0xf
	v_fmac_f32_dpp v169, v138, v78 quad_perm:[3,3,3,3] row_mask:0xf bank_mask:0xf
	v_fmac_f32_dpp v170, v139, v79 quad_perm:[3,3,3,3] row_mask:0xf bank_mask:0xf
	ds_read_b128 v[160:163], v10 offset:15904
	s_waitcnt lgkmcnt(5)
	v_fmac_f32_dpp v121, v140, v80 quad_perm:[0,0,0,0] row_mask:0xf bank_mask:0xf
	v_fmac_f32_dpp v168, v141, v81 quad_perm:[0,0,0,0] row_mask:0xf bank_mask:0xf
	v_fmac_f32_dpp v169, v142, v82 quad_perm:[0,0,0,0] row_mask:0xf bank_mask:0xf
	v_fmac_f32_dpp v170, v143, v83 quad_perm:[0,0,0,0] row_mask:0xf bank_mask:0xf
	v_fmac_f32_dpp v121, v140, v84 quad_perm:[1,1,1,1] row_mask:0xf bank_mask:0xf
	v_fmac_f32_dpp v168, v141, v85 quad_perm:[1,1,1,1] row_mask:0xf bank_mask:0xf
	v_fmac_f32_dpp v169, v142, v86 quad_perm:[1,1,1,1] row_mask:0xf bank_mask:0xf
	v_fmac_f32_dpp v170, v143, v87 quad_perm:[1,1,1,1] row_mask:0xf bank_mask:0xf
	v_fmac_f32_dpp v121, v140, v88 quad_perm:[2,2,2,2] row_mask:0xf bank_mask:0xf
	v_fmac_f32_dpp v168, v141, v89 quad_perm:[2,2,2,2] row_mask:0xf bank_mask:0xf
	v_fmac_f32_dpp v169, v142, v90 quad_perm:[2,2,2,2] row_mask:0xf bank_mask:0xf
	v_fmac_f32_dpp v170, v143, v91 quad_perm:[2,2,2,2] row_mask:0xf bank_mask:0xf
	v_fmac_f32_dpp v121, v140, v92 quad_perm:[3,3,3,3] row_mask:0xf bank_mask:0xf
	v_fmac_f32_dpp v168, v141, v93 quad_perm:[3,3,3,3] row_mask:0xf bank_mask:0xf
	v_fmac_f32_dpp v169, v142, v94 quad_perm:[3,3,3,3] row_mask:0xf bank_mask:0xf
	v_fmac_f32_dpp v170, v143, v95 quad_perm:[3,3,3,3] row_mask:0xf bank_mask:0xf
	ds_read_b128 v[164:167], v10 offset:15968
	s_waitcnt lgkmcnt(5)
	v_fmac_f32_dpp v121, v144, v96 quad_perm:[0,0,0,0] row_mask:0xf bank_mask:0xf
	v_fmac_f32_dpp v168, v145, v97 quad_perm:[0,0,0,0] row_mask:0xf bank_mask:0xf
	v_fmac_f32_dpp v169, v146, v98 quad_perm:[0,0,0,0] row_mask:0xf bank_mask:0xf
	v_fmac_f32_dpp v170, v147, v99 quad_perm:[0,0,0,0] row_mask:0xf bank_mask:0xf
	v_fmac_f32_dpp v121, v144, v100 quad_perm:[1,1,1,1] row_mask:0xf bank_mask:0xf
	v_fmac_f32_dpp v168, v145, v101 quad_perm:[1,1,1,1] row_mask:0xf bank_mask:0xf
	v_fmac_f32_dpp v169, v146, v102 quad_perm:[1,1,1,1] row_mask:0xf bank_mask:0xf
	v_fmac_f32_dpp v170, v147, v103 quad_perm:[1,1,1,1] row_mask:0xf bank_mask:0xf
	v_fmac_f32_dpp v121, v144, v104 quad_perm:[2,2,2,2] row_mask:0xf bank_mask:0xf
	v_fmac_f32_dpp v168, v145, v105 quad_perm:[2,2,2,2] row_mask:0xf bank_mask:0xf
	v_fmac_f32_dpp v169, v146, v106 quad_perm:[2,2,2,2] row_mask:0xf bank_mask:0xf
	v_fmac_f32_dpp v170, v147, v107 quad_perm:[2,2,2,2] row_mask:0xf bank_mask:0xf
	v_fmac_f32_dpp v121, v144, v108 quad_perm:[3,3,3,3] row_mask:0xf bank_mask:0xf
	v_fmac_f32_dpp v168, v145, v109 quad_perm:[3,3,3,3] row_mask:0xf bank_mask:0xf
	v_fmac_f32_dpp v169, v146, v110 quad_perm:[3,3,3,3] row_mask:0xf bank_mask:0xf
	v_fmac_f32_dpp v170, v147, v111 quad_perm:[3,3,3,3] row_mask:0xf bank_mask:0xf
	ds_read_b128 v[136:139], v10 offset:16048
	s_waitcnt lgkmcnt(5)
	v_fmac_f32_dpp v121, v148, v112 quad_perm:[0,0,0,0] row_mask:0xf bank_mask:0xf
	v_fmac_f32_dpp v168, v149, v113 quad_perm:[0,0,0,0] row_mask:0xf bank_mask:0xf
	v_fmac_f32_dpp v169, v150, v114 quad_perm:[0,0,0,0] row_mask:0xf bank_mask:0xf
	v_fmac_f32_dpp v170, v151, v115 quad_perm:[0,0,0,0] row_mask:0xf bank_mask:0xf
	v_fmac_f32_dpp v121, v148, v116 quad_perm:[1,1,1,1] row_mask:0xf bank_mask:0xf
	v_fmac_f32_dpp v168, v149, v117 quad_perm:[1,1,1,1] row_mask:0xf bank_mask:0xf
	v_fmac_f32_dpp v169, v150, v118 quad_perm:[1,1,1,1] row_mask:0xf bank_mask:0xf
	v_fmac_f32_dpp v170, v151, v119 quad_perm:[1,1,1,1] row_mask:0xf bank_mask:0xf
	v_fmac_f32_dpp v121, v148, v120 quad_perm:[2,2,2,2] row_mask:0xf bank_mask:0xf
	v_add_f32_e32 v121, v121, v168
	v_add_f32_e32 v169, v169, v170
	v_add_f32_e32 v121, v121, v169
	ds_read_b128 v[140:143], v10 offset:16112
	s_waitcnt lgkmcnt(5)
; __device__ void dn_d1(const Ctx& c, int ip) {
;     ...
;       a2 -= m[2] * x[14];
;       a3 -= m[3] * x[15];
;     }
;     { const f32x4 m = *(const f32x4*)(mr + 16);
;       a0 -= m[0] * x[16];
;       a1 -= m[1] * x[17];
;       a2 -= m[2] * x[18];
;       a3 -= m[3] * x[19];
;     }
;     { const f32x4 m = *(const f32x4*)(mr + 20);
;       a0 -= m[0] * x[20];
;       a1 -= m[1] * x[21];
;       a2 -= m[2] * x[22];
;       a3 -= m[3] * x[23];
;     }
;     { const f32x4 m = *(const f32x4*)(mr + 24);
;       a0 -= m[0] * x[24];
;       a1 -= m[1] * x[25];
;       a2 -= m[2] * x[26];
;       a3 -= m[3] * x[27];
;     }
;     { const f32x4 m = *(const f32x4*)(mr + 28);
;       a0 -= m[0] * x[28];
;       a1 -= m[1] * x[29];
;       a2 -= m[2] * x[30];
;       a3 -= m[3] * x[31];
;     }
;     { const f32x4 m = *(const f32x4*)(mr + 32);
;       a0 -= m[0] * x[32];
;       a1 -= m[1] * x[33];
;       a2 -= m[2] * x[34];
;       a3 -= m[3] * x[35];
;     }
;     { const f32x4 m = *(const f32x4*)(mr + 36);
;       a0 -= m[0] * x[36];
;       a1 -= m[1] * x[37];
;       a2 -= m[2] * x[38];
;       a3 -= m[3] * x[39];
;     }
;     { const f32x4 m = *(const f32x4*)(mr + 40);
;       a0 -= m[0] * x[40];
;       a1 -= m[1] * x[41];
;       a2 -= m[2] * x[42];
;       a3 -= m[3] * x[43];
;     }
;     { const f32x4 m = *(const f32x4*)(mr + 44);
;       a0 -= m[0] * x[44];
;       a1 -= m[1] * x[45];
;       a2 -= m[2] * x[46];
;       a3 -= m[3] * x[47];
;     }
;     { const f32x4 m = *(const f32x4*)(mr + 48);
;       a0 -= m[0] * x[48];
;       a1 -= m[1] * x[49];
;       a2 -= m[2] * x[50];
;       a3 -= m[3] * x[51];
;     }
;     { const f32x4 m = *(const f32x4*)(mr + 52);
;       a0 -= m[0] * x[52];
;       a1 -= m[1] * x[53];
	v_mov_b32_e32 v168, 0
	v_mov_b32_e32 v169, 0
	v_mov_b32_e32 v170, 0
	v_fmac_f32_dpp v122, v152, v64 quad_perm:[0,0,0,0] row_mask:0xf bank_mask:0xf
	v_fmac_f32_dpp v168, v153, v65 quad_perm:[0,0,0,0] row_mask:0xf bank_mask:0xf
	v_fmac_f32_dpp v169, v154, v66 quad_perm:[0,0,0,0] row_mask:0xf bank_mask:0xf
	v_fmac_f32_dpp v170, v155, v67 quad_perm:[0,0,0,0] row_mask:0xf bank_mask:0xf
	v_fmac_f32_dpp v122, v152, v68 quad_perm:[1,1,1,1] row_mask:0xf bank_mask:0xf
	v_fmac_f32_dpp v168, v153, v69 quad_perm:[1,1,1,1] row_mask:0xf bank_mask:0xf
	v_fmac_f32_dpp v169, v154, v70 quad_perm:[1,1,1,1] row_mask:0xf bank_mask:0xf
	v_fmac_f32_dpp v170, v155, v71 quad_perm:[1,1,1,1] row_mask:0xf bank_mask:0xf
	v_fmac_f32_dpp v122, v152, v72 quad_perm:[2,2,2,2] row_mask:0xf bank_mask:0xf
	v_fmac_f32_dpp v168, v153, v73 quad_perm:[2,2,2,2] row_mask:0xf bank_mask:0xf
	v_fmac_f32_dpp v169, v154, v74 quad_perm:[2,2,2,2] row_mask:0xf bank_mask:0xf
	v_fmac_f32_dpp v170, v155, v75 quad_perm:[2,2,2,2] row_mask:0xf bank_mask:0xf
	v_fmac_f32_dpp v122, v152, v76 quad_perm:[3,3,3,3] row_mask:0xf bank_mask:0xf
	v_fmac_f32_dpp v168, v153, v77 quad_perm:[3,3,3,3] row_mask:0xf bank_mask:0xf
	v_fmac_f32_dpp v169, v154, v78 quad_perm:[3,3,3,3] row_mask:0xf bank_mask:0xf
	v_fmac_f32_dpp v170, v155, v79 quad_perm:[3,3,3,3] row_mask:0xf bank_mask:0xf
	ds_read_b128 v[144:147], v10 offset:16176
	s_waitcnt lgkmcnt(5)
	v_fmac_f32_dpp v122, v156, v80 quad_perm:[0,0,0,0] row_mask:0xf bank_mask:0xf
	v_fmac_f32_dpp v168, v157, v81 quad_perm:[0,0,0,0] row_mask:0xf bank_mask:0xf
	v_fmac_f32_dpp v169, v158, v82 quad_perm:[0,0,0,0] row_mask:0xf bank_mask:0xf
	v_fmac_f32_dpp v170, v159, v83 quad_perm:[0,0,0,0] row_mask:0xf bank_mask:0xf
	v_fmac_f32_dpp v122, v156, v84 quad_perm:[1,1,1,1] row_mask:0xf bank_mask:0xf
	v_fmac_f32_dpp v168, v157, v85 quad_perm:[1,1,1,1] row_mask:0xf bank_mask:0xf
	v_fmac_f32_dpp v169, v158, v86 quad_perm:[1,1,1,1] row_mask:0xf bank_mask:0xf
	v_fmac_f32_dpp v170, v159, v87 quad_perm:[1,1,1,1] row_mask:0xf bank_mask:0xf
	v_fmac_f32_dpp v122, v156, v88 quad_perm:[2,2,2,2] row_mask:0xf bank_mask:0xf
	v_fmac_f32_dpp v168, v157, v89 quad_perm:[2,2,2,2] row_mask:0xf bank_mask:0xf
	v_fmac_f32_dpp v169, v158, v90 quad_perm:[2,2,2,2] row_mask:0xf bank_mask:0xf
	v_fmac_f32_dpp v170, v159, v91 quad_perm:[2,2,2,2] row_mask:0xf bank_mask:0xf
	v_fmac_f32_dpp v122, v156, v92 quad_perm:[3,3,3,3] row_mask:0xf bank_mask:0xf
	v_fmac_f32_dpp v168, v157, v93 quad_perm:[3,3,3,3] row_mask:0xf bank_mask:0xf
	v_fmac_f32_dpp v169, v158, v94 quad_perm:[3,3,3,3] row_mask:0xf bank_mask:0xf
	v_fmac_f32_dpp v170, v159, v95 quad_perm:[3,3,3,3] row_mask:0xf bank_mask:0xf
	ds_read_b128 v[148:151], v10 offset:16240
	s_waitcnt lgkmcnt(5)
	v_fmac_f32_dpp v122, v160, v96 quad_perm:[0,0,0,0] row_mask:0xf bank_mask:0xf
	v_fmac_f32_dpp v168, v161, v97 quad_perm:[0,0,0,0] row_mask:0xf bank_mask:0xf
	v_fmac_f32_dpp v169, v162, v98 quad_perm:[0,0,0,0] row_mask:0xf bank_mask:0xf
	v_fmac_f32_dpp v170, v163, v99 quad_perm:[0,0,0,0] row_mask:0xf bank_mask:0xf
	v_fmac_f32_dpp v122, v160, v100 quad_perm:[1,1,1,1] row_mask:0xf bank_mask:0xf
	v_fmac_f32_dpp v168, v161, v101 quad_perm:[1,1,1,1] row_mask:0xf bank_mask:0xf
	v_fmac_f32_dpp v169, v162, v102 quad_perm:[1,1,1,1] row_mask:0xf bank_mask:0xf
	v_fmac_f32_dpp v170, v163, v103 quad_perm:[1,1,1,1] row_mask:0xf bank_mask:0xf
	v_fmac_f32_dpp v122, v160, v104 quad_perm:[2,2,2,2] row_mask:0xf bank_mask:0xf
	v_fmac_f32_dpp v168, v161, v105 quad_perm:[2,2,2,2] row_mask:0xf bank_mask:0xf
	v_fmac_f32_dpp v169, v162, v106 quad_perm:[2,2,2,2] row_mask:0xf bank_mask:0xf
	v_fmac_f32_dpp v170, v163, v107 quad_perm:[2,2,2,2] row_mask:0xf bank_mask:0xf
	v_fmac_f32_dpp v122, v160, v108 quad_perm:[3,3,3,3] row_mask:0xf bank_mask:0xf
	v_fmac_f32_dpp v168, v161, v109 quad_perm:[3,3,3,3] row_mask:0xf bank_mask:0xf
	v_fmac_f32_dpp v169, v162, v110 quad_perm:[3,3,3,3] row_mask:0xf bank_mask:0xf
	v_fmac_f32_dpp v170, v163, v111 quad_perm:[3,3,3,3] row_mask:0xf bank_mask:0xf
	ds_read_b128 v[152:155], v10 offset:16320
	s_waitcnt lgkmcnt(5)
	v_fmac_f32_dpp v122, v164, v112 quad_perm:[0,0,0,0] row_mask:0xf bank_mask:0xf
	v_fmac_f32_dpp v168, v165, v113 quad_perm:[0,0,0,0] row_mask:0xf bank_mask:0xf
	v_fmac_f32_dpp v169, v166, v114 quad_perm:[0,0,0,0] row_mask:0xf bank_mask:0xf
	v_fmac_f32_dpp v170, v167, v115 quad_perm:[0,0,0,0] row_mask:0xf bank_mask:0xf
	v_fmac_f32_dpp v122, v164, v116 quad_perm:[1,1,1,1] row_mask:0xf bank_mask:0xf
	v_fmac_f32_dpp v168, v165, v117 quad_perm:[1,1,1,1] row_mask:0xf bank_mask:0xf
	v_fmac_f32_dpp v169, v166, v118 quad_perm:[1,1,1,1] row_mask:0xf bank_mask:0xf
	v_fmac_f32_dpp v170, v167, v119 quad_perm:[1,1,1,1] row_mask:0xf bank_mask:0xf
	v_fmac_f32_dpp v122, v164, v120 quad_perm:[2,2,2,2] row_mask:0xf bank_mask:0xf
	v_fmac_f32_dpp v168, v165, v121 quad_perm:[2,2,2,2] row_mask:0xf bank_mask:0xf
	v_add_f32_e32 v122, v122, v168
	v_add_f32_e32 v169, v169, v170
	v_add_f32_e32 v122, v122, v169
	ds_read_b128 v[156:159], v10 offset:16384
	s_waitcnt lgkmcnt(5)
; __device__ void dn_d1(const Ctx& c, int ip) {
;     ...
;       a2 -= m[2] * x[14];
;       a3 -= m[3] * x[15];
;     }
;     { const f32x4 m = *(const f32x4*)(mr + 16);
;       a0 -= m[0] * x[16];
;       a1 -= m[1] * x[17];
;       a2 -= m[2] * x[18];
;       a3 -= m[3] * x[19];
;     }
;     { const f32x4 m = *(const f32x4*)(mr + 20);
;       a0 -= m[0] * x[20];
;       a1 -= m[1] * x[21];
;       a2 -= m[2] * x[22];
;       a3 -= m[3] * x[23];
;     }
;     { const f32x4 m = *(const f32x4*)(mr + 24);
;       a0 -= m[0] * x[24];
;       a1 -= m[1] * x[25];
;       a2 -= m[2] * x[26];
;       a3 -= m[3] * x[27];
;     }
;     { const f32x4 m = *(const f32x4*)(mr + 28);
;       a0 -= m[0] * x[28];
;       a1 -= m[1] * x[29];
;       a2 -= m[2] * x[30];
;       a3 -= m[3] * x[31];
;     }
;     { const f32x4 m = *(const f32x4*)(mr + 32);
;       a0 -= m[0] * x[32];
;       a1 -= m[1] * x[33];
;       a2 -= m[2] * x[34];
;       a3 -= m[3] * x[35];
;     }
;     { const f32x4 m = *(const f32x4*)(mr + 36);
;       a0 -= m[0] * x[36];
;       a1 -= m[1] * x[37];
;       a2 -= m[2] * x[38];
;       a3 -= m[3] * x[39];
;     }
;     { const f32x4 m = *(const f32x4*)(mr + 40);
;       a0 -= m[0] * x[40];
;       a1 -= m[1] * x[41];
;       a2 -= m[2] * x[42];
;       a3 -= m[3] * x[43];
;     }
;     { const f32x4 m = *(const f32x4*)(mr + 44);
;       a0 -= m[0] * x[44];
;       a1 -= m[1] * x[45];
;       a2 -= m[2] * x[46];
;       a3 -= m[3] * x[47];
;     }
;     { const f32x4 m = *(const f32x4*)(mr + 48);
;       a0 -= m[0] * x[48];
;       a1 -= m[1] * x[49];
;       a2 -= m[2] * x[50];
;       a3 -= m[3] * x[51];
;     }
;     { const f32x4 m = *(const f32x4*)(mr + 52);
;       a0 -= m[0] * x[52];
;       a1 -= m[1] * x[53];
	v_mov_b32_e32 v168, 0
	v_mov_b32_e32 v169, 0
	v_mov_b32_e32 v170, 0
	v_fmac_f32_dpp v123, v136, v64 quad_perm:[0,0,0,0] row_mask:0xf bank_mask:0xf
	v_fmac_f32_dpp v168, v137, v65 quad_perm:[0,0,0,0] row_mask:0xf bank_mask:0xf
	v_fmac_f32_dpp v169, v138, v66 quad_perm:[0,0,0,0] row_mask:0xf bank_mask:0xf
	v_fmac_f32_dpp v170, v139, v67 quad_perm:[0,0,0,0] row_mask:0xf bank_mask:0xf
	v_fmac_f32_dpp v123, v136, v68 quad_perm:[1,1,1,1] row_mask:0xf bank_mask:0xf
	v_fmac_f32_dpp v168, v137, v69 quad_perm:[1,1,1,1] row_mask:0xf bank_mask:0xf
	v_fmac_f32_dpp v169, v138, v70 quad_perm:[1,1,1,1] row_mask:0xf bank_mask:0xf
	v_fmac_f32_dpp v170, v139, v71 quad_perm:[1,1,1,1] row_mask:0xf bank_mask:0xf
	v_fmac_f32_dpp v123, v136, v72 quad_perm:[2,2,2,2] row_mask:0xf bank_mask:0xf
	v_fmac_f32_dpp v168, v137, v73 quad_perm:[2,2,2,2] row_mask:0xf bank_mask:0xf
	v_fmac_f32_dpp v169, v138, v74 quad_perm:[2,2,2,2] row_mask:0xf bank_mask:0xf
	v_fmac_f32_dpp v170, v139, v75 quad_perm:[2,2,2,2] row_mask:0xf bank_mask:0xf
	v_fmac_f32_dpp v123, v136, v76 quad_perm:[3,3,3,3] row_mask:0xf bank_mask:0xf
	v_fmac_f32_dpp v168, v137, v77 quad_perm:[3,3,3,3] row_mask:0xf bank_mask:0xf
	v_fmac_f32_dpp v169, v138, v78 quad_perm:[3,3,3,3] row_mask:0xf bank_mask:0xf
	v_fmac_f32_dpp v170, v139, v79 quad_perm:[3,3,3,3] row_mask:0xf bank_mask:0xf
	ds_read_b128 v[160:163], v10 offset:16448
	s_waitcnt lgkmcnt(5)
	v_fmac_f32_dpp v123, v140, v80 quad_perm:[0,0,0,0] row_mask:0xf bank_mask:0xf
	v_fmac_f32_dpp v168, v141, v81 quad_perm:[0,0,0,0] row_mask:0xf bank_mask:0xf
	v_fmac_f32_dpp v169, v142, v82 quad_perm:[0,0,0,0] row_mask:0xf bank_mask:0xf
	v_fmac_f32_dpp v170, v143, v83 quad_perm:[0,0,0,0] row_mask:0xf bank_mask:0xf
	v_fmac_f32_dpp v123, v140, v84 quad_perm:[1,1,1,1] row_mask:0xf bank_mask:0xf
	v_fmac_f32_dpp v168, v141, v85 quad_perm:[1,1,1,1] row_mask:0xf bank_mask:0xf
	v_fmac_f32_dpp v169, v142, v86 quad_perm:[1,1,1,1] row_mask:0xf bank_mask:0xf
	v_fmac_f32_dpp v170, v143, v87 quad_perm:[1,1,1,1] row_mask:0xf bank_mask:0xf
	v_fmac_f32_dpp v123, v140, v88 quad_perm:[2,2,2,2] row_mask:0xf bank_mask:0xf
	v_fmac_f32_dpp v168, v141, v89 quad_perm:[2,2,2,2] row_mask:0xf bank_mask:0xf
	v_fmac_f32_dpp v169, v142, v90 quad_perm:[2,2,2,2] row_mask:0xf bank_mask:0xf
	v_fmac_f32_dpp v170, v143, v91 quad_perm:[2,2,2,2] row_mask:0xf bank_mask:0xf
	v_fmac_f32_dpp v123, v140, v92 quad_perm:[3,3,3,3] row_mask:0xf bank_mask:0xf
	v_fmac_f32_dpp v168, v141, v93 quad_perm:[3,3,3,3] row_mask:0xf bank_mask:0xf
	v_fmac_f32_dpp v169, v142, v94 quad_perm:[3,3,3,3] row_mask:0xf bank_mask:0xf
	v_fmac_f32_dpp v170, v143, v95 quad_perm:[3,3,3,3] row_mask:0xf bank_mask:0xf
	ds_read_b128 v[164:167], v10 offset:16512
	s_waitcnt lgkmcnt(5)
	v_fmac_f32_dpp v123, v144, v96 quad_perm:[0,0,0,0] row_mask:0xf bank_mask:0xf
	v_fmac_f32_dpp v168, v145, v97 quad_perm:[0,0,0,0] row_mask:0xf bank_mask:0xf
	v_fmac_f32_dpp v169, v146, v98 quad_perm:[0,0,0,0] row_mask:0xf bank_mask:0xf
	v_fmac_f32_dpp v170, v147, v99 quad_perm:[0,0,0,0] row_mask:0xf bank_mask:0xf
	v_fmac_f32_dpp v123, v144, v100 quad_perm:[1,1,1,1] row_mask:0xf bank_mask:0xf
	v_fmac_f32_dpp v168, v145, v101 quad_perm:[1,1,1,1] row_mask:0xf bank_mask:0xf
	v_fmac_f32_dpp v169, v146, v102 quad_perm:[1,1,1,1] row_mask:0xf bank_mask:0xf
	v_fmac_f32_dpp v170, v147, v103 quad_perm:[1,1,1,1] row_mask:0xf bank_mask:0xf
	v_fmac_f32_dpp v123, v144, v104 quad_perm:[2,2,2,2] row_mask:0xf bank_mask:0xf
	v_fmac_f32_dpp v168, v145, v105 quad_perm:[2,2,2,2] row_mask:0xf bank_mask:0xf
	v_fmac_f32_dpp v169, v146, v106 quad_perm:[2,2,2,2] row_mask:0xf bank_mask:0xf
	v_fmac_f32_dpp v170, v147, v107 quad_perm:[2,2,2,2] row_mask:0xf bank_mask:0xf
	v_fmac_f32_dpp v123, v144, v108 quad_perm:[3,3,3,3] row_mask:0xf bank_mask:0xf
	v_fmac_f32_dpp v168, v145, v109 quad_perm:[3,3,3,3] row_mask:0xf bank_mask:0xf
	v_fmac_f32_dpp v169, v146, v110 quad_perm:[3,3,3,3] row_mask:0xf bank_mask:0xf
	v_fmac_f32_dpp v170, v147, v111 quad_perm:[3,3,3,3] row_mask:0xf bank_mask:0xf
	ds_read_b128 v[136:139], v10 offset:16592
	s_waitcnt lgkmcnt(5)
	v_fmac_f32_dpp v123, v148, v112 quad_perm:[0,0,0,0] row_mask:0xf bank_mask:0xf
	v_fmac_f32_dpp v168, v149, v113 quad_perm:[0,0,0,0] row_mask:0xf bank_mask:0xf
	v_fmac_f32_dpp v169, v150, v114 quad_perm:[0,0,0,0] row_mask:0xf bank_mask:0xf
	v_fmac_f32_dpp v170, v151, v115 quad_perm:[0,0,0,0] row_mask:0xf bank_mask:0xf
	v_fmac_f32_dpp v123, v148, v116 quad_perm:[1,1,1,1] row_mask:0xf bank_mask:0xf
	v_fmac_f32_dpp v168, v149, v117 quad_perm:[1,1,1,1] row_mask:0xf bank_mask:0xf
	v_fmac_f32_dpp v169, v150, v118 quad_perm:[1,1,1,1] row_mask:0xf bank_mask:0xf
	v_fmac_f32_dpp v170, v151, v119 quad_perm:[1,1,1,1] row_mask:0xf bank_mask:0xf
	v_fmac_f32_dpp v123, v148, v120 quad_perm:[2,2,2,2] row_mask:0xf bank_mask:0xf
	v_fmac_f32_dpp v168, v149, v121 quad_perm:[2,2,2,2] row_mask:0xf bank_mask:0xf
	v_fmac_f32_dpp v169, v150, v122 quad_perm:[2,2,2,2] row_mask:0xf bank_mask:0xf
	v_add_f32_e32 v123, v123, v168
	v_add_f32_e32 v169, v169, v170
	v_add_f32_e32 v123, v123, v169
	ds_read_b128 v[140:143], v10 offset:16656
	s_waitcnt lgkmcnt(5)
; __device__ void dn_d1(const Ctx& c, int ip) {
;     ...
;       a1 -= m[1] * x[13];
;       a2 -= m[2] * x[14];
;       a3 -= m[3] * x[15];
;     }
;     { const f32x4 m = *(const f32x4*)(mr + 16);
;       a0 -= m[0] * x[16];
;       a1 -= m[1] * x[17];
;       a2 -= m[2] * x[18];
;       a3 -= m[3] * x[19];
;     }
;     { const f32x4 m = *(const f32x4*)(mr + 20);
;       a0 -= m[0] * x[20];
;       a1 -= m[1] * x[21];
;       a2 -= m[2] * x[22];
;       a3 -= m[3] * x[23];
;     }
;     { const f32x4 m = *(const f32x4*)(mr + 24);
;       a0 -= m[0] * x[24];
;       a1 -= m[1] * x[25];
;       a2 -= m[2] * x[26];
;       a3 -= m[3] * x[27];
;     }
;     { const f32x4 m = *(const f32x4*)(mr + 28);
;       a0 -= m[0] * x[28];
;       a1 -= m[1] * x[29];
;       a2 -= m[2] * x[30];
;       a3 -= m[3] * x[31];
;     }
;     { const f32x4 m = *(const f32x4*)(mr + 32);
;       a0 -= m[0] * x[32];
;       a1 -= m[1] * x[33];
;       a2 -= m[2] * x[34];
;       a3 -= m[3] * x[35];
;     }
;     { const f32x4 m = *(const f32x4*)(mr + 36);
;       a0 -= m[0] * x[36];
;       a1 -= m[1] * x[37];
;       a2 -= m[2] * x[38];
;       a3 -= m[3] * x[39];
;     }
;     { const f32x4 m = *(const f32x4*)(mr + 40);
;       a0 -= m[0] * x[40];
;       a1 -= m[1] * x[41];
;       a2 -= m[2] * x[42];
;       a3 -= m[3] * x[43];
;     }
;     { const f32x4 m = *(const f32x4*)(mr + 44);
;       a0 -= m[0] * x[44];
;       a1 -= m[1] * x[45];
;       a2 -= m[2] * x[46];
;       a3 -= m[3] * x[47];
;     }
;     { const f32x4 m = *(const f32x4*)(mr + 48);
;       a0 -= m[0] * x[48];
;       a1 -= m[1] * x[49];
;       a2 -= m[2] * x[50];
;       a3 -= m[3] * x[51];
;     }
;     { const f32x4 m = *(const f32x4*)(mr + 52);
;       a0 -= m[0] * x[52];
	v_mov_b32_e32 v168, 0
	v_mov_b32_e32 v169, 0
	v_mov_b32_e32 v170, 0
	v_fmac_f32_dpp v124, v152, v64 quad_perm:[0,0,0,0] row_mask:0xf bank_mask:0xf
	v_fmac_f32_dpp v168, v153, v65 quad_perm:[0,0,0,0] row_mask:0xf bank_mask:0xf
	v_fmac_f32_dpp v169, v154, v66 quad_perm:[0,0,0,0] row_mask:0xf bank_mask:0xf
	v_fmac_f32_dpp v170, v155, v67 quad_perm:[0,0,0,0] row_mask:0xf bank_mask:0xf
	v_fmac_f32_dpp v124, v152, v68 quad_perm:[1,1,1,1] row_mask:0xf bank_mask:0xf
	v_fmac_f32_dpp v168, v153, v69 quad_perm:[1,1,1,1] row_mask:0xf bank_mask:0xf
	v_fmac_f32_dpp v169, v154, v70 quad_perm:[1,1,1,1] row_mask:0xf bank_mask:0xf
	v_fmac_f32_dpp v170, v155, v71 quad_perm:[1,1,1,1] row_mask:0xf bank_mask:0xf
	v_fmac_f32_dpp v124, v152, v72 quad_perm:[2,2,2,2] row_mask:0xf bank_mask:0xf
	v_fmac_f32_dpp v168, v153, v73 quad_perm:[2,2,2,2] row_mask:0xf bank_mask:0xf
	v_fmac_f32_dpp v169, v154, v74 quad_perm:[2,2,2,2] row_mask:0xf bank_mask:0xf
	v_fmac_f32_dpp v170, v155, v75 quad_perm:[2,2,2,2] row_mask:0xf bank_mask:0xf
	v_fmac_f32_dpp v124, v152, v76 quad_perm:[3,3,3,3] row_mask:0xf bank_mask:0xf
	v_fmac_f32_dpp v168, v153, v77 quad_perm:[3,3,3,3] row_mask:0xf bank_mask:0xf
	v_fmac_f32_dpp v169, v154, v78 quad_perm:[3,3,3,3] row_mask:0xf bank_mask:0xf
	v_fmac_f32_dpp v170, v155, v79 quad_perm:[3,3,3,3] row_mask:0xf bank_mask:0xf
	ds_read_b128 v[144:147], v10 offset:16720
	s_waitcnt lgkmcnt(5)
	v_fmac_f32_dpp v124, v156, v80 quad_perm:[0,0,0,0] row_mask:0xf bank_mask:0xf
	v_fmac_f32_dpp v168, v157, v81 quad_perm:[0,0,0,0] row_mask:0xf bank_mask:0xf
	v_fmac_f32_dpp v169, v158, v82 quad_perm:[0,0,0,0] row_mask:0xf bank_mask:0xf
	v_fmac_f32_dpp v170, v159, v83 quad_perm:[0,0,0,0] row_mask:0xf bank_mask:0xf
	v_fmac_f32_dpp v124, v156, v84 quad_perm:[1,1,1,1] row_mask:0xf bank_mask:0xf
	v_fmac_f32_dpp v168, v157, v85 quad_perm:[1,1,1,1] row_mask:0xf bank_mask:0xf
	v_fmac_f32_dpp v169, v158, v86 quad_perm:[1,1,1,1] row_mask:0xf bank_mask:0xf
	v_fmac_f32_dpp v170, v159, v87 quad_perm:[1,1,1,1] row_mask:0xf bank_mask:0xf
	v_fmac_f32_dpp v124, v156, v88 quad_perm:[2,2,2,2] row_mask:0xf bank_mask:0xf
	v_fmac_f32_dpp v168, v157, v89 quad_perm:[2,2,2,2] row_mask:0xf bank_mask:0xf
	v_fmac_f32_dpp v169, v158, v90 quad_perm:[2,2,2,2] row_mask:0xf bank_mask:0xf
	v_fmac_f32_dpp v170, v159, v91 quad_perm:[2,2,2,2] row_mask:0xf bank_mask:0xf
	v_fmac_f32_dpp v124, v156, v92 quad_perm:[3,3,3,3] row_mask:0xf bank_mask:0xf
	v_fmac_f32_dpp v168, v157, v93 quad_perm:[3,3,3,3] row_mask:0xf bank_mask:0xf
	v_fmac_f32_dpp v169, v158, v94 quad_perm:[3,3,3,3] row_mask:0xf bank_mask:0xf
	v_fmac_f32_dpp v170, v159, v95 quad_perm:[3,3,3,3] row_mask:0xf bank_mask:0xf
	ds_read_b128 v[148:151], v10 offset:16784
	s_waitcnt lgkmcnt(5)
	v_fmac_f32_dpp v124, v160, v96 quad_perm:[0,0,0,0] row_mask:0xf bank_mask:0xf
	v_fmac_f32_dpp v168, v161, v97 quad_perm:[0,0,0,0] row_mask:0xf bank_mask:0xf
	v_fmac_f32_dpp v169, v162, v98 quad_perm:[0,0,0,0] row_mask:0xf bank_mask:0xf
	v_fmac_f32_dpp v170, v163, v99 quad_perm:[0,0,0,0] row_mask:0xf bank_mask:0xf
	v_fmac_f32_dpp v124, v160, v100 quad_perm:[1,1,1,1] row_mask:0xf bank_mask:0xf
	v_fmac_f32_dpp v168, v161, v101 quad_perm:[1,1,1,1] row_mask:0xf bank_mask:0xf
	v_fmac_f32_dpp v169, v162, v102 quad_perm:[1,1,1,1] row_mask:0xf bank_mask:0xf
	v_fmac_f32_dpp v170, v163, v103 quad_perm:[1,1,1,1] row_mask:0xf bank_mask:0xf
	v_fmac_f32_dpp v124, v160, v104 quad_perm:[2,2,2,2] row_mask:0xf bank_mask:0xf
	v_fmac_f32_dpp v168, v161, v105 quad_perm:[2,2,2,2] row_mask:0xf bank_mask:0xf
	v_fmac_f32_dpp v169, v162, v106 quad_perm:[2,2,2,2] row_mask:0xf bank_mask:0xf
	v_fmac_f32_dpp v170, v163, v107 quad_perm:[2,2,2,2] row_mask:0xf bank_mask:0xf
	v_fmac_f32_dpp v124, v160, v108 quad_perm:[3,3,3,3] row_mask:0xf bank_mask:0xf
	v_fmac_f32_dpp v168, v161, v109 quad_perm:[3,3,3,3] row_mask:0xf bank_mask:0xf
	v_fmac_f32_dpp v169, v162, v110 quad_perm:[3,3,3,3] row_mask:0xf bank_mask:0xf
	v_fmac_f32_dpp v170, v163, v111 quad_perm:[3,3,3,3] row_mask:0xf bank_mask:0xf
	ds_read_b128 v[152:155], v10 offset:16864
	s_waitcnt lgkmcnt(5)
	v_fmac_f32_dpp v124, v164, v112 quad_perm:[0,0,0,0] row_mask:0xf bank_mask:0xf
	v_fmac_f32_dpp v168, v165, v113 quad_perm:[0,0,0,0] row_mask:0xf bank_mask:0xf
	v_fmac_f32_dpp v169, v166, v114 quad_perm:[0,0,0,0] row_mask:0xf bank_mask:0xf
	v_fmac_f32_dpp v170, v167, v115 quad_perm:[0,0,0,0] row_mask:0xf bank_mask:0xf
	v_fmac_f32_dpp v124, v164, v116 quad_perm:[1,1,1,1] row_mask:0xf bank_mask:0xf
	v_fmac_f32_dpp v168, v165, v117 quad_perm:[1,1,1,1] row_mask:0xf bank_mask:0xf
	v_fmac_f32_dpp v169, v166, v118 quad_perm:[1,1,1,1] row_mask:0xf bank_mask:0xf
	v_fmac_f32_dpp v170, v167, v119 quad_perm:[1,1,1,1] row_mask:0xf bank_mask:0xf
	v_fmac_f32_dpp v124, v164, v120 quad_perm:[2,2,2,2] row_mask:0xf bank_mask:0xf
	v_fmac_f32_dpp v168, v165, v121 quad_perm:[2,2,2,2] row_mask:0xf bank_mask:0xf
	v_fmac_f32_dpp v169, v166, v122 quad_perm:[2,2,2,2] row_mask:0xf bank_mask:0xf
	v_fmac_f32_dpp v170, v167, v123 quad_perm:[2,2,2,2] row_mask:0xf bank_mask:0xf
	v_add_f32_e32 v124, v124, v168
	v_add_f32_e32 v169, v169, v170
	v_add_f32_e32 v124, v124, v169
	ds_read_b128 v[156:159], v10 offset:16928
	s_waitcnt lgkmcnt(5)
; __device__ void dn_d1(const Ctx& c, int ip) {
;     ...
;       a3 -= m[3] * x[19];
;     }
;     { const f32x4 m = *(const f32x4*)(mr + 20);
;       a0 -= m[0] * x[20];
;       a1 -= m[1] * x[21];
;       a2 -= m[2] * x[22];
;       a3 -= m[3] * x[23];
;     }
;     { const f32x4 m = *(const f32x4*)(mr + 24);
;       a0 -= m[0] * x[24];
;       a1 -= m[1] * x[25];
;       a2 -= m[2] * x[26];
;       a3 -= m[3] * x[27];
;     }
;     { const f32x4 m = *(const f32x4*)(mr + 28);
;       a0 -= m[0] * x[28];
;       a1 -= m[1] * x[29];
;       a2 -= m[2] * x[30];
;       a3 -= m[3] * x[31];
;     }
;     { const f32x4 m = *(const f32x4*)(mr + 32);
;       a0 -= m[0] * x[32];
;       a1 -= m[1] * x[33];
;       a2 -= m[2] * x[34];
;       a3 -= m[3] * x[35];
;     }
;     { const f32x4 m = *(const f32x4*)(mr + 36);
;       a0 -= m[0] * x[36];
;       a1 -= m[1] * x[37];
;       a2 -= m[2] * x[38];
;       a3 -= m[3] * x[39];
;     }
;     { const f32x4 m = *(const f32x4*)(mr + 40);
;       a0 -= m[0] * x[40];
;       a1 -= m[1] * x[41];
;       a2 -= m[2] * x[42];
;       a3 -= m[3] * x[43];
;     }
;     { const f32x4 m = *(const f32x4*)(mr + 44);
;       a0 -= m[0] * x[44];
;       a1 -= m[1] * x[45];
;       a2 -= m[2] * x[46];
;       a3 -= m[3] * x[47];
;     }
;     { const f32x4 m = *(const f32x4*)(mr + 48);
;       a0 -= m[0] * x[48];
;       a1 -= m[1] * x[49];
;       a2 -= m[2] * x[50];
;       a3 -= m[3] * x[51];
;     }
;     { const f32x4 m = *(const f32x4*)(mr + 52);
;       a0 -= m[0] * x[52];
;       a1 -= m[1] * x[53];
;       a2 -= m[2] * x[54];
;       a3 -= m[3] * x[55];
;     }
;     { const f32x4 m = *(const f32x4*)(mr + 56);
;       a0 -= m[0] * x[56];
;       a1 -= m[1] * x[57];
;       a2 -= m[2] * x[58];
	v_mov_b32_e32 v168, 0
	v_mov_b32_e32 v169, 0
	v_mov_b32_e32 v170, 0
	v_fmac_f32_dpp v125, v136, v64 quad_perm:[0,0,0,0] row_mask:0xf bank_mask:0xf
	v_fmac_f32_dpp v168, v137, v65 quad_perm:[0,0,0,0] row_mask:0xf bank_mask:0xf
	v_fmac_f32_dpp v169, v138, v66 quad_perm:[0,0,0,0] row_mask:0xf bank_mask:0xf
	v_fmac_f32_dpp v170, v139, v67 quad_perm:[0,0,0,0] row_mask:0xf bank_mask:0xf
	v_fmac_f32_dpp v125, v136, v68 quad_perm:[1,1,1,1] row_mask:0xf bank_mask:0xf
	v_fmac_f32_dpp v168, v137, v69 quad_perm:[1,1,1,1] row_mask:0xf bank_mask:0xf
	v_fmac_f32_dpp v169, v138, v70 quad_perm:[1,1,1,1] row_mask:0xf bank_mask:0xf
	v_fmac_f32_dpp v170, v139, v71 quad_perm:[1,1,1,1] row_mask:0xf bank_mask:0xf
	v_fmac_f32_dpp v125, v136, v72 quad_perm:[2,2,2,2] row_mask:0xf bank_mask:0xf
	v_fmac_f32_dpp v168, v137, v73 quad_perm:[2,2,2,2] row_mask:0xf bank_mask:0xf
	v_fmac_f32_dpp v169, v138, v74 quad_perm:[2,2,2,2] row_mask:0xf bank_mask:0xf
	v_fmac_f32_dpp v170, v139, v75 quad_perm:[2,2,2,2] row_mask:0xf bank_mask:0xf
	v_fmac_f32_dpp v125, v136, v76 quad_perm:[3,3,3,3] row_mask:0xf bank_mask:0xf
	v_fmac_f32_dpp v168, v137, v77 quad_perm:[3,3,3,3] row_mask:0xf bank_mask:0xf
	v_fmac_f32_dpp v169, v138, v78 quad_perm:[3,3,3,3] row_mask:0xf bank_mask:0xf
	v_fmac_f32_dpp v170, v139, v79 quad_perm:[3,3,3,3] row_mask:0xf bank_mask:0xf
	ds_read_b128 v[160:163], v10 offset:16992
	s_waitcnt lgkmcnt(5)
	v_fmac_f32_dpp v125, v140, v80 quad_perm:[0,0,0,0] row_mask:0xf bank_mask:0xf
	v_fmac_f32_dpp v168, v141, v81 quad_perm:[0,0,0,0] row_mask:0xf bank_mask:0xf
	v_fmac_f32_dpp v169, v142, v82 quad_perm:[0,0,0,0] row_mask:0xf bank_mask:0xf
	v_fmac_f32_dpp v170, v143, v83 quad_perm:[0,0,0,0] row_mask:0xf bank_mask:0xf
	v_fmac_f32_dpp v125, v140, v84 quad_perm:[1,1,1,1] row_mask:0xf bank_mask:0xf
	v_fmac_f32_dpp v168, v141, v85 quad_perm:[1,1,1,1] row_mask:0xf bank_mask:0xf
	v_fmac_f32_dpp v169, v142, v86 quad_perm:[1,1,1,1] row_mask:0xf bank_mask:0xf
	v_fmac_f32_dpp v170, v143, v87 quad_perm:[1,1,1,1] row_mask:0xf bank_mask:0xf
	v_fmac_f32_dpp v125, v140, v88 quad_perm:[2,2,2,2] row_mask:0xf bank_mask:0xf
	v_fmac_f32_dpp v168, v141, v89 quad_perm:[2,2,2,2] row_mask:0xf bank_mask:0xf
	v_fmac_f32_dpp v169, v142, v90 quad_perm:[2,2,2,2] row_mask:0xf bank_mask:0xf
	v_fmac_f32_dpp v170, v143, v91 quad_perm:[2,2,2,2] row_mask:0xf bank_mask:0xf
	v_fmac_f32_dpp v125, v140, v92 quad_perm:[3,3,3,3] row_mask:0xf bank_mask:0xf
	v_fmac_f32_dpp v168, v141, v93 quad_perm:[3,3,3,3] row_mask:0xf bank_mask:0xf
	v_fmac_f32_dpp v169, v142, v94 quad_perm:[3,3,3,3] row_mask:0xf bank_mask:0xf
	v_fmac_f32_dpp v170, v143, v95 quad_perm:[3,3,3,3] row_mask:0xf bank_mask:0xf
	ds_read_b128 v[164:167], v10 offset:17056
	s_waitcnt lgkmcnt(5)
	v_fmac_f32_dpp v125, v144, v96 quad_perm:[0,0,0,0] row_mask:0xf bank_mask:0xf
	v_fmac_f32_dpp v168, v145, v97 quad_perm:[0,0,0,0] row_mask:0xf bank_mask:0xf
	v_fmac_f32_dpp v169, v146, v98 quad_perm:[0,0,0,0] row_mask:0xf bank_mask:0xf
	v_fmac_f32_dpp v170, v147, v99 quad_perm:[0,0,0,0] row_mask:0xf bank_mask:0xf
	v_fmac_f32_dpp v125, v144, v100 quad_perm:[1,1,1,1] row_mask:0xf bank_mask:0xf
	v_fmac_f32_dpp v168, v145, v101 quad_perm:[1,1,1,1] row_mask:0xf bank_mask:0xf
	v_fmac_f32_dpp v169, v146, v102 quad_perm:[1,1,1,1] row_mask:0xf bank_mask:0xf
	v_fmac_f32_dpp v170, v147, v103 quad_perm:[1,1,1,1] row_mask:0xf bank_mask:0xf
	v_fmac_f32_dpp v125, v144, v104 quad_perm:[2,2,2,2] row_mask:0xf bank_mask:0xf
	v_fmac_f32_dpp v168, v145, v105 quad_perm:[2,2,2,2] row_mask:0xf bank_mask:0xf
	v_fmac_f32_dpp v169, v146, v106 quad_perm:[2,2,2,2] row_mask:0xf bank_mask:0xf
	v_fmac_f32_dpp v170, v147, v107 quad_perm:[2,2,2,2] row_mask:0xf bank_mask:0xf
	v_fmac_f32_dpp v125, v144, v108 quad_perm:[3,3,3,3] row_mask:0xf bank_mask:0xf
	v_fmac_f32_dpp v168, v145, v109 quad_perm:[3,3,3,3] row_mask:0xf bank_mask:0xf
	v_fmac_f32_dpp v169, v146, v110 quad_perm:[3,3,3,3] row_mask:0xf bank_mask:0xf
	v_fmac_f32_dpp v170, v147, v111 quad_perm:[3,3,3,3] row_mask:0xf bank_mask:0xf
	ds_read_b128 v[136:139], v10 offset:17136
	s_waitcnt lgkmcnt(5)
	v_fmac_f32_dpp v125, v148, v112 quad_perm:[0,0,0,0] row_mask:0xf bank_mask:0xf
	v_fmac_f32_dpp v168, v149, v113 quad_perm:[0,0,0,0] row_mask:0xf bank_mask:0xf
	v_fmac_f32_dpp v169, v150, v114 quad_perm:[0,0,0,0] row_mask:0xf bank_mask:0xf
	v_fmac_f32_dpp v170, v151, v115 quad_perm:[0,0,0,0] row_mask:0xf bank_mask:0xf
	v_fmac_f32_dpp v125, v148, v116 quad_perm:[1,1,1,1] row_mask:0xf bank_mask:0xf
	v_fmac_f32_dpp v168, v149, v117 quad_perm:[1,1,1,1] row_mask:0xf bank_mask:0xf
	v_fmac_f32_dpp v169, v150, v118 quad_perm:[1,1,1,1] row_mask:0xf bank_mask:0xf
	v_fmac_f32_dpp v170, v151, v119 quad_perm:[1,1,1,1] row_mask:0xf bank_mask:0xf
	v_fmac_f32_dpp v125, v148, v120 quad_perm:[2,2,2,2] row_mask:0xf bank_mask:0xf
	v_fmac_f32_dpp v168, v149, v121 quad_perm:[2,2,2,2] row_mask:0xf bank_mask:0xf
	v_fmac_f32_dpp v169, v150, v122 quad_perm:[2,2,2,2] row_mask:0xf bank_mask:0xf
	v_fmac_f32_dpp v170, v151, v123 quad_perm:[2,2,2,2] row_mask:0xf bank_mask:0xf
	v_fmac_f32_dpp v125, v148, v124 quad_perm:[3,3,3,3] row_mask:0xf bank_mask:0xf
	v_add_f32_e32 v125, v125, v168
	v_add_f32_e32 v169, v169, v170
	v_add_f32_e32 v125, v125, v169
	ds_read_b128 v[140:143], v10 offset:17200
	s_waitcnt lgkmcnt(5)
; __device__ void dn_d1(const Ctx& c, int ip) {
;     ...
;       a2 -= m[2] * x[22];
;       a3 -= m[3] * x[23];
;     }
;     { const f32x4 m = *(const f32x4*)(mr + 24);
;       a0 -= m[0] * x[24];
;       a1 -= m[1] * x[25];
;       a2 -= m[2] * x[26];
;       a3 -= m[3] * x[27];
;     }
;     { const f32x4 m = *(const f32x4*)(mr + 28);
;       a0 -= m[0] * x[28];
;       a1 -= m[1] * x[29];
;       a2 -= m[2] * x[30];
;       a3 -= m[3] * x[31];
;     }
;     { const f32x4 m = *(const f32x4*)(mr + 32);
;       a0 -= m[0] * x[32];
;       a1 -= m[1] * x[33];
;       a2 -= m[2] * x[34];
;       a3 -= m[3] * x[35];
;     }
;     { const f32x4 m = *(const f32x4*)(mr + 36);
;       a0 -= m[0] * x[36];
;       a1 -= m[1] * x[37];
;       a2 -= m[2] * x[38];
;       a3 -= m[3] * x[39];
;     }
;     { const f32x4 m = *(const f32x4*)(mr + 40);
;       a0 -= m[0] * x[40];
;       a1 -= m[1] * x[41];
;       a2 -= m[2] * x[42];
;       a3 -= m[3] * x[43];
;     }
;     { const f32x4 m = *(const f32x4*)(mr + 44);
;       a0 -= m[0] * x[44];
;       a1 -= m[1] * x[45];
;       a2 -= m[2] * x[46];
;       a3 -= m[3] * x[47];
;     }
;     { const f32x4 m = *(const f32x4*)(mr + 48);
;       a0 -= m[0] * x[48];
;       a1 -= m[1] * x[49];
;       a2 -= m[2] * x[50];
;       a3 -= m[3] * x[51];
;     }
;     { const f32x4 m = *(const f32x4*)(mr + 52);
;       a0 -= m[0] * x[52];
;       a1 -= m[1] * x[53];
;       a2 -= m[2] * x[54];
;       a3 -= m[3] * x[55];
;     }
;     { const f32x4 m = *(const f32x4*)(mr + 56);
;       a0 -= m[0] * x[56];
;       a1 -= m[1] * x[57];
;       a2 -= m[2] * x[58];
;       a3 -= m[3] * x[59];
;     }
;     { const f32x4 m = *(const f32x4*)(mr + 60);
;       a0 -= m[0] * x[60];
;       a1 -= m[1] * x[61];
	v_mov_b32_e32 v168, 0
	v_mov_b32_e32 v169, 0
	v_mov_b32_e32 v170, 0
	v_fmac_f32_dpp v126, v152, v64 quad_perm:[0,0,0,0] row_mask:0xf bank_mask:0xf
	v_fmac_f32_dpp v168, v153, v65 quad_perm:[0,0,0,0] row_mask:0xf bank_mask:0xf
	v_fmac_f32_dpp v169, v154, v66 quad_perm:[0,0,0,0] row_mask:0xf bank_mask:0xf
	v_fmac_f32_dpp v170, v155, v67 quad_perm:[0,0,0,0] row_mask:0xf bank_mask:0xf
	v_fmac_f32_dpp v126, v152, v68 quad_perm:[1,1,1,1] row_mask:0xf bank_mask:0xf
	v_fmac_f32_dpp v168, v153, v69 quad_perm:[1,1,1,1] row_mask:0xf bank_mask:0xf
	v_fmac_f32_dpp v169, v154, v70 quad_perm:[1,1,1,1] row_mask:0xf bank_mask:0xf
	v_fmac_f32_dpp v170, v155, v71 quad_perm:[1,1,1,1] row_mask:0xf bank_mask:0xf
	v_fmac_f32_dpp v126, v152, v72 quad_perm:[2,2,2,2] row_mask:0xf bank_mask:0xf
	v_fmac_f32_dpp v168, v153, v73 quad_perm:[2,2,2,2] row_mask:0xf bank_mask:0xf
	v_fmac_f32_dpp v169, v154, v74 quad_perm:[2,2,2,2] row_mask:0xf bank_mask:0xf
	v_fmac_f32_dpp v170, v155, v75 quad_perm:[2,2,2,2] row_mask:0xf bank_mask:0xf
	v_fmac_f32_dpp v126, v152, v76 quad_perm:[3,3,3,3] row_mask:0xf bank_mask:0xf
	v_fmac_f32_dpp v168, v153, v77 quad_perm:[3,3,3,3] row_mask:0xf bank_mask:0xf
	v_fmac_f32_dpp v169, v154, v78 quad_perm:[3,3,3,3] row_mask:0xf bank_mask:0xf
	v_fmac_f32_dpp v170, v155, v79 quad_perm:[3,3,3,3] row_mask:0xf bank_mask:0xf
	ds_read_b128 v[144:147], v10 offset:17264
	s_waitcnt lgkmcnt(5)
	v_fmac_f32_dpp v126, v156, v80 quad_perm:[0,0,0,0] row_mask:0xf bank_mask:0xf
	v_fmac_f32_dpp v168, v157, v81 quad_perm:[0,0,0,0] row_mask:0xf bank_mask:0xf
	v_fmac_f32_dpp v169, v158, v82 quad_perm:[0,0,0,0] row_mask:0xf bank_mask:0xf
	v_fmac_f32_dpp v170, v159, v83 quad_perm:[0,0,0,0] row_mask:0xf bank_mask:0xf
	v_fmac_f32_dpp v126, v156, v84 quad_perm:[1,1,1,1] row_mask:0xf bank_mask:0xf
	v_fmac_f32_dpp v168, v157, v85 quad_perm:[1,1,1,1] row_mask:0xf bank_mask:0xf
	v_fmac_f32_dpp v169, v158, v86 quad_perm:[1,1,1,1] row_mask:0xf bank_mask:0xf
	v_fmac_f32_dpp v170, v159, v87 quad_perm:[1,1,1,1] row_mask:0xf bank_mask:0xf
	v_fmac_f32_dpp v126, v156, v88 quad_perm:[2,2,2,2] row_mask:0xf bank_mask:0xf
	v_fmac_f32_dpp v168, v157, v89 quad_perm:[2,2,2,2] row_mask:0xf bank_mask:0xf
	v_fmac_f32_dpp v169, v158, v90 quad_perm:[2,2,2,2] row_mask:0xf bank_mask:0xf
	v_fmac_f32_dpp v170, v159, v91 quad_perm:[2,2,2,2] row_mask:0xf bank_mask:0xf
	v_fmac_f32_dpp v126, v156, v92 quad_perm:[3,3,3,3] row_mask:0xf bank_mask:0xf
	v_fmac_f32_dpp v168, v157, v93 quad_perm:[3,3,3,3] row_mask:0xf bank_mask:0xf
	v_fmac_f32_dpp v169, v158, v94 quad_perm:[3,3,3,3] row_mask:0xf bank_mask:0xf
	v_fmac_f32_dpp v170, v159, v95 quad_perm:[3,3,3,3] row_mask:0xf bank_mask:0xf
	ds_read_b128 v[148:151], v10 offset:17328
	s_waitcnt lgkmcnt(5)
	v_fmac_f32_dpp v126, v160, v96 quad_perm:[0,0,0,0] row_mask:0xf bank_mask:0xf
	v_fmac_f32_dpp v168, v161, v97 quad_perm:[0,0,0,0] row_mask:0xf bank_mask:0xf
	v_fmac_f32_dpp v169, v162, v98 quad_perm:[0,0,0,0] row_mask:0xf bank_mask:0xf
	v_fmac_f32_dpp v170, v163, v99 quad_perm:[0,0,0,0] row_mask:0xf bank_mask:0xf
	v_fmac_f32_dpp v126, v160, v100 quad_perm:[1,1,1,1] row_mask:0xf bank_mask:0xf
	v_fmac_f32_dpp v168, v161, v101 quad_perm:[1,1,1,1] row_mask:0xf bank_mask:0xf
	v_fmac_f32_dpp v169, v162, v102 quad_perm:[1,1,1,1] row_mask:0xf bank_mask:0xf
	v_fmac_f32_dpp v170, v163, v103 quad_perm:[1,1,1,1] row_mask:0xf bank_mask:0xf
	v_fmac_f32_dpp v126, v160, v104 quad_perm:[2,2,2,2] row_mask:0xf bank_mask:0xf
	v_fmac_f32_dpp v168, v161, v105 quad_perm:[2,2,2,2] row_mask:0xf bank_mask:0xf
	v_fmac_f32_dpp v169, v162, v106 quad_perm:[2,2,2,2] row_mask:0xf bank_mask:0xf
	v_fmac_f32_dpp v170, v163, v107 quad_perm:[2,2,2,2] row_mask:0xf bank_mask:0xf
	v_fmac_f32_dpp v126, v160, v108 quad_perm:[3,3,3,3] row_mask:0xf bank_mask:0xf
	v_fmac_f32_dpp v168, v161, v109 quad_perm:[3,3,3,3] row_mask:0xf bank_mask:0xf
	v_fmac_f32_dpp v169, v162, v110 quad_perm:[3,3,3,3] row_mask:0xf bank_mask:0xf
	v_fmac_f32_dpp v170, v163, v111 quad_perm:[3,3,3,3] row_mask:0xf bank_mask:0xf
	s_waitcnt lgkmcnt(4)
	v_fmac_f32_dpp v126, v164, v112 quad_perm:[0,0,0,0] row_mask:0xf bank_mask:0xf
	v_fmac_f32_dpp v168, v165, v113 quad_perm:[0,0,0,0] row_mask:0xf bank_mask:0xf
	v_fmac_f32_dpp v169, v166, v114 quad_perm:[0,0,0,0] row_mask:0xf bank_mask:0xf
	v_fmac_f32_dpp v170, v167, v115 quad_perm:[0,0,0,0] row_mask:0xf bank_mask:0xf
	v_fmac_f32_dpp v126, v164, v116 quad_perm:[1,1,1,1] row_mask:0xf bank_mask:0xf
	v_fmac_f32_dpp v168, v165, v117 quad_perm:[1,1,1,1] row_mask:0xf bank_mask:0xf
	v_fmac_f32_dpp v169, v166, v118 quad_perm:[1,1,1,1] row_mask:0xf bank_mask:0xf
	v_fmac_f32_dpp v170, v167, v119 quad_perm:[1,1,1,1] row_mask:0xf bank_mask:0xf
	v_fmac_f32_dpp v126, v164, v120 quad_perm:[2,2,2,2] row_mask:0xf bank_mask:0xf
	v_fmac_f32_dpp v168, v165, v121 quad_perm:[2,2,2,2] row_mask:0xf bank_mask:0xf
	v_fmac_f32_dpp v169, v166, v122 quad_perm:[2,2,2,2] row_mask:0xf bank_mask:0xf
	v_fmac_f32_dpp v170, v167, v123 quad_perm:[2,2,2,2] row_mask:0xf bank_mask:0xf
	v_fmac_f32_dpp v126, v164, v124 quad_perm:[3,3,3,3] row_mask:0xf bank_mask:0xf
	v_fmac_f32_dpp v168, v165, v125 quad_perm:[3,3,3,3] row_mask:0xf bank_mask:0xf
	v_add_f32_e32 v126, v126, v168
	v_add_f32_e32 v169, v169, v170
	v_add_f32_e32 v126, v126, v169
	s_waitcnt lgkmcnt(3)
; __device__ __forceinline__ unsigned pk2(float lo, float hi) { const f32v2_t v = {lo, hi}; const bf16v2_t b = __builtin_convertvector(v, bf16v2_t); return __builtin_bit_cast(unsigned, b); }
;     template <class Tp> __device__ __forceinline__ Tp* W(size_t off) const { return (Tp*)(ws + off); }
; __device__ void dn_d1(const Ctx& c, int ip) {
;     ...
;       a0 -= m[0] * x[44];
;       a1 -= m[1] * x[45];
;       a2 -= m[2] * x[46];
;       a3 -= m[3] * x[47];
;     }
;     { const f32x4 m = *(const f32x4*)(mr + 48);
;       a0 -= m[0] * x[48];
;       a1 -= m[1] * x[49];
;       a2 -= m[2] * x[50];
;       a3 -= m[3] * x[51];
;     }
;     { const f32x4 m = *(const f32x4*)(mr + 52);
;       a0 -= m[0] * x[52];
;       a1 -= m[1] * x[53];
;       a2 -= m[2] * x[54];
;       a3 -= m[3] * x[55];
;     }
;     { const f32x4 m = *(const f32x4*)(mr + 56);
;       a0 -= m[0] * x[56];
;       a1 -= m[1] * x[57];
;       a2 -= m[2] * x[58];
;       a3 -= m[3] * x[59];
;     }
;     { const f32x4 m = *(const f32x4*)(mr + 60);
;       a0 -= m[0] * x[60];
;       a1 -= m[1] * x[61];
;       a2 -= m[2] * x[62];
;     }
;     SOLVE_ROW_END(63)
;     ...
;     } else { bf16_t* dUT = c.W<bf16_t>(WS_DUT);
; #pragma unroll
;         for (int l0 = 0; l0 < 64; l0 += 8) { u32x4 a; a.x = pk2(x[l0], x[l0 + 1]); a.y = pk2(x[l0 + 2], x[l0 + 3]); a.z = pk2(x[l0 + 4], x[l0 + 5]); a.w = pk2(x[l0 + 6], x[l0 + 7]);
;             *(u32x4*)(dUT + (ch * 128 + col) * 64 + l0) = a; } }
	v_mov_b32_e32 v168, 0
	v_mov_b32_e32 v169, 0
	v_mov_b32_e32 v170, 0
	v_fmac_f32_dpp v127, v136, v64 quad_perm:[0,0,0,0] row_mask:0xf bank_mask:0xf
	v_fmac_f32_dpp v168, v137, v65 quad_perm:[0,0,0,0] row_mask:0xf bank_mask:0xf
	v_fmac_f32_dpp v169, v138, v66 quad_perm:[0,0,0,0] row_mask:0xf bank_mask:0xf
	v_fmac_f32_dpp v170, v139, v67 quad_perm:[0,0,0,0] row_mask:0xf bank_mask:0xf
	v_fmac_f32_dpp v127, v136, v68 quad_perm:[1,1,1,1] row_mask:0xf bank_mask:0xf
	v_fmac_f32_dpp v168, v137, v69 quad_perm:[1,1,1,1] row_mask:0xf bank_mask:0xf
	v_fmac_f32_dpp v169, v138, v70 quad_perm:[1,1,1,1] row_mask:0xf bank_mask:0xf
	v_fmac_f32_dpp v170, v139, v71 quad_perm:[1,1,1,1] row_mask:0xf bank_mask:0xf
	v_fmac_f32_dpp v127, v136, v72 quad_perm:[2,2,2,2] row_mask:0xf bank_mask:0xf
	v_fmac_f32_dpp v168, v137, v73 quad_perm:[2,2,2,2] row_mask:0xf bank_mask:0xf
	v_fmac_f32_dpp v169, v138, v74 quad_perm:[2,2,2,2] row_mask:0xf bank_mask:0xf
	v_fmac_f32_dpp v170, v139, v75 quad_perm:[2,2,2,2] row_mask:0xf bank_mask:0xf
	v_fmac_f32_dpp v127, v136, v76 quad_perm:[3,3,3,3] row_mask:0xf bank_mask:0xf
	v_fmac_f32_dpp v168, v137, v77 quad_perm:[3,3,3,3] row_mask:0xf bank_mask:0xf
	v_fmac_f32_dpp v169, v138, v78 quad_perm:[3,3,3,3] row_mask:0xf bank_mask:0xf
	v_fmac_f32_dpp v170, v139, v79 quad_perm:[3,3,3,3] row_mask:0xf bank_mask:0xf
	s_waitcnt lgkmcnt(2)
	v_fmac_f32_dpp v127, v140, v80 quad_perm:[0,0,0,0] row_mask:0xf bank_mask:0xf
	v_fmac_f32_dpp v168, v141, v81 quad_perm:[0,0,0,0] row_mask:0xf bank_mask:0xf
	v_fmac_f32_dpp v169, v142, v82 quad_perm:[0,0,0,0] row_mask:0xf bank_mask:0xf
	v_fmac_f32_dpp v170, v143, v83 quad_perm:[0,0,0,0] row_mask:0xf bank_mask:0xf
	v_fmac_f32_dpp v127, v140, v84 quad_perm:[1,1,1,1] row_mask:0xf bank_mask:0xf
	v_fmac_f32_dpp v168, v141, v85 quad_perm:[1,1,1,1] row_mask:0xf bank_mask:0xf
	v_fmac_f32_dpp v169, v142, v86 quad_perm:[1,1,1,1] row_mask:0xf bank_mask:0xf
	v_fmac_f32_dpp v170, v143, v87 quad_perm:[1,1,1,1] row_mask:0xf bank_mask:0xf
	v_fmac_f32_dpp v127, v140, v88 quad_perm:[2,2,2,2] row_mask:0xf bank_mask:0xf
	v_fmac_f32_dpp v168, v141, v89 quad_perm:[2,2,2,2] row_mask:0xf bank_mask:0xf
	v_fmac_f32_dpp v169, v142, v90 quad_perm:[2,2,2,2] row_mask:0xf bank_mask:0xf
	v_fmac_f32_dpp v170, v143, v91 quad_perm:[2,2,2,2] row_mask:0xf bank_mask:0xf
	v_fmac_f32_dpp v127, v140, v92 quad_perm:[3,3,3,3] row_mask:0xf bank_mask:0xf
	v_fmac_f32_dpp v168, v141, v93 quad_perm:[3,3,3,3] row_mask:0xf bank_mask:0xf
	v_fmac_f32_dpp v169, v142, v94 quad_perm:[3,3,3,3] row_mask:0xf bank_mask:0xf
	v_fmac_f32_dpp v170, v143, v95 quad_perm:[3,3,3,3] row_mask:0xf bank_mask:0xf
	s_waitcnt lgkmcnt(1)
	v_fmac_f32_dpp v127, v144, v96 quad_perm:[0,0,0,0] row_mask:0xf bank_mask:0xf
	v_fmac_f32_dpp v168, v145, v97 quad_perm:[0,0,0,0] row_mask:0xf bank_mask:0xf
	v_fmac_f32_dpp v169, v146, v98 quad_perm:[0,0,0,0] row_mask:0xf bank_mask:0xf
	v_fmac_f32_dpp v170, v147, v99 quad_perm:[0,0,0,0] row_mask:0xf bank_mask:0xf
	v_fmac_f32_dpp v127, v144, v100 quad_perm:[1,1,1,1] row_mask:0xf bank_mask:0xf
	v_fmac_f32_dpp v168, v145, v101 quad_perm:[1,1,1,1] row_mask:0xf bank_mask:0xf
	v_fmac_f32_dpp v169, v146, v102 quad_perm:[1,1,1,1] row_mask:0xf bank_mask:0xf
	v_fmac_f32_dpp v170, v147, v103 quad_perm:[1,1,1,1] row_mask:0xf bank_mask:0xf
	v_fmac_f32_dpp v127, v144, v104 quad_perm:[2,2,2,2] row_mask:0xf bank_mask:0xf
	v_fmac_f32_dpp v168, v145, v105 quad_perm:[2,2,2,2] row_mask:0xf bank_mask:0xf
	v_fmac_f32_dpp v169, v146, v106 quad_perm:[2,2,2,2] row_mask:0xf bank_mask:0xf
	v_fmac_f32_dpp v170, v147, v107 quad_perm:[2,2,2,2] row_mask:0xf bank_mask:0xf
	v_fmac_f32_dpp v127, v144, v108 quad_perm:[3,3,3,3] row_mask:0xf bank_mask:0xf
	v_fmac_f32_dpp v168, v145, v109 quad_perm:[3,3,3,3] row_mask:0xf bank_mask:0xf
	v_fmac_f32_dpp v169, v146, v110 quad_perm:[3,3,3,3] row_mask:0xf bank_mask:0xf
	v_fmac_f32_dpp v170, v147, v111 quad_perm:[3,3,3,3] row_mask:0xf bank_mask:0xf
	s_waitcnt lgkmcnt(0)
	v_fmac_f32_dpp v127, v148, v112 quad_perm:[0,0,0,0] row_mask:0xf bank_mask:0xf
	v_fmac_f32_dpp v168, v149, v113 quad_perm:[0,0,0,0] row_mask:0xf bank_mask:0xf
	v_fmac_f32_dpp v169, v150, v114 quad_perm:[0,0,0,0] row_mask:0xf bank_mask:0xf
	v_fmac_f32_dpp v170, v151, v115 quad_perm:[0,0,0,0] row_mask:0xf bank_mask:0xf
	v_fmac_f32_dpp v127, v148, v116 quad_perm:[1,1,1,1] row_mask:0xf bank_mask:0xf
	v_fmac_f32_dpp v168, v149, v117 quad_perm:[1,1,1,1] row_mask:0xf bank_mask:0xf
	v_fmac_f32_dpp v169, v150, v118 quad_perm:[1,1,1,1] row_mask:0xf bank_mask:0xf
	v_fmac_f32_dpp v170, v151, v119 quad_perm:[1,1,1,1] row_mask:0xf bank_mask:0xf
	v_fmac_f32_dpp v127, v148, v120 quad_perm:[2,2,2,2] row_mask:0xf bank_mask:0xf
	v_fmac_f32_dpp v168, v149, v121 quad_perm:[2,2,2,2] row_mask:0xf bank_mask:0xf
	v_fmac_f32_dpp v169, v150, v122 quad_perm:[2,2,2,2] row_mask:0xf bank_mask:0xf
	v_fmac_f32_dpp v170, v151, v123 quad_perm:[2,2,2,2] row_mask:0xf bank_mask:0xf
	v_fmac_f32_dpp v127, v148, v124 quad_perm:[3,3,3,3] row_mask:0xf bank_mask:0xf
	v_fmac_f32_dpp v168, v149, v125 quad_perm:[3,3,3,3] row_mask:0xf bank_mask:0xf
	v_fmac_f32_dpp v169, v150, v126 quad_perm:[3,3,3,3] row_mask:0xf bank_mask:0xf
	v_add_f32_e32 v127, v127, v168
	v_add_f32_e32 v169, v169, v170
	v_add_f32_e32 v127, v127, v169
	s_cmp_lg_u32 s30, 0
	s_cbranch_scc1 .Ldnd_wout
	v_and_b32_e32 v12, 0x7f, v0
	s_lshl_b32 s22, s14, 7
	v_add_u32_e32 v12, s22, v12
	v_lshlrev_b32_e32 v11, 7, v12
	v_add_u32_e32 v11, 0x23100000, v11
	v_cvt_pk_bf16_f32 v136, v64, v65
	v_cvt_pk_bf16_f32 v137, v66, v67
	v_cvt_pk_bf16_f32 v138, v68, v69
	v_cvt_pk_bf16_f32 v139, v70, v71
	global_store_dwordx4 v11, v[136:139], s[4:5] offset:0
	v_cvt_pk_bf16_f32 v140, v72, v73
	v_cvt_pk_bf16_f32 v141, v74, v75
	v_cvt_pk_bf16_f32 v142, v76, v77
	v_cvt_pk_bf16_f32 v143, v78, v79
	global_store_dwordx4 v11, v[140:143], s[4:5] offset:16
	v_cvt_pk_bf16_f32 v136, v80, v81
	v_cvt_pk_bf16_f32 v137, v82, v83
	v_cvt_pk_bf16_f32 v138, v84, v85
	v_cvt_pk_bf16_f32 v139, v86, v87
	global_store_dwordx4 v11, v[136:139], s[4:5] offset:32
	v_cvt_pk_bf16_f32 v140, v88, v89
	v_cvt_pk_bf16_f32 v141, v90, v91
	v_cvt_pk_bf16_f32 v142, v92, v93
	v_cvt_pk_bf16_f32 v143, v94, v95
	global_store_dwordx4 v11, v[140:143], s[4:5] offset:48
	v_cvt_pk_bf16_f32 v136, v96, v97
	v_cvt_pk_bf16_f32 v137, v98, v99
	v_cvt_pk_bf16_f32 v138, v100, v101
	v_cvt_pk_bf16_f32 v139, v102, v103
	global_store_dwordx4 v11, v[136:139], s[4:5] offset:64
	v_cvt_pk_bf16_f32 v140, v104, v105
	v_cvt_pk_bf16_f32 v141, v106, v107
	v_cvt_pk_bf16_f32 v142, v108, v109
	v_cvt_pk_bf16_f32 v143, v110, v111
	global_store_dwordx4 v11, v[140:143], s[4:5] offset:80
	v_cvt_pk_bf16_f32 v136, v112, v113
	v_cvt_pk_bf16_f32 v137, v114, v115
	v_cvt_pk_bf16_f32 v138, v116, v117
	v_cvt_pk_bf16_f32 v139, v118, v119
	global_store_dwordx4 v11, v[136:139], s[4:5] offset:96
	v_cvt_pk_bf16_f32 v140, v120, v121
	v_cvt_pk_bf16_f32 v141, v122, v123
	v_cvt_pk_bf16_f32 v142, v124, v125
	v_cvt_pk_bf16_f32 v143, v126, v127
	global_store_dwordx4 v11, v[140:143], s[4:5] offset:112
	s_branch .Ldnd_wsync
;     template <class Tp> __device__ __forceinline__ Tp* W(size_t off) const { return (Tp*)(ws + off); }
; __device__ void dn_d1(const Ctx& c, int ip) {
;     ...
;     if (isw) { bf16_t* dW = c.W<bf16_t>(WS_DW);
; #pragma unroll
;         for (int i = 0; i < 64; ++i) dW[(ch * 64 + i) * 128 + col] = f2bf(x[i]);
; __device__ __forceinline__ void run_phase(int ph, unsigned char* ldsraw) {
;     ...
;             dn_d1(c, ck * 4 + half * 2); dn_d1(c, ck * 4 + half * 2 + 1);
.Ldnd_wout:
	v_and_b32_e32 v12, 0x7f, v0
	v_lshl_add_u32 v12, v12, 1, s24
	v_cvt_pk_bf16_f32 v13, v64, v65
	ds_write_b16 v12, v13 offset:17408
	ds_write_b16_d16_hi v12, v13 offset:17680
	v_cvt_pk_bf16_f32 v14, v66, v67
	ds_write_b16 v12, v14 offset:17952
	ds_write_b16_d16_hi v12, v14 offset:18224
	v_cvt_pk_bf16_f32 v13, v68, v69
	ds_write_b16 v12, v13 offset:18496
	ds_write_b16_d16_hi v12, v13 offset:18768
	v_cvt_pk_bf16_f32 v14, v70, v71
	ds_write_b16 v12, v14 offset:19040
	ds_write_b16_d16_hi v12, v14 offset:19312
	v_cvt_pk_bf16_f32 v13, v72, v73
	ds_write_b16 v12, v13 offset:19584
	ds_write_b16_d16_hi v12, v13 offset:19856
	v_cvt_pk_bf16_f32 v14, v74, v75
	ds_write_b16 v12, v14 offset:20128
	ds_write_b16_d16_hi v12, v14 offset:20400
	v_cvt_pk_bf16_f32 v13, v76, v77
	ds_write_b16 v12, v13 offset:20672
	ds_write_b16_d16_hi v12, v13 offset:20944
	v_cvt_pk_bf16_f32 v14, v78, v79
	ds_write_b16 v12, v14 offset:21216
	ds_write_b16_d16_hi v12, v14 offset:21488
	v_cvt_pk_bf16_f32 v13, v80, v81
	ds_write_b16 v12, v13 offset:21760
	ds_write_b16_d16_hi v12, v13 offset:22032
	v_cvt_pk_bf16_f32 v14, v82, v83
	ds_write_b16 v12, v14 offset:22304
	ds_write_b16_d16_hi v12, v14 offset:22576
	v_cvt_pk_bf16_f32 v13, v84, v85
	ds_write_b16 v12, v13 offset:22848
	ds_write_b16_d16_hi v12, v13 offset:23120
	v_cvt_pk_bf16_f32 v14, v86, v87
	ds_write_b16 v12, v14 offset:23392
	ds_write_b16_d16_hi v12, v14 offset:23664
	v_cvt_pk_bf16_f32 v13, v88, v89
	ds_write_b16 v12, v13 offset:23936
	ds_write_b16_d16_hi v12, v13 offset:24208
	v_cvt_pk_bf16_f32 v14, v90, v91
	ds_write_b16 v12, v14 offset:24480
	ds_write_b16_d16_hi v12, v14 offset:24752
	v_cvt_pk_bf16_f32 v13, v92, v93
	ds_write_b16 v12, v13 offset:25024
	ds_write_b16_d16_hi v12, v13 offset:25296
	v_cvt_pk_bf16_f32 v14, v94, v95
	ds_write_b16 v12, v14 offset:25568
	ds_write_b16_d16_hi v12, v14 offset:25840
	v_cvt_pk_bf16_f32 v13, v96, v97
	ds_write_b16 v12, v13 offset:26112
	ds_write_b16_d16_hi v12, v13 offset:26384
	v_cvt_pk_bf16_f32 v14, v98, v99
	ds_write_b16 v12, v14 offset:26656
	ds_write_b16_d16_hi v12, v14 offset:26928
	v_cvt_pk_bf16_f32 v13, v100, v101
	ds_write_b16 v12, v13 offset:27200
	ds_write_b16_d16_hi v12, v13 offset:27472
	v_cvt_pk_bf16_f32 v14, v102, v103
	ds_write_b16 v12, v14 offset:27744
	ds_write_b16_d16_hi v12, v14 offset:28016
	v_cvt_pk_bf16_f32 v13, v104, v105
	ds_write_b16 v12, v13 offset:28288
	ds_write_b16_d16_hi v12, v13 offset:28560
	v_cvt_pk_bf16_f32 v14, v106, v107
	ds_write_b16 v12, v14 offset:28832
	ds_write_b16_d16_hi v12, v14 offset:29104
	v_cvt_pk_bf16_f32 v13, v108, v109
	ds_write_b16 v12, v13 offset:29376
	ds_write_b16_d16_hi v12, v13 offset:29648
	v_cvt_pk_bf16_f32 v14, v110, v111
	ds_write_b16 v12, v14 offset:29920
	ds_write_b16_d16_hi v12, v14 offset:30192
	v_cvt_pk_bf16_f32 v13, v112, v113
	ds_write_b16 v12, v13 offset:30464
	ds_write_b16_d16_hi v12, v13 offset:30736
	v_cvt_pk_bf16_f32 v14, v114, v115
	ds_write_b16 v12, v14 offset:31008
	ds_write_b16_d16_hi v12, v14 offset:31280
	v_cvt_pk_bf16_f32 v13, v116, v117
	ds_write_b16 v12, v13 offset:31552
	ds_write_b16_d16_hi v12, v13 offset:31824
	v_cvt_pk_bf16_f32 v14, v118, v119
	ds_write_b16 v12, v14 offset:32096
	ds_write_b16_d16_hi v12, v14 offset:32368
	v_cvt_pk_bf16_f32 v13, v120, v121
	ds_write_b16 v12, v13 offset:32640
	ds_write_b16_d16_hi v12, v13 offset:32912
	v_cvt_pk_bf16_f32 v14, v122, v123
	ds_write_b16 v12, v14 offset:33184
	ds_write_b16_d16_hi v12, v14 offset:33456
	v_cvt_pk_bf16_f32 v13, v124, v125
	ds_write_b16 v12, v13 offset:33728
	ds_write_b16_d16_hi v12, v13 offset:34000
	v_cvt_pk_bf16_f32 v14, v126, v127
	ds_write_b16 v12, v14 offset:34272
	ds_write_b16_d16_hi v12, v14 offset:34544
.Ldnd_wsync:
	s_waitcnt lgkmcnt(0)
	s_barrier
	ds_read_b128 v[16:19], v6 offset:17408
	ds_read_b128 v[20:23], v6 offset:21760
	ds_read_b128 v[24:27], v6 offset:26112
	ds_read_b128 v[28:31], v6 offset:30464
	s_waitcnt lgkmcnt(0)
	v_add_u32_e32 v12, 0x22100000, v7
	global_store_dwordx4 v12, v[16:19], s[4:5]
	v_add_u32_e32 v12, 0x22101000, v7
	global_store_dwordx4 v12, v[20:23], s[4:5]
	v_add_u32_e32 v12, 0x22102000, v7
	global_store_dwordx4 v12, v[24:27], s[4:5]
	v_add_u32_e32 v12, 0x22103000, v7
	global_store_dwordx4 v12, v[28:31], s[4:5]
	s_add_u32 s12, s12, 1
	s_cmp_lt_u32 s12, 2
	s_cbranch_scc1 .Ldnd_call
	s_waitcnt vmcnt(0) lgkmcnt(0)
	s_barrier
